# GEMM K-loops as 4 merged phases (8 barriers per 128 MFMA) plus prologue waits for all of K-tile 0 before the stagger barrier
# speedup vs baseline: 1.0132x; 1.0132x over previous
; #define PG8_STAGE(bufoff, gbase, voff) do { _Pragma("unroll") for (int _i = 0; _i < 2; ++_i) \
;         __builtin_amdgcn_global_load_lds((const unsigned*)((const char*)(gbase) + (voff)[_i]), (LAS unsigned*)(lds + (bufoff) + ldsw + _i * 8192), 16, 0, 0); } while (0)
; #define PG8_WAIT_V(n) asm volatile("s_waitcnt vmcnt(" #n ")" ::: "memory")
; #define PG8_BAR __builtin_amdgcn_s_barrier()
; template <class Epi, class AMap>
; __device__ __forceinline__ void gemm_phase(LAS unsigned char* lds, const AMap am, const int lda, const h16* Bt, const int ldb, const int M, const int N, const int K, const Epi& E) {
;     ...
;     for (int i = 0; i < 2; ++i) { int R, C; stage_rc(tid * 16 + i * 8192, R, C); const int Rb = Epi::PERM ? ((R & ~31) + perm32(R & 31)) : R;
;         voffA[i] = (unsigned)(R * lda + C) * 2u; voffB[i] = (unsigned)(Rb * ldb + C) * 2u; }
;     const size_t kstep = (size_t)(BK * 2);
;     const size_t hstepA = (size_t)HALF * lda * 2, hstepB = (size_t)HALF * ldb * 2;
;     const size_t tstepA = 2 * hstepA, tstepB = 2 * hstepB;
;     const unsigned ldsw = (unsigned)wid * 1024u;
;     const int aoff = lds_byte(wr * 64 + fr, fq * 8), boff = lds_byte(wc * 32 + fr, fq * 8);
;     ...
;     const char* cA = am(cur.pn) + (size_t)cur.pm * tstepA; const char* cB = (const char*)Bt + (size_t)cur.pn * tstepB;
;     PG8_STAGE(PG8_SB(0, 0), cB, voffB); PG8_STAGE(PG8_SA(0, 0), cA, voffA); PG8_STAGE(PG8_SB(0, 1), cB + hstepB, voffB); PG8_STAGE(PG8_SA(0, 1), cA + hstepA, voffA);
;     if (wr == 1) PG8_BAR;
;     PG8_WAIT_V(4); PG8_BAR;
;     PG8_STAGE(PG8_SB(1, 0), cB + kstep, voffB); PG8_STAGE(PG8_SA(1, 0), cA + kstep, voffA); PG8_STAGE(PG8_SB(1, 1), cB + hstepB + kstep, voffB);
;     PG8_WAIT_V(6); PG8_BAR;
.LBB0_49:
	v_lshrrev_b32_e32 v20, 1, v10
	s_lshr_b32 s20, s20, 2
	v_and_b32_e32 v20, 24, v20
	s_lshl_b32 s0, s0, 5
	s_sext_i32_i8 s50, s20
	v_and_b32_e32 v11, 15, v10
	v_lshlrev_b32_e32 v21, 1, v20
	v_lshlrev_b32_e32 v10, 2, v10
	s_and_b32 s20, s0, 0x60
	v_lshl_add_u64 v[12:13], s[26:27], 0, v[0:1]
	v_mov_b32_e32 v135, v1
	v_lshl_or_b32 v146, s1, 6, v11
	v_lshl_or_b32 v11, v11, 6, v21
	s_lshl_b32 s1, s1, 13
	v_and_b32_e32 v10, 32, v10
	s_lshl_b32 s0, s20, 7
	v_lshl_add_u64 v[14:15], s[26:27], 0, v[134:135]
	v_mov_b32_e32 v131, v1
	v_bitop3_b32 v21, v11, s1, v10 bitop3:0xde
	v_bitop3_b32 v147, v11, s0, v10 bitop3:0xde
	s_add_i32 m0, s63, 0x18000
	v_lshl_add_u64 v[10:11], v[12:13], 0, s[92:93]
	v_lshl_add_u64 v[16:17], s[22:23], 0, v[130:131]
	v_mov_b32_e32 v133, v1
	s_waitcnt vmcnt(0)
	s_barrier
	global_load_lds_dwordx4 v[10:11], off
	v_lshl_add_u64 v[10:11], v[14:15], 0, s[92:93]
	s_add_i32 m0, s63, 0x1a000
	s_add_i32 s69, s63, 0x8000
	s_add_i32 s70, s63, 0xa000
	v_lshl_add_u64 v[18:19], s[22:23], 0, v[132:133]
	global_load_lds_dwordx4 v[10:11], off
	v_lshl_add_u64 v[10:11], v[16:17], 0, s[92:93]
	s_mov_b32 m0, s69
	s_add_u32 s0, s26, 0x158080
	global_load_lds_dwordx4 v[10:11], off
	v_lshl_add_u64 v[10:11], v[18:19], 0, s[92:93]
	s_mov_b32 m0, s70
	s_addc_u32 s1, s27, 0
	global_load_lds_dwordx4 v[10:11], off
	s_add_i32 m0, s63, 0x1c000
	v_lshl_add_u64 v[10:11], s[0:1], 0, v[0:1]
	global_load_lds_dwordx4 v[10:11], off
	v_lshl_add_u64 v[10:11], s[0:1], 0, v[134:135]
	s_add_i32 m0, s63, 0x1e000
	s_mov_b32 s4, 0x15800
	global_load_lds_dwordx4 v[10:11], off
	v_lshrrev_b32_e32 v10, 1, v2
	v_mul_lo_u32 v2, v4, s3
	v_mad_u64_u32 v[10:11], s[0:1], v10, s4, v[2:3]
	v_or_b32_e32 v2, v10, v3
	v_add_lshl_u32 v2, v2, v5, 1
	v_mov_b32_e32 v3, v1
	s_mov_b64 s[6:7], 0x158080
	v_lshl_add_u64 v[136:137], v[2:3], 0, s[6:7]
	v_lshrrev_b32_e32 v3, 1, v6
	v_mul_lo_u32 v2, v8, s3
	v_mad_u64_u32 v[2:3], s[0:1], v3, s4, v[2:3]
	s_waitcnt vmcnt(6)
	v_or_b32_e32 v2, v2, v7
	v_add_lshl_u32 v2, v2, v9, 1
	v_mov_b32_e32 v3, v1
	v_or_b32_e32 v148, s20, v20
	v_lshl_add_u64 v[138:139], v[2:3], 0, s[6:7]
	s_mov_b32 s71, 0
	v_add_u32_e32 v149, 0, v21
	s_mov_b64 s[6:7], s[40:41]
	s_barrier

; #define PG8_STAGE(bufoff, gbase, voff) do { _Pragma("unroll") for (int _i = 0; _i < 2; ++_i) \
;         __builtin_amdgcn_global_load_lds((const unsigned*)((const char*)(gbase) + (voff)[_i]), (LAS unsigned*)(lds + (bufoff) + ldsw + _i * 8192), 16, 0, 0); } while (0)
; #define PG8_LDA(dst, b, h) do { _Pragma("unroll") for (int m = 0; m < 4; ++m) _Pragma("unroll") for (int k = 0; k < 2; ++k) dst[m][k] = *(const LAS h16x8*)(lds + PG8_SA(b, h) + aoff + m * 2048 + k * 1024); } while (0)
; #define PG8_LDB(dst, b, h) do { _Pragma("unroll") for (int n = 0; n < 2; ++n) _Pragma("unroll") for (int k = 0; k < 2; ++k) dst[n][k] = *(const LAS h16x8*)(lds + PG8_SB(b, h) + boff + n * 2048 + k * 1024); } while (0)
; #define PG8_MMA(ai, bj, At, Bt_) do { __builtin_amdgcn_s_setprio(1); _Pragma("unroll") for (int m = 0; m < 4; ++m) _Pragma("unroll") for (int n = 0; n < 2; ++n) _Pragma("unroll") for (int k = 0; k < 2; ++k) \
;         acc[ai][bj][m][n] = __builtin_amdgcn_mfma_f32_16x16x32_f16(Bt_[n][k], At[m][k], acc[ai][bj][m][n], 0, 0, 0); __builtin_amdgcn_s_setprio(0); } while (0)
; #define PG8_WAIT_V(n) asm volatile("s_waitcnt vmcnt(" #n ")" ::: "memory")
; template <class Epi, class AMap>
; __device__ __forceinline__ void gemm_phase(LAS unsigned char* lds, const AMap am, const int lda, const h16* Bt, const int ldb, const int M, const int N, const int K, const Epi& E) {
;     ...
;         for (int t = 0; t < nt; t += 2) {
;             const bool last = (t == nt - 2);
;             const char* a1 = cA + (size_t)(t + 1) * kstep;
;             const char* a2 = last ? nA : cA + (size_t)(t + 2) * kstep; const char* b2 = last ? nB : cB + (size_t)(t + 2) * kstep;
;             const char* a3 = a2 + kstep; const char* b3 = b2 + kstep;
;             PG8_LDB(B0, 0, 0); PG8_SCHED; PG8_LDA(At, 0, 0); PG8_STAGE(PG8_SA(1, 1), a1 + hstepA, voffA);
;             PG8_WAIT_L(8); PG8_BAR; PG8_WAIT_L(0); PG8_MMA(0, 0, At, B0); PG8_BAR; PG8_SCHED;
;             PG8_LDB(B1, 0, 1); PG8_STAGE(PG8_SB(0, 0), b2, voffB);
;             PG8_BAR; PG8_WAIT_L(0); PG8_MMA(0, 1, At, B1); PG8_BAR;
;             PG8_LDA(At, 0, 1); PG8_STAGE(PG8_SA(0, 0), a2, voffA);
;             PG8_BAR; PG8_WAIT_L(0); PG8_MMA(1, 0, At, B0); PG8_BAR; PG8_SCHED;
;             PG8_STAGE(PG8_SB(0, 1), b2 + hstepB, voffB);
;             PG8_WAIT_V(6); PG8_BAR; PG8_MMA(1, 1, At, B1); PG8_BAR;
.LBB0_61:
	s_add_u32 s26, s22, 0x100
	s_addc_u32 s27, s23, 0
	s_add_i32 s51, 0, 0x10000
	v_add_u32_e32 v144, s51, v147
	ds_read_b128 v[140:143], v144
	ds_read_b128 v[150:153], v144 offset:1024
	ds_read_b128 v[154:157], v144 offset:2048
	ds_read_b128 v[158:161], v144 offset:3072
	s_cmpk_eq_i32 s29, 0x52
	s_cselect_b32 s45, s1, s27
	s_cselect_b32 s44, s0, s26
	s_cselect_b32 s43, s41, s21
	s_cselect_b32 s42, s40, s20
	v_lshl_add_u64 v[144:145], s[22:23], 0, v[136:137]
	s_add_i32 m0, s63, 0xc000
	ds_read_b128 v[162:165], v149
	ds_read_b128 v[166:169], v149 offset:1024
	ds_read_b128 v[170:173], v149 offset:2048
	ds_read_b128 v[174:177], v149 offset:3072
	ds_read_b128 v[178:181], v149 offset:4096
	ds_read_b128 v[182:185], v149 offset:5120
	ds_read_b128 v[186:189], v149 offset:6144
	ds_read_b128 v[190:193], v149 offset:7168
	global_load_lds_dwordx4 v[144:145], off
	v_lshl_add_u64 v[144:145], s[22:23], 0, v[138:139]
	s_add_i32 m0, s63, 0xe000
	s_nop 0
	global_load_lds_dwordx4 v[144:145], off
	s_waitcnt lgkmcnt(11)
	s_add_i32 s60, 0, 0x14000
	v_add_u32_e32 v144, s60, v147
	s_add_i32 s22, s51, s48
	ds_read_b128 v[194:197], v144
	ds_read_b128 v[198:201], v144 offset:1024
	ds_read_b128 v[202:205], v144 offset:2048
	ds_read_b128 v[220:223], v144 offset:3072
	s_waitcnt lgkmcnt(0)
	s_barrier
	v_mfma_f32_16x16x32_f16 v[126:129], v[140:143], v[162:165], v[126:129]
	v_mfma_f32_16x16x32_f16 v[122:125], v[154:157], v[162:165], v[122:125]
	v_mfma_f32_16x16x32_f16 v[110:113], v[140:143], v[170:173], v[110:113]
	v_mfma_f32_16x16x32_f16 v[106:109], v[154:157], v[170:173], v[106:109]
	v_mfma_f32_16x16x32_f16 v[94:97], v[140:143], v[178:181], v[94:97]
	v_mfma_f32_16x16x32_f16 v[90:93], v[154:157], v[178:181], v[90:93]
	v_mfma_f32_16x16x32_f16 v[78:81], v[140:143], v[186:189], v[78:81]
	v_mfma_f32_16x16x32_f16 v[74:77], v[154:157], v[186:189], v[74:77]
	v_mfma_f32_16x16x32_f16 v[126:129], v[150:153], v[166:169], v[126:129]
	v_mfma_f32_16x16x32_f16 v[122:125], v[158:161], v[166:169], v[122:125]
	v_mfma_f32_16x16x32_f16 v[110:113], v[150:153], v[174:177], v[110:113]
	v_mfma_f32_16x16x32_f16 v[106:109], v[158:161], v[174:177], v[106:109]
	v_mfma_f32_16x16x32_f16 v[94:97], v[150:153], v[182:185], v[94:97]
	v_mfma_f32_16x16x32_f16 v[90:93], v[158:161], v[182:185], v[90:93]
	v_mfma_f32_16x16x32_f16 v[78:81], v[150:153], v[190:193], v[78:81]
	v_mfma_f32_16x16x32_f16 v[74:77], v[158:161], v[190:193], v[74:77]
	v_mfma_f32_16x16x32_f16 v[118:121], v[194:197], v[162:165], v[118:121]
	v_mfma_f32_16x16x32_f16 v[114:117], v[202:205], v[162:165], v[114:117]
	v_mfma_f32_16x16x32_f16 v[102:105], v[194:197], v[170:173], v[102:105]
	v_mfma_f32_16x16x32_f16 v[98:101], v[202:205], v[170:173], v[98:101]
	v_mfma_f32_16x16x32_f16 v[86:89], v[194:197], v[178:181], v[86:89]
	v_mfma_f32_16x16x32_f16 v[82:85], v[202:205], v[178:181], v[82:85]
	v_mfma_f32_16x16x32_f16 v[70:73], v[194:197], v[186:189], v[70:73]
	v_mfma_f32_16x16x32_f16 v[66:69], v[202:205], v[186:189], v[66:69]
	v_mfma_f32_16x16x32_f16 v[118:121], v[198:201], v[166:169], v[118:121]
	v_mfma_f32_16x16x32_f16 v[114:117], v[220:223], v[166:169], v[114:117]
	v_mfma_f32_16x16x32_f16 v[102:105], v[198:201], v[174:177], v[102:105]
	v_mfma_f32_16x16x32_f16 v[98:101], v[220:223], v[174:177], v[98:101]
	v_mfma_f32_16x16x32_f16 v[86:89], v[198:201], v[182:185], v[86:89]
	v_mfma_f32_16x16x32_f16 v[82:85], v[220:223], v[182:185], v[82:85]
	v_mfma_f32_16x16x32_f16 v[70:73], v[198:201], v[190:193], v[70:73]
	v_mfma_f32_16x16x32_f16 v[66:69], v[220:223], v[190:193], v[66:69]
	s_barrier
	v_lshl_add_u64 v[144:145], s[42:43], 0, v[0:1]
	s_mov_b32 m0, s22
	v_lshl_add_u64 v[206:207], s[42:43], 0, v[134:135]
	global_load_lds_dwordx4 v[144:145], off
	s_add_i32 m0, s22, 0x2000
	s_nop 0
	global_load_lds_dwordx4 v[206:207], off
	s_mov_b32 m0, s63
	v_lshl_add_u64 v[212:213], s[44:45], 0, v[130:131]
	ds_read_b128 v[162:165], v149 offset:16384
	ds_read_b128 v[166:169], v149 offset:17408
	ds_read_b128 v[170:173], v149 offset:18432
	ds_read_b128 v[174:177], v149 offset:19456
	ds_read_b128 v[178:181], v149 offset:20480
	ds_read_b128 v[182:185], v149 offset:21504
	ds_read_b128 v[186:189], v149 offset:22528
	ds_read_b128 v[190:193], v149 offset:23552
	global_load_lds_dwordx4 v[212:213], off
	v_lshl_add_u64 v[214:215], s[44:45], 0, v[132:133]
	s_mov_b32 m0, s64
	s_nop 0
	global_load_lds_dwordx4 v[214:215], off
	s_add_u32 s22, s42, 0x158000
	s_addc_u32 s23, s43, 0
	s_add_i32 s51, s60, s48
	v_lshl_add_u64 v[232:233], s[22:23], 0, v[0:1]
	s_mov_b32 m0, s51
	s_nop 0
	global_load_lds_dwordx4 v[232:233], off
	v_lshl_add_u64 v[232:233], s[22:23], 0, v[134:135]
	s_add_i32 m0, s51, 0x2000
	s_nop 0
	global_load_lds_dwordx4 v[232:233], off
	s_waitcnt vmcnt(6) lgkmcnt(0)
	s_barrier
; #define PG8_STAGE(bufoff, gbase, voff) do { _Pragma("unroll") for (int _i = 0; _i < 2; ++_i) \
;         __builtin_amdgcn_global_load_lds((const unsigned*)((const char*)(gbase) + (voff)[_i]), (LAS unsigned*)(lds + (bufoff) + ldsw + _i * 8192), 16, 0, 0); } while (0)
; #define PG8_LDA(dst, b, h) do { _Pragma("unroll") for (int m = 0; m < 4; ++m) _Pragma("unroll") for (int k = 0; k < 2; ++k) dst[m][k] = *(const LAS h16x8*)(lds + PG8_SA(b, h) + aoff + m * 2048 + k * 1024); } while (0)
; #define PG8_LDB(dst, b, h) do { _Pragma("unroll") for (int n = 0; n < 2; ++n) _Pragma("unroll") for (int k = 0; k < 2; ++k) dst[n][k] = *(const LAS h16x8*)(lds + PG8_SB(b, h) + boff + n * 2048 + k * 1024); } while (0)
; #define PG8_MMA(ai, bj, At, Bt_) do { __builtin_amdgcn_s_setprio(1); _Pragma("unroll") for (int m = 0; m < 4; ++m) _Pragma("unroll") for (int n = 0; n < 2; ++n) _Pragma("unroll") for (int k = 0; k < 2; ++k) \
;         acc[ai][bj][m][n] = __builtin_amdgcn_mfma_f32_16x16x32_f16(Bt_[n][k], At[m][k], acc[ai][bj][m][n], 0, 0, 0); __builtin_amdgcn_s_setprio(0); } while (0)
; #define PG8_WAIT_V(n) asm volatile("s_waitcnt vmcnt(" #n ")" ::: "memory")
; #define PG8_WAIT_L(n) asm volatile("s_waitcnt lgkmcnt(" #n ")" ::: "memory")
; #define PG8_BAR __builtin_amdgcn_s_barrier()
; #define PG8_SCHED __builtin_amdgcn_sched_barrier(0)
; template <class Epi, class AMap>
; __device__ __forceinline__ void gemm_phase(LAS unsigned char* lds, const AMap am, const int lda, const h16* Bt, const int ldb, const int M, const int N, const int K, const Epi& E) {
;     ...
;             PG8_BAR; PG8_WAIT_L(0); PG8_MMA(1, 0, At, B0); PG8_BAR; PG8_SCHED;
;             PG8_STAGE(PG8_SB(0, 1), b2 + hstepB, voffB);
;             PG8_WAIT_V(6); PG8_BAR; PG8_MMA(1, 1, At, B1); PG8_BAR;
;             PG8_LDB(B0, 1, 0); PG8_SCHED; PG8_LDA(At, 1, 0); PG8_STAGE(PG8_SA(0, 1), a2 + hstepA, voffA);
;             PG8_WAIT_L(8); PG8_BAR; PG8_WAIT_L(0); PG8_MMA(0, 0, At, B0); PG8_BAR; PG8_SCHED;
;             PG8_LDB(B1, 1, 1); PG8_STAGE(PG8_SB(1, 0), b3, voffB);
;             PG8_BAR; PG8_WAIT_L(0); PG8_MMA(0, 1, At, B1); PG8_BAR;
	v_mfma_f32_16x16x32_f16 v[62:65], v[140:143], v[162:165], v[62:65]
	v_mfma_f32_16x16x32_f16 v[58:61], v[154:157], v[162:165], v[58:61]
	v_mfma_f32_16x16x32_f16 v[46:49], v[140:143], v[170:173], v[46:49]
	v_mfma_f32_16x16x32_f16 v[42:45], v[154:157], v[170:173], v[42:45]
	v_mfma_f32_16x16x32_f16 v[30:33], v[140:143], v[178:181], v[30:33]
	v_mfma_f32_16x16x32_f16 v[26:29], v[154:157], v[178:181], v[26:29]
	v_mfma_f32_16x16x32_f16 v[14:17], v[140:143], v[186:189], v[14:17]
	v_mfma_f32_16x16x32_f16 v[10:13], v[154:157], v[186:189], v[10:13]
	v_mfma_f32_16x16x32_f16 v[62:65], v[150:153], v[166:169], v[62:65]
	v_mfma_f32_16x16x32_f16 v[58:61], v[158:161], v[166:169], v[58:61]
	v_mfma_f32_16x16x32_f16 v[46:49], v[150:153], v[174:177], v[46:49]
	v_mfma_f32_16x16x32_f16 v[42:45], v[158:161], v[174:177], v[42:45]
	v_mfma_f32_16x16x32_f16 v[30:33], v[150:153], v[182:185], v[30:33]
	v_mfma_f32_16x16x32_f16 v[26:29], v[158:161], v[182:185], v[26:29]
	v_mfma_f32_16x16x32_f16 v[14:17], v[150:153], v[190:193], v[14:17]
	v_mfma_f32_16x16x32_f16 v[10:13], v[158:161], v[190:193], v[10:13]
	v_mfma_f32_16x16x32_f16 v[54:57], v[194:197], v[162:165], v[54:57]
	v_mfma_f32_16x16x32_f16 v[50:53], v[202:205], v[162:165], v[50:53]
	v_mfma_f32_16x16x32_f16 v[38:41], v[194:197], v[170:173], v[38:41]
	v_mfma_f32_16x16x32_f16 v[34:37], v[202:205], v[170:173], v[34:37]
	v_mfma_f32_16x16x32_f16 v[22:25], v[194:197], v[178:181], v[22:25]
	v_mfma_f32_16x16x32_f16 v[18:21], v[202:205], v[178:181], v[18:21]
	v_mfma_f32_16x16x32_f16 v[6:9], v[194:197], v[186:189], v[6:9]
	v_mfma_f32_16x16x32_f16 v[2:5], v[202:205], v[186:189], v[2:5]
	v_mfma_f32_16x16x32_f16 v[54:57], v[198:201], v[166:169], v[54:57]
	v_mfma_f32_16x16x32_f16 v[50:53], v[220:223], v[166:169], v[50:53]
	v_mfma_f32_16x16x32_f16 v[38:41], v[198:201], v[174:177], v[38:41]
	v_mfma_f32_16x16x32_f16 v[34:37], v[220:223], v[174:177], v[34:37]
	v_mfma_f32_16x16x32_f16 v[22:25], v[198:201], v[182:185], v[22:25]
	v_mfma_f32_16x16x32_f16 v[18:21], v[220:223], v[182:185], v[18:21]
	v_mfma_f32_16x16x32_f16 v[6:9], v[198:201], v[190:193], v[6:9]
	v_mfma_f32_16x16x32_f16 v[2:5], v[220:223], v[190:193], v[2:5]
	s_barrier
	s_add_i32 s51, 0, 0x18000
	v_add_u32_e32 v234, s51, v147
	ds_read_b128 v[140:143], v234
	ds_read_b128 v[150:153], v234 offset:1024
	ds_read_b128 v[154:157], v234 offset:2048
	ds_read_b128 v[158:161], v234 offset:3072
	s_add_u32 s22, s44, 0x158000
	s_addc_u32 s23, s45, 0
	s_mov_b32 m0, s65
	v_lshl_add_u64 v[232:233], s[22:23], 0, v[130:131]
	ds_read_b128 v[162:165], v149 offset:32768
	ds_read_b128 v[166:169], v149 offset:33792
	ds_read_b128 v[170:173], v149 offset:34816
	ds_read_b128 v[174:177], v149 offset:35840
	ds_read_b128 v[178:181], v149 offset:36864
	ds_read_b128 v[182:185], v149 offset:37888
	ds_read_b128 v[186:189], v149 offset:38912
	ds_read_b128 v[190:193], v149 offset:39936
	global_load_lds_dwordx4 v[232:233], off
	v_lshl_add_u64 v[232:233], s[22:23], 0, v[132:133]
	s_mov_b32 m0, s68
	s_nop 0
	global_load_lds_dwordx4 v[232:233], off
	s_waitcnt lgkmcnt(11)
	s_add_i32 s44, 0, 0x1c000
	s_add_i32 s22, s51, s48
	v_add_u32_e32 v216, s44, v147
	v_lshl_add_u64 v[144:145], v[144:145], 0, s[92:93]
	s_mov_b32 m0, s22
	ds_read_b128 v[194:197], v216
	ds_read_b128 v[198:201], v216 offset:1024
	ds_read_b128 v[202:205], v216 offset:2048
	ds_read_b128 v[220:223], v216 offset:3072
	s_waitcnt lgkmcnt(0)
	s_barrier
	v_mfma_f32_16x16x32_f16 v[126:129], v[140:143], v[162:165], v[126:129]
	v_mfma_f32_16x16x32_f16 v[122:125], v[154:157], v[162:165], v[122:125]
	v_mfma_f32_16x16x32_f16 v[110:113], v[140:143], v[170:173], v[110:113]
	v_mfma_f32_16x16x32_f16 v[106:109], v[154:157], v[170:173], v[106:109]
	v_mfma_f32_16x16x32_f16 v[94:97], v[140:143], v[178:181], v[94:97]
	v_mfma_f32_16x16x32_f16 v[90:93], v[154:157], v[178:181], v[90:93]
	v_mfma_f32_16x16x32_f16 v[78:81], v[140:143], v[186:189], v[78:81]
	v_mfma_f32_16x16x32_f16 v[74:77], v[154:157], v[186:189], v[74:77]
	v_mfma_f32_16x16x32_f16 v[126:129], v[150:153], v[166:169], v[126:129]
	v_mfma_f32_16x16x32_f16 v[122:125], v[158:161], v[166:169], v[122:125]
	v_mfma_f32_16x16x32_f16 v[110:113], v[150:153], v[174:177], v[110:113]
	v_mfma_f32_16x16x32_f16 v[106:109], v[158:161], v[174:177], v[106:109]
	v_mfma_f32_16x16x32_f16 v[94:97], v[150:153], v[182:185], v[94:97]
	v_mfma_f32_16x16x32_f16 v[90:93], v[158:161], v[182:185], v[90:93]
	v_mfma_f32_16x16x32_f16 v[78:81], v[150:153], v[190:193], v[78:81]
	v_mfma_f32_16x16x32_f16 v[74:77], v[158:161], v[190:193], v[74:77]
	v_mfma_f32_16x16x32_f16 v[118:121], v[194:197], v[162:165], v[118:121]
	v_mfma_f32_16x16x32_f16 v[114:117], v[202:205], v[162:165], v[114:117]
	v_mfma_f32_16x16x32_f16 v[102:105], v[194:197], v[170:173], v[102:105]
	v_mfma_f32_16x16x32_f16 v[98:101], v[202:205], v[170:173], v[98:101]
	v_mfma_f32_16x16x32_f16 v[86:89], v[194:197], v[178:181], v[86:89]
	v_mfma_f32_16x16x32_f16 v[82:85], v[202:205], v[178:181], v[82:85]
	v_mfma_f32_16x16x32_f16 v[70:73], v[194:197], v[186:189], v[70:73]
	v_mfma_f32_16x16x32_f16 v[66:69], v[202:205], v[186:189], v[66:69]
	v_mfma_f32_16x16x32_f16 v[118:121], v[198:201], v[166:169], v[118:121]
	v_mfma_f32_16x16x32_f16 v[114:117], v[220:223], v[166:169], v[114:117]
	v_mfma_f32_16x16x32_f16 v[102:105], v[198:201], v[174:177], v[102:105]
	v_mfma_f32_16x16x32_f16 v[98:101], v[220:223], v[174:177], v[98:101]
	v_mfma_f32_16x16x32_f16 v[86:89], v[198:201], v[182:185], v[86:89]
	v_mfma_f32_16x16x32_f16 v[82:85], v[220:223], v[182:185], v[82:85]
	v_mfma_f32_16x16x32_f16 v[70:73], v[198:201], v[190:193], v[70:73]
	v_mfma_f32_16x16x32_f16 v[66:69], v[220:223], v[190:193], v[66:69]
	s_barrier
; #define PG8_STAGE(bufoff, gbase, voff) do { _Pragma("unroll") for (int _i = 0; _i < 2; ++_i) \
;         __builtin_amdgcn_global_load_lds((const unsigned*)((const char*)(gbase) + (voff)[_i]), (LAS unsigned*)(lds + (bufoff) + ldsw + _i * 8192), 16, 0, 0); } while (0)
; #define PG8_LDA(dst, b, h) do { _Pragma("unroll") for (int m = 0; m < 4; ++m) _Pragma("unroll") for (int k = 0; k < 2; ++k) dst[m][k] = *(const LAS h16x8*)(lds + PG8_SA(b, h) + aoff + m * 2048 + k * 1024); } while (0)
; #define PG8_LDB(dst, b, h) do { _Pragma("unroll") for (int n = 0; n < 2; ++n) _Pragma("unroll") for (int k = 0; k < 2; ++k) dst[n][k] = *(const LAS h16x8*)(lds + PG8_SB(b, h) + boff + n * 2048 + k * 1024); } while (0)
; #define PG8_MMA(ai, bj, At, Bt_) do { __builtin_amdgcn_s_setprio(1); _Pragma("unroll") for (int m = 0; m < 4; ++m) _Pragma("unroll") for (int n = 0; n < 2; ++n) _Pragma("unroll") for (int k = 0; k < 2; ++k) \
;         acc[ai][bj][m][n] = __builtin_amdgcn_mfma_f32_16x16x32_f16(Bt_[n][k], At[m][k], acc[ai][bj][m][n], 0, 0, 0); __builtin_amdgcn_s_setprio(0); } while (0)
; #define PG8_WAIT_V(n) asm volatile("s_waitcnt vmcnt(" #n ")" ::: "memory")
; #define PG8_WAIT_L(n) asm volatile("s_waitcnt lgkmcnt(" #n ")" ::: "memory")
; template <class Epi, class AMap>
; __device__ __forceinline__ void gemm_phase(LAS unsigned char* lds, const AMap am, const int lda, const h16* Bt, const int ldb, const int M, const int N, const int K, const Epi& E) {
;     ...
;             PG8_LDB(B1, 1, 1); PG8_STAGE(PG8_SB(1, 0), b3, voffB);
;             PG8_BAR; PG8_WAIT_L(0); PG8_MMA(0, 1, At, B1); PG8_BAR;
;             PG8_LDA(At, 1, 1); PG8_STAGE(PG8_SA(1, 0), a3, voffA);
;             PG8_BAR; PG8_WAIT_L(0); PG8_MMA(1, 0, At, B0); PG8_BAR; PG8_SCHED;
;             PG8_STAGE(PG8_SB(1, 1), b3 + hstepB, voffB);
;             PG8_WAIT_V(6); PG8_BAR; PG8_MMA(1, 1, At, B1); PG8_BAR;
;     __device__ __forceinline__ void operator()(const f32x4 (&acc)[2][2][4][2], const Unit& u, int wr, int wc, int fr, int fq) const {
;         EPI_ROWS_PERM
; #pragma unroll
;         for (int ai = 0; ai < 2; ++ai)
; #pragma unroll
;             for (int m = 0; m < 4; ++m) { const size_t off = (size_t)(row0 + ai * 128 + m * 16) * DM + colt;
; #pragma unroll
;                 for (int bj = 0; bj < 2; ++bj) {
;                     const h16x8 x = *(const h16x8*)(X + off + bj * 128);
	global_load_lds_dwordx4 v[144:145], off
	v_lshl_add_u64 v[144:145], v[206:207], 0, s[92:93]
	s_add_i32 m0, s22, 0x2000
	s_nop 0
	global_load_lds_dwordx4 v[144:145], off
	s_mov_b32 m0, s69
	v_lshl_add_u64 v[144:145], v[212:213], 0, s[92:93]
	ds_read_b128 v[162:165], v149 offset:49152
	ds_read_b128 v[166:169], v149 offset:50176
	ds_read_b128 v[170:173], v149 offset:51200
	ds_read_b128 v[174:177], v149 offset:52224
	ds_read_b128 v[178:181], v149 offset:53248
	ds_read_b128 v[182:185], v149 offset:54272
	ds_read_b128 v[186:189], v149 offset:55296
	ds_read_b128 v[190:193], v149 offset:56320
	global_load_lds_dwordx4 v[144:145], off
	v_lshl_add_u64 v[144:145], v[214:215], 0, s[92:93]
	s_mov_b32 m0, s70
	s_nop 0
	global_load_lds_dwordx4 v[144:145], off
	s_add_u32 s22, s42, 0x158080
	s_addc_u32 s23, s43, 0
	s_add_i32 s42, s44, s48
	v_lshl_add_u64 v[232:233], s[22:23], 0, v[0:1]
	s_mov_b32 m0, s42
	s_nop 0
	global_load_lds_dwordx4 v[232:233], off
	v_lshl_add_u64 v[232:233], s[22:23], 0, v[134:135]
	s_add_i32 m0, s42, 0x2000
	s_nop 0
	global_load_lds_dwordx4 v[232:233], off
	s_waitcnt vmcnt(6) lgkmcnt(0)
	s_barrier
	v_mfma_f32_16x16x32_f16 v[62:65], v[140:143], v[162:165], v[62:65]
	v_mfma_f32_16x16x32_f16 v[58:61], v[154:157], v[162:165], v[58:61]
	v_mfma_f32_16x16x32_f16 v[46:49], v[140:143], v[170:173], v[46:49]
	v_mfma_f32_16x16x32_f16 v[42:45], v[154:157], v[170:173], v[42:45]
	v_mfma_f32_16x16x32_f16 v[30:33], v[140:143], v[178:181], v[30:33]
	v_mfma_f32_16x16x32_f16 v[26:29], v[154:157], v[178:181], v[26:29]
	v_mfma_f32_16x16x32_f16 v[14:17], v[140:143], v[186:189], v[14:17]
	v_mfma_f32_16x16x32_f16 v[10:13], v[154:157], v[186:189], v[10:13]
	v_mfma_f32_16x16x32_f16 v[62:65], v[150:153], v[166:169], v[62:65]
	v_mfma_f32_16x16x32_f16 v[58:61], v[158:161], v[166:169], v[58:61]
	v_mfma_f32_16x16x32_f16 v[46:49], v[150:153], v[174:177], v[46:49]
	v_mfma_f32_16x16x32_f16 v[42:45], v[158:161], v[174:177], v[42:45]
	v_mfma_f32_16x16x32_f16 v[30:33], v[150:153], v[182:185], v[30:33]
	v_mfma_f32_16x16x32_f16 v[26:29], v[158:161], v[182:185], v[26:29]
	v_mfma_f32_16x16x32_f16 v[14:17], v[150:153], v[190:193], v[14:17]
	v_mfma_f32_16x16x32_f16 v[10:13], v[158:161], v[190:193], v[10:13]
	v_mfma_f32_16x16x32_f16 v[54:57], v[194:197], v[162:165], v[54:57]
	v_mfma_f32_16x16x32_f16 v[50:53], v[202:205], v[162:165], v[50:53]
	v_mfma_f32_16x16x32_f16 v[38:41], v[194:197], v[170:173], v[38:41]
	v_mfma_f32_16x16x32_f16 v[34:37], v[202:205], v[170:173], v[34:37]
	v_mfma_f32_16x16x32_f16 v[22:25], v[194:197], v[178:181], v[22:25]
	v_mfma_f32_16x16x32_f16 v[18:21], v[202:205], v[178:181], v[18:21]
	v_mfma_f32_16x16x32_f16 v[6:9], v[194:197], v[186:189], v[6:9]
	v_mfma_f32_16x16x32_f16 v[2:5], v[202:205], v[186:189], v[2:5]
	v_mfma_f32_16x16x32_f16 v[54:57], v[198:201], v[166:169], v[54:57]
	v_mfma_f32_16x16x32_f16 v[50:53], v[220:223], v[166:169], v[50:53]
	v_mfma_f32_16x16x32_f16 v[38:41], v[198:201], v[174:177], v[38:41]
	v_mfma_f32_16x16x32_f16 v[34:37], v[220:223], v[174:177], v[34:37]
	v_mfma_f32_16x16x32_f16 v[22:25], v[198:201], v[182:185], v[22:25]
	v_mfma_f32_16x16x32_f16 v[18:21], v[220:223], v[182:185], v[18:21]
	v_mfma_f32_16x16x32_f16 v[6:9], v[198:201], v[190:193], v[6:9]
	v_mfma_f32_16x16x32_f16 v[2:5], v[220:223], v[190:193], v[2:5]
	s_add_i32 s29, s29, 2
	s_add_u32 s20, s20, 0x100
	s_addc_u32 s21, s21, 0
	s_cmpk_gt_u32 s29, 0x53
	s_mov_b64 s[22:23], s[26:27]
	s_barrier
	s_cbranch_scc0 .LBB0_61
	v_lshl_add_u32 v144, s35, 8, v146
	v_lshl_or_b32 v142, s50, 8, v148
	v_ashrrev_i32_e32 v145, 31, v144
	v_ashrrev_i32_e32 v143, 31, v142
	v_lshlrev_b64 v[140:141], 11, v[144:145]
	v_lshl_add_u64 v[140:141], v[140:141], 0, v[142:143]
	v_lshlrev_b64 v[140:141], 1, v[140:141]
	v_lshl_add_u64 v[154:155], s[94:95], 0, v[140:141]
	s_mov_b32 s101, 0
	global_load_dwordx4 v[158:161], v[154:155], off
	global_load_dwordx4 v[162:165], v[154:155], off offset:256
	s_mov_b32 s100, 0x10000
	v_lshl_add_u64 v[232:233], v[154:155], 0, s[100:101]
	global_load_dwordx4 v[166:169], v[232:233], off
	global_load_dwordx4 v[170:173], v[232:233], off offset:256
	s_mov_b32 s100, 0x20000
	v_lshl_add_u64 v[232:233], v[154:155], 0, s[100:101]
	global_load_dwordx4 v[174:177], v[232:233], off
	global_load_dwordx4 v[178:181], v[232:233], off offset:256
	s_mov_b32 s100, 0x30000
	v_lshl_add_u64 v[232:233], v[154:155], 0, s[100:101]
	global_load_dwordx4 v[182:185], v[232:233], off
	global_load_dwordx4 v[186:189], v[232:233], off offset:256
	s_mov_b32 s100, 0x80000
	v_lshl_add_u64 v[232:233], v[154:155], 0, s[100:101]
	global_load_dwordx4 v[190:193], v[232:233], off
	global_load_dwordx4 v[194:197], v[232:233], off offset:256
	s_mov_b32 s100, 0x90000
	v_lshl_add_u64 v[232:233], v[154:155], 0, s[100:101]
	global_load_dwordx4 v[198:201], v[232:233], off
	global_load_dwordx4 v[202:205], v[232:233], off offset:256
	s_mov_b32 s100, 0xa0000
	v_lshl_add_u64 v[232:233], v[154:155], 0, s[100:101]
	global_load_dwordx4 v[212:215], v[232:233], off
	global_load_dwordx4 v[220:223], v[232:233], off offset:256
	s_mov_b32 s100, 0xb0000
	v_lshl_add_u64 v[232:233], v[154:155], 0, s[100:101]
	global_load_dwordx4 v[224:227], v[232:233], off
	global_load_dwordx4 v[228:231], v[232:233], off offset:256
	s_mov_b64 s[4:5], 0xb0000
	s_and_b64 vcc, exec, s[38:39]
	s_mov_b32 s50, s72
	s_mov_b64 s[26:27], s[40:41]
	s_mov_b64 s[22:23], s[0:1]
	s_waitcnt vmcnt(15)
;     __device__ __forceinline__ void operator()(const f32x4 (&acc)[2][2][4][2], const Unit& u, int wr, int wc, int fr, int fq) const {
;     ...
;             for (int m = 0; m < 4; ++m) { const size_t off = (size_t)(row0 + ai * 128 + m * 16) * DM + colt;
; #pragma unroll
;                 for (int bj = 0; bj < 2; ++bj) {
;                     const h16x8 x = *(const h16x8*)(X + off + bj * 128);
;                     f32x4 o0, o1;
; #pragma unroll
;                     for (int e = 0; e < 4; ++e) { o0[e] = (float)x[e] * ALPHA + acc[ai][bj][m][0][e]; o1[e] = (float)x[4 + e] * ALPHA + acc[ai][bj][m][1][e]; }
;                     *(u32x4*)(PRE + off + bj * 128) = pack8(o0, o1); } }
	v_mov_b64_e32 v[150:151], v[158:159]
	v_mov_b64_e32 v[152:153], v[160:161]
	v_cvt_f32_f16_e32 v156, v150
	v_cvt_f32_f16_sdwa v157, v150 dst_sel:DWORD dst_unused:UNUSED_PAD src0_sel:WORD_1
	v_cvt_f32_f16_e32 v150, v151
	v_cvt_f32_f16_sdwa v151, v151 dst_sel:DWORD dst_unused:UNUSED_PAD src0_sel:WORD_1
	v_pk_fma_f32 v[126:127], v[156:157], s[34:35], v[126:127] op_sel_hi:[1,0,1]
	s_nop 0
	v_cvt_pk_f16_f32 v126, v126, v127
	v_pk_fma_f32 v[128:129], v[150:151], s[34:35], v[128:129] op_sel_hi:[1,0,1]
	v_lshl_add_u64 v[150:151], s[8:9], 0, v[140:141]
	v_cvt_pk_f16_f32 v127, v128, v129
	v_cvt_f32_f16_e32 v128, v152
	v_cvt_f32_f16_sdwa v129, v152 dst_sel:DWORD dst_unused:UNUSED_PAD src0_sel:WORD_1
	v_pk_fma_f32 v[122:123], v[128:129], s[34:35], v[122:123] op_sel_hi:[1,0,1]
	s_nop 0
	v_cvt_pk_f16_f32 v128, v122, v123
	v_cvt_f32_f16_e32 v122, v153
	v_cvt_f32_f16_sdwa v123, v153 dst_sel:DWORD dst_unused:UNUSED_PAD src0_sel:WORD_1
	v_pk_fma_f32 v[122:123], v[122:123], s[34:35], v[124:125] op_sel_hi:[1,0,1]
	s_nop 0
	v_cvt_pk_f16_f32 v129, v122, v123
	s_nop 0
	global_store_dwordx4 v[150:151], v[126:129], off
	s_waitcnt vmcnt(15)
	v_mov_b64_e32 v[122:123], v[162:163]
	v_mov_b64_e32 v[124:125], v[164:165]
	s_nop 0
	v_cvt_f32_f16_e32 v126, v122
	v_cvt_f32_f16_sdwa v127, v122 dst_sel:DWORD dst_unused:UNUSED_PAD src0_sel:WORD_1
	v_cvt_f32_f16_e32 v122, v123
	v_cvt_f32_f16_sdwa v123, v123 dst_sel:DWORD dst_unused:UNUSED_PAD src0_sel:WORD_1
	v_pk_fma_f32 v[118:119], v[126:127], s[34:35], v[118:119] op_sel_hi:[1,0,1]
	s_nop 0
	v_cvt_pk_f16_f32 v118, v118, v119
	v_pk_fma_f32 v[120:121], v[122:123], s[34:35], v[120:121] op_sel_hi:[1,0,1]
	s_nop 0
	v_cvt_pk_f16_f32 v119, v120, v121
	v_cvt_f32_f16_e32 v120, v124
	v_cvt_f32_f16_sdwa v121, v124 dst_sel:DWORD dst_unused:UNUSED_PAD src0_sel:WORD_1
	v_pk_fma_f32 v[114:115], v[120:121], s[34:35], v[114:115] op_sel_hi:[1,0,1]
	s_nop 0
	v_cvt_pk_f16_f32 v120, v114, v115
	v_cvt_f32_f16_e32 v114, v125
	v_cvt_f32_f16_sdwa v115, v125 dst_sel:DWORD dst_unused:UNUSED_PAD src0_sel:WORD_1
	v_pk_fma_f32 v[114:115], v[114:115], s[34:35], v[116:117] op_sel_hi:[1,0,1]
	s_nop 0
	v_cvt_pk_f16_f32 v121, v114, v115
	v_or_b32_e32 v114, 16, v144
	v_ashrrev_i32_e32 v115, 31, v114
	v_lshlrev_b64 v[114:115], 11, v[114:115]
	v_lshl_add_u64 v[114:115], v[114:115], 0, v[142:143]
	global_store_dwordx4 v[150:151], v[118:121], off offset:256
	s_nop 1
	v_lshlrev_b64 v[118:119], 1, v[114:115]
	v_lshl_add_u64 v[120:121], s[94:95], 0, v[118:119]
	s_waitcnt vmcnt(15)
	v_mov_b64_e32 v[114:115], v[166:167]
	v_mov_b64_e32 v[116:117], v[168:169]
	v_cvt_f32_f16_e32 v122, v114
	v_cvt_f32_f16_sdwa v123, v114 dst_sel:DWORD dst_unused:UNUSED_PAD src0_sel:WORD_1
	v_cvt_f32_f16_e32 v114, v115
	v_cvt_f32_f16_sdwa v115, v115 dst_sel:DWORD dst_unused:UNUSED_PAD src0_sel:WORD_1
	v_pk_fma_f32 v[110:111], v[122:123], s[34:35], v[110:111] op_sel_hi:[1,0,1]
	s_nop 0
	v_cvt_pk_f16_f32 v110, v110, v111
	v_pk_fma_f32 v[112:113], v[114:115], s[34:35], v[112:113] op_sel_hi:[1,0,1]
	v_lshl_add_u64 v[114:115], s[8:9], 0, v[118:119]
	v_cvt_pk_f16_f32 v111, v112, v113
	v_cvt_f32_f16_e32 v112, v116
	v_cvt_f32_f16_sdwa v113, v116 dst_sel:DWORD dst_unused:UNUSED_PAD src0_sel:WORD_1
	v_pk_fma_f32 v[106:107], v[112:113], s[34:35], v[106:107] op_sel_hi:[1,0,1]
	s_nop 0
	v_cvt_pk_f16_f32 v112, v106, v107
	v_cvt_f32_f16_e32 v106, v117
	v_cvt_f32_f16_sdwa v107, v117 dst_sel:DWORD dst_unused:UNUSED_PAD src0_sel:WORD_1
	v_pk_fma_f32 v[106:107], v[106:107], s[34:35], v[108:109] op_sel_hi:[1,0,1]
	s_nop 0
	v_cvt_pk_f16_f32 v113, v106, v107
	s_nop 0
	global_store_dwordx4 v[114:115], v[110:113], off
	s_waitcnt vmcnt(15)
	v_mov_b64_e32 v[106:107], v[170:171]
	v_mov_b64_e32 v[108:109], v[172:173]
	s_nop 0
	v_cvt_f32_f16_e32 v110, v106
	v_cvt_f32_f16_sdwa v111, v106 dst_sel:DWORD dst_unused:UNUSED_PAD src0_sel:WORD_1
	v_cvt_f32_f16_e32 v106, v107
	v_cvt_f32_f16_sdwa v107, v107 dst_sel:DWORD dst_unused:UNUSED_PAD src0_sel:WORD_1
	v_pk_fma_f32 v[102:103], v[110:111], s[34:35], v[102:103] op_sel_hi:[1,0,1]
	s_nop 0
	v_cvt_pk_f16_f32 v102, v102, v103
	v_pk_fma_f32 v[104:105], v[106:107], s[34:35], v[104:105] op_sel_hi:[1,0,1]
	s_nop 0
	v_cvt_pk_f16_f32 v103, v104, v105
	v_cvt_f32_f16_e32 v104, v108
	v_cvt_f32_f16_sdwa v105, v108 dst_sel:DWORD dst_unused:UNUSED_PAD src0_sel:WORD_1
	v_pk_fma_f32 v[98:99], v[104:105], s[34:35], v[98:99] op_sel_hi:[1,0,1]
	s_nop 0
	v_cvt_pk_f16_f32 v104, v98, v99
	v_cvt_f32_f16_e32 v98, v109
	v_cvt_f32_f16_sdwa v99, v109 dst_sel:DWORD dst_unused:UNUSED_PAD src0_sel:WORD_1
	v_pk_fma_f32 v[98:99], v[98:99], s[34:35], v[100:101] op_sel_hi:[1,0,1]
	s_nop 0
	v_cvt_pk_f16_f32 v105, v98, v99
	v_or_b32_e32 v98, 32, v144
	v_ashrrev_i32_e32 v99, 31, v98
	v_lshlrev_b64 v[98:99], 11, v[98:99]
	v_lshl_add_u64 v[98:99], v[98:99], 0, v[142:143]
	global_store_dwordx4 v[114:115], v[102:105], off offset:256
	s_nop 1
	v_lshlrev_b64 v[102:103], 1, v[98:99]
	v_lshl_add_u64 v[104:105], s[94:95], 0, v[102:103]
	s_waitcnt vmcnt(15)
	v_mov_b64_e32 v[98:99], v[174:175]
	v_mov_b64_e32 v[100:101], v[176:177]
	v_cvt_f32_f16_e32 v106, v98
	v_cvt_f32_f16_sdwa v107, v98 dst_sel:DWORD dst_unused:UNUSED_PAD src0_sel:WORD_1
	v_cvt_f32_f16_e32 v98, v99
	v_cvt_f32_f16_sdwa v99, v99 dst_sel:DWORD dst_unused:UNUSED_PAD src0_sel:WORD_1
	v_pk_fma_f32 v[94:95], v[106:107], s[34:35], v[94:95] op_sel_hi:[1,0,1]
	s_nop 0
	v_cvt_pk_f16_f32 v94, v94, v95
	v_pk_fma_f32 v[96:97], v[98:99], s[34:35], v[96:97] op_sel_hi:[1,0,1]
	v_lshl_add_u64 v[98:99], s[8:9], 0, v[102:103]
	v_cvt_pk_f16_f32 v95, v96, v97
	v_cvt_f32_f16_e32 v96, v100
	v_cvt_f32_f16_sdwa v97, v100 dst_sel:DWORD dst_unused:UNUSED_PAD src0_sel:WORD_1
	v_pk_fma_f32 v[90:91], v[96:97], s[34:35], v[90:91] op_sel_hi:[1,0,1]
	s_nop 0
	v_cvt_pk_f16_f32 v96, v90, v91
	v_cvt_f32_f16_e32 v90, v101
	v_cvt_f32_f16_sdwa v91, v101 dst_sel:DWORD dst_unused:UNUSED_PAD src0_sel:WORD_1
	v_pk_fma_f32 v[90:91], v[90:91], s[34:35], v[92:93] op_sel_hi:[1,0,1]
	s_nop 0
	v_cvt_pk_f16_f32 v97, v90, v91
	s_nop 0
	global_store_dwordx4 v[98:99], v[94:97], off
	s_waitcnt vmcnt(15)
;     __device__ __forceinline__ void operator()(const f32x4 (&acc)[2][2][4][2], const Unit& u, int wr, int wc, int fr, int fq) const {
;     ...
; #pragma unroll
;         for (int ai = 0; ai < 2; ++ai)
; #pragma unroll
;             for (int m = 0; m < 4; ++m) { const size_t off = (size_t)(row0 + ai * 128 + m * 16) * DM + colt;
; #pragma unroll
;                 for (int bj = 0; bj < 2; ++bj) {
;                     const h16x8 x = *(const h16x8*)(X + off + bj * 128);
;                     f32x4 o0, o1;
; #pragma unroll
;                     for (int e = 0; e < 4; ++e) { o0[e] = (float)x[e] * ALPHA + acc[ai][bj][m][0][e]; o1[e] = (float)x[4 + e] * ALPHA + acc[ai][bj][m][1][e]; }
;                     *(u32x4*)(PRE + off + bj * 128) = pack8(o0, o1); } }
	v_mov_b64_e32 v[90:91], v[178:179]
	v_mov_b64_e32 v[92:93], v[180:181]
	s_nop 0
	v_cvt_f32_f16_e32 v94, v90
	v_cvt_f32_f16_sdwa v95, v90 dst_sel:DWORD dst_unused:UNUSED_PAD src0_sel:WORD_1
	v_cvt_f32_f16_e32 v90, v91
	v_cvt_f32_f16_sdwa v91, v91 dst_sel:DWORD dst_unused:UNUSED_PAD src0_sel:WORD_1
	v_pk_fma_f32 v[86:87], v[94:95], s[34:35], v[86:87] op_sel_hi:[1,0,1]
	s_nop 0
	v_cvt_pk_f16_f32 v86, v86, v87
	v_pk_fma_f32 v[88:89], v[90:91], s[34:35], v[88:89] op_sel_hi:[1,0,1]
	s_nop 0
	v_cvt_pk_f16_f32 v87, v88, v89
	v_cvt_f32_f16_e32 v88, v92
	v_cvt_f32_f16_sdwa v89, v92 dst_sel:DWORD dst_unused:UNUSED_PAD src0_sel:WORD_1
	v_pk_fma_f32 v[82:83], v[88:89], s[34:35], v[82:83] op_sel_hi:[1,0,1]
	s_nop 0
	v_cvt_pk_f16_f32 v88, v82, v83
	v_cvt_f32_f16_e32 v82, v93
	v_cvt_f32_f16_sdwa v83, v93 dst_sel:DWORD dst_unused:UNUSED_PAD src0_sel:WORD_1
	v_pk_fma_f32 v[82:83], v[82:83], s[34:35], v[84:85] op_sel_hi:[1,0,1]
	s_nop 0
	v_cvt_pk_f16_f32 v89, v82, v83
	v_or_b32_e32 v82, 48, v144
	v_ashrrev_i32_e32 v83, 31, v82
	v_lshlrev_b64 v[82:83], 11, v[82:83]
	v_lshl_add_u64 v[82:83], v[82:83], 0, v[142:143]
	global_store_dwordx4 v[98:99], v[86:89], off offset:256
	s_nop 1
	v_lshlrev_b64 v[86:87], 1, v[82:83]
	v_lshl_add_u64 v[88:89], s[94:95], 0, v[86:87]
	s_waitcnt vmcnt(15)
	v_mov_b64_e32 v[82:83], v[182:183]
	v_mov_b64_e32 v[84:85], v[184:185]
	v_cvt_f32_f16_e32 v90, v82
	v_cvt_f32_f16_sdwa v91, v82 dst_sel:DWORD dst_unused:UNUSED_PAD src0_sel:WORD_1
	v_cvt_f32_f16_e32 v82, v83
	v_cvt_f32_f16_sdwa v83, v83 dst_sel:DWORD dst_unused:UNUSED_PAD src0_sel:WORD_1
	v_pk_fma_f32 v[78:79], v[90:91], s[34:35], v[78:79] op_sel_hi:[1,0,1]
	s_nop 0
	v_cvt_pk_f16_f32 v78, v78, v79
	v_pk_fma_f32 v[80:81], v[82:83], s[34:35], v[80:81] op_sel_hi:[1,0,1]
	v_lshl_add_u64 v[82:83], s[8:9], 0, v[86:87]
	v_cvt_pk_f16_f32 v79, v80, v81
	v_cvt_f32_f16_e32 v80, v84
	v_cvt_f32_f16_sdwa v81, v84 dst_sel:DWORD dst_unused:UNUSED_PAD src0_sel:WORD_1
	v_pk_fma_f32 v[74:75], v[80:81], s[34:35], v[74:75] op_sel_hi:[1,0,1]
	s_nop 0
	v_cvt_pk_f16_f32 v80, v74, v75
	v_cvt_f32_f16_e32 v74, v85
	v_cvt_f32_f16_sdwa v75, v85 dst_sel:DWORD dst_unused:UNUSED_PAD src0_sel:WORD_1
	v_pk_fma_f32 v[74:75], v[74:75], s[34:35], v[76:77] op_sel_hi:[1,0,1]
	s_nop 0
	v_cvt_pk_f16_f32 v81, v74, v75
	s_nop 0
	global_store_dwordx4 v[82:83], v[78:81], off
	s_waitcnt vmcnt(15)
	v_mov_b64_e32 v[74:75], v[186:187]
	v_mov_b64_e32 v[76:77], v[188:189]
	s_nop 0
	v_cvt_f32_f16_e32 v78, v74
	v_cvt_f32_f16_sdwa v79, v74 dst_sel:DWORD dst_unused:UNUSED_PAD src0_sel:WORD_1
	v_cvt_f32_f16_e32 v74, v75
	v_cvt_f32_f16_sdwa v75, v75 dst_sel:DWORD dst_unused:UNUSED_PAD src0_sel:WORD_1
	v_pk_fma_f32 v[70:71], v[78:79], s[34:35], v[70:71] op_sel_hi:[1,0,1]
	s_nop 0
	v_cvt_pk_f16_f32 v70, v70, v71
	v_pk_fma_f32 v[72:73], v[74:75], s[34:35], v[72:73] op_sel_hi:[1,0,1]
	s_nop 0
	v_cvt_pk_f16_f32 v71, v72, v73
	v_cvt_f32_f16_e32 v72, v76
	v_cvt_f32_f16_sdwa v73, v76 dst_sel:DWORD dst_unused:UNUSED_PAD src0_sel:WORD_1
	v_pk_fma_f32 v[66:67], v[72:73], s[34:35], v[66:67] op_sel_hi:[1,0,1]
	s_nop 0
	v_cvt_pk_f16_f32 v72, v66, v67
	v_cvt_f32_f16_e32 v66, v77
	v_cvt_f32_f16_sdwa v67, v77 dst_sel:DWORD dst_unused:UNUSED_PAD src0_sel:WORD_1
	v_pk_fma_f32 v[66:67], v[66:67], s[34:35], v[68:69] op_sel_hi:[1,0,1]
	s_nop 0
	v_cvt_pk_f16_f32 v73, v66, v67
	global_store_dwordx4 v[82:83], v[70:73], off offset:256
	s_nop 1
	v_lshl_add_u64 v[70:71], v[140:141], 0, s[16:17]
	v_lshl_add_u64 v[72:73], s[94:95], 0, v[70:71]
	s_waitcnt vmcnt(15)
	v_mov_b64_e32 v[66:67], v[190:191]
	v_mov_b64_e32 v[68:69], v[192:193]
	v_cvt_f32_f16_e32 v74, v66
	v_cvt_f32_f16_sdwa v75, v66 dst_sel:DWORD dst_unused:UNUSED_PAD src0_sel:WORD_1
	v_cvt_f32_f16_e32 v66, v67
	v_cvt_f32_f16_sdwa v67, v67 dst_sel:DWORD dst_unused:UNUSED_PAD src0_sel:WORD_1
	v_pk_fma_f32 v[62:63], v[74:75], s[34:35], v[62:63] op_sel_hi:[1,0,1]
	s_nop 0
	v_cvt_pk_f16_f32 v62, v62, v63
	v_pk_fma_f32 v[64:65], v[66:67], s[34:35], v[64:65] op_sel_hi:[1,0,1]
	v_lshl_add_u64 v[66:67], s[8:9], 0, v[70:71]
	v_cvt_pk_f16_f32 v63, v64, v65
	v_cvt_f32_f16_e32 v64, v68
	v_cvt_f32_f16_sdwa v65, v68 dst_sel:DWORD dst_unused:UNUSED_PAD src0_sel:WORD_1
	v_pk_fma_f32 v[58:59], v[64:65], s[34:35], v[58:59] op_sel_hi:[1,0,1]
	s_nop 0
	v_cvt_pk_f16_f32 v64, v58, v59
	v_cvt_f32_f16_e32 v58, v69
	v_cvt_f32_f16_sdwa v59, v69 dst_sel:DWORD dst_unused:UNUSED_PAD src0_sel:WORD_1
	v_pk_fma_f32 v[58:59], v[58:59], s[34:35], v[60:61] op_sel_hi:[1,0,1]
	s_nop 0
	v_cvt_pk_f16_f32 v65, v58, v59
	s_nop 0
	global_store_dwordx4 v[66:67], v[62:65], off
	s_waitcnt vmcnt(15)
	v_mov_b64_e32 v[58:59], v[194:195]
	v_mov_b64_e32 v[60:61], v[196:197]
	s_nop 0
	v_cvt_f32_f16_e32 v62, v58
	v_cvt_f32_f16_sdwa v63, v58 dst_sel:DWORD dst_unused:UNUSED_PAD src0_sel:WORD_1
	v_cvt_f32_f16_e32 v58, v59
	v_cvt_f32_f16_sdwa v59, v59 dst_sel:DWORD dst_unused:UNUSED_PAD src0_sel:WORD_1
	v_pk_fma_f32 v[54:55], v[62:63], s[34:35], v[54:55] op_sel_hi:[1,0,1]
	s_nop 0
	v_cvt_pk_f16_f32 v54, v54, v55
	v_pk_fma_f32 v[56:57], v[58:59], s[34:35], v[56:57] op_sel_hi:[1,0,1]
	s_nop 0
	v_cvt_pk_f16_f32 v55, v56, v57
	v_cvt_f32_f16_e32 v56, v60
	v_cvt_f32_f16_sdwa v57, v60 dst_sel:DWORD dst_unused:UNUSED_PAD src0_sel:WORD_1
	v_pk_fma_f32 v[50:51], v[56:57], s[34:35], v[50:51] op_sel_hi:[1,0,1]
	s_nop 0
	v_cvt_pk_f16_f32 v56, v50, v51
	v_cvt_f32_f16_e32 v50, v61
	v_cvt_f32_f16_sdwa v51, v61 dst_sel:DWORD dst_unused:UNUSED_PAD src0_sel:WORD_1
	v_pk_fma_f32 v[50:51], v[50:51], s[34:35], v[52:53] op_sel_hi:[1,0,1]
	s_nop 0
	v_cvt_pk_f16_f32 v57, v50, v51
	global_store_dwordx4 v[66:67], v[54:57], off offset:256
	s_nop 1
	v_lshl_add_u64 v[54:55], v[140:141], 0, s[18:19]
	v_lshl_add_u64 v[56:57], s[94:95], 0, v[54:55]
	s_waitcnt vmcnt(15)
; #define PG8_WAIT_V(n) asm volatile("s_waitcnt vmcnt(" #n ")" ::: "memory")
; #define PG8_BAR __builtin_amdgcn_s_barrier()
; template <class Epi, class AMap>
; __device__ __forceinline__ void gemm_phase(LAS unsigned char* lds, const AMap am, const int lda, const h16* Bt, const int ldb, const int M, const int N, const int K, const Epi& E) {
;     ...
;         if (!has_next) break;
; #pragma unroll
;         for (int a = 0; a < 2; ++a)
; #pragma unroll
;             for (int b = 0; b < 2; ++b)
; #pragma unroll
;                 for (int m = 0; m < 4; ++m)
; #pragma unroll
;                     for (int n = 0; n < 2; ++n) acc[a][b][m][n] = (f32x4){0.f, 0.f, 0.f, 0.f};
;         cur = nxt; cA = nA; cB = nB; ++ui;
;     }
;     PG8_WAIT_V(0);
;     if (wr == 0) PG8_BAR;
;     PG8_BAR;
;     __device__ __forceinline__ void operator()(const f32x4 (&acc)[2][2][4][2], const Unit& u, int wr, int wc, int fr, int fq) const {
;     ...
; #pragma unroll
;         for (int ai = 0; ai < 2; ++ai)
; #pragma unroll
;             for (int m = 0; m < 4; ++m) { const size_t off = (size_t)(row0 + ai * 128 + m * 16) * DM + colt;
; #pragma unroll
;                 for (int bj = 0; bj < 2; ++bj) {
;                     const h16x8 x = *(const h16x8*)(X + off + bj * 128);
;                     f32x4 o0, o1;
; #pragma unroll
;                     for (int e = 0; e < 4; ++e) { o0[e] = (float)x[e] * ALPHA + acc[ai][bj][m][0][e]; o1[e] = (float)x[4 + e] * ALPHA + acc[ai][bj][m][1][e]; }
;                     *(u32x4*)(PRE + off + bj * 128) = pack8(o0, o1); } }
	v_mov_b64_e32 v[50:51], v[198:199]
	v_mov_b64_e32 v[52:53], v[200:201]
	v_cvt_f32_f16_e32 v58, v50
	v_cvt_f32_f16_sdwa v59, v50 dst_sel:DWORD dst_unused:UNUSED_PAD src0_sel:WORD_1
	v_cvt_f32_f16_e32 v50, v51
	v_cvt_f32_f16_sdwa v51, v51 dst_sel:DWORD dst_unused:UNUSED_PAD src0_sel:WORD_1
	v_pk_fma_f32 v[46:47], v[58:59], s[34:35], v[46:47] op_sel_hi:[1,0,1]
	s_nop 0
	v_cvt_pk_f16_f32 v46, v46, v47
	v_pk_fma_f32 v[48:49], v[50:51], s[34:35], v[48:49] op_sel_hi:[1,0,1]
	v_lshl_add_u64 v[50:51], s[8:9], 0, v[54:55]
	v_cvt_pk_f16_f32 v47, v48, v49
	v_cvt_f32_f16_e32 v48, v52
	v_cvt_f32_f16_sdwa v49, v52 dst_sel:DWORD dst_unused:UNUSED_PAD src0_sel:WORD_1
	v_pk_fma_f32 v[42:43], v[48:49], s[34:35], v[42:43] op_sel_hi:[1,0,1]
	s_nop 0
	v_cvt_pk_f16_f32 v48, v42, v43
	v_cvt_f32_f16_e32 v42, v53
	v_cvt_f32_f16_sdwa v43, v53 dst_sel:DWORD dst_unused:UNUSED_PAD src0_sel:WORD_1
	v_pk_fma_f32 v[42:43], v[42:43], s[34:35], v[44:45] op_sel_hi:[1,0,1]
	s_nop 0
	v_cvt_pk_f16_f32 v49, v42, v43
	s_nop 0
	global_store_dwordx4 v[50:51], v[46:49], off
	s_waitcnt vmcnt(15)
	v_mov_b64_e32 v[42:43], v[202:203]
	v_mov_b64_e32 v[44:45], v[204:205]
	s_nop 0
	v_cvt_f32_f16_e32 v46, v42
	v_cvt_f32_f16_sdwa v47, v42 dst_sel:DWORD dst_unused:UNUSED_PAD src0_sel:WORD_1
	v_cvt_f32_f16_e32 v42, v43
	v_cvt_f32_f16_sdwa v43, v43 dst_sel:DWORD dst_unused:UNUSED_PAD src0_sel:WORD_1
	v_pk_fma_f32 v[38:39], v[46:47], s[34:35], v[38:39] op_sel_hi:[1,0,1]
	s_nop 0
	v_cvt_pk_f16_f32 v38, v38, v39
	v_pk_fma_f32 v[40:41], v[42:43], s[34:35], v[40:41] op_sel_hi:[1,0,1]
	s_nop 0
	v_cvt_pk_f16_f32 v39, v40, v41
	v_cvt_f32_f16_e32 v40, v44
	v_cvt_f32_f16_sdwa v41, v44 dst_sel:DWORD dst_unused:UNUSED_PAD src0_sel:WORD_1
	v_pk_fma_f32 v[34:35], v[40:41], s[34:35], v[34:35] op_sel_hi:[1,0,1]
	s_nop 0
	v_cvt_pk_f16_f32 v40, v34, v35
	v_cvt_f32_f16_e32 v34, v45
	v_cvt_f32_f16_sdwa v35, v45 dst_sel:DWORD dst_unused:UNUSED_PAD src0_sel:WORD_1
	v_pk_fma_f32 v[34:35], v[34:35], s[34:35], v[36:37] op_sel_hi:[1,0,1]
	s_nop 0
	v_cvt_pk_f16_f32 v41, v34, v35
	global_store_dwordx4 v[50:51], v[38:41], off offset:256
	s_nop 1
	v_lshl_add_u64 v[38:39], v[140:141], 0, s[14:15]
	v_lshl_add_u64 v[40:41], s[94:95], 0, v[38:39]
	s_waitcnt vmcnt(15)
	v_mov_b64_e32 v[34:35], v[212:213]
	v_mov_b64_e32 v[36:37], v[214:215]
	v_cvt_f32_f16_e32 v42, v34
	v_cvt_f32_f16_sdwa v43, v34 dst_sel:DWORD dst_unused:UNUSED_PAD src0_sel:WORD_1
	v_cvt_f32_f16_e32 v34, v35
	v_cvt_f32_f16_sdwa v35, v35 dst_sel:DWORD dst_unused:UNUSED_PAD src0_sel:WORD_1
	v_pk_fma_f32 v[30:31], v[42:43], s[34:35], v[30:31] op_sel_hi:[1,0,1]
	s_nop 0
	v_cvt_pk_f16_f32 v30, v30, v31
	v_pk_fma_f32 v[32:33], v[34:35], s[34:35], v[32:33] op_sel_hi:[1,0,1]
	v_lshl_add_u64 v[34:35], s[8:9], 0, v[38:39]
	v_cvt_pk_f16_f32 v31, v32, v33
	v_cvt_f32_f16_e32 v32, v36
	v_cvt_f32_f16_sdwa v33, v36 dst_sel:DWORD dst_unused:UNUSED_PAD src0_sel:WORD_1
	v_pk_fma_f32 v[26:27], v[32:33], s[34:35], v[26:27] op_sel_hi:[1,0,1]
	s_nop 0
	v_cvt_pk_f16_f32 v32, v26, v27
	v_cvt_f32_f16_e32 v26, v37
	v_cvt_f32_f16_sdwa v27, v37 dst_sel:DWORD dst_unused:UNUSED_PAD src0_sel:WORD_1
	v_pk_fma_f32 v[26:27], v[26:27], s[34:35], v[28:29] op_sel_hi:[1,0,1]
	s_nop 0
	v_cvt_pk_f16_f32 v33, v26, v27
	s_nop 0
	global_store_dwordx4 v[34:35], v[30:33], off
	s_waitcnt vmcnt(15)
	v_mov_b64_e32 v[26:27], v[220:221]
	v_mov_b64_e32 v[28:29], v[222:223]
	s_nop 0
	v_cvt_f32_f16_e32 v30, v26
	v_cvt_f32_f16_sdwa v31, v26 dst_sel:DWORD dst_unused:UNUSED_PAD src0_sel:WORD_1
	v_cvt_f32_f16_e32 v26, v27
	v_cvt_f32_f16_sdwa v27, v27 dst_sel:DWORD dst_unused:UNUSED_PAD src0_sel:WORD_1
	v_pk_fma_f32 v[22:23], v[30:31], s[34:35], v[22:23] op_sel_hi:[1,0,1]
	s_nop 0
	v_cvt_pk_f16_f32 v22, v22, v23
	v_pk_fma_f32 v[24:25], v[26:27], s[34:35], v[24:25] op_sel_hi:[1,0,1]
	s_nop 0
	v_cvt_pk_f16_f32 v23, v24, v25
	v_cvt_f32_f16_e32 v24, v28
	v_cvt_f32_f16_sdwa v25, v28 dst_sel:DWORD dst_unused:UNUSED_PAD src0_sel:WORD_1
	v_pk_fma_f32 v[18:19], v[24:25], s[34:35], v[18:19] op_sel_hi:[1,0,1]
	s_nop 0
	v_cvt_pk_f16_f32 v24, v18, v19
	v_cvt_f32_f16_e32 v18, v29
	v_cvt_f32_f16_sdwa v19, v29 dst_sel:DWORD dst_unused:UNUSED_PAD src0_sel:WORD_1
	v_pk_fma_f32 v[18:19], v[18:19], s[34:35], v[20:21] op_sel_hi:[1,0,1]
	s_nop 0
	v_cvt_pk_f16_f32 v25, v18, v19
	global_store_dwordx4 v[34:35], v[22:25], off offset:256
	s_nop 1
	v_lshl_add_u64 v[22:23], v[140:141], 0, s[4:5]
	v_lshl_add_u64 v[24:25], s[94:95], 0, v[22:23]
	s_waitcnt vmcnt(15)
	v_mov_b64_e32 v[18:19], v[224:225]
	v_mov_b64_e32 v[20:21], v[226:227]
	v_cvt_f32_f16_e32 v26, v18
	v_cvt_f32_f16_sdwa v27, v18 dst_sel:DWORD dst_unused:UNUSED_PAD src0_sel:WORD_1
	v_cvt_f32_f16_e32 v18, v19
	v_cvt_f32_f16_sdwa v19, v19 dst_sel:DWORD dst_unused:UNUSED_PAD src0_sel:WORD_1
	v_pk_fma_f32 v[14:15], v[26:27], s[34:35], v[14:15] op_sel_hi:[1,0,1]
	s_nop 0
	v_cvt_pk_f16_f32 v14, v14, v15
	v_pk_fma_f32 v[16:17], v[18:19], s[34:35], v[16:17] op_sel_hi:[1,0,1]
	v_lshl_add_u64 v[18:19], s[8:9], 0, v[22:23]
	v_cvt_pk_f16_f32 v15, v16, v17
	v_cvt_f32_f16_e32 v16, v20
	v_cvt_f32_f16_sdwa v17, v20 dst_sel:DWORD dst_unused:UNUSED_PAD src0_sel:WORD_1
	v_pk_fma_f32 v[10:11], v[16:17], s[34:35], v[10:11] op_sel_hi:[1,0,1]
	s_nop 0
	v_cvt_pk_f16_f32 v16, v10, v11
	v_cvt_f32_f16_e32 v10, v21
	v_cvt_f32_f16_sdwa v11, v21 dst_sel:DWORD dst_unused:UNUSED_PAD src0_sel:WORD_1
	v_pk_fma_f32 v[10:11], v[10:11], s[34:35], v[12:13] op_sel_hi:[1,0,1]
	s_nop 0
	v_cvt_pk_f16_f32 v17, v10, v11
	s_nop 0
	global_store_dwordx4 v[18:19], v[14:17], off
	s_waitcnt vmcnt(15)
	v_mov_b64_e32 v[10:11], v[228:229]
	v_mov_b64_e32 v[12:13], v[230:231]
	s_nop 0
	v_cvt_f32_f16_e32 v14, v10
	v_cvt_f32_f16_sdwa v15, v10 dst_sel:DWORD dst_unused:UNUSED_PAD src0_sel:WORD_1
	v_cvt_f32_f16_e32 v10, v11
	v_cvt_f32_f16_sdwa v11, v11 dst_sel:DWORD dst_unused:UNUSED_PAD src0_sel:WORD_1
	v_pk_fma_f32 v[6:7], v[14:15], s[34:35], v[6:7] op_sel_hi:[1,0,1]
	s_nop 0
	v_cvt_pk_f16_f32 v6, v6, v7
	v_pk_fma_f32 v[8:9], v[10:11], s[34:35], v[8:9] op_sel_hi:[1,0,1]
	s_nop 0
	v_cvt_pk_f16_f32 v7, v8, v9
	v_cvt_f32_f16_e32 v8, v12
	v_cvt_f32_f16_sdwa v9, v12 dst_sel:DWORD dst_unused:UNUSED_PAD src0_sel:WORD_1
	v_pk_fma_f32 v[2:3], v[8:9], s[34:35], v[2:3] op_sel_hi:[1,0,1]
	s_nop 0
	v_cvt_pk_f16_f32 v8, v2, v3
	v_cvt_f32_f16_e32 v2, v13
	v_cvt_f32_f16_sdwa v3, v13 dst_sel:DWORD dst_unused:UNUSED_PAD src0_sel:WORD_1
	v_pk_fma_f32 v[2:3], v[2:3], s[34:35], v[4:5] op_sel_hi:[1,0,1]
	s_nop 0
	v_cvt_pk_f16_f32 v9, v2, v3
	s_mov_b32 s35, s73
	global_store_dwordx4 v[18:19], v[6:9], off offset:256
	s_cbranch_vccz .LBB0_50
	s_waitcnt vmcnt(0)
	s_cmpk_gt_u32 s46, 0xff
	s_cbranch_scc1 .LBB0_65
	s_barrier

; __device__ __forceinline__ int otid() { int t = (int)threadIdx.x; asm volatile("" : "+v"(t)); return t; }
; __device__ __forceinline__ int obid() { int t = (int)blockIdx.x; asm volatile("" : "+s"(t)); return t; }
; #define PG8_STAGE(bufoff, gbase, voff) do { _Pragma("unroll") for (int _i = 0; _i < 2; ++_i) \
;         __builtin_amdgcn_global_load_lds((const unsigned*)((const char*)(gbase) + (voff)[_i]), (LAS unsigned*)(lds + (bufoff) + ldsw + _i * 8192), 16, 0, 0); } while (0)
; #define PG8_WAIT_V(n) asm volatile("s_waitcnt vmcnt(" #n ")" ::: "memory")
; #define PG8_BAR __builtin_amdgcn_s_barrier()
; template <class Epi, class AMap>
; __device__ __forceinline__ void gemm_phase(LAS unsigned char* lds, const AMap am, const int lda, const h16* Bt, const int ldb, const int M, const int N, const int K, const Epi& E) {
;     const int tid = otid(), wid = __builtin_amdgcn_readfirstlane(tid >> 6), lane = tid & 63, wr = wid >> 2, wc = wid & 3, fr = lane & 15, fq = lane >> 4;
;     const int nt = K / BK;
;     Order S; S.init(M, N, (int)gridDim.x, obid());
;     unsigned voffA[2], voffB[2];
; #pragma unroll
;     for (int i = 0; i < 2; ++i) { int R, C; stage_rc(tid * 16 + i * 8192, R, C); const int Rb = Epi::PERM ? ((R & ~31) + perm32(R & 31)) : R;
;         voffA[i] = (unsigned)(R * lda + C) * 2u; voffB[i] = (unsigned)(Rb * ldb + C) * 2u; }
;     const size_t kstep = (size_t)(BK * 2);
;     const size_t hstepA = (size_t)HALF * lda * 2, hstepB = (size_t)HALF * ldb * 2;
;     const size_t tstepA = 2 * hstepA, tstepB = 2 * hstepB;
;     const unsigned ldsw = (unsigned)wid * 1024u;
;     const int aoff = lds_byte(wr * 64 + fr, fq * 8), boff = lds_byte(wc * 32 + fr, fq * 8);
;     ...
;     const char* cA = am(cur.pn) + (size_t)cur.pm * tstepA; const char* cB = (const char*)Bt + (size_t)cur.pn * tstepB;
;     PG8_STAGE(PG8_SB(0, 0), cB, voffB); PG8_STAGE(PG8_SA(0, 0), cA, voffA); PG8_STAGE(PG8_SB(0, 1), cB + hstepB, voffB); PG8_STAGE(PG8_SA(0, 1), cA + hstepA, voffA);
;     if (wr == 1) PG8_BAR;
;     PG8_WAIT_V(4); PG8_BAR;
;     PG8_STAGE(PG8_SB(1, 0), cB + kstep, voffB); PG8_STAGE(PG8_SA(1, 0), cA + kstep, voffA); PG8_STAGE(PG8_SB(1, 1), cB + hstepB + kstep, voffB);
;     PG8_WAIT_V(6); PG8_BAR;
.LBB0_87:
	s_lshl_b32 s0, s0, 5
	s_and_b32 s0, s0, 0x60
	s_lshl_b32 s51, s1, 6
	s_lshl_b32 s1, s1, 13
	s_lshl_b32 s29, s0, 7
	s_add_u32 s8, s74, 0x5600
	s_addc_u32 s9, s75, 0
	s_add_u32 s70, s74, 0xac00
	s_addc_u32 s71, s75, 0
	s_add_i32 m0, s81, 0x18000
	v_lshl_add_u64 v[8:9], v[8:9], 0, s[92:93]
	s_waitcnt vmcnt(0)
	s_barrier
	global_load_lds_dwordx4 v[8:9], off
	v_lshl_add_u64 v[6:7], v[6:7], 0, s[92:93]
	s_add_i32 m0, s81, 0x1a000
	s_add_i32 s89, s81, 0x8000
	s_add_i32 s35, s81, 0xa000
	global_load_lds_dwordx4 v[6:7], off
	v_lshl_add_u64 v[4:5], v[4:5], 0, s[92:93]
	s_mov_b32 m0, s89
	s_add_u32 s20, s48, 0x80080
	global_load_lds_dwordx4 v[4:5], off
	v_lshl_add_u64 v[2:3], v[2:3], 0, s[92:93]
	s_mov_b32 m0, s35
	s_addc_u32 s21, s49, 0
	global_load_lds_dwordx4 v[2:3], off
	s_add_i32 m0, s81, 0x1c000
	v_lshl_add_u64 v[2:3], s[20:21], 0, v[0:1]
	global_load_lds_dwordx4 v[2:3], off
	v_lshl_add_u64 v[2:3], s[20:21], 0, v[162:163]
	s_add_i32 m0, s81, 0x1e000
	v_and_b32_e32 v168, 15, v10
	global_load_lds_dwordx4 v[2:3], off
	v_lshrrev_b32_e32 v2, 1, v10
	v_and_b32_e32 v2, 24, v2
	v_lshlrev_b32_e32 v3, 1, v2
	v_lshlrev_b32_e32 v4, 2, v10
	v_or_b32_e32 v194, s0, v2
	v_lshlrev_b32_e32 v2, 15, v15
	v_lshl_or_b32 v3, v168, 6, v3
	v_and_b32_e32 v4, 32, v4
	v_and_b32_e32 v2, 0xffff0000, v2
	v_bitop3_b32 v5, v3, s1, v4 bitop3:0xde
	v_bitop3_b32 v169, v3, s29, v4 bitop3:0xde
	v_lshl_add_u32 v2, v14, 12, v2
	v_and_b32_e32 v3, 1, v15
	v_lshl_or_b32 v2, v3, 6, v2
	v_lshl_add_u32 v172, v16, 1, v2
	v_lshlrev_b32_e32 v2, 15, v11
	v_and_b32_e32 v2, 0xffff0000, v2
	s_waitcnt vmcnt(6)
	v_lshl_add_u32 v2, v12, 12, v2
	v_and_b32_e32 v3, 1, v11
	v_lshl_or_b32 v2, v3, 6, v2
	s_sext_i32_i16 s23, s24
	s_mov_b32 s24, 0
	v_cmp_eq_u32_e64 s[38:39], 0, v168
	v_cmp_lt_u32_e64 s[40:41], 1, v168
	v_cmp_gt_u32_e64 s[42:43], 2, v168
	v_cmp_lt_u32_e64 s[44:45], 13, v168
	v_add_u32_e32 v170, -14, v168
	v_mov_b32_e32 v171, v1
	v_mov_b32_e32 v173, v1
	v_lshl_add_u32 v174, v13, 1, v2
	v_mov_b32_e32 v175, v1
	v_add_u32_e32 v195, 0, v5
	s_barrier
	s_branch .LBB0_89

; #define PG8_STAGE(bufoff, gbase, voff) do { _Pragma("unroll") for (int _i = 0; _i < 2; ++_i) \
;         __builtin_amdgcn_global_load_lds((const unsigned*)((const char*)(gbase) + (voff)[_i]), (LAS unsigned*)(lds + (bufoff) + ldsw + _i * 8192), 16, 0, 0); } while (0)
; #define PG8_LDA(dst, b, h) do { _Pragma("unroll") for (int m = 0; m < 4; ++m) _Pragma("unroll") for (int k = 0; k < 2; ++k) dst[m][k] = *(const LAS h16x8*)(lds + PG8_SA(b, h) + aoff + m * 2048 + k * 1024); } while (0)
; #define PG8_LDB(dst, b, h) do { _Pragma("unroll") for (int n = 0; n < 2; ++n) _Pragma("unroll") for (int k = 0; k < 2; ++k) dst[n][k] = *(const LAS h16x8*)(lds + PG8_SB(b, h) + boff + n * 2048 + k * 1024); } while (0)
; #define PG8_MMA(ai, bj, At, Bt_) do { __builtin_amdgcn_s_setprio(1); _Pragma("unroll") for (int m = 0; m < 4; ++m) _Pragma("unroll") for (int n = 0; n < 2; ++n) _Pragma("unroll") for (int k = 0; k < 2; ++k) \
;         acc[ai][bj][m][n] = __builtin_amdgcn_mfma_f32_16x16x32_f16(Bt_[n][k], At[m][k], acc[ai][bj][m][n], 0, 0, 0); __builtin_amdgcn_s_setprio(0); } while (0)
; #define PG8_WAIT_V(n) asm volatile("s_waitcnt vmcnt(" #n ")" ::: "memory")
; #define PG8_WAIT_L(n) asm volatile("s_waitcnt lgkmcnt(" #n ")" ::: "memory")
; #define PG8_BAR __builtin_amdgcn_s_barrier()
; #define PG8_SCHED __builtin_amdgcn_sched_barrier(0)
; template <class Epi, class AMap>
; __device__ __forceinline__ void gemm_phase(LAS unsigned char* lds, const AMap am, const int lda, const h16* Bt, const int ldb, const int M, const int N, const int K, const Epi& E) {
;     ...
;             PG8_LDB(B0, 0, 0); PG8_SCHED; PG8_LDA(At, 0, 0); PG8_STAGE(PG8_SA(1, 1), a1 + hstepA, voffA);
;             PG8_WAIT_L(8); PG8_BAR; PG8_WAIT_L(0); PG8_MMA(0, 0, At, B0); PG8_BAR; PG8_SCHED;
;             PG8_LDB(B1, 0, 1); PG8_STAGE(PG8_SB(0, 0), b2, voffB);
;             PG8_BAR; PG8_WAIT_L(0); PG8_MMA(0, 1, At, B1); PG8_BAR;
;             PG8_LDA(At, 0, 1); PG8_STAGE(PG8_SA(0, 0), a2, voffA);
;             PG8_BAR; PG8_WAIT_L(0); PG8_MMA(1, 0, At, B0); PG8_BAR; PG8_SCHED;
;             PG8_STAGE(PG8_SB(0, 1), b2 + hstepB, voffB);
;             PG8_WAIT_V(6); PG8_BAR; PG8_MMA(1, 1, At, B1); PG8_BAR;
.LBB0_92:
	s_add_u32 s0, vcc_lo, 0xfff80080
	s_addc_u32 s1, vcc_hi, -1
	s_add_i32 s67, 0, 0x10000
	v_add_u32_e32 v226, s67, v169
	ds_read_b128 v[66:69], v226
	ds_read_b128 v[70:73], v226 offset:1024
	ds_read_b128 v[74:77], v226 offset:2048
	ds_read_b128 v[78:81], v226 offset:3072
	s_cmp_eq_u32 s60, 28
	s_cselect_b32 s27, s69, s1
	s_cselect_b32 s26, s29, s0
	s_cselect_b32 s49, s73, s66
	s_cselect_b32 s48, s20, s21
	v_lshl_add_u64 v[192:193], vcc, 0, v[172:173]
	s_add_i32 m0, s81, 0xc000
	ds_read_b128 v[90:93], v195
	ds_read_b128 v[94:97], v195 offset:1024
	ds_read_b128 v[98:101], v195 offset:2048
	ds_read_b128 v[102:105], v195 offset:3072
	ds_read_b128 v[176:179], v195 offset:4096
	ds_read_b128 v[180:183], v195 offset:5120
	ds_read_b128 v[184:187], v195 offset:6144
	ds_read_b128 v[188:191], v195 offset:7168
	global_load_lds_dwordx4 v[192:193], off
	v_lshl_add_u64 v[192:193], vcc, 0, v[174:175]
	s_add_i32 m0, s81, 0xe000
	s_nop 0
	global_load_lds_dwordx4 v[192:193], off
	s_waitcnt lgkmcnt(11)
	s_add_i32 s65, 0, 0x14000
	v_add_u32_e32 v192, s65, v169
	s_add_i32 s0, s67, s64
	ds_read_b128 v[196:199], v192
	ds_read_b128 v[200:203], v192 offset:1024
	ds_read_b128 v[204:207], v192 offset:2048
	ds_read_b128 v[220:223], v192 offset:3072
	s_waitcnt lgkmcnt(0)
	s_barrier
	v_mfma_f32_16x16x32_f16 v[158:161], v[66:69], v[90:93], v[158:161]
	v_mfma_f32_16x16x32_f16 v[154:157], v[74:77], v[90:93], v[154:157]
	v_mfma_f32_16x16x32_f16 v[142:145], v[66:69], v[98:101], v[142:145]
	v_mfma_f32_16x16x32_f16 v[134:137], v[74:77], v[98:101], v[134:137]
	v_mfma_f32_16x16x32_f16 v[126:129], v[66:69], v[176:179], v[126:129]
	v_mfma_f32_16x16x32_f16 v[118:121], v[74:77], v[176:179], v[118:121]
	v_mfma_f32_16x16x32_f16 v[110:113], v[66:69], v[184:187], v[110:113]
	v_mfma_f32_16x16x32_f16 v[106:109], v[74:77], v[184:187], v[106:109]
	v_mfma_f32_16x16x32_f16 v[158:161], v[70:73], v[94:97], v[158:161]
	v_mfma_f32_16x16x32_f16 v[154:157], v[78:81], v[94:97], v[154:157]
	v_mfma_f32_16x16x32_f16 v[142:145], v[70:73], v[102:105], v[142:145]
	v_mfma_f32_16x16x32_f16 v[134:137], v[78:81], v[102:105], v[134:137]
	v_mfma_f32_16x16x32_f16 v[126:129], v[70:73], v[180:183], v[126:129]
	v_mfma_f32_16x16x32_f16 v[118:121], v[78:81], v[180:183], v[118:121]
	v_mfma_f32_16x16x32_f16 v[110:113], v[70:73], v[188:191], v[110:113]
	v_mfma_f32_16x16x32_f16 v[106:109], v[78:81], v[188:191], v[106:109]
	v_mfma_f32_16x16x32_f16 v[150:153], v[196:199], v[90:93], v[150:153]
	v_mfma_f32_16x16x32_f16 v[146:149], v[204:207], v[90:93], v[146:149]
	v_mfma_f32_16x16x32_f16 v[150:153], v[200:203], v[94:97], v[150:153]
	v_mfma_f32_16x16x32_f16 v[146:149], v[220:223], v[94:97], v[146:149]
	v_mfma_f32_16x16x32_f16 v[138:141], v[196:199], v[98:101], v[138:141]
	v_mfma_f32_16x16x32_f16 v[130:133], v[204:207], v[98:101], v[130:133]
	v_mfma_f32_16x16x32_f16 v[114:117], v[204:207], v[176:179], v[114:117]
	v_mfma_f32_16x16x32_f16 v[86:89], v[196:199], v[184:187], v[86:89]
	v_mfma_f32_16x16x32_f16 v[82:85], v[204:207], v[184:187], v[82:85]
	v_mfma_f32_16x16x32_f16 v[138:141], v[200:203], v[102:105], v[138:141]
	v_mfma_f32_16x16x32_f16 v[130:133], v[220:223], v[102:105], v[130:133]
	v_mfma_f32_16x16x32_f16 v[122:125], v[196:199], v[176:179], v[122:125]
	v_mfma_f32_16x16x32_f16 v[114:117], v[220:223], v[180:183], v[114:117]
	v_mfma_f32_16x16x32_f16 v[86:89], v[200:203], v[188:191], v[86:89]
	v_mfma_f32_16x16x32_f16 v[82:85], v[220:223], v[188:191], v[82:85]
	v_mfma_f32_16x16x32_f16 v[122:125], v[200:203], v[180:183], v[122:125]
	s_barrier
	v_lshl_add_u64 v[192:193], s[48:49], 0, v[0:1]
	s_mov_b32 m0, s0
	v_lshl_add_u64 v[212:213], s[48:49], 0, v[162:163]
	global_load_lds_dwordx4 v[192:193], off
	s_add_i32 m0, s0, 0x2000
	s_nop 0
	global_load_lds_dwordx4 v[212:213], off
	s_mov_b32 m0, s81
	v_lshl_add_u64 v[214:215], s[26:27], 0, v[166:167]
	ds_read_b128 v[90:93], v195 offset:16384
	ds_read_b128 v[94:97], v195 offset:17408
	ds_read_b128 v[98:101], v195 offset:18432
	ds_read_b128 v[102:105], v195 offset:19456
	ds_read_b128 v[176:179], v195 offset:20480
	ds_read_b128 v[180:183], v195 offset:21504
	ds_read_b128 v[184:187], v195 offset:22528
	ds_read_b128 v[188:191], v195 offset:23552
	global_load_lds_dwordx4 v[214:215], off
	v_lshl_add_u64 v[216:217], s[26:27], 0, v[164:165]
	s_mov_b32 m0, s82
	s_nop 0
	global_load_lds_dwordx4 v[216:217], off
	s_add_u32 s0, s48, 0x80000
	s_addc_u32 s1, s49, 0
	s_add_i32 s65, s65, s64
	v_lshl_add_u64 v[224:225], s[0:1], 0, v[0:1]
	s_mov_b32 m0, s65
	s_nop 0
	global_load_lds_dwordx4 v[224:225], off
	v_lshl_add_u64 v[224:225], s[0:1], 0, v[162:163]
	s_add_i32 m0, s65, 0x2000
	s_nop 0
	global_load_lds_dwordx4 v[224:225], off
	s_waitcnt vmcnt(6) lgkmcnt(0)
	s_barrier
; #define PG8_STAGE(bufoff, gbase, voff) do { _Pragma("unroll") for (int _i = 0; _i < 2; ++_i) \
;         __builtin_amdgcn_global_load_lds((const unsigned*)((const char*)(gbase) + (voff)[_i]), (LAS unsigned*)(lds + (bufoff) + ldsw + _i * 8192), 16, 0, 0); } while (0)
; #define PG8_LDA(dst, b, h) do { _Pragma("unroll") for (int m = 0; m < 4; ++m) _Pragma("unroll") for (int k = 0; k < 2; ++k) dst[m][k] = *(const LAS h16x8*)(lds + PG8_SA(b, h) + aoff + m * 2048 + k * 1024); } while (0)
; #define PG8_LDB(dst, b, h) do { _Pragma("unroll") for (int n = 0; n < 2; ++n) _Pragma("unroll") for (int k = 0; k < 2; ++k) dst[n][k] = *(const LAS h16x8*)(lds + PG8_SB(b, h) + boff + n * 2048 + k * 1024); } while (0)
; #define PG8_MMA(ai, bj, At, Bt_) do { __builtin_amdgcn_s_setprio(1); _Pragma("unroll") for (int m = 0; m < 4; ++m) _Pragma("unroll") for (int n = 0; n < 2; ++n) _Pragma("unroll") for (int k = 0; k < 2; ++k) \
;         acc[ai][bj][m][n] = __builtin_amdgcn_mfma_f32_16x16x32_f16(Bt_[n][k], At[m][k], acc[ai][bj][m][n], 0, 0, 0); __builtin_amdgcn_s_setprio(0); } while (0)
; #define PG8_WAIT_V(n) asm volatile("s_waitcnt vmcnt(" #n ")" ::: "memory")
; #define PG8_WAIT_L(n) asm volatile("s_waitcnt lgkmcnt(" #n ")" ::: "memory")
; #define PG8_BAR __builtin_amdgcn_s_barrier()
; #define PG8_SCHED __builtin_amdgcn_sched_barrier(0)
; template <class Epi, class AMap>
; __device__ __forceinline__ void gemm_phase(LAS unsigned char* lds, const AMap am, const int lda, const h16* Bt, const int ldb, const int M, const int N, const int K, const Epi& E) {
;     ...
;             PG8_BAR; PG8_WAIT_L(0); PG8_MMA(1, 0, At, B0); PG8_BAR; PG8_SCHED;
;             PG8_STAGE(PG8_SB(0, 1), b2 + hstepB, voffB);
;             PG8_WAIT_V(6); PG8_BAR; PG8_MMA(1, 1, At, B1); PG8_BAR;
;             PG8_LDB(B0, 1, 0); PG8_SCHED; PG8_LDA(At, 1, 0); PG8_STAGE(PG8_SA(0, 1), a2 + hstepA, voffA);
;             PG8_WAIT_L(8); PG8_BAR; PG8_WAIT_L(0); PG8_MMA(0, 0, At, B0); PG8_BAR; PG8_SCHED;
;             PG8_LDB(B1, 1, 1); PG8_STAGE(PG8_SB(1, 0), b3, voffB);
;             PG8_BAR; PG8_WAIT_L(0); PG8_MMA(0, 1, At, B1); PG8_BAR;
	v_mfma_f32_16x16x32_f16 v[62:65], v[66:69], v[90:93], v[62:65]
	v_mfma_f32_16x16x32_f16 v[58:61], v[74:77], v[90:93], v[58:61]
	v_mfma_f32_16x16x32_f16 v[46:49], v[66:69], v[98:101], v[46:49]
	v_mfma_f32_16x16x32_f16 v[38:41], v[74:77], v[98:101], v[38:41]
	v_mfma_f32_16x16x32_f16 v[30:33], v[66:69], v[176:179], v[30:33]
	v_mfma_f32_16x16x32_f16 v[22:25], v[74:77], v[176:179], v[22:25]
	v_mfma_f32_16x16x32_f16 v[14:17], v[66:69], v[184:187], v[14:17]
	v_mfma_f32_16x16x32_f16 v[10:13], v[74:77], v[184:187], v[10:13]
	v_mfma_f32_16x16x32_f16 v[62:65], v[70:73], v[94:97], v[62:65]
	v_mfma_f32_16x16x32_f16 v[58:61], v[78:81], v[94:97], v[58:61]
	v_mfma_f32_16x16x32_f16 v[46:49], v[70:73], v[102:105], v[46:49]
	v_mfma_f32_16x16x32_f16 v[38:41], v[78:81], v[102:105], v[38:41]
	v_mfma_f32_16x16x32_f16 v[30:33], v[70:73], v[180:183], v[30:33]
	v_mfma_f32_16x16x32_f16 v[22:25], v[78:81], v[180:183], v[22:25]
	v_mfma_f32_16x16x32_f16 v[14:17], v[70:73], v[188:191], v[14:17]
	v_mfma_f32_16x16x32_f16 v[10:13], v[78:81], v[188:191], v[10:13]
	v_mfma_f32_16x16x32_f16 v[54:57], v[196:199], v[90:93], v[54:57]
	v_mfma_f32_16x16x32_f16 v[50:53], v[204:207], v[90:93], v[50:53]
	v_mfma_f32_16x16x32_f16 v[42:45], v[196:199], v[98:101], v[42:45]
	v_mfma_f32_16x16x32_f16 v[34:37], v[204:207], v[98:101], v[34:37]
	v_mfma_f32_16x16x32_f16 v[26:29], v[196:199], v[176:179], v[26:29]
	v_mfma_f32_16x16x32_f16 v[18:21], v[204:207], v[176:179], v[18:21]
	v_mfma_f32_16x16x32_f16 v[6:9], v[196:199], v[184:187], v[6:9]
	v_mfma_f32_16x16x32_f16 v[2:5], v[204:207], v[184:187], v[2:5]
	v_mfma_f32_16x16x32_f16 v[54:57], v[200:203], v[94:97], v[54:57]
	v_mfma_f32_16x16x32_f16 v[50:53], v[220:223], v[94:97], v[50:53]
	v_mfma_f32_16x16x32_f16 v[42:45], v[200:203], v[102:105], v[42:45]
	v_mfma_f32_16x16x32_f16 v[34:37], v[220:223], v[102:105], v[34:37]
	v_mfma_f32_16x16x32_f16 v[26:29], v[200:203], v[180:183], v[26:29]
	v_mfma_f32_16x16x32_f16 v[18:21], v[220:223], v[180:183], v[18:21]
	v_mfma_f32_16x16x32_f16 v[6:9], v[200:203], v[188:191], v[6:9]
	v_mfma_f32_16x16x32_f16 v[2:5], v[220:223], v[188:191], v[2:5]
	s_barrier
	s_add_i32 s65, 0, 0x18000
	v_add_u32_e32 v226, s65, v169
	ds_read_b128 v[66:69], v226
	ds_read_b128 v[70:73], v226 offset:1024
	ds_read_b128 v[74:77], v226 offset:2048
	ds_read_b128 v[78:81], v226 offset:3072
	s_add_u32 s0, s26, 0x80000
	s_addc_u32 s1, s27, 0
	s_mov_b32 m0, s83
	v_lshl_add_u64 v[224:225], s[0:1], 0, v[166:167]
	ds_read_b128 v[90:93], v195 offset:32768
	ds_read_b128 v[94:97], v195 offset:33792
	ds_read_b128 v[98:101], v195 offset:34816
	ds_read_b128 v[102:105], v195 offset:35840
	ds_read_b128 v[176:179], v195 offset:36864
	ds_read_b128 v[180:183], v195 offset:37888
	ds_read_b128 v[184:187], v195 offset:38912
	ds_read_b128 v[188:191], v195 offset:39936
	global_load_lds_dwordx4 v[224:225], off
	v_lshl_add_u64 v[224:225], s[0:1], 0, v[164:165]
	s_mov_b32 m0, s50
	s_nop 0
	global_load_lds_dwordx4 v[224:225], off
	s_waitcnt lgkmcnt(11)
	s_add_i32 s26, 0, 0x1c000
	v_add_u32_e32 v226, s26, v169
	s_add_i32 s0, s65, s64
	ds_read_b128 v[196:199], v226
	ds_read_b128 v[200:203], v226 offset:1024
	ds_read_b128 v[204:207], v226 offset:2048
	ds_read_b128 v[220:223], v226 offset:3072
	s_waitcnt lgkmcnt(0)
	s_barrier
	v_mfma_f32_16x16x32_f16 v[158:161], v[66:69], v[90:93], v[158:161]
	v_mfma_f32_16x16x32_f16 v[158:161], v[70:73], v[94:97], v[158:161]
	v_mfma_f32_16x16x32_f16 v[154:157], v[74:77], v[90:93], v[154:157]
	v_mfma_f32_16x16x32_f16 v[154:157], v[78:81], v[94:97], v[154:157]
	v_mfma_f32_16x16x32_f16 v[142:145], v[66:69], v[98:101], v[142:145]
	v_mfma_f32_16x16x32_f16 v[134:137], v[74:77], v[98:101], v[134:137]
	v_mfma_f32_16x16x32_f16 v[126:129], v[66:69], v[176:179], v[126:129]
	v_mfma_f32_16x16x32_f16 v[118:121], v[74:77], v[176:179], v[118:121]
	v_mfma_f32_16x16x32_f16 v[110:113], v[66:69], v[184:187], v[110:113]
	v_mfma_f32_16x16x32_f16 v[106:109], v[74:77], v[184:187], v[106:109]
	v_mfma_f32_16x16x32_f16 v[142:145], v[70:73], v[102:105], v[142:145]
	v_mfma_f32_16x16x32_f16 v[134:137], v[78:81], v[102:105], v[134:137]
	v_mfma_f32_16x16x32_f16 v[126:129], v[70:73], v[180:183], v[126:129]
	v_mfma_f32_16x16x32_f16 v[118:121], v[78:81], v[180:183], v[118:121]
	v_mfma_f32_16x16x32_f16 v[110:113], v[70:73], v[188:191], v[110:113]
	v_mfma_f32_16x16x32_f16 v[106:109], v[78:81], v[188:191], v[106:109]
	v_mfma_f32_16x16x32_f16 v[146:149], v[204:207], v[90:93], v[146:149]
	v_mfma_f32_16x16x32_f16 v[150:153], v[196:199], v[90:93], v[150:153]
	v_mfma_f32_16x16x32_f16 v[146:149], v[220:223], v[94:97], v[146:149]
	v_mfma_f32_16x16x32_f16 v[138:141], v[196:199], v[98:101], v[138:141]
	v_mfma_f32_16x16x32_f16 v[150:153], v[200:203], v[94:97], v[150:153]
	v_mfma_f32_16x16x32_f16 v[138:141], v[200:203], v[102:105], v[138:141]
	v_mfma_f32_16x16x32_f16 v[130:133], v[204:207], v[98:101], v[130:133]
	v_mfma_f32_16x16x32_f16 v[130:133], v[220:223], v[102:105], v[130:133]
	v_mfma_f32_16x16x32_f16 v[122:125], v[196:199], v[176:179], v[122:125]
	v_mfma_f32_16x16x32_f16 v[122:125], v[200:203], v[180:183], v[122:125]
	v_mfma_f32_16x16x32_f16 v[114:117], v[204:207], v[176:179], v[114:117]
	v_mfma_f32_16x16x32_f16 v[86:89], v[196:199], v[184:187], v[86:89]
	v_mfma_f32_16x16x32_f16 v[82:85], v[204:207], v[184:187], v[82:85]
	v_mfma_f32_16x16x32_f16 v[114:117], v[220:223], v[180:183], v[114:117]
	v_mfma_f32_16x16x32_f16 v[86:89], v[200:203], v[188:191], v[86:89]
	v_mfma_f32_16x16x32_f16 v[82:85], v[220:223], v[188:191], v[82:85]
	s_barrier
; #define PG8_STAGE(bufoff, gbase, voff) do { _Pragma("unroll") for (int _i = 0; _i < 2; ++_i) \
;         __builtin_amdgcn_global_load_lds((const unsigned*)((const char*)(gbase) + (voff)[_i]), (LAS unsigned*)(lds + (bufoff) + ldsw + _i * 8192), 16, 0, 0); } while (0)
; #define PG8_LDA(dst, b, h) do { _Pragma("unroll") for (int m = 0; m < 4; ++m) _Pragma("unroll") for (int k = 0; k < 2; ++k) dst[m][k] = *(const LAS h16x8*)(lds + PG8_SA(b, h) + aoff + m * 2048 + k * 1024); } while (0)
; #define PG8_LDB(dst, b, h) do { _Pragma("unroll") for (int n = 0; n < 2; ++n) _Pragma("unroll") for (int k = 0; k < 2; ++k) dst[n][k] = *(const LAS h16x8*)(lds + PG8_SB(b, h) + boff + n * 2048 + k * 1024); } while (0)
; #define PG8_MMA(ai, bj, At, Bt_) do { __builtin_amdgcn_s_setprio(1); _Pragma("unroll") for (int m = 0; m < 4; ++m) _Pragma("unroll") for (int n = 0; n < 2; ++n) _Pragma("unroll") for (int k = 0; k < 2; ++k) \
;         acc[ai][bj][m][n] = __builtin_amdgcn_mfma_f32_16x16x32_f16(Bt_[n][k], At[m][k], acc[ai][bj][m][n], 0, 0, 0); __builtin_amdgcn_s_setprio(0); } while (0)
; #define PG8_WAIT_V(n) asm volatile("s_waitcnt vmcnt(" #n ")" ::: "memory")
; #define PG8_WAIT_L(n) asm volatile("s_waitcnt lgkmcnt(" #n ")" ::: "memory")
; #define PG8_BAR __builtin_amdgcn_s_barrier()
; #define PG8_SCHED __builtin_amdgcn_sched_barrier(0)
; template <class Epi, class AMap>
; __device__ __forceinline__ void gemm_phase(LAS unsigned char* lds, const AMap am, const int lda, const h16* Bt, const int ldb, const int M, const int N, const int K, const Epi& E) {
;     ...
;             PG8_LDB(B0, 1, 0); PG8_SCHED; PG8_LDA(At, 1, 0); PG8_STAGE(PG8_SA(0, 1), a2 + hstepA, voffA);
;             PG8_WAIT_L(8); PG8_BAR; PG8_WAIT_L(0); PG8_MMA(0, 0, At, B0); PG8_BAR; PG8_SCHED;
;             PG8_LDB(B1, 1, 1); PG8_STAGE(PG8_SB(1, 0), b3, voffB);
;             PG8_BAR; PG8_WAIT_L(0); PG8_MMA(0, 1, At, B1); PG8_BAR;
;             PG8_LDA(At, 1, 1); PG8_STAGE(PG8_SA(1, 0), a3, voffA);
;             PG8_BAR; PG8_WAIT_L(0); PG8_MMA(1, 0, At, B0); PG8_BAR; PG8_SCHED;
;             PG8_STAGE(PG8_SB(1, 1), b3 + hstepB, voffB);
;             PG8_WAIT_V(6); PG8_BAR; PG8_MMA(1, 1, At, B1); PG8_BAR;
	v_lshl_add_u64 v[224:225], v[192:193], 0, s[92:93]
	s_mov_b32 m0, s0
	s_nop 0
	global_load_lds_dwordx4 v[224:225], off
	v_lshl_add_u64 v[224:225], v[212:213], 0, s[92:93]
	s_add_i32 m0, s0, 0x2000
	s_nop 0
	global_load_lds_dwordx4 v[224:225], off
	s_mov_b32 m0, s89
	v_lshl_add_u64 v[192:193], v[214:215], 0, s[92:93]
	ds_read_b128 v[90:93], v195 offset:49152
	ds_read_b128 v[94:97], v195 offset:50176
	ds_read_b128 v[98:101], v195 offset:51200
	ds_read_b128 v[102:105], v195 offset:52224
	ds_read_b128 v[176:179], v195 offset:53248
	ds_read_b128 v[180:183], v195 offset:54272
	ds_read_b128 v[184:187], v195 offset:55296
	ds_read_b128 v[188:191], v195 offset:56320
	global_load_lds_dwordx4 v[192:193], off
	v_lshl_add_u64 v[192:193], v[216:217], 0, s[92:93]
	s_mov_b32 m0, s35
	s_nop 0
	global_load_lds_dwordx4 v[192:193], off
	s_add_u32 s0, s48, 0x80080
	s_addc_u32 s1, s49, 0
	s_add_i32 s26, s26, s64
	v_lshl_add_u64 v[224:225], s[0:1], 0, v[0:1]
	s_mov_b32 m0, s26
	s_nop 0
	global_load_lds_dwordx4 v[224:225], off
	v_lshl_add_u64 v[224:225], s[0:1], 0, v[162:163]
	s_add_i32 m0, s26, 0x2000
	s_nop 0
	global_load_lds_dwordx4 v[224:225], off
	s_waitcnt vmcnt(6) lgkmcnt(0)
	s_barrier
	v_mfma_f32_16x16x32_f16 v[62:65], v[66:69], v[90:93], v[62:65]
	v_mfma_f32_16x16x32_f16 v[58:61], v[74:77], v[90:93], v[58:61]
	v_mfma_f32_16x16x32_f16 v[46:49], v[66:69], v[98:101], v[46:49]
	v_mfma_f32_16x16x32_f16 v[38:41], v[74:77], v[98:101], v[38:41]
	v_mfma_f32_16x16x32_f16 v[30:33], v[66:69], v[176:179], v[30:33]
	v_mfma_f32_16x16x32_f16 v[22:25], v[74:77], v[176:179], v[22:25]
	v_mfma_f32_16x16x32_f16 v[14:17], v[66:69], v[184:187], v[14:17]
	v_mfma_f32_16x16x32_f16 v[10:13], v[74:77], v[184:187], v[10:13]
	v_mfma_f32_16x16x32_f16 v[62:65], v[70:73], v[94:97], v[62:65]
	v_mfma_f32_16x16x32_f16 v[58:61], v[78:81], v[94:97], v[58:61]
	v_mfma_f32_16x16x32_f16 v[46:49], v[70:73], v[102:105], v[46:49]
	v_mfma_f32_16x16x32_f16 v[38:41], v[78:81], v[102:105], v[38:41]
	v_mfma_f32_16x16x32_f16 v[30:33], v[70:73], v[180:183], v[30:33]
	v_mfma_f32_16x16x32_f16 v[22:25], v[78:81], v[180:183], v[22:25]
	v_mfma_f32_16x16x32_f16 v[14:17], v[70:73], v[188:191], v[14:17]
	v_mfma_f32_16x16x32_f16 v[10:13], v[78:81], v[188:191], v[10:13]
	v_mfma_f32_16x16x32_f16 v[54:57], v[196:199], v[90:93], v[54:57]
	v_mfma_f32_16x16x32_f16 v[50:53], v[204:207], v[90:93], v[50:53]
	v_mfma_f32_16x16x32_f16 v[42:45], v[196:199], v[98:101], v[42:45]
	v_mfma_f32_16x16x32_f16 v[34:37], v[204:207], v[98:101], v[34:37]
	v_mfma_f32_16x16x32_f16 v[26:29], v[196:199], v[176:179], v[26:29]
	v_mfma_f32_16x16x32_f16 v[18:21], v[204:207], v[176:179], v[18:21]
	v_mfma_f32_16x16x32_f16 v[6:9], v[196:199], v[184:187], v[6:9]
	v_mfma_f32_16x16x32_f16 v[2:5], v[204:207], v[184:187], v[2:5]
	v_mfma_f32_16x16x32_f16 v[54:57], v[200:203], v[94:97], v[54:57]
	v_mfma_f32_16x16x32_f16 v[50:53], v[220:223], v[94:97], v[50:53]
	v_mfma_f32_16x16x32_f16 v[42:45], v[200:203], v[102:105], v[42:45]
	v_mfma_f32_16x16x32_f16 v[34:37], v[220:223], v[102:105], v[34:37]
	v_mfma_f32_16x16x32_f16 v[26:29], v[200:203], v[180:183], v[26:29]
	v_mfma_f32_16x16x32_f16 v[18:21], v[220:223], v[180:183], v[18:21]
	v_mfma_f32_16x16x32_f16 v[6:9], v[200:203], v[188:191], v[6:9]
	v_mfma_f32_16x16x32_f16 v[2:5], v[220:223], v[188:191], v[2:5]
	s_add_i32 s60, s60, 2
	s_add_u32 vcc_lo, vcc_lo, 0x100
	s_addc_u32 vcc_hi, vcc_hi, 0
	s_add_u32 s21, s21, 0x100
	s_addc_u32 s66, s66, 0
	s_cmp_gt_u32 s60, 29
	s_barrier
	s_cbranch_scc0 .LBB0_92
; template <int CTRL> __device__ __forceinline__ float dpp_f(float x) { return __int_as_float(__builtin_amdgcn_update_dpp(0, __float_as_int(x), CTRL, 0xF, 0xF, true)); }
;     __device__ __forceinline__ void operator()(const f32x4 (&acc)[2][2][4][2], const Unit& u, int wr, int wc, int fr, int fq) const {
;         const int row0 = u.pm * 256 + wr * 64 + fr, f0 = u.pn * 128 + wc * 32 + 8 * fq;
;         f32x4 w0[2], w1[2], w2[2], bb[2];
; #pragma unroll
;         for (int n = 0; n < 2; ++n) { w0[n] = *(const f32x4*)(cw + f0 + 4 * n); w1[n] = *(const f32x4*)(cw + FF + f0 + 4 * n); w2[n] = *(const f32x4*)(cw + 2 * FF + f0 + 4 * n); bb[n] = *(const f32x4*)(cb + f0 + 4 * n); }
; #pragma unroll
;         for (int ai = 0; ai < 2; ++ai) {
;             f32x4 p1[2], p2[2];
; #pragma unroll
;             for (int n = 0; n < 2; ++n) { p1[n] = (f32x4){0.f, 0.f, 0.f, 0.f}; p2[n] = p1[n]; }
; #pragma unroll
;             for (int m = 0; m < 4; ++m) {
;                 const int row = row0 + ai * 128 + m * 16;
;                 f32x4 r1[2], r2[2], o[2];
; #pragma unroll
;                 for (int n = 0; n < 2; ++n)
; #pragma unroll
;                     for (int e = 0; e < 4; ++e) {
;                         const float g = acc[ai][1][m][n][e];
;                         r1[n][e] = dpp_f<0x121>(g); r2[n][e] = dpp_f<0x122>(g);
;                         const float g1 = fr >= 1 ? r1[n][e] : p1[n][e], g2 = fr >= 2 ? r2[n][e] : p2[n][e];
;                         const float gc = bb[n][e] + g2 * w0[n][e] + g1 * w1[n][e] + g * w2[n][e];
;                         o[n][e] = gelu_mul(acc[ai][0][m][n][e], gc);
;                     }
;                 if (m > 0 || fr >= 2) *(u32x4*)(ACT + (size_t)row * FF + f0) = pack8(o[0], o[1]);
	v_lshl_or_b32 v176, s23, 7, v194
	v_ashrrev_i32_e32 v177, 31, v176
	v_lshlrev_b64 v[66:67], 2, v[176:177]
	v_lshl_add_u64 v[70:71], s[74:75], 0, v[66:67]
	v_lshl_add_u64 v[74:75], s[8:9], 0, v[66:67]
	v_lshl_add_u64 v[78:79], s[70:71], 0, v[66:67]
	v_lshl_add_u64 v[102:103], s[78:79], 0, v[66:67]
	global_load_dwordx4 v[66:69], v[70:71], off offset:16
	global_load_dwordx4 v[90:93], v[70:71], off
	s_nop 0
	global_load_dwordx4 v[70:73], v[74:75], off offset:16
	global_load_dwordx4 v[94:97], v[74:75], off
	s_nop 0
	global_load_dwordx4 v[74:77], v[78:79], off offset:16
	global_load_dwordx4 v[98:101], v[78:79], off
	s_nop 0
	global_load_dwordx4 v[78:81], v[102:103], off offset:16
	s_nop 0
	global_load_dwordx4 v[102:105], v[102:103], off
	s_lshl_b32 s20, s22, 8
	s_add_i32 s20, s20, s51
	v_or_b32_e32 v196, s20, v168
	v_mov_b32_dpp v192, v150 row_ror:1 row_mask:0xf bank_mask:0xf bound_ctrl:1
	v_mov_b32_dpp v190, v150 row_ror:2 row_mask:0xf bank_mask:0xf bound_ctrl:1
	v_mov_b32_dpp v193, v151 row_ror:1 row_mask:0xf bank_mask:0xf bound_ctrl:1
	v_mov_b32_dpp v191, v151 row_ror:2 row_mask:0xf bank_mask:0xf bound_ctrl:1
	v_mov_b32_dpp v188, v152 row_ror:1 row_mask:0xf bank_mask:0xf bound_ctrl:1
	v_mov_b32_dpp v186, v152 row_ror:2 row_mask:0xf bank_mask:0xf bound_ctrl:1
	v_mov_b32_dpp v189, v153 row_ror:1 row_mask:0xf bank_mask:0xf bound_ctrl:1
	v_mov_b32_dpp v187, v153 row_ror:2 row_mask:0xf bank_mask:0xf bound_ctrl:1
	v_mov_b32_dpp v184, v146 row_ror:1 row_mask:0xf bank_mask:0xf bound_ctrl:1
	v_mov_b32_dpp v182, v146 row_ror:2 row_mask:0xf bank_mask:0xf bound_ctrl:1
	v_mov_b32_dpp v185, v147 row_ror:1 row_mask:0xf bank_mask:0xf bound_ctrl:1
	v_mov_b32_dpp v183, v147 row_ror:2 row_mask:0xf bank_mask:0xf bound_ctrl:1
	v_mov_b32_dpp v180, v148 row_ror:1 row_mask:0xf bank_mask:0xf bound_ctrl:1
	v_mov_b32_dpp v178, v148 row_ror:2 row_mask:0xf bank_mask:0xf bound_ctrl:1
	v_mov_b32_dpp v181, v149 row_ror:1 row_mask:0xf bank_mask:0xf bound_ctrl:1
	v_mov_b32_dpp v179, v149 row_ror:2 row_mask:0xf bank_mask:0xf bound_ctrl:1
	s_and_saveexec_b64 s[22:23], s[40:41]
	s_cbranch_execz .LBB0_95
	s_waitcnt vmcnt(0)
	v_pk_fma_f32 v[198:199], v[90:91], v[190:191], v[102:103]
	v_readlane_b32 s0, v254, 58
	v_pk_fma_f32 v[198:199], v[94:95], v[192:193], v[198:199]
	v_readlane_b32 s1, v254, 59
	v_pk_fma_f32 v[198:199], v[150:151], v[98:99], v[198:199]
	s_nop 0
	v_pk_mul_f32 v[200:201], v[198:199], v[198:199]
	v_pk_mul_f32 v[202:203], v[158:159], v[198:199]
	v_fmamk_f32 v197, v201, 0x3dd2d3e7, v241
	v_mul_f32_e64 v197, v199, -v197
	v_exp_f32_e32 v197, v197
	s_nop 0
	v_add_f32_e32 v197, 1.0, v197
	v_rcp_f32_e32 v201, v197
	v_fmamk_f32 v197, v200, 0x3dd2d3e7, v241
	v_mul_f32_e64 v197, v198, -v197
	v_exp_f32_e32 v197, v197
	s_nop 0
	v_add_f32_e32 v197, 1.0, v197
	v_rcp_f32_e32 v200, v197
	s_nop 0
	v_pk_mul_f32 v[198:199], v[202:203], v[200:201]
	v_pk_fma_f32 v[200:201], v[92:93], v[186:187], v[104:105]
	v_cvt_pk_f16_f32 v198, v198, v199
	v_pk_fma_f32 v[200:201], v[96:97], v[188:189], v[200:201]
	s_nop 0
	v_pk_fma_f32 v[200:201], v[152:153], v[100:101], v[200:201]
	s_nop 0
	v_pk_mul_f32 v[202:203], v[200:201], v[200:201]
	v_pk_mul_f32 v[204:205], v[160:161], v[200:201]
	v_fmamk_f32 v197, v203, 0x3dd2d3e7, v241
	v_mul_f32_e64 v197, v201, -v197
	v_exp_f32_e32 v197, v197
	s_nop 0
	v_add_f32_e32 v197, 1.0, v197
	v_rcp_f32_e32 v203, v197
	v_fmamk_f32 v197, v202, 0x3dd2d3e7, v241
	v_mul_f32_e64 v197, v200, -v197
	v_exp_f32_e32 v197, v197
	s_nop 0
	v_add_f32_e32 v197, 1.0, v197
	v_rcp_f32_e32 v202, v197
	s_nop 0
	v_pk_mul_f32 v[200:201], v[204:205], v[202:203]
	s_nop 0
	v_cvt_pk_f16_f32 v199, v200, v201
	v_pk_fma_f32 v[200:201], v[66:67], v[182:183], v[78:79]
	s_nop 0
	v_pk_fma_f32 v[200:201], v[70:71], v[184:185], v[200:201]
	s_nop 0
	v_pk_fma_f32 v[200:201], v[146:147], v[74:75], v[200:201]
	s_nop 0
	v_pk_mul_f32 v[202:203], v[200:201], v[200:201]
	v_pk_mul_f32 v[204:205], v[154:155], v[200:201]
	v_fmamk_f32 v197, v203, 0x3dd2d3e7, v241
	v_mul_f32_e64 v197, v201, -v197
	v_exp_f32_e32 v197, v197
	s_nop 0
	v_add_f32_e32 v197, 1.0, v197
	v_rcp_f32_e32 v203, v197
	v_fmamk_f32 v197, v202, 0x3dd2d3e7, v241
	v_mul_f32_e64 v197, v200, -v197
	v_exp_f32_e32 v197, v197
	s_nop 0
	v_add_f32_e32 v197, 1.0, v197
	v_rcp_f32_e32 v202, v197
	s_nop 0
	v_pk_mul_f32 v[200:201], v[204:205], v[202:203]
	v_pk_fma_f32 v[202:203], v[68:69], v[178:179], v[80:81]
	v_cvt_pk_f16_f32 v200, v200, v201
	v_pk_fma_f32 v[202:203], v[72:73], v[180:181], v[202:203]
	s_nop 0
	v_pk_fma_f32 v[202:203], v[148:149], v[76:77], v[202:203]
	s_nop 0
	v_pk_mul_f32 v[204:205], v[202:203], v[202:203]
	v_pk_mul_f32 v[206:207], v[156:157], v[202:203]
	v_fmamk_f32 v197, v204, 0x3dd2d3e7, v241
	v_mul_f32_e64 v197, v202, -v197
	v_exp_f32_e32 v197, v197
	s_nop 0
	v_add_f32_e32 v197, 1.0, v197
	v_rcp_f32_e32 v204, v197
	v_fmamk_f32 v197, v205, 0x3dd2d3e7, v241
	v_mul_f32_e64 v197, v203, -v197
	v_exp_f32_e32 v197, v197
	s_nop 0
	v_add_f32_e32 v197, 1.0, v197
	v_rcp_f32_e32 v205, v197
	s_nop 0
	v_pk_mul_f32 v[202:203], v[206:207], v[204:205]
	s_nop 0
	v_cvt_pk_f16_f32 v201, v202, v203
	v_mov_b64_e32 v[202:203], s[0:1]
	v_mad_i64_i32 v[202:203], s[26:27], v196, s13, v[202:203]
	v_lshl_add_u64 v[202:203], v[176:177], 1, v[202:203]
	global_store_dwordx4 v[202:203], v[198:201], off

; __device__ __forceinline__ int otid() { int t = (int)threadIdx.x; asm volatile("" : "+v"(t)); return t; }
; __device__ __forceinline__ int obid() { int t = (int)blockIdx.x; asm volatile("" : "+s"(t)); return t; }
; #define PG8_STAGE(bufoff, gbase, voff) do { _Pragma("unroll") for (int _i = 0; _i < 2; ++_i) \
;         __builtin_amdgcn_global_load_lds((const unsigned*)((const char*)(gbase) + (voff)[_i]), (LAS unsigned*)(lds + (bufoff) + ldsw + _i * 8192), 16, 0, 0); } while (0)
; #define PG8_WAIT_V(n) asm volatile("s_waitcnt vmcnt(" #n ")" ::: "memory")
; #define PG8_BAR __builtin_amdgcn_s_barrier()
; template <class Epi, class AMap>
; __device__ __forceinline__ void gemm_phase(LAS unsigned char* lds, const AMap am, const int lda, const h16* Bt, const int ldb, const int M, const int N, const int K, const Epi& E) {
;     const int tid = otid(), wid = __builtin_amdgcn_readfirstlane(tid >> 6), lane = tid & 63, wr = wid >> 2, wc = wid & 3, fr = lane & 15, fq = lane >> 4;
;     const int nt = K / BK;
;     Order S; S.init(M, N, (int)gridDim.x, obid());
;     unsigned voffA[2], voffB[2];
; #pragma unroll
;     for (int i = 0; i < 2; ++i) { int R, C; stage_rc(tid * 16 + i * 8192, R, C); const int Rb = Epi::PERM ? ((R & ~31) + perm32(R & 31)) : R;
;         voffA[i] = (unsigned)(R * lda + C) * 2u; voffB[i] = (unsigned)(Rb * ldb + C) * 2u; }
;     const size_t kstep = (size_t)(BK * 2);
;     const size_t hstepA = (size_t)HALF * lda * 2, hstepB = (size_t)HALF * ldb * 2;
;     const size_t tstepA = 2 * hstepA, tstepB = 2 * hstepB;
;     const unsigned ldsw = (unsigned)wid * 1024u;
;     const int aoff = lds_byte(wr * 64 + fr, fq * 8), boff = lds_byte(wc * 32 + fr, fq * 8);
;     ...
;     const char* cA = am(cur.pn) + (size_t)cur.pm * tstepA; const char* cB = (const char*)Bt + (size_t)cur.pn * tstepB;
;     PG8_STAGE(PG8_SB(0, 0), cB, voffB); PG8_STAGE(PG8_SA(0, 0), cA, voffA); PG8_STAGE(PG8_SB(0, 1), cB + hstepB, voffB); PG8_STAGE(PG8_SA(0, 1), cA + hstepA, voffA);
;     if (wr == 1) PG8_BAR;
;     PG8_WAIT_V(4); PG8_BAR;
;     PG8_STAGE(PG8_SB(1, 0), cB + kstep, voffB); PG8_STAGE(PG8_SA(1, 0), cA + kstep, voffA); PG8_STAGE(PG8_SB(1, 1), cB + hstepB + kstep, voffB);
;     PG8_WAIT_V(6); PG8_BAR;
.LBB0_139:
	v_lshrrev_b32_e32 v18, 1, v8
	v_and_b32_e32 v18, 24, v18
	v_and_b32_e32 v9, 15, v8
	v_lshlrev_b32_e32 v19, 1, v18
	v_lshlrev_b32_e32 v8, 2, v8
	s_sext_i32_i8 s35, s0
	v_lshl_or_b32 v146, s20, 6, v9
	v_lshl_or_b32 v9, v9, 6, v19
	s_lshl_b32 s0, s20, 13
	v_and_b32_e32 v8, 32, v8
	v_bitop3_b32 v19, v9, s0, v8 bitop3:0xde
	s_lshl_b32 s0, s1, 5
	s_and_b32 s20, s0, 0x60
	v_lshl_add_u64 v[10:11], s[46:47], 0, v[0:1]
	v_mov_b32_e32 v135, v1
	s_lshl_b32 s0, s20, 7
	v_lshl_add_u64 v[12:13], s[46:47], 0, v[134:135]
	v_mov_b32_e32 v131, v1
	v_bitop3_b32 v147, v9, s0, v8 bitop3:0xde
	s_add_i32 m0, s23, 0x18000
	v_lshl_add_u64 v[8:9], v[10:11], 0, s[92:93]
	v_lshl_add_u64 v[14:15], s[26:27], 0, v[130:131]
	v_mov_b32_e32 v133, v1
	s_waitcnt vmcnt(0)
	s_barrier
	global_load_lds_dwordx4 v[8:9], off
	v_lshl_add_u64 v[8:9], v[12:13], 0, s[92:93]
	s_add_i32 m0, s23, 0x1a000
	s_add_i32 s74, s23, 0x8000
	s_add_i32 s75, s23, 0xa000
	v_lshl_add_u64 v[16:17], s[26:27], 0, v[132:133]
	global_load_lds_dwordx4 v[8:9], off
	v_lshl_add_u64 v[8:9], v[14:15], 0, s[92:93]
	s_mov_b32 m0, s74
	s_add_u32 s0, s46, 0x80080
	global_load_lds_dwordx4 v[8:9], off
	v_lshl_add_u64 v[8:9], v[16:17], 0, s[92:93]
	s_mov_b32 m0, s75
	s_addc_u32 s1, s47, 0
	global_load_lds_dwordx4 v[8:9], off
	s_add_i32 m0, s23, 0x1c000
	v_lshl_add_u64 v[8:9], s[0:1], 0, v[0:1]
	global_load_lds_dwordx4 v[8:9], off
	v_lshl_add_u64 v[8:9], s[0:1], 0, v[134:135]
	s_add_i32 m0, s23, 0x1e000
	v_or_b32_e32 v148, s20, v18
	global_load_lds_dwordx4 v[8:9], off
	v_lshlrev_b32_e32 v8, 15, v2
	v_and_b32_e32 v8, 0xffff0000, v8
	v_lshl_add_u32 v3, v3, 12, v8
	v_and_b32_e32 v2, 1, v2
	v_lshl_or_b32 v2, v2, 6, v3
	v_lshl_add_u32 v136, v4, 1, v2
	v_lshlrev_b32_e32 v2, 15, v5
	v_and_b32_e32 v2, 0xffff0000, v2
	s_waitcnt vmcnt(6)
	v_lshl_add_u32 v2, v6, 12, v2
	v_and_b32_e32 v3, 1, v5
	v_lshl_or_b32 v2, v3, 6, v2
	v_mov_b32_e32 v137, v1
	v_lshl_add_u32 v138, v7, 1, v2
	v_mov_b32_e32 v139, v1
	s_mov_b32 s76, 0
	v_add_u32_e32 v149, 0, v19
	s_barrier

; #define PG8_STAGE(bufoff, gbase, voff) do { _Pragma("unroll") for (int _i = 0; _i < 2; ++_i) \
;         __builtin_amdgcn_global_load_lds((const unsigned*)((const char*)(gbase) + (voff)[_i]), (LAS unsigned*)(lds + (bufoff) + ldsw + _i * 8192), 16, 0, 0); } while (0)
; #define PG8_LDA(dst, b, h) do { _Pragma("unroll") for (int m = 0; m < 4; ++m) _Pragma("unroll") for (int k = 0; k < 2; ++k) dst[m][k] = *(const LAS h16x8*)(lds + PG8_SA(b, h) + aoff + m * 2048 + k * 1024); } while (0)
; #define PG8_LDB(dst, b, h) do { _Pragma("unroll") for (int n = 0; n < 2; ++n) _Pragma("unroll") for (int k = 0; k < 2; ++k) dst[n][k] = *(const LAS h16x8*)(lds + PG8_SB(b, h) + boff + n * 2048 + k * 1024); } while (0)
; #define PG8_MMA(ai, bj, At, Bt_) do { __builtin_amdgcn_s_setprio(1); _Pragma("unroll") for (int m = 0; m < 4; ++m) _Pragma("unroll") for (int n = 0; n < 2; ++n) _Pragma("unroll") for (int k = 0; k < 2; ++k) \
;         acc[ai][bj][m][n] = __builtin_amdgcn_mfma_f32_16x16x32_f16(Bt_[n][k], At[m][k], acc[ai][bj][m][n], 0, 0, 0); __builtin_amdgcn_s_setprio(0); } while (0)
; #define PG8_WAIT_L(n) asm volatile("s_waitcnt lgkmcnt(" #n ")" ::: "memory")
; #define PG8_BAR __builtin_amdgcn_s_barrier()
; #define PG8_SCHED __builtin_amdgcn_sched_barrier(0)
; template <class Epi, class AMap>
; __device__ __forceinline__ void gemm_phase(LAS unsigned char* lds, const AMap am, const int lda, const h16* Bt, const int ldb, const int M, const int N, const int K, const Epi& E) {
;     ...
;             PG8_LDB(B0, 0, 0); PG8_SCHED; PG8_LDA(At, 0, 0); PG8_STAGE(PG8_SA(1, 1), a1 + hstepA, voffA);
;             PG8_WAIT_L(8); PG8_BAR; PG8_WAIT_L(0); PG8_MMA(0, 0, At, B0); PG8_BAR; PG8_SCHED;
;             PG8_LDB(B1, 0, 1); PG8_STAGE(PG8_SB(0, 0), b2, voffB);
;             PG8_BAR; PG8_WAIT_L(0); PG8_MMA(0, 1, At, B1); PG8_BAR;
;             PG8_LDA(At, 0, 1); PG8_STAGE(PG8_SA(0, 0), a2, voffA);
;             PG8_BAR; PG8_WAIT_L(0); PG8_MMA(1, 0, At, B0); PG8_BAR; PG8_SCHED;
.LBB0_147:
	s_add_u32 s46, s26, 0xfff80080
	s_addc_u32 s47, s27, -1
	s_add_i32 s60, 0, 0x10000
	v_add_u32_e32 v144, s60, v147
	ds_read_b128 v[140:143], v144
	ds_read_b128 v[150:153], v144 offset:1024
	ds_read_b128 v[154:157], v144 offset:2048
	ds_read_b128 v[158:161], v144 offset:3072
	s_cmp_eq_u32 s51, 28
	s_cselect_b32 s49, s41, s47
	s_cselect_b32 s48, s29, s46
	s_cselect_b32 s47, s1, s50
	s_cselect_b32 s46, s20, s21
	v_lshl_add_u64 v[144:145], s[26:27], 0, v[136:137]
	s_add_i32 m0, s23, 0xc000
	ds_read_b128 v[162:165], v149
	ds_read_b128 v[166:169], v149 offset:1024
	ds_read_b128 v[170:173], v149 offset:2048
	ds_read_b128 v[174:177], v149 offset:3072
	ds_read_b128 v[178:181], v149 offset:4096
	ds_read_b128 v[182:185], v149 offset:5120
	ds_read_b128 v[186:189], v149 offset:6144
	ds_read_b128 v[190:193], v149 offset:7168
	global_load_lds_dwordx4 v[144:145], off
	v_lshl_add_u64 v[144:145], s[26:27], 0, v[138:139]
	s_add_i32 m0, s23, 0xe000
	s_nop 0
	global_load_lds_dwordx4 v[144:145], off
	s_waitcnt lgkmcnt(11)
	s_add_i32 s66, 0, 0x14000
	v_add_u32_e32 v144, s66, v147
	s_add_i32 s60, s60, s64
	ds_read_b128 v[194:197], v144
	ds_read_b128 v[198:201], v144 offset:1024
	ds_read_b128 v[202:205], v144 offset:2048
	ds_read_b128 v[220:223], v144 offset:3072
	s_waitcnt lgkmcnt(0)
	s_barrier
	v_mfma_f32_16x16x32_f16 v[126:129], v[140:143], v[162:165], v[126:129]
	v_mfma_f32_16x16x32_f16 v[122:125], v[154:157], v[162:165], v[122:125]
	v_mfma_f32_16x16x32_f16 v[110:113], v[140:143], v[170:173], v[110:113]
	v_mfma_f32_16x16x32_f16 v[106:109], v[154:157], v[170:173], v[106:109]
	v_mfma_f32_16x16x32_f16 v[94:97], v[140:143], v[178:181], v[94:97]
	v_mfma_f32_16x16x32_f16 v[90:93], v[154:157], v[178:181], v[90:93]
	v_mfma_f32_16x16x32_f16 v[78:81], v[140:143], v[186:189], v[78:81]
	v_mfma_f32_16x16x32_f16 v[74:77], v[154:157], v[186:189], v[74:77]
	v_mfma_f32_16x16x32_f16 v[126:129], v[150:153], v[166:169], v[126:129]
	v_mfma_f32_16x16x32_f16 v[122:125], v[158:161], v[166:169], v[122:125]
	v_mfma_f32_16x16x32_f16 v[110:113], v[150:153], v[174:177], v[110:113]
	v_mfma_f32_16x16x32_f16 v[106:109], v[158:161], v[174:177], v[106:109]
	v_mfma_f32_16x16x32_f16 v[94:97], v[150:153], v[182:185], v[94:97]
	v_mfma_f32_16x16x32_f16 v[90:93], v[158:161], v[182:185], v[90:93]
	v_mfma_f32_16x16x32_f16 v[78:81], v[150:153], v[190:193], v[78:81]
	v_mfma_f32_16x16x32_f16 v[74:77], v[158:161], v[190:193], v[74:77]
	v_mfma_f32_16x16x32_f16 v[118:121], v[194:197], v[162:165], v[118:121]
	v_mfma_f32_16x16x32_f16 v[114:117], v[202:205], v[162:165], v[114:117]
	v_mfma_f32_16x16x32_f16 v[102:105], v[194:197], v[170:173], v[102:105]
	v_mfma_f32_16x16x32_f16 v[98:101], v[202:205], v[170:173], v[98:101]
	v_mfma_f32_16x16x32_f16 v[86:89], v[194:197], v[178:181], v[86:89]
	v_mfma_f32_16x16x32_f16 v[82:85], v[202:205], v[178:181], v[82:85]
	v_mfma_f32_16x16x32_f16 v[70:73], v[194:197], v[186:189], v[70:73]
	v_mfma_f32_16x16x32_f16 v[66:69], v[202:205], v[186:189], v[66:69]
	v_mfma_f32_16x16x32_f16 v[118:121], v[198:201], v[166:169], v[118:121]
	v_mfma_f32_16x16x32_f16 v[114:117], v[220:223], v[166:169], v[114:117]
	v_mfma_f32_16x16x32_f16 v[102:105], v[198:201], v[174:177], v[102:105]
	v_mfma_f32_16x16x32_f16 v[98:101], v[220:223], v[174:177], v[98:101]
	v_mfma_f32_16x16x32_f16 v[86:89], v[198:201], v[182:185], v[86:89]
	v_mfma_f32_16x16x32_f16 v[82:85], v[220:223], v[182:185], v[82:85]
	v_mfma_f32_16x16x32_f16 v[70:73], v[198:201], v[190:193], v[70:73]
	v_mfma_f32_16x16x32_f16 v[66:69], v[220:223], v[190:193], v[66:69]
	s_barrier
	v_lshl_add_u64 v[144:145], s[46:47], 0, v[0:1]
	s_mov_b32 m0, s60
	v_lshl_add_u64 v[206:207], s[46:47], 0, v[134:135]
	global_load_lds_dwordx4 v[144:145], off
	s_add_i32 m0, s60, 0x2000
	s_nop 0
	global_load_lds_dwordx4 v[206:207], off
	s_mov_b32 m0, s23
	v_lshl_add_u64 v[212:213], s[48:49], 0, v[130:131]
	ds_read_b128 v[162:165], v149 offset:16384
	ds_read_b128 v[166:169], v149 offset:17408
	ds_read_b128 v[170:173], v149 offset:18432
	ds_read_b128 v[174:177], v149 offset:19456
	ds_read_b128 v[178:181], v149 offset:20480
	ds_read_b128 v[182:185], v149 offset:21504
	ds_read_b128 v[186:189], v149 offset:22528
	ds_read_b128 v[190:193], v149 offset:23552
	global_load_lds_dwordx4 v[212:213], off
	v_lshl_add_u64 v[214:215], s[48:49], 0, v[132:133]
	s_mov_b32 m0, s71
	s_nop 0
	global_load_lds_dwordx4 v[214:215], off
	s_add_u32 s78, s46, 0x80000
	s_addc_u32 s79, s47, 0
	s_add_i32 s60, s66, s64
	v_lshl_add_u64 v[232:233], s[78:79], 0, v[0:1]
	s_mov_b32 m0, s60
	s_nop 0
	global_load_lds_dwordx4 v[232:233], off
	v_lshl_add_u64 v[232:233], s[78:79], 0, v[134:135]
	s_add_i32 m0, s60, 0x2000
	s_nop 0
	global_load_lds_dwordx4 v[232:233], off
	s_waitcnt vmcnt(6) lgkmcnt(0)
	s_barrier
; #define PG8_STAGE(bufoff, gbase, voff) do { _Pragma("unroll") for (int _i = 0; _i < 2; ++_i) \
;         __builtin_amdgcn_global_load_lds((const unsigned*)((const char*)(gbase) + (voff)[_i]), (LAS unsigned*)(lds + (bufoff) + ldsw + _i * 8192), 16, 0, 0); } while (0)
; #define PG8_LDA(dst, b, h) do { _Pragma("unroll") for (int m = 0; m < 4; ++m) _Pragma("unroll") for (int k = 0; k < 2; ++k) dst[m][k] = *(const LAS h16x8*)(lds + PG8_SA(b, h) + aoff + m * 2048 + k * 1024); } while (0)
; #define PG8_LDB(dst, b, h) do { _Pragma("unroll") for (int n = 0; n < 2; ++n) _Pragma("unroll") for (int k = 0; k < 2; ++k) dst[n][k] = *(const LAS h16x8*)(lds + PG8_SB(b, h) + boff + n * 2048 + k * 1024); } while (0)
; #define PG8_MMA(ai, bj, At, Bt_) do { __builtin_amdgcn_s_setprio(1); _Pragma("unroll") for (int m = 0; m < 4; ++m) _Pragma("unroll") for (int n = 0; n < 2; ++n) _Pragma("unroll") for (int k = 0; k < 2; ++k) \
;         acc[ai][bj][m][n] = __builtin_amdgcn_mfma_f32_16x16x32_f16(Bt_[n][k], At[m][k], acc[ai][bj][m][n], 0, 0, 0); __builtin_amdgcn_s_setprio(0); } while (0)
; #define PG8_WAIT_V(n) asm volatile("s_waitcnt vmcnt(" #n ")" ::: "memory")
; #define PG8_WAIT_L(n) asm volatile("s_waitcnt lgkmcnt(" #n ")" ::: "memory")
; #define PG8_BAR __builtin_amdgcn_s_barrier()
; #define PG8_SCHED __builtin_amdgcn_sched_barrier(0)
; template <class Epi, class AMap>
; __device__ __forceinline__ void gemm_phase(LAS unsigned char* lds, const AMap am, const int lda, const h16* Bt, const int ldb, const int M, const int N, const int K, const Epi& E) {
;     ...
;             PG8_BAR; PG8_WAIT_L(0); PG8_MMA(1, 0, At, B0); PG8_BAR; PG8_SCHED;
;             PG8_STAGE(PG8_SB(0, 1), b2 + hstepB, voffB);
;             PG8_WAIT_V(6); PG8_BAR; PG8_MMA(1, 1, At, B1); PG8_BAR;
;             PG8_LDB(B0, 1, 0); PG8_SCHED; PG8_LDA(At, 1, 0); PG8_STAGE(PG8_SA(0, 1), a2 + hstepA, voffA);
;             PG8_WAIT_L(8); PG8_BAR; PG8_WAIT_L(0); PG8_MMA(0, 0, At, B0); PG8_BAR; PG8_SCHED;
;             PG8_LDB(B1, 1, 1); PG8_STAGE(PG8_SB(1, 0), b3, voffB);
;             PG8_BAR; PG8_WAIT_L(0); PG8_MMA(0, 1, At, B1); PG8_BAR;
	v_mfma_f32_16x16x32_f16 v[62:65], v[140:143], v[162:165], v[62:65]
	v_mfma_f32_16x16x32_f16 v[58:61], v[154:157], v[162:165], v[58:61]
	v_mfma_f32_16x16x32_f16 v[46:49], v[140:143], v[170:173], v[46:49]
	v_mfma_f32_16x16x32_f16 v[42:45], v[154:157], v[170:173], v[42:45]
	v_mfma_f32_16x16x32_f16 v[30:33], v[140:143], v[178:181], v[30:33]
	v_mfma_f32_16x16x32_f16 v[26:29], v[154:157], v[178:181], v[26:29]
	v_mfma_f32_16x16x32_f16 v[14:17], v[140:143], v[186:189], v[14:17]
	v_mfma_f32_16x16x32_f16 v[10:13], v[154:157], v[186:189], v[10:13]
	v_mfma_f32_16x16x32_f16 v[62:65], v[150:153], v[166:169], v[62:65]
	v_mfma_f32_16x16x32_f16 v[58:61], v[158:161], v[166:169], v[58:61]
	v_mfma_f32_16x16x32_f16 v[46:49], v[150:153], v[174:177], v[46:49]
	v_mfma_f32_16x16x32_f16 v[42:45], v[158:161], v[174:177], v[42:45]
	v_mfma_f32_16x16x32_f16 v[30:33], v[150:153], v[182:185], v[30:33]
	v_mfma_f32_16x16x32_f16 v[26:29], v[158:161], v[182:185], v[26:29]
	v_mfma_f32_16x16x32_f16 v[14:17], v[150:153], v[190:193], v[14:17]
	v_mfma_f32_16x16x32_f16 v[10:13], v[158:161], v[190:193], v[10:13]
	v_mfma_f32_16x16x32_f16 v[54:57], v[194:197], v[162:165], v[54:57]
	v_mfma_f32_16x16x32_f16 v[50:53], v[202:205], v[162:165], v[50:53]
	v_mfma_f32_16x16x32_f16 v[38:41], v[194:197], v[170:173], v[38:41]
	v_mfma_f32_16x16x32_f16 v[34:37], v[202:205], v[170:173], v[34:37]
	v_mfma_f32_16x16x32_f16 v[22:25], v[194:197], v[178:181], v[22:25]
	v_mfma_f32_16x16x32_f16 v[18:21], v[202:205], v[178:181], v[18:21]
	v_mfma_f32_16x16x32_f16 v[6:9], v[194:197], v[186:189], v[6:9]
	v_mfma_f32_16x16x32_f16 v[2:5], v[202:205], v[186:189], v[2:5]
	v_mfma_f32_16x16x32_f16 v[54:57], v[198:201], v[166:169], v[54:57]
	v_mfma_f32_16x16x32_f16 v[50:53], v[220:223], v[166:169], v[50:53]
	v_mfma_f32_16x16x32_f16 v[38:41], v[198:201], v[174:177], v[38:41]
	v_mfma_f32_16x16x32_f16 v[34:37], v[220:223], v[174:177], v[34:37]
	v_mfma_f32_16x16x32_f16 v[22:25], v[198:201], v[182:185], v[22:25]
	v_mfma_f32_16x16x32_f16 v[18:21], v[220:223], v[182:185], v[18:21]
	v_mfma_f32_16x16x32_f16 v[6:9], v[198:201], v[190:193], v[6:9]
	v_mfma_f32_16x16x32_f16 v[2:5], v[220:223], v[190:193], v[2:5]
	s_barrier
	s_add_i32 s60, 0, 0x18000
	v_add_u32_e32 v234, s60, v147
	ds_read_b128 v[140:143], v234
	ds_read_b128 v[150:153], v234 offset:1024
	ds_read_b128 v[154:157], v234 offset:2048
	ds_read_b128 v[158:161], v234 offset:3072
	s_add_u32 s48, s48, 0x80000
	s_addc_u32 s49, s49, 0
	s_mov_b32 m0, s72
	v_lshl_add_u64 v[232:233], s[48:49], 0, v[130:131]
	ds_read_b128 v[162:165], v149 offset:32768
	ds_read_b128 v[166:169], v149 offset:33792
	ds_read_b128 v[170:173], v149 offset:34816
	ds_read_b128 v[174:177], v149 offset:35840
	ds_read_b128 v[178:181], v149 offset:36864
	ds_read_b128 v[182:185], v149 offset:37888
	ds_read_b128 v[186:189], v149 offset:38912
	ds_read_b128 v[190:193], v149 offset:39936
	global_load_lds_dwordx4 v[232:233], off
	v_lshl_add_u64 v[232:233], s[48:49], 0, v[132:133]
	s_mov_b32 m0, s73
	s_nop 0
	global_load_lds_dwordx4 v[232:233], off
	s_waitcnt lgkmcnt(11)
	s_add_i32 s48, 0, 0x1c000
	s_add_i32 s49, s60, s64
	v_add_u32_e32 v216, s48, v147
	v_lshl_add_u64 v[144:145], v[144:145], 0, s[92:93]
	s_mov_b32 m0, s49
	ds_read_b128 v[194:197], v216
	ds_read_b128 v[198:201], v216 offset:1024
	ds_read_b128 v[202:205], v216 offset:2048
	ds_read_b128 v[220:223], v216 offset:3072
	s_waitcnt lgkmcnt(0)
	s_barrier
	v_mfma_f32_16x16x32_f16 v[126:129], v[140:143], v[162:165], v[126:129]
	v_mfma_f32_16x16x32_f16 v[122:125], v[154:157], v[162:165], v[122:125]
	v_mfma_f32_16x16x32_f16 v[110:113], v[140:143], v[170:173], v[110:113]
	v_mfma_f32_16x16x32_f16 v[106:109], v[154:157], v[170:173], v[106:109]
	v_mfma_f32_16x16x32_f16 v[94:97], v[140:143], v[178:181], v[94:97]
	v_mfma_f32_16x16x32_f16 v[90:93], v[154:157], v[178:181], v[90:93]
	v_mfma_f32_16x16x32_f16 v[78:81], v[140:143], v[186:189], v[78:81]
	v_mfma_f32_16x16x32_f16 v[74:77], v[154:157], v[186:189], v[74:77]
	v_mfma_f32_16x16x32_f16 v[126:129], v[150:153], v[166:169], v[126:129]
	v_mfma_f32_16x16x32_f16 v[122:125], v[158:161], v[166:169], v[122:125]
	v_mfma_f32_16x16x32_f16 v[110:113], v[150:153], v[174:177], v[110:113]
	v_mfma_f32_16x16x32_f16 v[106:109], v[158:161], v[174:177], v[106:109]
	v_mfma_f32_16x16x32_f16 v[94:97], v[150:153], v[182:185], v[94:97]
	v_mfma_f32_16x16x32_f16 v[90:93], v[158:161], v[182:185], v[90:93]
	v_mfma_f32_16x16x32_f16 v[78:81], v[150:153], v[190:193], v[78:81]
	v_mfma_f32_16x16x32_f16 v[74:77], v[158:161], v[190:193], v[74:77]
	v_mfma_f32_16x16x32_f16 v[118:121], v[194:197], v[162:165], v[118:121]
	v_mfma_f32_16x16x32_f16 v[114:117], v[202:205], v[162:165], v[114:117]
	v_mfma_f32_16x16x32_f16 v[102:105], v[194:197], v[170:173], v[102:105]
	v_mfma_f32_16x16x32_f16 v[98:101], v[202:205], v[170:173], v[98:101]
	v_mfma_f32_16x16x32_f16 v[86:89], v[194:197], v[178:181], v[86:89]
	v_mfma_f32_16x16x32_f16 v[82:85], v[202:205], v[178:181], v[82:85]
	v_mfma_f32_16x16x32_f16 v[70:73], v[194:197], v[186:189], v[70:73]
	v_mfma_f32_16x16x32_f16 v[66:69], v[202:205], v[186:189], v[66:69]
	v_mfma_f32_16x16x32_f16 v[118:121], v[198:201], v[166:169], v[118:121]
	v_mfma_f32_16x16x32_f16 v[114:117], v[220:223], v[166:169], v[114:117]
	v_mfma_f32_16x16x32_f16 v[102:105], v[198:201], v[174:177], v[102:105]
	v_mfma_f32_16x16x32_f16 v[98:101], v[220:223], v[174:177], v[98:101]
	v_mfma_f32_16x16x32_f16 v[86:89], v[198:201], v[182:185], v[86:89]
	v_mfma_f32_16x16x32_f16 v[82:85], v[220:223], v[182:185], v[82:85]
	v_mfma_f32_16x16x32_f16 v[70:73], v[198:201], v[190:193], v[70:73]
	v_mfma_f32_16x16x32_f16 v[66:69], v[220:223], v[190:193], v[66:69]
	s_barrier
; #define PG8_STAGE(bufoff, gbase, voff) do { _Pragma("unroll") for (int _i = 0; _i < 2; ++_i) \
;         __builtin_amdgcn_global_load_lds((const unsigned*)((const char*)(gbase) + (voff)[_i]), (LAS unsigned*)(lds + (bufoff) + ldsw + _i * 8192), 16, 0, 0); } while (0)
; #define PG8_LDA(dst, b, h) do { _Pragma("unroll") for (int m = 0; m < 4; ++m) _Pragma("unroll") for (int k = 0; k < 2; ++k) dst[m][k] = *(const LAS h16x8*)(lds + PG8_SA(b, h) + aoff + m * 2048 + k * 1024); } while (0)
; #define PG8_LDB(dst, b, h) do { _Pragma("unroll") for (int n = 0; n < 2; ++n) _Pragma("unroll") for (int k = 0; k < 2; ++k) dst[n][k] = *(const LAS h16x8*)(lds + PG8_SB(b, h) + boff + n * 2048 + k * 1024); } while (0)
; #define PG8_MMA(ai, bj, At, Bt_) do { __builtin_amdgcn_s_setprio(1); _Pragma("unroll") for (int m = 0; m < 4; ++m) _Pragma("unroll") for (int n = 0; n < 2; ++n) _Pragma("unroll") for (int k = 0; k < 2; ++k) \
;         acc[ai][bj][m][n] = __builtin_amdgcn_mfma_f32_16x16x32_f16(Bt_[n][k], At[m][k], acc[ai][bj][m][n], 0, 0, 0); __builtin_amdgcn_s_setprio(0); } while (0)
; #define PG8_WAIT_V(n) asm volatile("s_waitcnt vmcnt(" #n ")" ::: "memory")
; template <class Epi, class AMap>
; __device__ __forceinline__ void gemm_phase(LAS unsigned char* lds, const AMap am, const int lda, const h16* Bt, const int ldb, const int M, const int N, const int K, const Epi& E) {
;     ...
;             PG8_LDB(B0, 1, 0); PG8_SCHED; PG8_LDA(At, 1, 0); PG8_STAGE(PG8_SA(0, 1), a2 + hstepA, voffA);
;             PG8_WAIT_L(8); PG8_BAR; PG8_WAIT_L(0); PG8_MMA(0, 0, At, B0); PG8_BAR; PG8_SCHED;
;             PG8_LDB(B1, 1, 1); PG8_STAGE(PG8_SB(1, 0), b3, voffB);
;             PG8_BAR; PG8_WAIT_L(0); PG8_MMA(0, 1, At, B1); PG8_BAR;
;             PG8_LDA(At, 1, 1); PG8_STAGE(PG8_SA(1, 0), a3, voffA);
;             PG8_BAR; PG8_WAIT_L(0); PG8_MMA(1, 0, At, B0); PG8_BAR; PG8_SCHED;
;             PG8_STAGE(PG8_SB(1, 1), b3 + hstepB, voffB);
;             PG8_WAIT_V(6); PG8_BAR; PG8_MMA(1, 1, At, B1); PG8_BAR;
;     __device__ __forceinline__ void operator()(const f32x4 (&acc)[2][2][4][2], const Unit& u, int wr, int wc, int fr, int fq) const {
;     ...
;             for (int m = 0; m < 4; ++m) { const size_t off = (size_t)(row0 + ai * 128 + m * 16) * DM + colt;
; #pragma unroll
;                 for (int bj = 0; bj < 2; ++bj) {
;                     const h16x8 x = *(const h16x8*)(X + off + bj * 128);
	global_load_lds_dwordx4 v[144:145], off
	v_lshl_add_u64 v[144:145], v[206:207], 0, s[92:93]
	s_add_i32 m0, s49, 0x2000
	s_nop 0
	global_load_lds_dwordx4 v[144:145], off
	s_mov_b32 m0, s74
	v_lshl_add_u64 v[144:145], v[212:213], 0, s[92:93]
	ds_read_b128 v[162:165], v149 offset:49152
	ds_read_b128 v[166:169], v149 offset:50176
	ds_read_b128 v[170:173], v149 offset:51200
	ds_read_b128 v[174:177], v149 offset:52224
	ds_read_b128 v[178:181], v149 offset:53248
	ds_read_b128 v[182:185], v149 offset:54272
	ds_read_b128 v[186:189], v149 offset:55296
	ds_read_b128 v[190:193], v149 offset:56320
	global_load_lds_dwordx4 v[144:145], off
	v_lshl_add_u64 v[144:145], v[214:215], 0, s[92:93]
	s_mov_b32 m0, s75
	s_nop 0
	global_load_lds_dwordx4 v[144:145], off
	s_add_u32 s46, s46, 0x80080
	s_addc_u32 s47, s47, 0
	s_add_i32 s48, s48, s64
	v_lshl_add_u64 v[232:233], s[46:47], 0, v[0:1]
	s_mov_b32 m0, s48
	s_nop 0
	global_load_lds_dwordx4 v[232:233], off
	v_lshl_add_u64 v[232:233], s[46:47], 0, v[134:135]
	s_add_i32 m0, s48, 0x2000
	s_nop 0
	global_load_lds_dwordx4 v[232:233], off
	s_waitcnt vmcnt(6) lgkmcnt(0)
	s_barrier
	v_mfma_f32_16x16x32_f16 v[62:65], v[140:143], v[162:165], v[62:65]
	v_mfma_f32_16x16x32_f16 v[58:61], v[154:157], v[162:165], v[58:61]
	v_mfma_f32_16x16x32_f16 v[46:49], v[140:143], v[170:173], v[46:49]
	v_mfma_f32_16x16x32_f16 v[42:45], v[154:157], v[170:173], v[42:45]
	v_mfma_f32_16x16x32_f16 v[30:33], v[140:143], v[178:181], v[30:33]
	v_mfma_f32_16x16x32_f16 v[26:29], v[154:157], v[178:181], v[26:29]
	v_mfma_f32_16x16x32_f16 v[14:17], v[140:143], v[186:189], v[14:17]
	v_mfma_f32_16x16x32_f16 v[10:13], v[154:157], v[186:189], v[10:13]
	v_mfma_f32_16x16x32_f16 v[62:65], v[150:153], v[166:169], v[62:65]
	v_mfma_f32_16x16x32_f16 v[58:61], v[158:161], v[166:169], v[58:61]
	v_mfma_f32_16x16x32_f16 v[46:49], v[150:153], v[174:177], v[46:49]
	v_mfma_f32_16x16x32_f16 v[42:45], v[158:161], v[174:177], v[42:45]
	v_mfma_f32_16x16x32_f16 v[30:33], v[150:153], v[182:185], v[30:33]
	v_mfma_f32_16x16x32_f16 v[26:29], v[158:161], v[182:185], v[26:29]
	v_mfma_f32_16x16x32_f16 v[14:17], v[150:153], v[190:193], v[14:17]
	v_mfma_f32_16x16x32_f16 v[10:13], v[158:161], v[190:193], v[10:13]
	v_mfma_f32_16x16x32_f16 v[54:57], v[194:197], v[162:165], v[54:57]
	v_mfma_f32_16x16x32_f16 v[50:53], v[202:205], v[162:165], v[50:53]
	v_mfma_f32_16x16x32_f16 v[38:41], v[194:197], v[170:173], v[38:41]
	v_mfma_f32_16x16x32_f16 v[34:37], v[202:205], v[170:173], v[34:37]
	v_mfma_f32_16x16x32_f16 v[22:25], v[194:197], v[178:181], v[22:25]
	v_mfma_f32_16x16x32_f16 v[18:21], v[202:205], v[178:181], v[18:21]
	v_mfma_f32_16x16x32_f16 v[6:9], v[194:197], v[186:189], v[6:9]
	v_mfma_f32_16x16x32_f16 v[2:5], v[202:205], v[186:189], v[2:5]
	v_mfma_f32_16x16x32_f16 v[54:57], v[198:201], v[166:169], v[54:57]
	v_mfma_f32_16x16x32_f16 v[50:53], v[220:223], v[166:169], v[50:53]
	v_mfma_f32_16x16x32_f16 v[38:41], v[198:201], v[174:177], v[38:41]
	v_mfma_f32_16x16x32_f16 v[34:37], v[220:223], v[174:177], v[34:37]
	v_mfma_f32_16x16x32_f16 v[22:25], v[198:201], v[182:185], v[22:25]
	v_mfma_f32_16x16x32_f16 v[18:21], v[220:223], v[182:185], v[18:21]
	v_mfma_f32_16x16x32_f16 v[6:9], v[198:201], v[190:193], v[6:9]
	v_mfma_f32_16x16x32_f16 v[2:5], v[220:223], v[190:193], v[2:5]
	s_add_i32 s51, s51, 2
	s_add_u32 s26, s26, 0x100
	s_addc_u32 s27, s27, 0
	s_add_u32 s21, s21, 0x100
	s_addc_u32 s50, s50, 0
	s_cmp_gt_u32 s51, 29
	s_barrier
	s_cbranch_scc0 .LBB0_147
	v_lshl_add_u32 v144, s22, 8, v146
	v_lshl_or_b32 v142, s35, 8, v148
	v_ashrrev_i32_e32 v145, 31, v144
	v_ashrrev_i32_e32 v143, 31, v142
	v_lshlrev_b64 v[140:141], 11, v[144:145]
	v_lshl_add_u64 v[140:141], v[140:141], 0, v[142:143]
	v_lshlrev_b64 v[140:141], 1, v[140:141]
	v_lshl_add_u64 v[154:155], s[94:95], 0, v[140:141]
	s_mov_b32 s101, 0
	global_load_dwordx4 v[158:161], v[154:155], off
	global_load_dwordx4 v[162:165], v[154:155], off offset:256
	s_mov_b32 s100, 0x10000
	v_lshl_add_u64 v[232:233], v[154:155], 0, s[100:101]
	global_load_dwordx4 v[166:169], v[232:233], off
	global_load_dwordx4 v[170:173], v[232:233], off offset:256
	s_mov_b32 s100, 0x20000
	v_lshl_add_u64 v[232:233], v[154:155], 0, s[100:101]
	global_load_dwordx4 v[174:177], v[232:233], off
	global_load_dwordx4 v[178:181], v[232:233], off offset:256
	s_mov_b32 s100, 0x30000
	v_lshl_add_u64 v[232:233], v[154:155], 0, s[100:101]
	global_load_dwordx4 v[182:185], v[232:233], off
	global_load_dwordx4 v[186:189], v[232:233], off offset:256
	s_mov_b32 s100, 0x80000
	v_lshl_add_u64 v[232:233], v[154:155], 0, s[100:101]
	global_load_dwordx4 v[190:193], v[232:233], off
	global_load_dwordx4 v[194:197], v[232:233], off offset:256
	s_mov_b32 s100, 0x90000
	v_lshl_add_u64 v[232:233], v[154:155], 0, s[100:101]
	global_load_dwordx4 v[198:201], v[232:233], off
	global_load_dwordx4 v[202:205], v[232:233], off offset:256
	s_mov_b32 s100, 0xa0000
	v_lshl_add_u64 v[232:233], v[154:155], 0, s[100:101]
	global_load_dwordx4 v[212:215], v[232:233], off
	global_load_dwordx4 v[220:223], v[232:233], off offset:256
	s_mov_b32 s100, 0xb0000
	v_lshl_add_u64 v[232:233], v[154:155], 0, s[100:101]
	global_load_dwordx4 v[224:227], v[232:233], off
	global_load_dwordx4 v[228:231], v[232:233], off offset:256
	s_mov_b64 s[2:3], 0xb0000
	s_and_b64 vcc, exec, s[38:39]
	s_mov_b32 s22, s40
	s_mov_b64 s[46:47], s[44:45]
	s_mov_b64 s[26:27], s[42:43]
	s_movk_i32 s66, 0x80
	s_waitcnt vmcnt(15)
;     __device__ __forceinline__ void operator()(const f32x4 (&acc)[2][2][4][2], const Unit& u, int wr, int wc, int fr, int fq) const {
;     ...
; #pragma unroll
;         for (int ai = 0; ai < 2; ++ai)
; #pragma unroll
;             for (int m = 0; m < 4; ++m) { const size_t off = (size_t)(row0 + ai * 128 + m * 16) * DM + colt;
; #pragma unroll
;                 for (int bj = 0; bj < 2; ++bj) {
;                     const h16x8 x = *(const h16x8*)(X + off + bj * 128);
;                     f32x4 o0, o1;
; #pragma unroll
;                     for (int e = 0; e < 4; ++e) { o0[e] = (float)x[e] * ALPHA + acc[ai][bj][m][0][e]; o1[e] = (float)x[4 + e] * ALPHA + acc[ai][bj][m][1][e]; }
;                     *(u32x4*)(PRE + off + bj * 128) = pack8(o0, o1); } }
	v_mov_b64_e32 v[150:151], v[158:159]
	v_mov_b64_e32 v[152:153], v[160:161]
	v_cvt_f32_f16_e32 v156, v150
	v_cvt_f32_f16_sdwa v157, v150 dst_sel:DWORD dst_unused:UNUSED_PAD src0_sel:WORD_1
	v_cvt_f32_f16_e32 v150, v151
	v_cvt_f32_f16_sdwa v151, v151 dst_sel:DWORD dst_unused:UNUSED_PAD src0_sel:WORD_1
	v_pk_fma_f32 v[126:127], v[156:157], s[34:35], v[126:127] op_sel_hi:[1,0,1]
	s_nop 0
	v_cvt_pk_f16_f32 v126, v126, v127
	v_pk_fma_f32 v[128:129], v[150:151], s[34:35], v[128:129] op_sel_hi:[1,0,1]
	v_lshl_add_u64 v[150:151], s[4:5], 0, v[140:141]
	v_cvt_pk_f16_f32 v127, v128, v129
	v_cvt_f32_f16_e32 v128, v152
	v_cvt_f32_f16_sdwa v129, v152 dst_sel:DWORD dst_unused:UNUSED_PAD src0_sel:WORD_1
	v_pk_fma_f32 v[122:123], v[128:129], s[34:35], v[122:123] op_sel_hi:[1,0,1]
	s_nop 0
	v_cvt_pk_f16_f32 v128, v122, v123
	v_cvt_f32_f16_e32 v122, v153
	v_cvt_f32_f16_sdwa v123, v153 dst_sel:DWORD dst_unused:UNUSED_PAD src0_sel:WORD_1
	v_pk_fma_f32 v[122:123], v[122:123], s[34:35], v[124:125] op_sel_hi:[1,0,1]
	s_nop 0
	v_cvt_pk_f16_f32 v129, v122, v123
	s_nop 0
	global_store_dwordx4 v[150:151], v[126:129], off
	s_waitcnt vmcnt(15)
	v_mov_b64_e32 v[122:123], v[162:163]
	v_mov_b64_e32 v[124:125], v[164:165]
	s_nop 0
	v_cvt_f32_f16_e32 v126, v122
	v_cvt_f32_f16_sdwa v127, v122 dst_sel:DWORD dst_unused:UNUSED_PAD src0_sel:WORD_1
	v_cvt_f32_f16_e32 v122, v123
	v_cvt_f32_f16_sdwa v123, v123 dst_sel:DWORD dst_unused:UNUSED_PAD src0_sel:WORD_1
	v_pk_fma_f32 v[118:119], v[126:127], s[34:35], v[118:119] op_sel_hi:[1,0,1]
	s_nop 0
	v_cvt_pk_f16_f32 v118, v118, v119
	v_pk_fma_f32 v[120:121], v[122:123], s[34:35], v[120:121] op_sel_hi:[1,0,1]
	s_nop 0
	v_cvt_pk_f16_f32 v119, v120, v121
	v_cvt_f32_f16_e32 v120, v124
	v_cvt_f32_f16_sdwa v121, v124 dst_sel:DWORD dst_unused:UNUSED_PAD src0_sel:WORD_1
	v_pk_fma_f32 v[114:115], v[120:121], s[34:35], v[114:115] op_sel_hi:[1,0,1]
	s_nop 0
	v_cvt_pk_f16_f32 v120, v114, v115
	v_cvt_f32_f16_e32 v114, v125
	v_cvt_f32_f16_sdwa v115, v125 dst_sel:DWORD dst_unused:UNUSED_PAD src0_sel:WORD_1
	v_pk_fma_f32 v[114:115], v[114:115], s[34:35], v[116:117] op_sel_hi:[1,0,1]
	s_nop 0
	v_cvt_pk_f16_f32 v121, v114, v115
	v_or_b32_e32 v114, 16, v144
	v_ashrrev_i32_e32 v115, 31, v114
	v_lshlrev_b64 v[114:115], 11, v[114:115]
	v_lshl_add_u64 v[114:115], v[114:115], 0, v[142:143]
	global_store_dwordx4 v[150:151], v[118:121], off offset:256
	s_nop 1
	v_lshlrev_b64 v[118:119], 1, v[114:115]
	v_lshl_add_u64 v[120:121], s[94:95], 0, v[118:119]
	s_waitcnt vmcnt(15)
	v_mov_b64_e32 v[114:115], v[166:167]
	v_mov_b64_e32 v[116:117], v[168:169]
	v_cvt_f32_f16_e32 v122, v114
	v_cvt_f32_f16_sdwa v123, v114 dst_sel:DWORD dst_unused:UNUSED_PAD src0_sel:WORD_1
	v_cvt_f32_f16_e32 v114, v115
	v_cvt_f32_f16_sdwa v115, v115 dst_sel:DWORD dst_unused:UNUSED_PAD src0_sel:WORD_1
	v_pk_fma_f32 v[110:111], v[122:123], s[34:35], v[110:111] op_sel_hi:[1,0,1]
	s_nop 0
	v_cvt_pk_f16_f32 v110, v110, v111
	v_pk_fma_f32 v[112:113], v[114:115], s[34:35], v[112:113] op_sel_hi:[1,0,1]
	v_lshl_add_u64 v[114:115], s[4:5], 0, v[118:119]
	v_cvt_pk_f16_f32 v111, v112, v113
	v_cvt_f32_f16_e32 v112, v116
	v_cvt_f32_f16_sdwa v113, v116 dst_sel:DWORD dst_unused:UNUSED_PAD src0_sel:WORD_1
	v_pk_fma_f32 v[106:107], v[112:113], s[34:35], v[106:107] op_sel_hi:[1,0,1]
	s_nop 0
	v_cvt_pk_f16_f32 v112, v106, v107
	v_cvt_f32_f16_e32 v106, v117
	v_cvt_f32_f16_sdwa v107, v117 dst_sel:DWORD dst_unused:UNUSED_PAD src0_sel:WORD_1
	v_pk_fma_f32 v[106:107], v[106:107], s[34:35], v[108:109] op_sel_hi:[1,0,1]
	s_nop 0
	v_cvt_pk_f16_f32 v113, v106, v107
	s_nop 0
	global_store_dwordx4 v[114:115], v[110:113], off
	s_waitcnt vmcnt(15)
	v_mov_b64_e32 v[106:107], v[170:171]
	v_mov_b64_e32 v[108:109], v[172:173]
	s_nop 0
	v_cvt_f32_f16_e32 v110, v106
	v_cvt_f32_f16_sdwa v111, v106 dst_sel:DWORD dst_unused:UNUSED_PAD src0_sel:WORD_1
	v_cvt_f32_f16_e32 v106, v107
	v_cvt_f32_f16_sdwa v107, v107 dst_sel:DWORD dst_unused:UNUSED_PAD src0_sel:WORD_1
	v_pk_fma_f32 v[102:103], v[110:111], s[34:35], v[102:103] op_sel_hi:[1,0,1]
	s_nop 0
	v_cvt_pk_f16_f32 v102, v102, v103
	v_pk_fma_f32 v[104:105], v[106:107], s[34:35], v[104:105] op_sel_hi:[1,0,1]
	s_nop 0
	v_cvt_pk_f16_f32 v103, v104, v105
	v_cvt_f32_f16_e32 v104, v108
	v_cvt_f32_f16_sdwa v105, v108 dst_sel:DWORD dst_unused:UNUSED_PAD src0_sel:WORD_1
	v_pk_fma_f32 v[98:99], v[104:105], s[34:35], v[98:99] op_sel_hi:[1,0,1]
	s_nop 0
	v_cvt_pk_f16_f32 v104, v98, v99
	v_cvt_f32_f16_e32 v98, v109
	v_cvt_f32_f16_sdwa v99, v109 dst_sel:DWORD dst_unused:UNUSED_PAD src0_sel:WORD_1
	v_pk_fma_f32 v[98:99], v[98:99], s[34:35], v[100:101] op_sel_hi:[1,0,1]
	s_nop 0
	v_cvt_pk_f16_f32 v105, v98, v99
	v_or_b32_e32 v98, 32, v144
	v_ashrrev_i32_e32 v99, 31, v98
	v_lshlrev_b64 v[98:99], 11, v[98:99]
	v_lshl_add_u64 v[98:99], v[98:99], 0, v[142:143]
	global_store_dwordx4 v[114:115], v[102:105], off offset:256
	s_nop 1
	v_lshlrev_b64 v[102:103], 1, v[98:99]
	v_lshl_add_u64 v[104:105], s[94:95], 0, v[102:103]
	s_waitcnt vmcnt(15)
	v_mov_b64_e32 v[98:99], v[174:175]
	v_mov_b64_e32 v[100:101], v[176:177]
	v_cvt_f32_f16_e32 v106, v98
	v_cvt_f32_f16_sdwa v107, v98 dst_sel:DWORD dst_unused:UNUSED_PAD src0_sel:WORD_1
	v_cvt_f32_f16_e32 v98, v99
	v_cvt_f32_f16_sdwa v99, v99 dst_sel:DWORD dst_unused:UNUSED_PAD src0_sel:WORD_1
	v_pk_fma_f32 v[94:95], v[106:107], s[34:35], v[94:95] op_sel_hi:[1,0,1]
	s_nop 0
	v_cvt_pk_f16_f32 v94, v94, v95
	v_pk_fma_f32 v[96:97], v[98:99], s[34:35], v[96:97] op_sel_hi:[1,0,1]
	v_lshl_add_u64 v[98:99], s[4:5], 0, v[102:103]
	v_cvt_pk_f16_f32 v95, v96, v97
	v_cvt_f32_f16_e32 v96, v100
	v_cvt_f32_f16_sdwa v97, v100 dst_sel:DWORD dst_unused:UNUSED_PAD src0_sel:WORD_1
	v_pk_fma_f32 v[90:91], v[96:97], s[34:35], v[90:91] op_sel_hi:[1,0,1]
	s_nop 0
	v_cvt_pk_f16_f32 v96, v90, v91
	v_cvt_f32_f16_e32 v90, v101
	v_cvt_f32_f16_sdwa v91, v101 dst_sel:DWORD dst_unused:UNUSED_PAD src0_sel:WORD_1
	v_pk_fma_f32 v[90:91], v[90:91], s[34:35], v[92:93] op_sel_hi:[1,0,1]
	s_nop 0
	v_cvt_pk_f16_f32 v97, v90, v91
	s_nop 0
	global_store_dwordx4 v[98:99], v[94:97], off
	s_waitcnt vmcnt(15)
;     __device__ __forceinline__ void operator()(const f32x4 (&acc)[2][2][4][2], const Unit& u, int wr, int wc, int fr, int fq) const {
;     ...
; #pragma unroll
;         for (int ai = 0; ai < 2; ++ai)
; #pragma unroll
;             for (int m = 0; m < 4; ++m) { const size_t off = (size_t)(row0 + ai * 128 + m * 16) * DM + colt;
; #pragma unroll
;                 for (int bj = 0; bj < 2; ++bj) {
;                     const h16x8 x = *(const h16x8*)(X + off + bj * 128);
;                     f32x4 o0, o1;
; #pragma unroll
;                     for (int e = 0; e < 4; ++e) { o0[e] = (float)x[e] * ALPHA + acc[ai][bj][m][0][e]; o1[e] = (float)x[4 + e] * ALPHA + acc[ai][bj][m][1][e]; }
;                     *(u32x4*)(PRE + off + bj * 128) = pack8(o0, o1); } }
	v_mov_b64_e32 v[90:91], v[178:179]
	v_mov_b64_e32 v[92:93], v[180:181]
	s_nop 0
	v_cvt_f32_f16_e32 v94, v90
	v_cvt_f32_f16_sdwa v95, v90 dst_sel:DWORD dst_unused:UNUSED_PAD src0_sel:WORD_1
	v_cvt_f32_f16_e32 v90, v91
	v_cvt_f32_f16_sdwa v91, v91 dst_sel:DWORD dst_unused:UNUSED_PAD src0_sel:WORD_1
	v_pk_fma_f32 v[86:87], v[94:95], s[34:35], v[86:87] op_sel_hi:[1,0,1]
	s_nop 0
	v_cvt_pk_f16_f32 v86, v86, v87
	v_pk_fma_f32 v[88:89], v[90:91], s[34:35], v[88:89] op_sel_hi:[1,0,1]
	s_nop 0
	v_cvt_pk_f16_f32 v87, v88, v89
	v_cvt_f32_f16_e32 v88, v92
	v_cvt_f32_f16_sdwa v89, v92 dst_sel:DWORD dst_unused:UNUSED_PAD src0_sel:WORD_1
	v_pk_fma_f32 v[82:83], v[88:89], s[34:35], v[82:83] op_sel_hi:[1,0,1]
	s_nop 0
	v_cvt_pk_f16_f32 v88, v82, v83
	v_cvt_f32_f16_e32 v82, v93
	v_cvt_f32_f16_sdwa v83, v93 dst_sel:DWORD dst_unused:UNUSED_PAD src0_sel:WORD_1
	v_pk_fma_f32 v[82:83], v[82:83], s[34:35], v[84:85] op_sel_hi:[1,0,1]
	s_nop 0
	v_cvt_pk_f16_f32 v89, v82, v83
	v_or_b32_e32 v82, 48, v144
	v_ashrrev_i32_e32 v83, 31, v82
	v_lshlrev_b64 v[82:83], 11, v[82:83]
	v_lshl_add_u64 v[82:83], v[82:83], 0, v[142:143]
	global_store_dwordx4 v[98:99], v[86:89], off offset:256
	s_nop 1
	v_lshlrev_b64 v[86:87], 1, v[82:83]
	v_lshl_add_u64 v[88:89], s[94:95], 0, v[86:87]
	s_waitcnt vmcnt(15)
	v_mov_b64_e32 v[82:83], v[182:183]
	v_mov_b64_e32 v[84:85], v[184:185]
	v_cvt_f32_f16_e32 v90, v82
	v_cvt_f32_f16_sdwa v91, v82 dst_sel:DWORD dst_unused:UNUSED_PAD src0_sel:WORD_1
	v_cvt_f32_f16_e32 v82, v83
	v_cvt_f32_f16_sdwa v83, v83 dst_sel:DWORD dst_unused:UNUSED_PAD src0_sel:WORD_1
	v_pk_fma_f32 v[78:79], v[90:91], s[34:35], v[78:79] op_sel_hi:[1,0,1]
	s_nop 0
	v_cvt_pk_f16_f32 v78, v78, v79
	v_pk_fma_f32 v[80:81], v[82:83], s[34:35], v[80:81] op_sel_hi:[1,0,1]
	v_lshl_add_u64 v[82:83], s[4:5], 0, v[86:87]
	v_cvt_pk_f16_f32 v79, v80, v81
	v_cvt_f32_f16_e32 v80, v84
	v_cvt_f32_f16_sdwa v81, v84 dst_sel:DWORD dst_unused:UNUSED_PAD src0_sel:WORD_1
	v_pk_fma_f32 v[74:75], v[80:81], s[34:35], v[74:75] op_sel_hi:[1,0,1]
	s_nop 0
	v_cvt_pk_f16_f32 v80, v74, v75
	v_cvt_f32_f16_e32 v74, v85
	v_cvt_f32_f16_sdwa v75, v85 dst_sel:DWORD dst_unused:UNUSED_PAD src0_sel:WORD_1
	v_pk_fma_f32 v[74:75], v[74:75], s[34:35], v[76:77] op_sel_hi:[1,0,1]
	s_nop 0
	v_cvt_pk_f16_f32 v81, v74, v75
	s_nop 0
	global_store_dwordx4 v[82:83], v[78:81], off
	s_waitcnt vmcnt(15)
	v_mov_b64_e32 v[74:75], v[186:187]
	v_mov_b64_e32 v[76:77], v[188:189]
	s_nop 0
	v_cvt_f32_f16_e32 v78, v74
	v_cvt_f32_f16_sdwa v79, v74 dst_sel:DWORD dst_unused:UNUSED_PAD src0_sel:WORD_1
	v_cvt_f32_f16_e32 v74, v75
	v_cvt_f32_f16_sdwa v75, v75 dst_sel:DWORD dst_unused:UNUSED_PAD src0_sel:WORD_1
	v_pk_fma_f32 v[70:71], v[78:79], s[34:35], v[70:71] op_sel_hi:[1,0,1]
	s_nop 0
	v_cvt_pk_f16_f32 v70, v70, v71
	v_pk_fma_f32 v[72:73], v[74:75], s[34:35], v[72:73] op_sel_hi:[1,0,1]
	s_nop 0
	v_cvt_pk_f16_f32 v71, v72, v73
	v_cvt_f32_f16_e32 v72, v76
	v_cvt_f32_f16_sdwa v73, v76 dst_sel:DWORD dst_unused:UNUSED_PAD src0_sel:WORD_1
	v_pk_fma_f32 v[66:67], v[72:73], s[34:35], v[66:67] op_sel_hi:[1,0,1]
	s_nop 0
	v_cvt_pk_f16_f32 v72, v66, v67
	v_cvt_f32_f16_e32 v66, v77
	v_cvt_f32_f16_sdwa v67, v77 dst_sel:DWORD dst_unused:UNUSED_PAD src0_sel:WORD_1
	v_pk_fma_f32 v[66:67], v[66:67], s[34:35], v[68:69] op_sel_hi:[1,0,1]
	s_nop 0
	v_cvt_pk_f16_f32 v73, v66, v67
	global_store_dwordx4 v[82:83], v[70:73], off offset:256
	s_nop 1
	v_lshl_add_u64 v[70:71], v[140:141], 0, s[16:17]
	v_lshl_add_u64 v[72:73], s[94:95], 0, v[70:71]
	s_waitcnt vmcnt(15)
	v_mov_b64_e32 v[66:67], v[190:191]
	v_mov_b64_e32 v[68:69], v[192:193]
	v_cvt_f32_f16_e32 v74, v66
	v_cvt_f32_f16_sdwa v75, v66 dst_sel:DWORD dst_unused:UNUSED_PAD src0_sel:WORD_1
	v_cvt_f32_f16_e32 v66, v67
	v_cvt_f32_f16_sdwa v67, v67 dst_sel:DWORD dst_unused:UNUSED_PAD src0_sel:WORD_1
	v_pk_fma_f32 v[62:63], v[74:75], s[34:35], v[62:63] op_sel_hi:[1,0,1]
	s_nop 0
	v_cvt_pk_f16_f32 v62, v62, v63
	v_pk_fma_f32 v[64:65], v[66:67], s[34:35], v[64:65] op_sel_hi:[1,0,1]
	v_lshl_add_u64 v[66:67], s[4:5], 0, v[70:71]
	v_cvt_pk_f16_f32 v63, v64, v65
	v_cvt_f32_f16_e32 v64, v68
	v_cvt_f32_f16_sdwa v65, v68 dst_sel:DWORD dst_unused:UNUSED_PAD src0_sel:WORD_1
	v_pk_fma_f32 v[58:59], v[64:65], s[34:35], v[58:59] op_sel_hi:[1,0,1]
	s_nop 0
	v_cvt_pk_f16_f32 v64, v58, v59
	v_cvt_f32_f16_e32 v58, v69
	v_cvt_f32_f16_sdwa v59, v69 dst_sel:DWORD dst_unused:UNUSED_PAD src0_sel:WORD_1
	v_pk_fma_f32 v[58:59], v[58:59], s[34:35], v[60:61] op_sel_hi:[1,0,1]
	s_nop 0
	v_cvt_pk_f16_f32 v65, v58, v59
	s_nop 0
	global_store_dwordx4 v[66:67], v[62:65], off
	s_waitcnt vmcnt(15)
	v_mov_b64_e32 v[58:59], v[194:195]
	v_mov_b64_e32 v[60:61], v[196:197]
	s_nop 0
	v_cvt_f32_f16_e32 v62, v58
	v_cvt_f32_f16_sdwa v63, v58 dst_sel:DWORD dst_unused:UNUSED_PAD src0_sel:WORD_1
	v_cvt_f32_f16_e32 v58, v59
	v_cvt_f32_f16_sdwa v59, v59 dst_sel:DWORD dst_unused:UNUSED_PAD src0_sel:WORD_1
	v_pk_fma_f32 v[54:55], v[62:63], s[34:35], v[54:55] op_sel_hi:[1,0,1]
	s_nop 0
	v_cvt_pk_f16_f32 v54, v54, v55
	v_pk_fma_f32 v[56:57], v[58:59], s[34:35], v[56:57] op_sel_hi:[1,0,1]
	s_nop 0
	v_cvt_pk_f16_f32 v55, v56, v57
	v_cvt_f32_f16_e32 v56, v60
	v_cvt_f32_f16_sdwa v57, v60 dst_sel:DWORD dst_unused:UNUSED_PAD src0_sel:WORD_1
	v_pk_fma_f32 v[50:51], v[56:57], s[34:35], v[50:51] op_sel_hi:[1,0,1]
	s_nop 0
	v_cvt_pk_f16_f32 v56, v50, v51
	v_cvt_f32_f16_e32 v50, v61
	v_cvt_f32_f16_sdwa v51, v61 dst_sel:DWORD dst_unused:UNUSED_PAD src0_sel:WORD_1
	v_pk_fma_f32 v[50:51], v[50:51], s[34:35], v[52:53] op_sel_hi:[1,0,1]
	s_nop 0
	v_cvt_pk_f16_f32 v57, v50, v51
	global_store_dwordx4 v[66:67], v[54:57], off offset:256
	s_nop 1
	v_lshl_add_u64 v[54:55], v[140:141], 0, s[18:19]
	v_lshl_add_u64 v[56:57], s[94:95], 0, v[54:55]
	s_waitcnt vmcnt(15)
; #define PG8_WAIT_V(n) asm volatile("s_waitcnt vmcnt(" #n ")" ::: "memory")
; #define PG8_BAR __builtin_amdgcn_s_barrier()
; template <class Epi, class AMap>
; __device__ __forceinline__ void gemm_phase(LAS unsigned char* lds, const AMap am, const int lda, const h16* Bt, const int ldb, const int M, const int N, const int K, const Epi& E) {
;     ...
;         if (!has_next) break;
; #pragma unroll
;         for (int a = 0; a < 2; ++a)
; #pragma unroll
;             for (int b = 0; b < 2; ++b)
; #pragma unroll
;                 for (int m = 0; m < 4; ++m)
; #pragma unroll
;                     for (int n = 0; n < 2; ++n) acc[a][b][m][n] = (f32x4){0.f, 0.f, 0.f, 0.f};
;         cur = nxt; cA = nA; cB = nB; ++ui;
;     }
;     PG8_WAIT_V(0);
;     if (wr == 0) PG8_BAR;
;     PG8_BAR;
;     __device__ __forceinline__ void operator()(const f32x4 (&acc)[2][2][4][2], const Unit& u, int wr, int wc, int fr, int fq) const {
;     ...
; #pragma unroll
;         for (int ai = 0; ai < 2; ++ai)
; #pragma unroll
;             for (int m = 0; m < 4; ++m) { const size_t off = (size_t)(row0 + ai * 128 + m * 16) * DM + colt;
; #pragma unroll
;                 for (int bj = 0; bj < 2; ++bj) {
;                     const h16x8 x = *(const h16x8*)(X + off + bj * 128);
;                     f32x4 o0, o1;
; #pragma unroll
;                     for (int e = 0; e < 4; ++e) { o0[e] = (float)x[e] * ALPHA + acc[ai][bj][m][0][e]; o1[e] = (float)x[4 + e] * ALPHA + acc[ai][bj][m][1][e]; }
;                     *(u32x4*)(PRE + off + bj * 128) = pack8(o0, o1); } }
	v_mov_b64_e32 v[50:51], v[198:199]
	v_mov_b64_e32 v[52:53], v[200:201]
	v_cvt_f32_f16_e32 v58, v50
	v_cvt_f32_f16_sdwa v59, v50 dst_sel:DWORD dst_unused:UNUSED_PAD src0_sel:WORD_1
	v_cvt_f32_f16_e32 v50, v51
	v_cvt_f32_f16_sdwa v51, v51 dst_sel:DWORD dst_unused:UNUSED_PAD src0_sel:WORD_1
	v_pk_fma_f32 v[46:47], v[58:59], s[34:35], v[46:47] op_sel_hi:[1,0,1]
	s_nop 0
	v_cvt_pk_f16_f32 v46, v46, v47
	v_pk_fma_f32 v[48:49], v[50:51], s[34:35], v[48:49] op_sel_hi:[1,0,1]
	v_lshl_add_u64 v[50:51], s[4:5], 0, v[54:55]
	v_cvt_pk_f16_f32 v47, v48, v49
	v_cvt_f32_f16_e32 v48, v52
	v_cvt_f32_f16_sdwa v49, v52 dst_sel:DWORD dst_unused:UNUSED_PAD src0_sel:WORD_1
	v_pk_fma_f32 v[42:43], v[48:49], s[34:35], v[42:43] op_sel_hi:[1,0,1]
	s_nop 0
	v_cvt_pk_f16_f32 v48, v42, v43
	v_cvt_f32_f16_e32 v42, v53
	v_cvt_f32_f16_sdwa v43, v53 dst_sel:DWORD dst_unused:UNUSED_PAD src0_sel:WORD_1
	v_pk_fma_f32 v[42:43], v[42:43], s[34:35], v[44:45] op_sel_hi:[1,0,1]
	s_nop 0
	v_cvt_pk_f16_f32 v49, v42, v43
	s_nop 0
	global_store_dwordx4 v[50:51], v[46:49], off
	s_waitcnt vmcnt(15)
	v_mov_b64_e32 v[42:43], v[202:203]
	v_mov_b64_e32 v[44:45], v[204:205]
	s_nop 0
	v_cvt_f32_f16_e32 v46, v42
	v_cvt_f32_f16_sdwa v47, v42 dst_sel:DWORD dst_unused:UNUSED_PAD src0_sel:WORD_1
	v_cvt_f32_f16_e32 v42, v43
	v_cvt_f32_f16_sdwa v43, v43 dst_sel:DWORD dst_unused:UNUSED_PAD src0_sel:WORD_1
	v_pk_fma_f32 v[38:39], v[46:47], s[34:35], v[38:39] op_sel_hi:[1,0,1]
	s_nop 0
	v_cvt_pk_f16_f32 v38, v38, v39
	v_pk_fma_f32 v[40:41], v[42:43], s[34:35], v[40:41] op_sel_hi:[1,0,1]
	s_nop 0
	v_cvt_pk_f16_f32 v39, v40, v41
	v_cvt_f32_f16_e32 v40, v44
	v_cvt_f32_f16_sdwa v41, v44 dst_sel:DWORD dst_unused:UNUSED_PAD src0_sel:WORD_1
	v_pk_fma_f32 v[34:35], v[40:41], s[34:35], v[34:35] op_sel_hi:[1,0,1]
	s_nop 0
	v_cvt_pk_f16_f32 v40, v34, v35
	v_cvt_f32_f16_e32 v34, v45
	v_cvt_f32_f16_sdwa v35, v45 dst_sel:DWORD dst_unused:UNUSED_PAD src0_sel:WORD_1
	v_pk_fma_f32 v[34:35], v[34:35], s[34:35], v[36:37] op_sel_hi:[1,0,1]
	s_nop 0
	v_cvt_pk_f16_f32 v41, v34, v35
	global_store_dwordx4 v[50:51], v[38:41], off offset:256
	s_nop 1
	v_lshl_add_u64 v[38:39], v[140:141], 0, s[8:9]
	v_lshl_add_u64 v[40:41], s[94:95], 0, v[38:39]
	s_waitcnt vmcnt(15)
	v_mov_b64_e32 v[34:35], v[212:213]
	v_mov_b64_e32 v[36:37], v[214:215]
	v_cvt_f32_f16_e32 v42, v34
	v_cvt_f32_f16_sdwa v43, v34 dst_sel:DWORD dst_unused:UNUSED_PAD src0_sel:WORD_1
	v_cvt_f32_f16_e32 v34, v35
	v_cvt_f32_f16_sdwa v35, v35 dst_sel:DWORD dst_unused:UNUSED_PAD src0_sel:WORD_1
	v_pk_fma_f32 v[30:31], v[42:43], s[34:35], v[30:31] op_sel_hi:[1,0,1]
	s_nop 0
	v_cvt_pk_f16_f32 v30, v30, v31
	v_pk_fma_f32 v[32:33], v[34:35], s[34:35], v[32:33] op_sel_hi:[1,0,1]
	v_lshl_add_u64 v[34:35], s[4:5], 0, v[38:39]
	v_cvt_pk_f16_f32 v31, v32, v33
	v_cvt_f32_f16_e32 v32, v36
	v_cvt_f32_f16_sdwa v33, v36 dst_sel:DWORD dst_unused:UNUSED_PAD src0_sel:WORD_1
	v_pk_fma_f32 v[26:27], v[32:33], s[34:35], v[26:27] op_sel_hi:[1,0,1]
	s_nop 0
	v_cvt_pk_f16_f32 v32, v26, v27
	v_cvt_f32_f16_e32 v26, v37
	v_cvt_f32_f16_sdwa v27, v37 dst_sel:DWORD dst_unused:UNUSED_PAD src0_sel:WORD_1
	v_pk_fma_f32 v[26:27], v[26:27], s[34:35], v[28:29] op_sel_hi:[1,0,1]
	s_nop 0
	v_cvt_pk_f16_f32 v33, v26, v27
	s_nop 0
	global_store_dwordx4 v[34:35], v[30:33], off
	s_waitcnt vmcnt(15)
	v_mov_b64_e32 v[26:27], v[220:221]
	v_mov_b64_e32 v[28:29], v[222:223]
	s_nop 0
	v_cvt_f32_f16_e32 v30, v26
	v_cvt_f32_f16_sdwa v31, v26 dst_sel:DWORD dst_unused:UNUSED_PAD src0_sel:WORD_1
	v_cvt_f32_f16_e32 v26, v27
	v_cvt_f32_f16_sdwa v27, v27 dst_sel:DWORD dst_unused:UNUSED_PAD src0_sel:WORD_1
	v_pk_fma_f32 v[22:23], v[30:31], s[34:35], v[22:23] op_sel_hi:[1,0,1]
	s_nop 0
	v_cvt_pk_f16_f32 v22, v22, v23
	v_pk_fma_f32 v[24:25], v[26:27], s[34:35], v[24:25] op_sel_hi:[1,0,1]
	s_nop 0
	v_cvt_pk_f16_f32 v23, v24, v25
	v_cvt_f32_f16_e32 v24, v28
	v_cvt_f32_f16_sdwa v25, v28 dst_sel:DWORD dst_unused:UNUSED_PAD src0_sel:WORD_1
	v_pk_fma_f32 v[18:19], v[24:25], s[34:35], v[18:19] op_sel_hi:[1,0,1]
	s_nop 0
	v_cvt_pk_f16_f32 v24, v18, v19
	v_cvt_f32_f16_e32 v18, v29
	v_cvt_f32_f16_sdwa v19, v29 dst_sel:DWORD dst_unused:UNUSED_PAD src0_sel:WORD_1
	v_pk_fma_f32 v[18:19], v[18:19], s[34:35], v[20:21] op_sel_hi:[1,0,1]
	s_nop 0
	v_cvt_pk_f16_f32 v25, v18, v19
	global_store_dwordx4 v[34:35], v[22:25], off offset:256
	s_nop 1
	v_lshl_add_u64 v[22:23], v[140:141], 0, s[2:3]
	v_lshl_add_u64 v[24:25], s[94:95], 0, v[22:23]
	s_waitcnt vmcnt(15)
	v_mov_b64_e32 v[18:19], v[224:225]
	v_mov_b64_e32 v[20:21], v[226:227]
	v_cvt_f32_f16_e32 v26, v18
	v_cvt_f32_f16_sdwa v27, v18 dst_sel:DWORD dst_unused:UNUSED_PAD src0_sel:WORD_1
	v_cvt_f32_f16_e32 v18, v19
	v_cvt_f32_f16_sdwa v19, v19 dst_sel:DWORD dst_unused:UNUSED_PAD src0_sel:WORD_1
	v_pk_fma_f32 v[14:15], v[26:27], s[34:35], v[14:15] op_sel_hi:[1,0,1]
	s_nop 0
	v_cvt_pk_f16_f32 v14, v14, v15
	v_pk_fma_f32 v[16:17], v[18:19], s[34:35], v[16:17] op_sel_hi:[1,0,1]
	v_lshl_add_u64 v[18:19], s[4:5], 0, v[22:23]
	v_cvt_pk_f16_f32 v15, v16, v17
	v_cvt_f32_f16_e32 v16, v20
	v_cvt_f32_f16_sdwa v17, v20 dst_sel:DWORD dst_unused:UNUSED_PAD src0_sel:WORD_1
	v_pk_fma_f32 v[10:11], v[16:17], s[34:35], v[10:11] op_sel_hi:[1,0,1]
	s_nop 0
	v_cvt_pk_f16_f32 v16, v10, v11
	v_cvt_f32_f16_e32 v10, v21
	v_cvt_f32_f16_sdwa v11, v21 dst_sel:DWORD dst_unused:UNUSED_PAD src0_sel:WORD_1
	v_pk_fma_f32 v[10:11], v[10:11], s[34:35], v[12:13] op_sel_hi:[1,0,1]
	s_nop 0
	v_cvt_pk_f16_f32 v17, v10, v11
	s_nop 0
	global_store_dwordx4 v[18:19], v[14:17], off
	s_waitcnt vmcnt(15)
	v_mov_b64_e32 v[10:11], v[228:229]
	v_mov_b64_e32 v[12:13], v[230:231]
	s_nop 0
	v_cvt_f32_f16_e32 v14, v10
	v_cvt_f32_f16_sdwa v15, v10 dst_sel:DWORD dst_unused:UNUSED_PAD src0_sel:WORD_1
	v_cvt_f32_f16_e32 v10, v11
	v_cvt_f32_f16_sdwa v11, v11 dst_sel:DWORD dst_unused:UNUSED_PAD src0_sel:WORD_1
	v_pk_fma_f32 v[6:7], v[14:15], s[34:35], v[6:7] op_sel_hi:[1,0,1]
	s_nop 0
	v_cvt_pk_f16_f32 v6, v6, v7
	v_pk_fma_f32 v[8:9], v[10:11], s[34:35], v[8:9] op_sel_hi:[1,0,1]
	s_nop 0
	v_cvt_pk_f16_f32 v7, v8, v9
	v_cvt_f32_f16_e32 v8, v12
	v_cvt_f32_f16_sdwa v9, v12 dst_sel:DWORD dst_unused:UNUSED_PAD src0_sel:WORD_1
	v_pk_fma_f32 v[2:3], v[8:9], s[34:35], v[2:3] op_sel_hi:[1,0,1]
	s_nop 0
	v_cvt_pk_f16_f32 v8, v2, v3
	v_cvt_f32_f16_e32 v2, v13
	v_cvt_f32_f16_sdwa v3, v13 dst_sel:DWORD dst_unused:UNUSED_PAD src0_sel:WORD_1
	v_pk_fma_f32 v[2:3], v[2:3], s[34:35], v[4:5] op_sel_hi:[1,0,1]
	s_nop 0
	v_cvt_pk_f16_f32 v9, v2, v3
	s_mov_b32 s35, s0
	global_store_dwordx4 v[18:19], v[6:9], off offset:256
	s_cbranch_vccz .LBB0_140
	s_waitcnt vmcnt(0)
	s_cmpk_gt_u32 s62, 0xff
	s_cbranch_scc1 .LBB0_151
	s_barrier

; __device__ __forceinline__ int otid() { int t = (int)threadIdx.x; asm volatile("" : "+v"(t)); return t; }
; __device__ __forceinline__ int obid() { int t = (int)blockIdx.x; asm volatile("" : "+s"(t)); return t; }
; #define PG8_STAGE(bufoff, gbase, voff) do { _Pragma("unroll") for (int _i = 0; _i < 2; ++_i) \
;         __builtin_amdgcn_global_load_lds((const unsigned*)((const char*)(gbase) + (voff)[_i]), (LAS unsigned*)(lds + (bufoff) + ldsw + _i * 8192), 16, 0, 0); } while (0)
; #define PG8_WAIT_V(n) asm volatile("s_waitcnt vmcnt(" #n ")" ::: "memory")
; #define PG8_BAR __builtin_amdgcn_s_barrier()
; template <class Epi, class AMap>
; __device__ __forceinline__ void gemm_phase(LAS unsigned char* lds, const AMap am, const int lda, const h16* Bt, const int ldb, const int M, const int N, const int K, const Epi& E) {
;     const int tid = otid(), wid = __builtin_amdgcn_readfirstlane(tid >> 6), lane = tid & 63, wr = wid >> 2, wc = wid & 3, fr = lane & 15, fq = lane >> 4;
;     const int nt = K / BK;
;     Order S; S.init(M, N, (int)gridDim.x, obid());
;     unsigned voffA[2], voffB[2];
; #pragma unroll
;     for (int i = 0; i < 2; ++i) { int R, C; stage_rc(tid * 16 + i * 8192, R, C); const int Rb = Epi::PERM ? ((R & ~31) + perm32(R & 31)) : R;
;         voffA[i] = (unsigned)(R * lda + C) * 2u; voffB[i] = (unsigned)(Rb * ldb + C) * 2u; }
;     const size_t kstep = (size_t)(BK * 2);
;     const size_t hstepA = (size_t)HALF * lda * 2, hstepB = (size_t)HALF * ldb * 2;
;     const size_t tstepA = 2 * hstepA, tstepB = 2 * hstepB;
;     const unsigned ldsw = (unsigned)wid * 1024u;
;     const int aoff = lds_byte(wr * 64 + fr, fq * 8), boff = lds_byte(wc * 32 + fr, fq * 8);
;     ...
;     const char* cA = am(cur.pn) + (size_t)cur.pm * tstepA; const char* cB = (const char*)Bt + (size_t)cur.pn * tstepB;
;     PG8_STAGE(PG8_SB(0, 0), cB, voffB); PG8_STAGE(PG8_SA(0, 0), cA, voffA); PG8_STAGE(PG8_SB(0, 1), cB + hstepB, voffB); PG8_STAGE(PG8_SA(0, 1), cA + hstepA, voffA);
;     if (wr == 1) PG8_BAR;
;     PG8_WAIT_V(4); PG8_BAR;
;     PG8_STAGE(PG8_SB(1, 0), cB + kstep, voffB); PG8_STAGE(PG8_SA(1, 0), cA + kstep, voffA); PG8_STAGE(PG8_SB(1, 1), cB + hstepB + kstep, voffB);
;     PG8_WAIT_V(6); PG8_BAR;
.LBB0_263:
	v_lshrrev_b32_e32 v16, 1, v0
	v_and_b32_e32 v17, 24, v16
	v_and_b32_e32 v148, 15, v0
	v_lshlrev_b32_e32 v18, 1, v17
	v_lshlrev_b32_e32 v19, 2, v0
	s_lshl_b32 s76, s0, 6
	v_lshl_or_b32 v18, v148, 6, v18
	s_lshl_b32 s0, s0, 13
	v_and_b32_e32 v19, 32, v19
	v_bitop3_b32 v20, v18, s0, v19 bitop3:0xde
	s_lshl_b32 s0, s1, 5
	s_and_b32 s20, s0, 0x60
	s_add_i32 m0, s72, 0x18000
	v_lshl_add_u64 v[8:9], v[8:9], 0, s[92:93]
	s_lshl_b32 s0, s20, 7
	s_waitcnt vmcnt(0)
	s_barrier
	global_load_lds_dwordx4 v[8:9], off
	v_lshl_add_u64 v[6:7], v[6:7], 0, s[92:93]
	s_add_i32 m0, s72, 0x1a000
	s_add_i32 s77, s72, 0x8000
	s_add_i32 s78, s72, 0xa000
	v_bitop3_b32 v149, v18, s0, v19 bitop3:0xde
	global_load_lds_dwordx4 v[6:7], off
	v_lshl_add_u64 v[4:5], v[4:5], 0, s[92:93]
	s_mov_b32 m0, s77
	s_add_u32 s0, s42, 0x80080
	global_load_lds_dwordx4 v[4:5], off
	v_lshl_add_u64 v[2:3], v[2:3], 0, s[92:93]
	s_mov_b32 m0, s78
	s_addc_u32 s1, s43, 0
	global_load_lds_dwordx4 v[2:3], off
	s_add_i32 m0, s72, 0x1c000
	v_lshl_add_u64 v[2:3], s[0:1], 0, v[132:133]
	global_load_lds_dwordx4 v[2:3], off
	v_lshl_add_u64 v[2:3], s[0:1], 0, v[136:137]
	s_add_i32 m0, s72, 0x1e000
	v_lshlrev_b32_e32 v0, 1, v0
	global_load_lds_dwordx4 v[2:3], off
	v_and_b32_e32 v2, 4, v16
	v_and_or_b32 v151, v0, 8, v2
	v_lshlrev_b32_e32 v0, 15, v10
	v_and_b32_e32 v0, 0xffff0000, v0
	v_lshl_add_u32 v0, v11, 12, v0
	v_and_b32_e32 v2, 1, v10
	v_lshl_or_b32 v0, v2, 6, v0
	v_lshl_add_u32 v138, v12, 1, v0
	v_lshlrev_b32_e32 v0, 15, v13
	v_and_b32_e32 v0, 0xffff0000, v0
	s_waitcnt vmcnt(6)
	v_lshl_add_u32 v0, v14, 12, v0
	v_and_b32_e32 v2, 1, v13
	v_or_b32_e32 v150, s20, v17
	v_lshl_or_b32 v0, v2, 6, v0
	v_or_b32_e32 v152, 0x80, v150
	v_mov_b32_e32 v139, v1
	v_lshl_add_u32 v140, v15, 1, v0
	v_mov_b32_e32 v141, v1
	s_mov_b32 s79, 0
	v_add_u32_e32 v153, 0, v20
	s_barrier
	s_branch .LBB0_265

; #define PG8_STAGE(bufoff, gbase, voff) do { _Pragma("unroll") for (int _i = 0; _i < 2; ++_i) \
;         __builtin_amdgcn_global_load_lds((const unsigned*)((const char*)(gbase) + (voff)[_i]), (LAS unsigned*)(lds + (bufoff) + ldsw + _i * 8192), 16, 0, 0); } while (0)
; #define PG8_LDA(dst, b, h) do { _Pragma("unroll") for (int m = 0; m < 4; ++m) _Pragma("unroll") for (int k = 0; k < 2; ++k) dst[m][k] = *(const LAS h16x8*)(lds + PG8_SA(b, h) + aoff + m * 2048 + k * 1024); } while (0)
; #define PG8_LDB(dst, b, h) do { _Pragma("unroll") for (int n = 0; n < 2; ++n) _Pragma("unroll") for (int k = 0; k < 2; ++k) dst[n][k] = *(const LAS h16x8*)(lds + PG8_SB(b, h) + boff + n * 2048 + k * 1024); } while (0)
; #define PG8_MMA(ai, bj, At, Bt_) do { __builtin_amdgcn_s_setprio(1); _Pragma("unroll") for (int m = 0; m < 4; ++m) _Pragma("unroll") for (int n = 0; n < 2; ++n) _Pragma("unroll") for (int k = 0; k < 2; ++k) \
;         acc[ai][bj][m][n] = __builtin_amdgcn_mfma_f32_16x16x32_f16(Bt_[n][k], At[m][k], acc[ai][bj][m][n], 0, 0, 0); __builtin_amdgcn_s_setprio(0); } while (0)
; #define PG8_WAIT_L(n) asm volatile("s_waitcnt lgkmcnt(" #n ")" ::: "memory")
; #define PG8_BAR __builtin_amdgcn_s_barrier()
; #define PG8_SCHED __builtin_amdgcn_sched_barrier(0)
; template <class Epi, class AMap>
; __device__ __forceinline__ void gemm_phase(LAS unsigned char* lds, const AMap am, const int lda, const h16* Bt, const int ldb, const int M, const int N, const int K, const Epi& E) {
;     ...
;             PG8_LDB(B0, 0, 0); PG8_SCHED; PG8_LDA(At, 0, 0); PG8_STAGE(PG8_SA(1, 1), a1 + hstepA, voffA);
;             PG8_WAIT_L(8); PG8_BAR; PG8_WAIT_L(0); PG8_MMA(0, 0, At, B0); PG8_BAR; PG8_SCHED;
;             PG8_LDB(B1, 0, 1); PG8_STAGE(PG8_SB(0, 0), b2, voffB);
;             PG8_BAR; PG8_WAIT_L(0); PG8_MMA(0, 1, At, B1); PG8_BAR;
;             PG8_LDA(At, 0, 1); PG8_STAGE(PG8_SA(0, 0), a2, voffA);
;             PG8_BAR; PG8_WAIT_L(0); PG8_MMA(1, 0, At, B0); PG8_BAR; PG8_SCHED;
.LBB0_268:
	s_add_u32 s42, s40, 0xfff80080
	s_addc_u32 s43, s41, -1
	s_add_i32 s45, 0, 0x10000
	v_add_u32_e32 v0, s45, v149
	ds_read_b128 v[142:145], v0
	ds_read_b128 v[154:157], v0 offset:1024
	ds_read_b128 v[158:161], v0 offset:2048
	ds_read_b128 v[162:165], v0 offset:3072
	s_cmp_eq_u32 s35, 28
	s_cselect_b32 s49, s23, s43
	s_cselect_b32 s48, s27, s42
	s_cselect_b32 s43, s1, s29
	s_cselect_b32 s42, s20, s21
	v_lshl_add_u64 v[146:147], s[40:41], 0, v[138:139]
	s_add_i32 m0, s72, 0xc000
	ds_read_b128 v[166:169], v153
	ds_read_b128 v[170:173], v153 offset:1024
	ds_read_b128 v[174:177], v153 offset:2048
	ds_read_b128 v[178:181], v153 offset:3072
	ds_read_b128 v[182:185], v153 offset:4096
	ds_read_b128 v[186:189], v153 offset:5120
	ds_read_b128 v[190:193], v153 offset:6144
	ds_read_b128 v[194:197], v153 offset:7168
	global_load_lds_dwordx4 v[146:147], off
	v_lshl_add_u64 v[146:147], s[40:41], 0, v[140:141]
	s_add_i32 m0, s72, 0xe000
	s_nop 0
	global_load_lds_dwordx4 v[146:147], off
	s_waitcnt lgkmcnt(11)
	s_add_i32 s60, 0, 0x14000
	s_add_i32 s45, s45, s65
	v_add_u32_e32 v0, s60, v149
	v_lshl_add_u64 v[146:147], s[42:43], 0, v[132:133]
	s_mov_b32 m0, s45
	ds_read_b128 v[198:201], v0
	ds_read_b128 v[202:205], v0 offset:1024
	ds_read_b128 v[220:223], v0 offset:2048
	ds_read_b128 v[224:227], v0 offset:3072
	s_waitcnt lgkmcnt(0)
	s_barrier
	v_mfma_f32_16x16x32_f16 v[126:129], v[142:145], v[166:169], v[126:129]
	v_mfma_f32_16x16x32_f16 v[122:125], v[158:161], v[166:169], v[122:125]
	v_mfma_f32_16x16x32_f16 v[110:113], v[142:145], v[174:177], v[110:113]
	v_mfma_f32_16x16x32_f16 v[106:109], v[158:161], v[174:177], v[106:109]
	v_mfma_f32_16x16x32_f16 v[94:97], v[142:145], v[182:185], v[94:97]
	v_mfma_f32_16x16x32_f16 v[90:93], v[158:161], v[182:185], v[90:93]
	v_mfma_f32_16x16x32_f16 v[78:81], v[142:145], v[190:193], v[78:81]
	v_mfma_f32_16x16x32_f16 v[74:77], v[158:161], v[190:193], v[74:77]
	v_mfma_f32_16x16x32_f16 v[126:129], v[154:157], v[170:173], v[126:129]
	v_mfma_f32_16x16x32_f16 v[122:125], v[162:165], v[170:173], v[122:125]
	v_mfma_f32_16x16x32_f16 v[110:113], v[154:157], v[178:181], v[110:113]
	v_mfma_f32_16x16x32_f16 v[106:109], v[162:165], v[178:181], v[106:109]
	v_mfma_f32_16x16x32_f16 v[94:97], v[154:157], v[186:189], v[94:97]
	v_mfma_f32_16x16x32_f16 v[90:93], v[162:165], v[186:189], v[90:93]
	v_mfma_f32_16x16x32_f16 v[78:81], v[154:157], v[194:197], v[78:81]
	v_mfma_f32_16x16x32_f16 v[74:77], v[162:165], v[194:197], v[74:77]
	v_mfma_f32_16x16x32_f16 v[118:121], v[198:201], v[166:169], v[118:121]
	v_mfma_f32_16x16x32_f16 v[114:117], v[220:223], v[166:169], v[114:117]
	v_mfma_f32_16x16x32_f16 v[102:105], v[198:201], v[174:177], v[102:105]
	v_mfma_f32_16x16x32_f16 v[98:101], v[220:223], v[174:177], v[98:101]
	v_mfma_f32_16x16x32_f16 v[86:89], v[198:201], v[182:185], v[86:89]
	v_mfma_f32_16x16x32_f16 v[82:85], v[220:223], v[182:185], v[82:85]
	v_mfma_f32_16x16x32_f16 v[70:73], v[198:201], v[190:193], v[70:73]
	v_mfma_f32_16x16x32_f16 v[66:69], v[220:223], v[190:193], v[66:69]
	v_mfma_f32_16x16x32_f16 v[118:121], v[202:205], v[170:173], v[118:121]
	v_mfma_f32_16x16x32_f16 v[114:117], v[224:227], v[170:173], v[114:117]
	v_mfma_f32_16x16x32_f16 v[102:105], v[202:205], v[178:181], v[102:105]
	v_mfma_f32_16x16x32_f16 v[98:101], v[224:227], v[178:181], v[98:101]
	v_mfma_f32_16x16x32_f16 v[86:89], v[202:205], v[186:189], v[86:89]
	v_mfma_f32_16x16x32_f16 v[82:85], v[224:227], v[186:189], v[82:85]
	v_mfma_f32_16x16x32_f16 v[70:73], v[202:205], v[194:197], v[70:73]
	v_mfma_f32_16x16x32_f16 v[66:69], v[224:227], v[194:197], v[66:69]
	s_barrier
	global_load_lds_dwordx4 v[146:147], off
	v_lshl_add_u64 v[206:207], s[42:43], 0, v[136:137]
	s_add_i32 m0, s45, 0x2000
	s_nop 0
	global_load_lds_dwordx4 v[206:207], off
	s_mov_b32 m0, s72
	v_lshl_add_u64 v[212:213], s[48:49], 0, v[130:131]
	ds_read_b128 v[166:169], v153 offset:16384
	ds_read_b128 v[170:173], v153 offset:17408
	ds_read_b128 v[174:177], v153 offset:18432
	ds_read_b128 v[178:181], v153 offset:19456
	ds_read_b128 v[182:185], v153 offset:20480
	ds_read_b128 v[186:189], v153 offset:21504
	ds_read_b128 v[190:193], v153 offset:22528
	ds_read_b128 v[194:197], v153 offset:23552
	global_load_lds_dwordx4 v[212:213], off
	v_lshl_add_u64 v[228:229], s[48:49], 0, v[134:135]
	s_mov_b32 m0, s73
	s_nop 0
	global_load_lds_dwordx4 v[228:229], off
	s_add_u32 s50, s42, 0x80000
	s_addc_u32 s51, s43, 0
	s_add_i32 s45, s60, s65
	v_lshl_add_u64 v[232:233], s[50:51], 0, v[132:133]
	s_mov_b32 m0, s45
	s_nop 0
	global_load_lds_dwordx4 v[232:233], off
	v_lshl_add_u64 v[232:233], s[50:51], 0, v[136:137]
	s_add_i32 m0, s45, 0x2000
	s_nop 0
	global_load_lds_dwordx4 v[232:233], off
	s_waitcnt vmcnt(6) lgkmcnt(0)
	s_barrier
; #define PG8_STAGE(bufoff, gbase, voff) do { _Pragma("unroll") for (int _i = 0; _i < 2; ++_i) \
;         __builtin_amdgcn_global_load_lds((const unsigned*)((const char*)(gbase) + (voff)[_i]), (LAS unsigned*)(lds + (bufoff) + ldsw + _i * 8192), 16, 0, 0); } while (0)
; #define PG8_LDA(dst, b, h) do { _Pragma("unroll") for (int m = 0; m < 4; ++m) _Pragma("unroll") for (int k = 0; k < 2; ++k) dst[m][k] = *(const LAS h16x8*)(lds + PG8_SA(b, h) + aoff + m * 2048 + k * 1024); } while (0)
; #define PG8_LDB(dst, b, h) do { _Pragma("unroll") for (int n = 0; n < 2; ++n) _Pragma("unroll") for (int k = 0; k < 2; ++k) dst[n][k] = *(const LAS h16x8*)(lds + PG8_SB(b, h) + boff + n * 2048 + k * 1024); } while (0)
; #define PG8_MMA(ai, bj, At, Bt_) do { __builtin_amdgcn_s_setprio(1); _Pragma("unroll") for (int m = 0; m < 4; ++m) _Pragma("unroll") for (int n = 0; n < 2; ++n) _Pragma("unroll") for (int k = 0; k < 2; ++k) \
;         acc[ai][bj][m][n] = __builtin_amdgcn_mfma_f32_16x16x32_f16(Bt_[n][k], At[m][k], acc[ai][bj][m][n], 0, 0, 0); __builtin_amdgcn_s_setprio(0); } while (0)
; #define PG8_WAIT_V(n) asm volatile("s_waitcnt vmcnt(" #n ")" ::: "memory")
; #define PG8_WAIT_L(n) asm volatile("s_waitcnt lgkmcnt(" #n ")" ::: "memory")
; #define PG8_BAR __builtin_amdgcn_s_barrier()
; #define PG8_SCHED __builtin_amdgcn_sched_barrier(0)
; template <class Epi, class AMap>
; __device__ __forceinline__ void gemm_phase(LAS unsigned char* lds, const AMap am, const int lda, const h16* Bt, const int ldb, const int M, const int N, const int K, const Epi& E) {
;     ...
;             PG8_BAR; PG8_WAIT_L(0); PG8_MMA(1, 0, At, B0); PG8_BAR; PG8_SCHED;
;             PG8_STAGE(PG8_SB(0, 1), b2 + hstepB, voffB);
;             PG8_WAIT_V(6); PG8_BAR; PG8_MMA(1, 1, At, B1); PG8_BAR;
;             PG8_LDB(B0, 1, 0); PG8_SCHED; PG8_LDA(At, 1, 0); PG8_STAGE(PG8_SA(0, 1), a2 + hstepA, voffA);
;             PG8_WAIT_L(8); PG8_BAR; PG8_WAIT_L(0); PG8_MMA(0, 0, At, B0); PG8_BAR; PG8_SCHED;
;             PG8_LDB(B1, 1, 1); PG8_STAGE(PG8_SB(1, 0), b3, voffB);
;             PG8_BAR; PG8_WAIT_L(0); PG8_MMA(0, 1, At, B1); PG8_BAR;
	v_mfma_f32_16x16x32_f16 v[62:65], v[142:145], v[166:169], v[62:65]
	v_mfma_f32_16x16x32_f16 v[58:61], v[158:161], v[166:169], v[58:61]
	v_mfma_f32_16x16x32_f16 v[46:49], v[142:145], v[174:177], v[46:49]
	v_mfma_f32_16x16x32_f16 v[42:45], v[158:161], v[174:177], v[42:45]
	v_mfma_f32_16x16x32_f16 v[30:33], v[142:145], v[182:185], v[30:33]
	v_mfma_f32_16x16x32_f16 v[26:29], v[158:161], v[182:185], v[26:29]
	v_mfma_f32_16x16x32_f16 v[14:17], v[142:145], v[190:193], v[14:17]
	v_mfma_f32_16x16x32_f16 v[10:13], v[158:161], v[190:193], v[10:13]
	v_mfma_f32_16x16x32_f16 v[62:65], v[154:157], v[170:173], v[62:65]
	v_mfma_f32_16x16x32_f16 v[58:61], v[162:165], v[170:173], v[58:61]
	v_mfma_f32_16x16x32_f16 v[46:49], v[154:157], v[178:181], v[46:49]
	v_mfma_f32_16x16x32_f16 v[42:45], v[162:165], v[178:181], v[42:45]
	v_mfma_f32_16x16x32_f16 v[30:33], v[154:157], v[186:189], v[30:33]
	v_mfma_f32_16x16x32_f16 v[26:29], v[162:165], v[186:189], v[26:29]
	v_mfma_f32_16x16x32_f16 v[14:17], v[154:157], v[194:197], v[14:17]
	v_mfma_f32_16x16x32_f16 v[10:13], v[162:165], v[194:197], v[10:13]
	v_mfma_f32_16x16x32_f16 v[54:57], v[198:201], v[166:169], v[54:57]
	v_mfma_f32_16x16x32_f16 v[50:53], v[220:223], v[166:169], v[50:53]
	v_mfma_f32_16x16x32_f16 v[38:41], v[198:201], v[174:177], v[38:41]
	v_mfma_f32_16x16x32_f16 v[34:37], v[220:223], v[174:177], v[34:37]
	v_mfma_f32_16x16x32_f16 v[22:25], v[198:201], v[182:185], v[22:25]
	v_mfma_f32_16x16x32_f16 v[18:21], v[220:223], v[182:185], v[18:21]
	v_mfma_f32_16x16x32_f16 v[6:9], v[198:201], v[190:193], v[6:9]
	v_mfma_f32_16x16x32_f16 v[2:5], v[220:223], v[190:193], v[2:5]
	v_mfma_f32_16x16x32_f16 v[54:57], v[202:205], v[170:173], v[54:57]
	v_mfma_f32_16x16x32_f16 v[50:53], v[224:227], v[170:173], v[50:53]
	v_mfma_f32_16x16x32_f16 v[38:41], v[202:205], v[178:181], v[38:41]
	v_mfma_f32_16x16x32_f16 v[34:37], v[224:227], v[178:181], v[34:37]
	v_mfma_f32_16x16x32_f16 v[22:25], v[202:205], v[186:189], v[22:25]
	v_mfma_f32_16x16x32_f16 v[18:21], v[224:227], v[186:189], v[18:21]
	v_mfma_f32_16x16x32_f16 v[6:9], v[202:205], v[194:197], v[6:9]
	v_mfma_f32_16x16x32_f16 v[2:5], v[224:227], v[194:197], v[2:5]
	s_barrier
	s_add_i32 s45, 0, 0x18000
	v_add_u32_e32 v0, s45, v149
	ds_read_b128 v[142:145], v0
	ds_read_b128 v[154:157], v0 offset:1024
	ds_read_b128 v[158:161], v0 offset:2048
	ds_read_b128 v[162:165], v0 offset:3072
	s_add_u32 s48, s48, 0x80000
	s_addc_u32 s49, s49, 0
	s_mov_b32 m0, s74
	v_lshl_add_u64 v[232:233], s[48:49], 0, v[130:131]
	ds_read_b128 v[166:169], v153 offset:32768
	ds_read_b128 v[170:173], v153 offset:33792
	ds_read_b128 v[174:177], v153 offset:34816
	ds_read_b128 v[178:181], v153 offset:35840
	ds_read_b128 v[182:185], v153 offset:36864
	ds_read_b128 v[186:189], v153 offset:37888
	ds_read_b128 v[190:193], v153 offset:38912
	ds_read_b128 v[194:197], v153 offset:39936
	global_load_lds_dwordx4 v[232:233], off
	v_lshl_add_u64 v[232:233], s[48:49], 0, v[134:135]
	s_mov_b32 m0, s75
	s_nop 0
	global_load_lds_dwordx4 v[232:233], off
	s_waitcnt lgkmcnt(11)
	s_add_i32 s48, 0, 0x1c000
	s_add_i32 s45, s45, s65
	v_add_u32_e32 v0, s48, v149
	v_lshl_add_u64 v[146:147], v[146:147], 0, s[92:93]
	s_mov_b32 m0, s45
	ds_read_b128 v[198:201], v0
	ds_read_b128 v[202:205], v0 offset:1024
	ds_read_b128 v[220:223], v0 offset:2048
	ds_read_b128 v[224:227], v0 offset:3072
	s_waitcnt lgkmcnt(0)
	s_barrier
	v_mfma_f32_16x16x32_f16 v[126:129], v[142:145], v[166:169], v[126:129]
	v_mfma_f32_16x16x32_f16 v[122:125], v[158:161], v[166:169], v[122:125]
	v_mfma_f32_16x16x32_f16 v[110:113], v[142:145], v[174:177], v[110:113]
	v_mfma_f32_16x16x32_f16 v[106:109], v[158:161], v[174:177], v[106:109]
	v_mfma_f32_16x16x32_f16 v[94:97], v[142:145], v[182:185], v[94:97]
	v_mfma_f32_16x16x32_f16 v[90:93], v[158:161], v[182:185], v[90:93]
	v_mfma_f32_16x16x32_f16 v[78:81], v[142:145], v[190:193], v[78:81]
	v_mfma_f32_16x16x32_f16 v[74:77], v[158:161], v[190:193], v[74:77]
	v_mfma_f32_16x16x32_f16 v[126:129], v[154:157], v[170:173], v[126:129]
	v_mfma_f32_16x16x32_f16 v[122:125], v[162:165], v[170:173], v[122:125]
	v_mfma_f32_16x16x32_f16 v[110:113], v[154:157], v[178:181], v[110:113]
	v_mfma_f32_16x16x32_f16 v[106:109], v[162:165], v[178:181], v[106:109]
	v_mfma_f32_16x16x32_f16 v[94:97], v[154:157], v[186:189], v[94:97]
	v_mfma_f32_16x16x32_f16 v[90:93], v[162:165], v[186:189], v[90:93]
	v_mfma_f32_16x16x32_f16 v[78:81], v[154:157], v[194:197], v[78:81]
	v_mfma_f32_16x16x32_f16 v[74:77], v[162:165], v[194:197], v[74:77]
	v_mfma_f32_16x16x32_f16 v[118:121], v[198:201], v[166:169], v[118:121]
	v_mfma_f32_16x16x32_f16 v[114:117], v[220:223], v[166:169], v[114:117]
	v_mfma_f32_16x16x32_f16 v[102:105], v[198:201], v[174:177], v[102:105]
	v_mfma_f32_16x16x32_f16 v[98:101], v[220:223], v[174:177], v[98:101]
	v_mfma_f32_16x16x32_f16 v[86:89], v[198:201], v[182:185], v[86:89]
	v_mfma_f32_16x16x32_f16 v[82:85], v[220:223], v[182:185], v[82:85]
	v_mfma_f32_16x16x32_f16 v[70:73], v[198:201], v[190:193], v[70:73]
	v_mfma_f32_16x16x32_f16 v[66:69], v[220:223], v[190:193], v[66:69]
	v_mfma_f32_16x16x32_f16 v[118:121], v[202:205], v[170:173], v[118:121]
	v_mfma_f32_16x16x32_f16 v[114:117], v[224:227], v[170:173], v[114:117]
	v_mfma_f32_16x16x32_f16 v[102:105], v[202:205], v[178:181], v[102:105]
	v_mfma_f32_16x16x32_f16 v[98:101], v[224:227], v[178:181], v[98:101]
	v_mfma_f32_16x16x32_f16 v[86:89], v[202:205], v[186:189], v[86:89]
	v_mfma_f32_16x16x32_f16 v[82:85], v[224:227], v[186:189], v[82:85]
	v_mfma_f32_16x16x32_f16 v[70:73], v[202:205], v[194:197], v[70:73]
	v_mfma_f32_16x16x32_f16 v[66:69], v[224:227], v[194:197], v[66:69]
	s_barrier
; #define PG8_STAGE(bufoff, gbase, voff) do { _Pragma("unroll") for (int _i = 0; _i < 2; ++_i) \
;         __builtin_amdgcn_global_load_lds((const unsigned*)((const char*)(gbase) + (voff)[_i]), (LAS unsigned*)(lds + (bufoff) + ldsw + _i * 8192), 16, 0, 0); } while (0)
; template <class Epi, class AMap>
; __device__ __forceinline__ void gemm_phase(LAS unsigned char* lds, const AMap am, const int lda, const h16* Bt, const int ldb, const int M, const int N, const int K, const Epi& E) {
;     ...
;             PG8_LDB(B0, 1, 0); PG8_SCHED; PG8_LDA(At, 1, 0); PG8_STAGE(PG8_SA(0, 1), a2 + hstepA, voffA);
;             PG8_WAIT_L(8); PG8_BAR; PG8_WAIT_L(0); PG8_MMA(0, 0, At, B0); PG8_BAR; PG8_SCHED;
;             PG8_LDB(B1, 1, 1); PG8_STAGE(PG8_SB(1, 0), b3, voffB);
;             PG8_BAR; PG8_WAIT_L(0); PG8_MMA(0, 1, At, B1); PG8_BAR;
;             PG8_LDA(At, 1, 1); PG8_STAGE(PG8_SA(1, 0), a3, voffA);
;             PG8_BAR; PG8_WAIT_L(0); PG8_MMA(1, 0, At, B0); PG8_BAR; PG8_SCHED;
;             PG8_STAGE(PG8_SB(1, 1), b3 + hstepB, voffB);
;             PG8_WAIT_V(6); PG8_BAR; PG8_MMA(1, 1, At, B1); PG8_BAR;
;     __device__ __forceinline__ void operator()(const f32x4 (&acc)[2][2][4][2], const Unit& u, int wr, int wc, int fr, int fq) const {
;         const int row0 = u.pm * 256 + wr * 64 + fr; const int part = u.pn >> 3; const int colt = (u.pn & 7) * 256 + wc * 32 + 8 * fq;
; #pragma unroll
;         for (int ai = 0; ai < 2; ++ai)
; #pragma unroll
;             for (int m = 0; m < 4; ++m) { const int row = row0 + ai * 128 + m * 16;
; #pragma unroll
;                 for (int bj = 0; bj < 2; ++bj) { const int c = colt + bj * 128;
;                     if (part == 0) *(u32x4*)(Qb + (size_t)row * DM + c) = pack8(acc[ai][bj][m][0] * QSCALE, acc[ai][bj][m][1] * QSCALE);
;                     else if (part == 1) *(u32x4*)(Kb + (size_t)row * DM + c) = pack8(acc[ai][bj][m][0], acc[ai][bj][m][1]);
;                     else {
;                         const int b = row >> 13, t = row & 8191, hd = c >> 8, dv = c & 255;
;                         const int pos = (t & ~12) | ((t & 4) << 1) | ((t & 8) >> 1);
;                         h16* vp = Vt + ((size_t)((b * 8 + hd) * 256 + dv)) * SEQ + pos;
; #pragma unroll
;                         for (int j = 0; j < 4; ++j) { vp[(size_t)j * SEQ] = (h16)acc[ai][bj][m][0][j]; vp[(size_t)(4 + j) * SEQ] = (h16)acc[ai][bj][m][1][j]; }
	global_load_lds_dwordx4 v[146:147], off
	v_lshl_add_u64 v[146:147], v[206:207], 0, s[92:93]
	s_add_i32 m0, s45, 0x2000
	s_nop 0
	global_load_lds_dwordx4 v[146:147], off
	s_mov_b32 m0, s77
	v_lshl_add_u64 v[146:147], v[212:213], 0, s[92:93]
	ds_read_b128 v[166:169], v153 offset:49152
	ds_read_b128 v[170:173], v153 offset:50176
	ds_read_b128 v[174:177], v153 offset:51200
	ds_read_b128 v[178:181], v153 offset:52224
	ds_read_b128 v[182:185], v153 offset:53248
	ds_read_b128 v[186:189], v153 offset:54272
	ds_read_b128 v[190:193], v153 offset:55296
	ds_read_b128 v[194:197], v153 offset:56320
	global_load_lds_dwordx4 v[146:147], off
	v_lshl_add_u64 v[146:147], v[228:229], 0, s[92:93]
	s_mov_b32 m0, s78
	s_nop 0
	global_load_lds_dwordx4 v[146:147], off
	s_add_u32 s42, s42, 0x80080
	s_addc_u32 s43, s43, 0
	s_add_i32 s45, s48, s65
	v_lshl_add_u64 v[232:233], s[42:43], 0, v[132:133]
	s_mov_b32 m0, s45
	s_nop 0
	global_load_lds_dwordx4 v[232:233], off
	v_lshl_add_u64 v[232:233], s[42:43], 0, v[136:137]
	s_add_i32 m0, s45, 0x2000
	s_nop 0
	global_load_lds_dwordx4 v[232:233], off
	s_waitcnt vmcnt(6) lgkmcnt(0)
	s_barrier
	v_mfma_f32_16x16x32_f16 v[62:65], v[142:145], v[166:169], v[62:65]
	v_mfma_f32_16x16x32_f16 v[58:61], v[158:161], v[166:169], v[58:61]
	v_mfma_f32_16x16x32_f16 v[46:49], v[142:145], v[174:177], v[46:49]
	v_mfma_f32_16x16x32_f16 v[42:45], v[158:161], v[174:177], v[42:45]
	v_mfma_f32_16x16x32_f16 v[30:33], v[142:145], v[182:185], v[30:33]
	v_mfma_f32_16x16x32_f16 v[26:29], v[158:161], v[182:185], v[26:29]
	v_mfma_f32_16x16x32_f16 v[14:17], v[142:145], v[190:193], v[14:17]
	v_mfma_f32_16x16x32_f16 v[10:13], v[158:161], v[190:193], v[10:13]
	v_mfma_f32_16x16x32_f16 v[62:65], v[154:157], v[170:173], v[62:65]
	v_mfma_f32_16x16x32_f16 v[58:61], v[162:165], v[170:173], v[58:61]
	v_mfma_f32_16x16x32_f16 v[46:49], v[154:157], v[178:181], v[46:49]
	v_mfma_f32_16x16x32_f16 v[42:45], v[162:165], v[178:181], v[42:45]
	v_mfma_f32_16x16x32_f16 v[30:33], v[154:157], v[186:189], v[30:33]
	v_mfma_f32_16x16x32_f16 v[26:29], v[162:165], v[186:189], v[26:29]
	v_mfma_f32_16x16x32_f16 v[14:17], v[154:157], v[194:197], v[14:17]
	v_mfma_f32_16x16x32_f16 v[10:13], v[162:165], v[194:197], v[10:13]
	v_mfma_f32_16x16x32_f16 v[54:57], v[198:201], v[166:169], v[54:57]
	v_mfma_f32_16x16x32_f16 v[50:53], v[220:223], v[166:169], v[50:53]
	v_mfma_f32_16x16x32_f16 v[38:41], v[198:201], v[174:177], v[38:41]
	v_mfma_f32_16x16x32_f16 v[34:37], v[220:223], v[174:177], v[34:37]
	v_mfma_f32_16x16x32_f16 v[22:25], v[198:201], v[182:185], v[22:25]
	v_mfma_f32_16x16x32_f16 v[18:21], v[220:223], v[182:185], v[18:21]
	v_mfma_f32_16x16x32_f16 v[6:9], v[198:201], v[190:193], v[6:9]
	v_mfma_f32_16x16x32_f16 v[2:5], v[220:223], v[190:193], v[2:5]
	v_mfma_f32_16x16x32_f16 v[54:57], v[202:205], v[170:173], v[54:57]
	v_mfma_f32_16x16x32_f16 v[50:53], v[224:227], v[170:173], v[50:53]
	v_mfma_f32_16x16x32_f16 v[38:41], v[202:205], v[178:181], v[38:41]
	v_mfma_f32_16x16x32_f16 v[34:37], v[224:227], v[178:181], v[34:37]
	v_mfma_f32_16x16x32_f16 v[22:25], v[202:205], v[186:189], v[22:25]
	v_mfma_f32_16x16x32_f16 v[18:21], v[224:227], v[186:189], v[18:21]
	v_mfma_f32_16x16x32_f16 v[6:9], v[202:205], v[194:197], v[6:9]
	v_mfma_f32_16x16x32_f16 v[2:5], v[224:227], v[194:197], v[2:5]
	s_add_i32 s35, s35, 2
	s_add_u32 s40, s40, 0x100
	s_addc_u32 s41, s41, 0
	s_add_u32 s21, s21, 0x100
	s_addc_u32 s29, s29, 0
	s_cmp_gt_u32 s35, 29
	s_barrier
	s_cbranch_scc0 .LBB0_268
	s_lshl_b32 s1, s26, 8
	s_add_i32 s20, s1, s76
	s_lshl_b32 s1, s22, 8
	s_and_b32 s1, s1, 0x700
	s_cmp_gt_u32 s22, 7
	s_cselect_b64 s[26:27], -1, 0
	s_and_b32 s21, s22, -8
	v_or_b32_e32 v142, s20, v148
	s_cmp_lg_u32 s21, 8
	s_cselect_b64 s[22:23], -1, 0
	s_ashr_i32 s20, s20, 2
	v_ashrrev_i32_e32 v143, 31, v142
	v_or_b32_e32 v154, s1, v150
	s_and_b32 s35, s20, 0xfffff800
	v_and_or_b32 v155, v142, s5, v151
	v_lshlrev_b64 v[144:145], 12, v[142:143]
	s_mov_b64 s[40:41], -1
	s_and_b64 vcc, exec, s[26:27]
	s_cbranch_vccz .LBB0_275
	s_and_b64 vcc, exec, s[22:23]
	s_cbranch_vccz .LBB0_272
	v_or_b32_e32 v146, s35, v154
	v_ashrrev_i32_e32 v147, 31, v146
	v_lshlrev_b64 v[146:147], 14, v[146:147]
	v_lshl_add_u64 v[146:147], s[30:31], 0, v[146:147]
	v_lshlrev_b32_e32 v0, 1, v155
	v_lshl_add_u64 v[146:147], v[146:147], 0, v[0:1]
	v_cvt_f16_f32_e32 v0, v126
	v_add_co_u32_e32 v156, vcc, 0x10000, v146
	s_mov_b64 s[40:41], 0
	global_store_short v[146:147], v0, off
	v_cvt_f16_f32_e32 v0, v122
	v_addc_co_u32_e32 v157, vcc, 0, v147, vcc
	global_store_short v[156:157], v0, off
	v_cvt_f16_f32_e32 v0, v127
	v_add_co_u32_e32 v156, vcc, 0x4000, v146
	s_nop 1
	v_addc_co_u32_e32 v157, vcc, 0, v147, vcc
	global_store_short v[156:157], v0, off
	v_cvt_f16_f32_e32 v0, v123
	v_add_co_u32_e32 v156, vcc, 0x14000, v146
	s_nop 1
	v_addc_co_u32_e32 v157, vcc, 0, v147, vcc
	global_store_short v[156:157], v0, off
	v_cvt_f16_f32_e32 v0, v128
	v_add_co_u32_e32 v156, vcc, 0x8000, v146
	s_nop 1
	v_addc_co_u32_e32 v157, vcc, 0, v147, vcc
	global_store_short v[156:157], v0, off
	v_cvt_f16_f32_e32 v0, v124
	v_add_co_u32_e32 v156, vcc, 0x18000, v146
	s_nop 1
	v_addc_co_u32_e32 v157, vcc, 0, v147, vcc
	global_store_short v[156:157], v0, off
	v_cvt_f16_f32_e32 v0, v129
	v_add_co_u32_e32 v156, vcc, 0xc000, v146
	s_nop 1
	v_addc_co_u32_e32 v157, vcc, 0, v147, vcc
	global_store_short v[156:157], v0, off
	v_cvt_f16_f32_e32 v0, v125
	v_add_co_u32_e32 v146, vcc, 0x1c000, v146
	s_nop 1
	v_addc_co_u32_e32 v147, vcc, 0, v147, vcc
	global_store_short v[146:147], v0, off

; __device__ __forceinline__ int otid() { int t = (int)threadIdx.x; asm volatile("" : "+v"(t)); return t; }
; __device__ __forceinline__ int obid() { int t = (int)blockIdx.x; asm volatile("" : "+s"(t)); return t; }
; #define PG8_STAGE(bufoff, gbase, voff) do { _Pragma("unroll") for (int _i = 0; _i < 2; ++_i) \
;         __builtin_amdgcn_global_load_lds((const unsigned*)((const char*)(gbase) + (voff)[_i]), (LAS unsigned*)(lds + (bufoff) + ldsw + _i * 8192), 16, 0, 0); } while (0)
; #define PG8_WAIT_V(n) asm volatile("s_waitcnt vmcnt(" #n ")" ::: "memory")
; #define PG8_BAR __builtin_amdgcn_s_barrier()
; template <class Epi, class AMap>
; __device__ __forceinline__ void gemm_phase(LAS unsigned char* lds, const AMap am, const int lda, const h16* Bt, const int ldb, const int M, const int N, const int K, const Epi& E) {
;     const int tid = otid(), wid = __builtin_amdgcn_readfirstlane(tid >> 6), lane = tid & 63, wr = wid >> 2, wc = wid & 3, fr = lane & 15, fq = lane >> 4;
;     const int nt = K / BK;
;     Order S; S.init(M, N, (int)gridDim.x, obid());
;     unsigned voffA[2], voffB[2];
; #pragma unroll
;     for (int i = 0; i < 2; ++i) { int R, C; stage_rc(tid * 16 + i * 8192, R, C); const int Rb = Epi::PERM ? ((R & ~31) + perm32(R & 31)) : R;
;         voffA[i] = (unsigned)(R * lda + C) * 2u; voffB[i] = (unsigned)(Rb * ldb + C) * 2u; }
;     const size_t kstep = (size_t)(BK * 2);
;     const size_t hstepA = (size_t)HALF * lda * 2, hstepB = (size_t)HALF * ldb * 2;
;     const size_t tstepA = 2 * hstepA, tstepB = 2 * hstepB;
;     const unsigned ldsw = (unsigned)wid * 1024u;
;     const int aoff = lds_byte(wr * 64 + fr, fq * 8), boff = lds_byte(wc * 32 + fr, fq * 8);
;     ...
;     const char* cA = am(cur.pn) + (size_t)cur.pm * tstepA; const char* cB = (const char*)Bt + (size_t)cur.pn * tstepB;
;     PG8_STAGE(PG8_SB(0, 0), cB, voffB); PG8_STAGE(PG8_SA(0, 0), cA, voffA); PG8_STAGE(PG8_SB(0, 1), cB + hstepB, voffB); PG8_STAGE(PG8_SA(0, 1), cA + hstepA, voffA);
;     if (wr == 1) PG8_BAR;
;     PG8_WAIT_V(4); PG8_BAR;
;     PG8_STAGE(PG8_SB(1, 0), cB + kstep, voffB); PG8_STAGE(PG8_SA(1, 0), cA + kstep, voffA); PG8_STAGE(PG8_SB(1, 1), cB + hstepB + kstep, voffB);
;     PG8_WAIT_V(6); PG8_BAR;
.LBB0_609:
	v_lshrrev_b32_e32 v20, 1, v18
	v_and_b32_e32 v20, 24, v20
	v_and_b32_e32 v19, 15, v18
	v_lshlrev_b32_e32 v21, 1, v20
	v_lshlrev_b32_e32 v18, 2, v18
	s_sext_i32_i8 s50, s0
	v_lshl_or_b32 v154, s20, 6, v19
	v_lshl_or_b32 v19, v19, 6, v21
	s_lshl_b32 s0, s20, 13
	v_and_b32_e32 v18, 32, v18
	v_bitop3_b32 v21, v19, s0, v18 bitop3:0xde
	s_lshl_b32 s0, s1, 5
	s_and_b32 s20, s0, 0x60
	s_lshl_b32 s0, s20, 7
	v_bitop3_b32 v155, v19, s0, v18 bitop3:0xde
	v_readlane_b32 s0, v254, 38
	v_readlane_b32 s10, v254, 48
	v_readlane_b32 s11, v254, 49
	s_add_u32 s40, s10, s46
	s_addc_u32 s41, s11, s47
	s_add_i32 m0, s76, 0x18000
	v_lshl_add_u64 v[8:9], v[8:9], 0, s[92:93]
	s_waitcnt vmcnt(0)
	s_barrier
	global_load_lds_dwordx4 v[8:9], off
	v_lshl_add_u64 v[6:7], v[6:7], 0, s[92:93]
	s_add_i32 m0, s76, 0x1a000
	s_add_i32 s80, s76, 0x8000
	s_add_i32 s81, s76, 0xa000
	v_readlane_b32 s1, v254, 39
	global_load_lds_dwordx4 v[6:7], off
	v_lshl_add_u64 v[4:5], v[4:5], 0, s[92:93]
	s_mov_b32 m0, s80
	s_add_u32 s0, s26, 0x10080
	global_load_lds_dwordx4 v[4:5], off
	v_lshl_add_u64 v[2:3], v[2:3], 0, s[92:93]
	s_mov_b32 m0, s81
	s_addc_u32 s1, s27, 0
	global_load_lds_dwordx4 v[2:3], off
	s_add_i32 m0, s76, 0x1c000
	v_lshl_add_u64 v[2:3], s[0:1], 0, v[0:1]
	global_load_lds_dwordx4 v[2:3], off
	v_lshl_add_u64 v[2:3], s[0:1], 0, v[142:143]
	s_add_i32 m0, s76, 0x1e000
	v_readlane_b32 s3, v254, 41
	global_load_lds_dwordx4 v[2:3], off
	v_readlane_b32 s2, v254, 40
	s_movk_i32 s3, 0x1c00
	v_lshrrev_b32_e32 v3, 1, v10
	v_mul_lo_u32 v2, v12, s3
	s_mov_b32 s2, 0x1c000
	v_mad_u64_u32 v[2:3], s[0:1], v3, s2, v[2:3]
	v_readlane_b32 s4, v254, 42
	v_readlane_b32 s5, v254, 43
	v_or_b32_e32 v2, v2, v11
	v_add_lshl_u32 v2, v2, v13, 1
	v_mov_b32_e32 v3, v1
	s_mov_b64 s[4:5], 0x1c0080
	v_lshl_add_u64 v[144:145], v[2:3], 0, s[4:5]
	v_lshrrev_b32_e32 v3, 1, v14
	v_mul_lo_u32 v2, v16, s3
	v_mad_u64_u32 v[2:3], s[0:1], v3, s2, v[2:3]
	v_readlane_b32 s8, v254, 46
	v_readlane_b32 s9, v254, 47
	s_waitcnt vmcnt(6)
	v_or_b32_e32 v2, v2, v15
	v_readlane_b32 s12, v254, 50
	v_readlane_b32 s13, v254, 51
	v_readlane_b32 s14, v254, 52
	v_readlane_b32 s15, v254, 53
	s_cmp_gt_i32 s61, 63
	v_add_lshl_u32 v2, v2, v17, 1
	v_mov_b32_e32 v3, v1
	v_readlane_b32 s8, v254, 58
	s_cselect_b64 s[42:43], -1, 0
	s_add_i32 s82, s24, -2
	v_or_b32_e32 v156, s20, v20
	v_lshl_add_u64 v[146:147], v[2:3], 0, s[4:5]
	s_mov_b32 s83, 0
	v_add_u32_e32 v157, 0, v21
	v_readlane_b32 s9, v254, 59
	v_readlane_b32 s12, v254, 62
	v_readlane_b32 s2, v252, 33
	s_movk_i32 s5, 0x3800
	s_movk_i32 s13, 0x2b00
	s_mov_b64 s[10:11], 0x80000
	s_mov_b64 s[14:15], 0xa0000
	v_readlane_b32 s6, v254, 44
	v_readlane_b32 s7, v254, 45
	s_barrier
	s_branch .LBB0_611

; #define PG8_STAGE(bufoff, gbase, voff) do { _Pragma("unroll") for (int _i = 0; _i < 2; ++_i) \
;         __builtin_amdgcn_global_load_lds((const unsigned*)((const char*)(gbase) + (voff)[_i]), (LAS unsigned*)(lds + (bufoff) + ldsw + _i * 8192), 16, 0, 0); } while (0)
; #define PG8_LDA(dst, b, h) do { _Pragma("unroll") for (int m = 0; m < 4; ++m) _Pragma("unroll") for (int k = 0; k < 2; ++k) dst[m][k] = *(const LAS h16x8*)(lds + PG8_SA(b, h) + aoff + m * 2048 + k * 1024); } while (0)
; #define PG8_LDB(dst, b, h) do { _Pragma("unroll") for (int n = 0; n < 2; ++n) _Pragma("unroll") for (int k = 0; k < 2; ++k) dst[n][k] = *(const LAS h16x8*)(lds + PG8_SB(b, h) + boff + n * 2048 + k * 1024); } while (0)
; #define PG8_MMA(ai, bj, At, Bt_) do { __builtin_amdgcn_s_setprio(1); _Pragma("unroll") for (int m = 0; m < 4; ++m) _Pragma("unroll") for (int n = 0; n < 2; ++n) _Pragma("unroll") for (int k = 0; k < 2; ++k) \
;         acc[ai][bj][m][n] = __builtin_amdgcn_mfma_f32_16x16x32_f16(Bt_[n][k], At[m][k], acc[ai][bj][m][n], 0, 0, 0); __builtin_amdgcn_s_setprio(0); } while (0)
; #define PG8_WAIT_L(n) asm volatile("s_waitcnt lgkmcnt(" #n ")" ::: "memory")
; #define PG8_BAR __builtin_amdgcn_s_barrier()
; #define PG8_SCHED __builtin_amdgcn_sched_barrier(0)
; template <class Epi, class AMap>
; __device__ __forceinline__ void gemm_phase(LAS unsigned char* lds, const AMap am, const int lda, const h16* Bt, const int ldb, const int M, const int N, const int K, const Epi& E) {
;     ...
;             PG8_LDB(B0, 0, 0); PG8_SCHED; PG8_LDA(At, 0, 0); PG8_STAGE(PG8_SA(1, 1), a1 + hstepA, voffA);
;             PG8_WAIT_L(8); PG8_BAR; PG8_WAIT_L(0); PG8_MMA(0, 0, At, B0); PG8_BAR; PG8_SCHED;
;             PG8_LDB(B1, 0, 1); PG8_STAGE(PG8_SB(0, 0), b2, voffB);
;             PG8_BAR; PG8_WAIT_L(0); PG8_MMA(0, 1, At, B1); PG8_BAR;
;             PG8_LDA(At, 0, 1); PG8_STAGE(PG8_SA(0, 0), a2, voffA);
;             PG8_BAR; PG8_WAIT_L(0); PG8_MMA(1, 0, At, B0); PG8_BAR; PG8_SCHED;
.LBB0_621:
	s_add_i32 s51, s26, 2
	s_add_u32 s0, s22, 0x100
	s_addc_u32 s1, s23, 0
	s_add_i32 s60, 0, 0x10000
	v_add_u32_e32 v152, s60, v155
	ds_read_b128 v[90:93], v152
	ds_read_b128 v[94:97], v152 offset:1024
	ds_read_b128 v[148:151], v152 offset:2048
	ds_read_b128 v[158:161], v152 offset:3072
	s_cmp_eq_u32 s82, s26
	s_cselect_b32 s26, s21, s29
	s_cselect_b32 s49, s65, s1
	s_cselect_b32 s48, s64, s0
	s_cselect_b32 s27, s20, s45
	v_lshl_add_u64 v[152:153], s[22:23], 0, v[144:145]
	s_add_i32 m0, s76, 0xc000
	ds_read_b128 v[162:165], v157
	ds_read_b128 v[166:169], v157 offset:1024
	ds_read_b128 v[170:173], v157 offset:2048
	ds_read_b128 v[174:177], v157 offset:3072
	ds_read_b128 v[178:181], v157 offset:4096
	ds_read_b128 v[182:185], v157 offset:5120
	ds_read_b128 v[186:189], v157 offset:6144
	ds_read_b128 v[190:193], v157 offset:7168
	global_load_lds_dwordx4 v[152:153], off
	v_lshl_add_u64 v[152:153], s[22:23], 0, v[146:147]
	s_add_i32 m0, s76, 0xe000
	s_nop 0
	global_load_lds_dwordx4 v[152:153], off
	s_waitcnt lgkmcnt(11)
	s_add_i32 s62, 0, 0x14000
	v_add_u32_e32 v152, s62, v155
	s_add_i32 s22, s60, s73
	ds_read_b128 v[194:197], v152
	ds_read_b128 v[198:201], v152 offset:1024
	ds_read_b128 v[202:205], v152 offset:2048
	ds_read_b128 v[220:223], v152 offset:3072
	s_waitcnt lgkmcnt(0)
	s_barrier
	v_mfma_f32_16x16x32_f16 v[130:133], v[90:93], v[162:165], v[130:133]
	v_mfma_f32_16x16x32_f16 v[134:137], v[148:151], v[162:165], v[134:137]
	v_mfma_f32_16x16x32_f16 v[126:129], v[90:93], v[170:173], v[126:129]
	v_mfma_f32_16x16x32_f16 v[122:125], v[148:151], v[170:173], v[122:125]
	v_mfma_f32_16x16x32_f16 v[118:121], v[90:93], v[178:181], v[118:121]
	v_mfma_f32_16x16x32_f16 v[114:117], v[148:151], v[178:181], v[114:117]
	v_mfma_f32_16x16x32_f16 v[110:113], v[90:93], v[186:189], v[110:113]
	v_mfma_f32_16x16x32_f16 v[106:109], v[148:151], v[186:189], v[106:109]
	v_mfma_f32_16x16x32_f16 v[130:133], v[94:97], v[166:169], v[130:133]
	v_mfma_f32_16x16x32_f16 v[134:137], v[158:161], v[166:169], v[134:137]
	v_mfma_f32_16x16x32_f16 v[126:129], v[94:97], v[174:177], v[126:129]
	v_mfma_f32_16x16x32_f16 v[122:125], v[158:161], v[174:177], v[122:125]
	v_mfma_f32_16x16x32_f16 v[118:121], v[94:97], v[182:185], v[118:121]
	v_mfma_f32_16x16x32_f16 v[114:117], v[158:161], v[182:185], v[114:117]
	v_mfma_f32_16x16x32_f16 v[110:113], v[94:97], v[190:193], v[110:113]
	v_mfma_f32_16x16x32_f16 v[106:109], v[158:161], v[190:193], v[106:109]
	v_mfma_f32_16x16x32_f16 v[62:65], v[194:197], v[162:165], v[62:65]
	v_mfma_f32_16x16x32_f16 v[58:61], v[202:205], v[162:165], v[58:61]
	v_mfma_f32_16x16x32_f16 v[54:57], v[194:197], v[170:173], v[54:57]
	v_mfma_f32_16x16x32_f16 v[50:53], v[202:205], v[170:173], v[50:53]
	v_mfma_f32_16x16x32_f16 v[46:49], v[194:197], v[178:181], v[46:49]
	v_mfma_f32_16x16x32_f16 v[42:45], v[202:205], v[178:181], v[42:45]
	v_mfma_f32_16x16x32_f16 v[38:41], v[194:197], v[186:189], v[38:41]
	v_mfma_f32_16x16x32_f16 v[34:37], v[202:205], v[186:189], v[34:37]
	v_mfma_f32_16x16x32_f16 v[62:65], v[198:201], v[166:169], v[62:65]
	v_mfma_f32_16x16x32_f16 v[58:61], v[220:223], v[166:169], v[58:61]
	v_mfma_f32_16x16x32_f16 v[54:57], v[198:201], v[174:177], v[54:57]
	v_mfma_f32_16x16x32_f16 v[50:53], v[220:223], v[174:177], v[50:53]
	v_mfma_f32_16x16x32_f16 v[46:49], v[198:201], v[182:185], v[46:49]
	v_mfma_f32_16x16x32_f16 v[42:45], v[220:223], v[182:185], v[42:45]
	v_mfma_f32_16x16x32_f16 v[38:41], v[198:201], v[190:193], v[38:41]
	v_mfma_f32_16x16x32_f16 v[34:37], v[220:223], v[190:193], v[34:37]
	s_barrier
	v_lshl_add_u64 v[152:153], s[26:27], 0, v[0:1]
	s_mov_b32 m0, s22
	v_lshl_add_u64 v[206:207], s[26:27], 0, v[142:143]
	global_load_lds_dwordx4 v[152:153], off
	s_add_i32 m0, s22, 0x2000
	s_nop 0
	global_load_lds_dwordx4 v[206:207], off
	s_mov_b32 m0, s76
	v_lshl_add_u64 v[212:213], s[48:49], 0, v[138:139]
	ds_read_b128 v[162:165], v157 offset:16384
	ds_read_b128 v[166:169], v157 offset:17408
	ds_read_b128 v[170:173], v157 offset:18432
	ds_read_b128 v[174:177], v157 offset:19456
	ds_read_b128 v[178:181], v157 offset:20480
	ds_read_b128 v[182:185], v157 offset:21504
	ds_read_b128 v[186:189], v157 offset:22528
	ds_read_b128 v[190:193], v157 offset:23552
	global_load_lds_dwordx4 v[212:213], off
	v_lshl_add_u64 v[224:225], s[48:49], 0, v[140:141]
	s_mov_b32 m0, s77
	s_nop 0
	global_load_lds_dwordx4 v[224:225], off
	s_add_u32 s22, s26, 0x10000
	s_addc_u32 s23, s27, 0
	s_add_i32 s60, s62, s73
	v_lshl_add_u64 v[232:233], s[22:23], 0, v[0:1]
	s_mov_b32 m0, s60
	s_nop 0
	global_load_lds_dwordx4 v[232:233], off
	v_lshl_add_u64 v[232:233], s[22:23], 0, v[142:143]
	s_add_i32 m0, s60, 0x2000
	s_nop 0
	global_load_lds_dwordx4 v[232:233], off
	s_waitcnt vmcnt(6) lgkmcnt(0)
	s_barrier
; #define PG8_STAGE(bufoff, gbase, voff) do { _Pragma("unroll") for (int _i = 0; _i < 2; ++_i) \
;         __builtin_amdgcn_global_load_lds((const unsigned*)((const char*)(gbase) + (voff)[_i]), (LAS unsigned*)(lds + (bufoff) + ldsw + _i * 8192), 16, 0, 0); } while (0)
; #define PG8_LDA(dst, b, h) do { _Pragma("unroll") for (int m = 0; m < 4; ++m) _Pragma("unroll") for (int k = 0; k < 2; ++k) dst[m][k] = *(const LAS h16x8*)(lds + PG8_SA(b, h) + aoff + m * 2048 + k * 1024); } while (0)
; #define PG8_LDB(dst, b, h) do { _Pragma("unroll") for (int n = 0; n < 2; ++n) _Pragma("unroll") for (int k = 0; k < 2; ++k) dst[n][k] = *(const LAS h16x8*)(lds + PG8_SB(b, h) + boff + n * 2048 + k * 1024); } while (0)
; #define PG8_MMA(ai, bj, At, Bt_) do { __builtin_amdgcn_s_setprio(1); _Pragma("unroll") for (int m = 0; m < 4; ++m) _Pragma("unroll") for (int n = 0; n < 2; ++n) _Pragma("unroll") for (int k = 0; k < 2; ++k) \
;         acc[ai][bj][m][n] = __builtin_amdgcn_mfma_f32_16x16x32_f16(Bt_[n][k], At[m][k], acc[ai][bj][m][n], 0, 0, 0); __builtin_amdgcn_s_setprio(0); } while (0)
; #define PG8_WAIT_V(n) asm volatile("s_waitcnt vmcnt(" #n ")" ::: "memory")
; #define PG8_WAIT_L(n) asm volatile("s_waitcnt lgkmcnt(" #n ")" ::: "memory")
; #define PG8_BAR __builtin_amdgcn_s_barrier()
; #define PG8_SCHED __builtin_amdgcn_sched_barrier(0)
; template <class Epi, class AMap>
; __device__ __forceinline__ void gemm_phase(LAS unsigned char* lds, const AMap am, const int lda, const h16* Bt, const int ldb, const int M, const int N, const int K, const Epi& E) {
;     ...
;             PG8_BAR; PG8_WAIT_L(0); PG8_MMA(1, 0, At, B0); PG8_BAR; PG8_SCHED;
;             PG8_STAGE(PG8_SB(0, 1), b2 + hstepB, voffB);
;             PG8_WAIT_V(6); PG8_BAR; PG8_MMA(1, 1, At, B1); PG8_BAR;
;             PG8_LDB(B0, 1, 0); PG8_SCHED; PG8_LDA(At, 1, 0); PG8_STAGE(PG8_SA(0, 1), a2 + hstepA, voffA);
;             PG8_WAIT_L(8); PG8_BAR; PG8_WAIT_L(0); PG8_MMA(0, 0, At, B0); PG8_BAR; PG8_SCHED;
;             PG8_LDB(B1, 1, 1); PG8_STAGE(PG8_SB(1, 0), b3, voffB);
;             PG8_BAR; PG8_WAIT_L(0); PG8_MMA(0, 1, At, B1); PG8_BAR;
	v_mfma_f32_16x16x32_f16 v[102:105], v[90:93], v[162:165], v[102:105]
	v_mfma_f32_16x16x32_f16 v[98:101], v[148:151], v[162:165], v[98:101]
	v_mfma_f32_16x16x32_f16 v[86:89], v[90:93], v[170:173], v[86:89]
	v_mfma_f32_16x16x32_f16 v[82:85], v[148:151], v[170:173], v[82:85]
	v_mfma_f32_16x16x32_f16 v[78:81], v[90:93], v[178:181], v[78:81]
	v_mfma_f32_16x16x32_f16 v[74:77], v[148:151], v[178:181], v[74:77]
	v_mfma_f32_16x16x32_f16 v[70:73], v[90:93], v[186:189], v[70:73]
	v_mfma_f32_16x16x32_f16 v[66:69], v[148:151], v[186:189], v[66:69]
	v_mfma_f32_16x16x32_f16 v[102:105], v[94:97], v[166:169], v[102:105]
	v_mfma_f32_16x16x32_f16 v[98:101], v[158:161], v[166:169], v[98:101]
	v_mfma_f32_16x16x32_f16 v[86:89], v[94:97], v[174:177], v[86:89]
	v_mfma_f32_16x16x32_f16 v[82:85], v[158:161], v[174:177], v[82:85]
	v_mfma_f32_16x16x32_f16 v[78:81], v[94:97], v[182:185], v[78:81]
	v_mfma_f32_16x16x32_f16 v[74:77], v[158:161], v[182:185], v[74:77]
	v_mfma_f32_16x16x32_f16 v[70:73], v[94:97], v[190:193], v[70:73]
	v_mfma_f32_16x16x32_f16 v[66:69], v[158:161], v[190:193], v[66:69]
	v_mfma_f32_16x16x32_f16 v[30:33], v[194:197], v[162:165], v[30:33]
	v_mfma_f32_16x16x32_f16 v[26:29], v[202:205], v[162:165], v[26:29]
	v_mfma_f32_16x16x32_f16 v[22:25], v[194:197], v[170:173], v[22:25]
	v_mfma_f32_16x16x32_f16 v[18:21], v[202:205], v[170:173], v[18:21]
	v_mfma_f32_16x16x32_f16 v[14:17], v[194:197], v[178:181], v[14:17]
	v_mfma_f32_16x16x32_f16 v[10:13], v[202:205], v[178:181], v[10:13]
	v_mfma_f32_16x16x32_f16 v[6:9], v[194:197], v[186:189], v[6:9]
	v_mfma_f32_16x16x32_f16 v[2:5], v[202:205], v[186:189], v[2:5]
	v_mfma_f32_16x16x32_f16 v[30:33], v[198:201], v[166:169], v[30:33]
	v_mfma_f32_16x16x32_f16 v[26:29], v[220:223], v[166:169], v[26:29]
	v_mfma_f32_16x16x32_f16 v[22:25], v[198:201], v[174:177], v[22:25]
	v_mfma_f32_16x16x32_f16 v[18:21], v[220:223], v[174:177], v[18:21]
	v_mfma_f32_16x16x32_f16 v[14:17], v[198:201], v[182:185], v[14:17]
	v_mfma_f32_16x16x32_f16 v[10:13], v[220:223], v[182:185], v[10:13]
	v_mfma_f32_16x16x32_f16 v[6:9], v[198:201], v[190:193], v[6:9]
	v_mfma_f32_16x16x32_f16 v[2:5], v[220:223], v[190:193], v[2:5]
	s_barrier
	s_add_i32 s60, 0, 0x18000
	v_add_u32_e32 v234, s60, v155
	ds_read_b128 v[90:93], v234
	ds_read_b128 v[94:97], v234 offset:1024
	ds_read_b128 v[148:151], v234 offset:2048
	ds_read_b128 v[158:161], v234 offset:3072
	s_add_u32 s22, s48, 0x1c0000
	s_addc_u32 s23, s49, 0
	s_mov_b32 m0, s78
	v_lshl_add_u64 v[232:233], s[22:23], 0, v[138:139]
	ds_read_b128 v[162:165], v157 offset:32768
	ds_read_b128 v[166:169], v157 offset:33792
	ds_read_b128 v[170:173], v157 offset:34816
	ds_read_b128 v[174:177], v157 offset:35840
	ds_read_b128 v[178:181], v157 offset:36864
	ds_read_b128 v[182:185], v157 offset:37888
	ds_read_b128 v[186:189], v157 offset:38912
	ds_read_b128 v[190:193], v157 offset:39936
	global_load_lds_dwordx4 v[232:233], off
	v_lshl_add_u64 v[232:233], s[22:23], 0, v[140:141]
	s_mov_b32 m0, s79
	s_nop 0
	global_load_lds_dwordx4 v[232:233], off
	s_waitcnt lgkmcnt(11)
	s_add_i32 s48, 0, 0x1c000
	s_add_i32 s22, s60, s73
	v_add_u32_e32 v214, s48, v155
	v_lshl_add_u64 v[152:153], v[152:153], 0, s[92:93]
	s_mov_b32 m0, s22
	ds_read_b128 v[194:197], v214
	ds_read_b128 v[198:201], v214 offset:1024
	ds_read_b128 v[202:205], v214 offset:2048
	ds_read_b128 v[220:223], v214 offset:3072
	s_waitcnt lgkmcnt(0)
	s_barrier
	v_mfma_f32_16x16x32_f16 v[130:133], v[90:93], v[162:165], v[130:133]
	v_mfma_f32_16x16x32_f16 v[134:137], v[148:151], v[162:165], v[134:137]
	v_mfma_f32_16x16x32_f16 v[126:129], v[90:93], v[170:173], v[126:129]
	v_mfma_f32_16x16x32_f16 v[122:125], v[148:151], v[170:173], v[122:125]
	v_mfma_f32_16x16x32_f16 v[118:121], v[90:93], v[178:181], v[118:121]
	v_mfma_f32_16x16x32_f16 v[114:117], v[148:151], v[178:181], v[114:117]
	v_mfma_f32_16x16x32_f16 v[110:113], v[90:93], v[186:189], v[110:113]
	v_mfma_f32_16x16x32_f16 v[106:109], v[148:151], v[186:189], v[106:109]
	v_mfma_f32_16x16x32_f16 v[130:133], v[94:97], v[166:169], v[130:133]
	v_mfma_f32_16x16x32_f16 v[134:137], v[158:161], v[166:169], v[134:137]
	v_mfma_f32_16x16x32_f16 v[126:129], v[94:97], v[174:177], v[126:129]
	v_mfma_f32_16x16x32_f16 v[122:125], v[158:161], v[174:177], v[122:125]
	v_mfma_f32_16x16x32_f16 v[118:121], v[94:97], v[182:185], v[118:121]
	v_mfma_f32_16x16x32_f16 v[114:117], v[158:161], v[182:185], v[114:117]
	v_mfma_f32_16x16x32_f16 v[110:113], v[94:97], v[190:193], v[110:113]
	v_mfma_f32_16x16x32_f16 v[106:109], v[158:161], v[190:193], v[106:109]
	v_mfma_f32_16x16x32_f16 v[62:65], v[194:197], v[162:165], v[62:65]
	v_mfma_f32_16x16x32_f16 v[58:61], v[202:205], v[162:165], v[58:61]
	v_mfma_f32_16x16x32_f16 v[54:57], v[194:197], v[170:173], v[54:57]
	v_mfma_f32_16x16x32_f16 v[50:53], v[202:205], v[170:173], v[50:53]
	v_mfma_f32_16x16x32_f16 v[46:49], v[194:197], v[178:181], v[46:49]
	v_mfma_f32_16x16x32_f16 v[42:45], v[202:205], v[178:181], v[42:45]
	v_mfma_f32_16x16x32_f16 v[38:41], v[194:197], v[186:189], v[38:41]
	v_mfma_f32_16x16x32_f16 v[34:37], v[202:205], v[186:189], v[34:37]
	v_mfma_f32_16x16x32_f16 v[62:65], v[198:201], v[166:169], v[62:65]
	v_mfma_f32_16x16x32_f16 v[58:61], v[220:223], v[166:169], v[58:61]
	v_mfma_f32_16x16x32_f16 v[54:57], v[198:201], v[174:177], v[54:57]
	v_mfma_f32_16x16x32_f16 v[50:53], v[220:223], v[174:177], v[50:53]
	v_mfma_f32_16x16x32_f16 v[46:49], v[198:201], v[182:185], v[46:49]
	v_mfma_f32_16x16x32_f16 v[42:45], v[220:223], v[182:185], v[42:45]
	v_mfma_f32_16x16x32_f16 v[38:41], v[198:201], v[190:193], v[38:41]
	v_mfma_f32_16x16x32_f16 v[34:37], v[220:223], v[190:193], v[34:37]
	s_barrier
; #define PG8_STAGE(bufoff, gbase, voff) do { _Pragma("unroll") for (int _i = 0; _i < 2; ++_i) \
;         __builtin_amdgcn_global_load_lds((const unsigned*)((const char*)(gbase) + (voff)[_i]), (LAS unsigned*)(lds + (bufoff) + ldsw + _i * 8192), 16, 0, 0); } while (0)
; #define PG8_LDA(dst, b, h) do { _Pragma("unroll") for (int m = 0; m < 4; ++m) _Pragma("unroll") for (int k = 0; k < 2; ++k) dst[m][k] = *(const LAS h16x8*)(lds + PG8_SA(b, h) + aoff + m * 2048 + k * 1024); } while (0)
; #define PG8_LDB(dst, b, h) do { _Pragma("unroll") for (int n = 0; n < 2; ++n) _Pragma("unroll") for (int k = 0; k < 2; ++k) dst[n][k] = *(const LAS h16x8*)(lds + PG8_SB(b, h) + boff + n * 2048 + k * 1024); } while (0)
; #define PG8_MMA(ai, bj, At, Bt_) do { __builtin_amdgcn_s_setprio(1); _Pragma("unroll") for (int m = 0; m < 4; ++m) _Pragma("unroll") for (int n = 0; n < 2; ++n) _Pragma("unroll") for (int k = 0; k < 2; ++k) \
;         acc[ai][bj][m][n] = __builtin_amdgcn_mfma_f32_16x16x32_f16(Bt_[n][k], At[m][k], acc[ai][bj][m][n], 0, 0, 0); __builtin_amdgcn_s_setprio(0); } while (0)
; #define PG8_WAIT_V(n) asm volatile("s_waitcnt vmcnt(" #n ")" ::: "memory")
; #define PG8_WAIT_L(n) asm volatile("s_waitcnt lgkmcnt(" #n ")" ::: "memory")
; #define PG8_BAR __builtin_amdgcn_s_barrier()
; #define PG8_SCHED __builtin_amdgcn_sched_barrier(0)
; template <class Epi, class AMap>
; __device__ __forceinline__ void gemm_phase(LAS unsigned char* lds, const AMap am, const int lda, const h16* Bt, const int ldb, const int M, const int N, const int K, const Epi& E) {
;     ...
;             PG8_LDB(B0, 1, 0); PG8_SCHED; PG8_LDA(At, 1, 0); PG8_STAGE(PG8_SA(0, 1), a2 + hstepA, voffA);
;             PG8_WAIT_L(8); PG8_BAR; PG8_WAIT_L(0); PG8_MMA(0, 0, At, B0); PG8_BAR; PG8_SCHED;
;             PG8_LDB(B1, 1, 1); PG8_STAGE(PG8_SB(1, 0), b3, voffB);
;             PG8_BAR; PG8_WAIT_L(0); PG8_MMA(0, 1, At, B1); PG8_BAR;
;             PG8_LDA(At, 1, 1); PG8_STAGE(PG8_SA(1, 0), a3, voffA);
;             PG8_BAR; PG8_WAIT_L(0); PG8_MMA(1, 0, At, B0); PG8_BAR; PG8_SCHED;
;             PG8_STAGE(PG8_SB(1, 1), b3 + hstepB, voffB);
;             PG8_WAIT_V(6); PG8_BAR; PG8_MMA(1, 1, At, B1); PG8_BAR;
	global_load_lds_dwordx4 v[152:153], off
	v_lshl_add_u64 v[152:153], v[206:207], 0, s[92:93]
	s_add_i32 m0, s22, 0x2000
	s_nop 0
	global_load_lds_dwordx4 v[152:153], off
	s_mov_b32 m0, s80
	v_lshl_add_u64 v[152:153], v[212:213], 0, s[92:93]
	ds_read_b128 v[162:165], v157 offset:49152
	ds_read_b128 v[166:169], v157 offset:50176
	ds_read_b128 v[170:173], v157 offset:51200
	ds_read_b128 v[174:177], v157 offset:52224
	ds_read_b128 v[178:181], v157 offset:53248
	ds_read_b128 v[182:185], v157 offset:54272
	ds_read_b128 v[186:189], v157 offset:55296
	ds_read_b128 v[190:193], v157 offset:56320
	global_load_lds_dwordx4 v[152:153], off
	v_lshl_add_u64 v[152:153], v[224:225], 0, s[92:93]
	s_mov_b32 m0, s81
	s_nop 0
	global_load_lds_dwordx4 v[152:153], off
	s_add_u32 s22, s26, 0x10080
	s_addc_u32 s23, s27, 0
	s_add_i32 s26, s48, s73
	v_lshl_add_u64 v[232:233], s[22:23], 0, v[0:1]
	s_mov_b32 m0, s26
	s_nop 0
	global_load_lds_dwordx4 v[232:233], off
	v_lshl_add_u64 v[232:233], s[22:23], 0, v[142:143]
	s_add_i32 m0, s26, 0x2000
	s_nop 0
	global_load_lds_dwordx4 v[232:233], off
	s_waitcnt vmcnt(6) lgkmcnt(0)
	s_barrier
	v_mfma_f32_16x16x32_f16 v[102:105], v[90:93], v[162:165], v[102:105]
	v_mfma_f32_16x16x32_f16 v[98:101], v[148:151], v[162:165], v[98:101]
	v_mfma_f32_16x16x32_f16 v[86:89], v[90:93], v[170:173], v[86:89]
	v_mfma_f32_16x16x32_f16 v[82:85], v[148:151], v[170:173], v[82:85]
	v_mfma_f32_16x16x32_f16 v[78:81], v[90:93], v[178:181], v[78:81]
	v_mfma_f32_16x16x32_f16 v[74:77], v[148:151], v[178:181], v[74:77]
	v_mfma_f32_16x16x32_f16 v[70:73], v[90:93], v[186:189], v[70:73]
	v_mfma_f32_16x16x32_f16 v[66:69], v[148:151], v[186:189], v[66:69]
	v_mfma_f32_16x16x32_f16 v[102:105], v[94:97], v[166:169], v[102:105]
	v_mfma_f32_16x16x32_f16 v[98:101], v[158:161], v[166:169], v[98:101]
	v_mfma_f32_16x16x32_f16 v[86:89], v[94:97], v[174:177], v[86:89]
	v_mfma_f32_16x16x32_f16 v[82:85], v[158:161], v[174:177], v[82:85]
	v_mfma_f32_16x16x32_f16 v[78:81], v[94:97], v[182:185], v[78:81]
	v_mfma_f32_16x16x32_f16 v[74:77], v[158:161], v[182:185], v[74:77]
	v_mfma_f32_16x16x32_f16 v[70:73], v[94:97], v[190:193], v[70:73]
	v_mfma_f32_16x16x32_f16 v[66:69], v[158:161], v[190:193], v[66:69]
	v_mfma_f32_16x16x32_f16 v[30:33], v[194:197], v[162:165], v[30:33]
	v_mfma_f32_16x16x32_f16 v[26:29], v[202:205], v[162:165], v[26:29]
	v_mfma_f32_16x16x32_f16 v[22:25], v[194:197], v[170:173], v[22:25]
	v_mfma_f32_16x16x32_f16 v[18:21], v[202:205], v[170:173], v[18:21]
	v_mfma_f32_16x16x32_f16 v[14:17], v[194:197], v[178:181], v[14:17]
	v_mfma_f32_16x16x32_f16 v[10:13], v[202:205], v[178:181], v[10:13]
	v_mfma_f32_16x16x32_f16 v[6:9], v[194:197], v[186:189], v[6:9]
	v_mfma_f32_16x16x32_f16 v[2:5], v[202:205], v[186:189], v[2:5]
	v_mfma_f32_16x16x32_f16 v[30:33], v[198:201], v[166:169], v[30:33]
	v_mfma_f32_16x16x32_f16 v[26:29], v[220:223], v[166:169], v[26:29]
	v_mfma_f32_16x16x32_f16 v[22:25], v[198:201], v[174:177], v[22:25]
	v_mfma_f32_16x16x32_f16 v[18:21], v[220:223], v[174:177], v[18:21]
	v_mfma_f32_16x16x32_f16 v[14:17], v[198:201], v[182:185], v[14:17]
	v_mfma_f32_16x16x32_f16 v[10:13], v[220:223], v[182:185], v[10:13]
	v_mfma_f32_16x16x32_f16 v[6:9], v[198:201], v[190:193], v[6:9]
	v_mfma_f32_16x16x32_f16 v[2:5], v[220:223], v[190:193], v[2:5]
	s_add_u32 s29, s29, 0x100
	s_addc_u32 s45, s45, 0
	s_cmp_ge_i32 s51, s24
	s_mov_b64 s[22:23], s[0:1]
	s_mov_b32 s26, s51
	s_barrier
	s_cbranch_scc0 .LBB0_621
	s_branch .LBB0_610

; __device__ __forceinline__ int otid() { int t = (int)threadIdx.x; asm volatile("" : "+v"(t)); return t; }
; __device__ __forceinline__ int obid() { int t = (int)blockIdx.x; asm volatile("" : "+s"(t)); return t; }
; #define PG8_STAGE(bufoff, gbase, voff) do { _Pragma("unroll") for (int _i = 0; _i < 2; ++_i) \
;         __builtin_amdgcn_global_load_lds((const unsigned*)((const char*)(gbase) + (voff)[_i]), (LAS unsigned*)(lds + (bufoff) + ldsw + _i * 8192), 16, 0, 0); } while (0)
; #define PG8_WAIT_V(n) asm volatile("s_waitcnt vmcnt(" #n ")" ::: "memory")
; #define PG8_BAR __builtin_amdgcn_s_barrier()
; template <class Epi, class AMap>
; __device__ __forceinline__ void gemm_phase(LAS unsigned char* lds, const AMap am, const int lda, const h16* Bt, const int ldb, const int M, const int N, const int K, const Epi& E) {
;     const int tid = otid(), wid = __builtin_amdgcn_readfirstlane(tid >> 6), lane = tid & 63, wr = wid >> 2, wc = wid & 3, fr = lane & 15, fq = lane >> 4;
;     const int nt = K / BK;
;     Order S; S.init(M, N, (int)gridDim.x, obid());
;     unsigned voffA[2], voffB[2];
; #pragma unroll
;     for (int i = 0; i < 2; ++i) { int R, C; stage_rc(tid * 16 + i * 8192, R, C); const int Rb = Epi::PERM ? ((R & ~31) + perm32(R & 31)) : R;
;         voffA[i] = (unsigned)(R * lda + C) * 2u; voffB[i] = (unsigned)(Rb * ldb + C) * 2u; }
;     const size_t kstep = (size_t)(BK * 2);
;     const size_t hstepA = (size_t)HALF * lda * 2, hstepB = (size_t)HALF * ldb * 2;
;     const size_t tstepA = 2 * hstepA, tstepB = 2 * hstepB;
;     const unsigned ldsw = (unsigned)wid * 1024u;
;     const int aoff = lds_byte(wr * 64 + fr, fq * 8), boff = lds_byte(wc * 32 + fr, fq * 8);
;     ...
;     const char* cA = am(cur.pn) + (size_t)cur.pm * tstepA; const char* cB = (const char*)Bt + (size_t)cur.pn * tstepB;
;     PG8_STAGE(PG8_SB(0, 0), cB, voffB); PG8_STAGE(PG8_SA(0, 0), cA, voffA); PG8_STAGE(PG8_SB(0, 1), cB + hstepB, voffB); PG8_STAGE(PG8_SA(0, 1), cA + hstepA, voffA);
;     if (wr == 1) PG8_BAR;
;     PG8_WAIT_V(4); PG8_BAR;
;     PG8_STAGE(PG8_SB(1, 0), cB + kstep, voffB); PG8_STAGE(PG8_SA(1, 0), cA + kstep, voffA); PG8_STAGE(PG8_SB(1, 1), cB + hstepB + kstep, voffB);
;     PG8_WAIT_V(6); PG8_BAR;
.LBB0_632:
	v_lshrrev_b32_e32 v20, 1, v18
	v_and_b32_e32 v20, 24, v20
	v_and_b32_e32 v19, 15, v18
	v_lshlrev_b32_e32 v21, 1, v20
	v_lshlrev_b32_e32 v18, 2, v18
	s_sext_i32_i8 s50, s0
	s_and_b32 s20, s20, 3
	v_lshl_or_b32 v202, s1, 6, v19
	v_lshl_or_b32 v19, v19, 6, v21
	s_lshl_b32 s0, s1, 13
	v_and_b32_e32 v18, 32, v18
	v_bitop3_b32 v21, v19, s0, v18 bitop3:0xde
	s_lshl_b32 s0, s20, 12
	v_bitop3_b32 v203, v19, s0, v18 bitop3:0xde
	v_readlane_b32 s0, v251, 37
	v_readlane_b32 s1, v251, 38
	s_add_u32 s40, s0, s46
	s_addc_u32 s41, s1, s47
	s_add_i32 m0, s74, 0x18000
	v_lshl_add_u64 v[8:9], v[8:9], 0, s[92:93]
	s_waitcnt vmcnt(0)
	s_barrier
	global_load_lds_dwordx4 v[8:9], off
	v_lshl_add_u64 v[6:7], v[6:7], 0, s[92:93]
	s_add_i32 m0, s74, 0x1a000
	s_add_i32 s78, s74, 0x8000
	s_add_i32 s79, s74, 0xa000
	global_load_lds_dwordx4 v[6:7], off
	v_lshl_add_u64 v[4:5], v[4:5], 0, s[92:93]
	s_mov_b32 m0, s78
	s_add_u32 s0, s26, 0x10080
	global_load_lds_dwordx4 v[4:5], off
	v_lshl_add_u64 v[2:3], v[2:3], 0, s[92:93]
	s_mov_b32 m0, s79
	s_addc_u32 s1, s27, 0
	global_load_lds_dwordx4 v[2:3], off
	s_add_i32 m0, s74, 0x1c000
	v_lshl_add_u64 v[2:3], s[0:1], 0, v[0:1]
	global_load_lds_dwordx4 v[2:3], off
	v_lshl_add_u64 v[2:3], s[0:1], 0, v[146:147]
	s_add_i32 m0, s74, 0x1e000
	v_readlane_b32 s3, v251, 40
	global_load_lds_dwordx4 v[2:3], off
	v_readlane_b32 s2, v251, 39
	s_movk_i32 s3, 0x1c00
	v_lshrrev_b32_e32 v3, 1, v10
	v_mul_lo_u32 v2, v12, s3
	s_mov_b32 s2, 0x1c000
	v_mad_u64_u32 v[2:3], s[0:1], v3, s2, v[2:3]
	v_readlane_b32 s4, v251, 41
	v_readlane_b32 s5, v251, 42
	v_or_b32_e32 v2, v2, v11
	v_add_lshl_u32 v2, v2, v13, 1
	v_mov_b32_e32 v3, v1
	s_mov_b64 s[4:5], 0x1c0080
	v_lshl_add_u64 v[148:149], v[2:3], 0, s[4:5]
	v_lshrrev_b32_e32 v3, 1, v14
	v_mul_lo_u32 v2, v16, s3
	v_mad_u64_u32 v[2:3], s[0:1], v3, s2, v[2:3]
	v_readlane_b32 s8, v251, 45
	v_readlane_b32 s9, v251, 46
	s_waitcnt vmcnt(6)
	v_or_b32_e32 v2, v2, v15
	v_readlane_b32 s12, v251, 49
	v_readlane_b32 s13, v251, 50
	v_readlane_b32 s14, v251, 51
	v_readlane_b32 s15, v251, 52
	s_cmp_gt_i32 s61, 63
	v_add_lshl_u32 v2, v2, v17, 1
	v_mov_b32_e32 v3, v1
	v_readlane_b32 s8, v254, 58
	v_readlane_b32 s2, v251, 7
	s_cselect_b64 s[42:43], -1, 0
	s_add_i32 s80, s24, -2
	v_lshl_or_b32 v204, s20, 6, v20
	v_lshl_add_u64 v[150:151], v[2:3], 0, s[4:5]
	s_mov_b32 s81, 0
	v_add_u32_e32 v205, 0, v21
	v_readlane_b32 s9, v254, 59
	v_readlane_b32 s3, v251, 8
	v_readlane_b32 s12, v254, 62
	s_movk_i32 s5, 0x3800
	s_movk_i32 s13, 0x2b00
	s_mov_b64 s[14:15], 0xa0000
	v_readlane_b32 s6, v251, 43
	v_readlane_b32 s7, v251, 44
	v_readlane_b32 s10, v251, 47
	v_readlane_b32 s11, v251, 48
	s_barrier
	s_branch .LBB0_634

; #define PG8_STAGE(bufoff, gbase, voff) do { _Pragma("unroll") for (int _i = 0; _i < 2; ++_i) \
;         __builtin_amdgcn_global_load_lds((const unsigned*)((const char*)(gbase) + (voff)[_i]), (LAS unsigned*)(lds + (bufoff) + ldsw + _i * 8192), 16, 0, 0); } while (0)
; #define PG8_LDA(dst, b, h) do { _Pragma("unroll") for (int m = 0; m < 4; ++m) _Pragma("unroll") for (int k = 0; k < 2; ++k) dst[m][k] = *(const LAS h16x8*)(lds + PG8_SA(b, h) + aoff + m * 2048 + k * 1024); } while (0)
; #define PG8_LDB(dst, b, h) do { _Pragma("unroll") for (int n = 0; n < 2; ++n) _Pragma("unroll") for (int k = 0; k < 2; ++k) dst[n][k] = *(const LAS h16x8*)(lds + PG8_SB(b, h) + boff + n * 2048 + k * 1024); } while (0)
; #define PG8_MMA(ai, bj, At, Bt_) do { __builtin_amdgcn_s_setprio(1); _Pragma("unroll") for (int m = 0; m < 4; ++m) _Pragma("unroll") for (int n = 0; n < 2; ++n) _Pragma("unroll") for (int k = 0; k < 2; ++k) \
;         acc[ai][bj][m][n] = __builtin_amdgcn_mfma_f32_16x16x32_f16(Bt_[n][k], At[m][k], acc[ai][bj][m][n], 0, 0, 0); __builtin_amdgcn_s_setprio(0); } while (0)
; #define PG8_WAIT_V(n) asm volatile("s_waitcnt vmcnt(" #n ")" ::: "memory")
; template <class Epi, class AMap>
; __device__ __forceinline__ void gemm_phase(LAS unsigned char* lds, const AMap am, const int lda, const h16* Bt, const int ldb, const int M, const int N, const int K, const Epi& E) {
;     ...
;         for (int t = 0; t < nt; t += 2) {
;             const bool last = (t == nt - 2);
;             const char* a1 = cA + (size_t)(t + 1) * kstep;
;             const char* a2 = last ? nA : cA + (size_t)(t + 2) * kstep; const char* b2 = last ? nB : cB + (size_t)(t + 2) * kstep;
;             const char* a3 = a2 + kstep; const char* b3 = b2 + kstep;
;             PG8_LDB(B0, 0, 0); PG8_SCHED; PG8_LDA(At, 0, 0); PG8_STAGE(PG8_SA(1, 1), a1 + hstepA, voffA);
;             PG8_WAIT_L(8); PG8_BAR; PG8_WAIT_L(0); PG8_MMA(0, 0, At, B0); PG8_BAR; PG8_SCHED;
;             PG8_LDB(B1, 0, 1); PG8_STAGE(PG8_SB(0, 0), b2, voffB);
;             PG8_BAR; PG8_WAIT_L(0); PG8_MMA(0, 1, At, B1); PG8_BAR;
;             PG8_LDA(At, 0, 1); PG8_STAGE(PG8_SA(0, 0), a2, voffA);
;             PG8_BAR; PG8_WAIT_L(0); PG8_MMA(1, 0, At, B0); PG8_BAR; PG8_SCHED;
;             PG8_STAGE(PG8_SB(0, 1), b2 + hstepB, voffB);
;             PG8_WAIT_V(6); PG8_BAR; PG8_MMA(1, 1, At, B1); PG8_BAR;
.LBB0_644:
	s_add_i32 s51, s26, 2
	s_add_u32 s0, s22, 0x100
	s_addc_u32 s1, s23, 0
	s_add_i32 s60, 0, 0x10000
	v_add_u32_e32 v234, s60, v203
	ds_read_b128 v[130:133], v234
	ds_read_b128 v[134:137], v234 offset:1024
	ds_read_b128 v[138:141], v234 offset:2048
	ds_read_b128 v[152:155], v234 offset:3072
	s_cmp_eq_u32 s80, s26
	s_cselect_b32 s26, s21, s29
	s_cselect_b32 s49, s47, s1
	s_cselect_b32 s48, s46, s0
	s_cselect_b32 s27, s20, s45
	v_lshl_add_u64 v[232:233], s[22:23], 0, v[148:149]
	s_add_i32 m0, s74, 0xc000
	ds_read_b128 v[156:159], v205
	ds_read_b128 v[160:163], v205 offset:1024
	ds_read_b128 v[164:167], v205 offset:2048
	ds_read_b128 v[168:171], v205 offset:3072
	ds_read_b128 v[172:175], v205 offset:4096
	ds_read_b128 v[176:179], v205 offset:5120
	ds_read_b128 v[180:183], v205 offset:6144
	ds_read_b128 v[184:187], v205 offset:7168
	global_load_lds_dwordx4 v[232:233], off
	v_lshl_add_u64 v[232:233], s[22:23], 0, v[150:151]
	s_add_i32 m0, s74, 0xe000
	s_nop 0
	global_load_lds_dwordx4 v[232:233], off
	s_waitcnt lgkmcnt(11)
	s_add_i32 s62, 0, 0x14000
	v_add_u32_e32 v200, s62, v203
	s_add_i32 s22, s60, s71
	ds_read_b128 v[188:191], v200
	ds_read_b128 v[192:195], v200 offset:1024
	ds_read_b128 v[196:199], v200 offset:2048
	ds_read_b128 v[220:223], v200 offset:3072
	s_waitcnt lgkmcnt(0)
	s_barrier
	v_mfma_f32_16x16x32_f16 v[122:125], v[130:133], v[156:159], v[122:125]
	v_mfma_f32_16x16x32_f16 v[126:129], v[138:141], v[156:159], v[126:129]
	v_mfma_f32_16x16x32_f16 v[110:113], v[130:133], v[164:167], v[110:113]
	v_mfma_f32_16x16x32_f16 v[106:109], v[138:141], v[164:167], v[106:109]
	v_mfma_f32_16x16x32_f16 v[94:97], v[130:133], v[172:175], v[94:97]
	v_mfma_f32_16x16x32_f16 v[90:93], v[138:141], v[172:175], v[90:93]
	v_mfma_f32_16x16x32_f16 v[78:81], v[130:133], v[180:183], v[78:81]
	v_mfma_f32_16x16x32_f16 v[74:77], v[138:141], v[180:183], v[74:77]
	v_mfma_f32_16x16x32_f16 v[122:125], v[134:137], v[160:163], v[122:125]
	v_mfma_f32_16x16x32_f16 v[126:129], v[152:155], v[160:163], v[126:129]
	v_mfma_f32_16x16x32_f16 v[110:113], v[134:137], v[168:171], v[110:113]
	v_mfma_f32_16x16x32_f16 v[106:109], v[152:155], v[168:171], v[106:109]
	v_mfma_f32_16x16x32_f16 v[94:97], v[134:137], v[176:179], v[94:97]
	v_mfma_f32_16x16x32_f16 v[90:93], v[152:155], v[176:179], v[90:93]
	v_mfma_f32_16x16x32_f16 v[78:81], v[134:137], v[184:187], v[78:81]
	v_mfma_f32_16x16x32_f16 v[74:77], v[152:155], v[184:187], v[74:77]
	v_mfma_f32_16x16x32_f16 v[118:121], v[188:191], v[156:159], v[118:121]
	v_mfma_f32_16x16x32_f16 v[114:117], v[196:199], v[156:159], v[114:117]
	v_mfma_f32_16x16x32_f16 v[102:105], v[188:191], v[164:167], v[102:105]
	v_mfma_f32_16x16x32_f16 v[98:101], v[196:199], v[164:167], v[98:101]
	v_mfma_f32_16x16x32_f16 v[86:89], v[188:191], v[172:175], v[86:89]
	v_mfma_f32_16x16x32_f16 v[82:85], v[196:199], v[172:175], v[82:85]
	v_mfma_f32_16x16x32_f16 v[70:73], v[188:191], v[180:183], v[70:73]
	v_mfma_f32_16x16x32_f16 v[66:69], v[196:199], v[180:183], v[66:69]
	v_mfma_f32_16x16x32_f16 v[118:121], v[192:195], v[160:163], v[118:121]
	v_mfma_f32_16x16x32_f16 v[114:117], v[220:223], v[160:163], v[114:117]
	v_mfma_f32_16x16x32_f16 v[102:105], v[192:195], v[168:171], v[102:105]
	v_mfma_f32_16x16x32_f16 v[98:101], v[220:223], v[168:171], v[98:101]
	v_mfma_f32_16x16x32_f16 v[86:89], v[192:195], v[176:179], v[86:89]
	v_mfma_f32_16x16x32_f16 v[82:85], v[220:223], v[176:179], v[82:85]
	v_mfma_f32_16x16x32_f16 v[70:73], v[192:195], v[184:187], v[70:73]
	v_mfma_f32_16x16x32_f16 v[66:69], v[220:223], v[184:187], v[66:69]
	s_barrier
	v_lshl_add_u64 v[200:201], s[26:27], 0, v[0:1]
	s_mov_b32 m0, s22
	v_lshl_add_u64 v[206:207], s[26:27], 0, v[146:147]
	global_load_lds_dwordx4 v[200:201], off
	s_add_i32 m0, s22, 0x2000
	s_nop 0
	global_load_lds_dwordx4 v[206:207], off
	s_mov_b32 m0, s74
	v_lshl_add_u64 v[212:213], s[48:49], 0, v[142:143]
	ds_read_b128 v[156:159], v205 offset:16384
	ds_read_b128 v[160:163], v205 offset:17408
	ds_read_b128 v[164:167], v205 offset:18432
	ds_read_b128 v[168:171], v205 offset:19456
	ds_read_b128 v[172:175], v205 offset:20480
	ds_read_b128 v[176:179], v205 offset:21504
	ds_read_b128 v[180:183], v205 offset:22528
	ds_read_b128 v[184:187], v205 offset:23552
	global_load_lds_dwordx4 v[212:213], off
	v_lshl_add_u64 v[224:225], s[48:49], 0, v[144:145]
	s_mov_b32 m0, s75
	s_nop 0
	global_load_lds_dwordx4 v[224:225], off
	s_add_u32 s22, s26, 0x10000
	s_addc_u32 s23, s27, 0
	s_add_i32 s60, s62, s71
	v_lshl_add_u64 v[232:233], s[22:23], 0, v[0:1]
	s_mov_b32 m0, s60
	s_nop 0
	global_load_lds_dwordx4 v[232:233], off
	v_lshl_add_u64 v[232:233], s[22:23], 0, v[146:147]
	s_add_i32 m0, s60, 0x2000
	s_nop 0
	global_load_lds_dwordx4 v[232:233], off
	s_waitcnt vmcnt(6) lgkmcnt(0)
	s_barrier
; #define PG8_STAGE(bufoff, gbase, voff) do { _Pragma("unroll") for (int _i = 0; _i < 2; ++_i) \
;         __builtin_amdgcn_global_load_lds((const unsigned*)((const char*)(gbase) + (voff)[_i]), (LAS unsigned*)(lds + (bufoff) + ldsw + _i * 8192), 16, 0, 0); } while (0)
; #define PG8_LDA(dst, b, h) do { _Pragma("unroll") for (int m = 0; m < 4; ++m) _Pragma("unroll") for (int k = 0; k < 2; ++k) dst[m][k] = *(const LAS h16x8*)(lds + PG8_SA(b, h) + aoff + m * 2048 + k * 1024); } while (0)
; #define PG8_LDB(dst, b, h) do { _Pragma("unroll") for (int n = 0; n < 2; ++n) _Pragma("unroll") for (int k = 0; k < 2; ++k) dst[n][k] = *(const LAS h16x8*)(lds + PG8_SB(b, h) + boff + n * 2048 + k * 1024); } while (0)
; #define PG8_MMA(ai, bj, At, Bt_) do { __builtin_amdgcn_s_setprio(1); _Pragma("unroll") for (int m = 0; m < 4; ++m) _Pragma("unroll") for (int n = 0; n < 2; ++n) _Pragma("unroll") for (int k = 0; k < 2; ++k) \
;         acc[ai][bj][m][n] = __builtin_amdgcn_mfma_f32_16x16x32_f16(Bt_[n][k], At[m][k], acc[ai][bj][m][n], 0, 0, 0); __builtin_amdgcn_s_setprio(0); } while (0)
; #define PG8_WAIT_V(n) asm volatile("s_waitcnt vmcnt(" #n ")" ::: "memory")
; #define PG8_WAIT_L(n) asm volatile("s_waitcnt lgkmcnt(" #n ")" ::: "memory")
; #define PG8_BAR __builtin_amdgcn_s_barrier()
; #define PG8_SCHED __builtin_amdgcn_sched_barrier(0)
; template <class Epi, class AMap>
; __device__ __forceinline__ void gemm_phase(LAS unsigned char* lds, const AMap am, const int lda, const h16* Bt, const int ldb, const int M, const int N, const int K, const Epi& E) {
;     ...
;             PG8_BAR; PG8_WAIT_L(0); PG8_MMA(1, 0, At, B0); PG8_BAR; PG8_SCHED;
;             PG8_STAGE(PG8_SB(0, 1), b2 + hstepB, voffB);
;             PG8_WAIT_V(6); PG8_BAR; PG8_MMA(1, 1, At, B1); PG8_BAR;
;             PG8_LDB(B0, 1, 0); PG8_SCHED; PG8_LDA(At, 1, 0); PG8_STAGE(PG8_SA(0, 1), a2 + hstepA, voffA);
;             PG8_WAIT_L(8); PG8_BAR; PG8_WAIT_L(0); PG8_MMA(0, 0, At, B0); PG8_BAR; PG8_SCHED;
;             PG8_LDB(B1, 1, 1); PG8_STAGE(PG8_SB(1, 0), b3, voffB);
;             PG8_BAR; PG8_WAIT_L(0); PG8_MMA(0, 1, At, B1); PG8_BAR;
;             PG8_LDA(At, 1, 1); PG8_STAGE(PG8_SA(1, 0), a3, voffA);
;             PG8_BAR; PG8_WAIT_L(0); PG8_MMA(1, 0, At, B0); PG8_BAR; PG8_SCHED;
	v_mfma_f32_16x16x32_f16 v[62:65], v[130:133], v[156:159], v[62:65]
	v_mfma_f32_16x16x32_f16 v[58:61], v[138:141], v[156:159], v[58:61]
	v_mfma_f32_16x16x32_f16 v[46:49], v[130:133], v[164:167], v[46:49]
	v_mfma_f32_16x16x32_f16 v[42:45], v[138:141], v[164:167], v[42:45]
	v_mfma_f32_16x16x32_f16 v[30:33], v[130:133], v[172:175], v[30:33]
	v_mfma_f32_16x16x32_f16 v[26:29], v[138:141], v[172:175], v[26:29]
	v_mfma_f32_16x16x32_f16 v[14:17], v[130:133], v[180:183], v[14:17]
	v_mfma_f32_16x16x32_f16 v[10:13], v[138:141], v[180:183], v[10:13]
	v_mfma_f32_16x16x32_f16 v[62:65], v[134:137], v[160:163], v[62:65]
	v_mfma_f32_16x16x32_f16 v[58:61], v[152:155], v[160:163], v[58:61]
	v_mfma_f32_16x16x32_f16 v[46:49], v[134:137], v[168:171], v[46:49]
	v_mfma_f32_16x16x32_f16 v[42:45], v[152:155], v[168:171], v[42:45]
	v_mfma_f32_16x16x32_f16 v[30:33], v[134:137], v[176:179], v[30:33]
	v_mfma_f32_16x16x32_f16 v[26:29], v[152:155], v[176:179], v[26:29]
	v_mfma_f32_16x16x32_f16 v[14:17], v[134:137], v[184:187], v[14:17]
	v_mfma_f32_16x16x32_f16 v[10:13], v[152:155], v[184:187], v[10:13]
	v_mfma_f32_16x16x32_f16 v[54:57], v[188:191], v[156:159], v[54:57]
	v_mfma_f32_16x16x32_f16 v[50:53], v[196:199], v[156:159], v[50:53]
	v_mfma_f32_16x16x32_f16 v[38:41], v[188:191], v[164:167], v[38:41]
	v_mfma_f32_16x16x32_f16 v[34:37], v[196:199], v[164:167], v[34:37]
	v_mfma_f32_16x16x32_f16 v[22:25], v[188:191], v[172:175], v[22:25]
	v_mfma_f32_16x16x32_f16 v[18:21], v[196:199], v[172:175], v[18:21]
	v_mfma_f32_16x16x32_f16 v[6:9], v[188:191], v[180:183], v[6:9]
	v_mfma_f32_16x16x32_f16 v[2:5], v[196:199], v[180:183], v[2:5]
	v_mfma_f32_16x16x32_f16 v[54:57], v[192:195], v[160:163], v[54:57]
	v_mfma_f32_16x16x32_f16 v[50:53], v[220:223], v[160:163], v[50:53]
	v_mfma_f32_16x16x32_f16 v[38:41], v[192:195], v[168:171], v[38:41]
	v_mfma_f32_16x16x32_f16 v[34:37], v[220:223], v[168:171], v[34:37]
	v_mfma_f32_16x16x32_f16 v[22:25], v[192:195], v[176:179], v[22:25]
	v_mfma_f32_16x16x32_f16 v[18:21], v[220:223], v[176:179], v[18:21]
	v_mfma_f32_16x16x32_f16 v[6:9], v[192:195], v[184:187], v[6:9]
	v_mfma_f32_16x16x32_f16 v[2:5], v[220:223], v[184:187], v[2:5]
	s_barrier
	s_add_i32 s60, 0, 0x18000
	v_add_u32_e32 v234, s60, v203
	ds_read_b128 v[130:133], v234
	ds_read_b128 v[134:137], v234 offset:1024
	ds_read_b128 v[138:141], v234 offset:2048
	ds_read_b128 v[152:155], v234 offset:3072
	s_add_u32 s22, s48, 0x1c0000
	s_addc_u32 s23, s49, 0
	s_mov_b32 m0, s76
	v_lshl_add_u64 v[232:233], s[22:23], 0, v[142:143]
	ds_read_b128 v[156:159], v205 offset:32768
	ds_read_b128 v[160:163], v205 offset:33792
	ds_read_b128 v[164:167], v205 offset:34816
	ds_read_b128 v[168:171], v205 offset:35840
	ds_read_b128 v[172:175], v205 offset:36864
	ds_read_b128 v[176:179], v205 offset:37888
	ds_read_b128 v[180:183], v205 offset:38912
	ds_read_b128 v[184:187], v205 offset:39936
	global_load_lds_dwordx4 v[232:233], off
	v_lshl_add_u64 v[232:233], s[22:23], 0, v[144:145]
	s_mov_b32 m0, s77
	s_nop 0
	global_load_lds_dwordx4 v[232:233], off
	s_waitcnt lgkmcnt(11)
	s_add_i32 s48, 0, 0x1c000
	s_add_i32 s22, s60, s71
	v_add_u32_e32 v214, s48, v203
	v_lshl_add_u64 v[200:201], v[200:201], 0, s[92:93]
	s_mov_b32 m0, s22
	ds_read_b128 v[188:191], v214
	ds_read_b128 v[192:195], v214 offset:1024
	ds_read_b128 v[196:199], v214 offset:2048
	ds_read_b128 v[220:223], v214 offset:3072
	s_waitcnt lgkmcnt(0)
	s_barrier
	v_mfma_f32_16x16x32_f16 v[122:125], v[130:133], v[156:159], v[122:125]
	v_mfma_f32_16x16x32_f16 v[126:129], v[138:141], v[156:159], v[126:129]
	v_mfma_f32_16x16x32_f16 v[110:113], v[130:133], v[164:167], v[110:113]
	v_mfma_f32_16x16x32_f16 v[106:109], v[138:141], v[164:167], v[106:109]
	v_mfma_f32_16x16x32_f16 v[94:97], v[130:133], v[172:175], v[94:97]
	v_mfma_f32_16x16x32_f16 v[90:93], v[138:141], v[172:175], v[90:93]
	v_mfma_f32_16x16x32_f16 v[78:81], v[130:133], v[180:183], v[78:81]
	v_mfma_f32_16x16x32_f16 v[74:77], v[138:141], v[180:183], v[74:77]
	v_mfma_f32_16x16x32_f16 v[122:125], v[134:137], v[160:163], v[122:125]
	v_mfma_f32_16x16x32_f16 v[126:129], v[152:155], v[160:163], v[126:129]
	v_mfma_f32_16x16x32_f16 v[110:113], v[134:137], v[168:171], v[110:113]
	v_mfma_f32_16x16x32_f16 v[106:109], v[152:155], v[168:171], v[106:109]
	v_mfma_f32_16x16x32_f16 v[94:97], v[134:137], v[176:179], v[94:97]
	v_mfma_f32_16x16x32_f16 v[90:93], v[152:155], v[176:179], v[90:93]
	v_mfma_f32_16x16x32_f16 v[78:81], v[134:137], v[184:187], v[78:81]
	v_mfma_f32_16x16x32_f16 v[74:77], v[152:155], v[184:187], v[74:77]
	v_mfma_f32_16x16x32_f16 v[118:121], v[188:191], v[156:159], v[118:121]
	v_mfma_f32_16x16x32_f16 v[114:117], v[196:199], v[156:159], v[114:117]
	v_mfma_f32_16x16x32_f16 v[102:105], v[188:191], v[164:167], v[102:105]
	v_mfma_f32_16x16x32_f16 v[98:101], v[196:199], v[164:167], v[98:101]
	v_mfma_f32_16x16x32_f16 v[86:89], v[188:191], v[172:175], v[86:89]
	v_mfma_f32_16x16x32_f16 v[82:85], v[196:199], v[172:175], v[82:85]
	v_mfma_f32_16x16x32_f16 v[70:73], v[188:191], v[180:183], v[70:73]
	v_mfma_f32_16x16x32_f16 v[66:69], v[196:199], v[180:183], v[66:69]
	v_mfma_f32_16x16x32_f16 v[118:121], v[192:195], v[160:163], v[118:121]
	v_mfma_f32_16x16x32_f16 v[114:117], v[220:223], v[160:163], v[114:117]
	v_mfma_f32_16x16x32_f16 v[102:105], v[192:195], v[168:171], v[102:105]
	v_mfma_f32_16x16x32_f16 v[98:101], v[220:223], v[168:171], v[98:101]
	v_mfma_f32_16x16x32_f16 v[86:89], v[192:195], v[176:179], v[86:89]
	v_mfma_f32_16x16x32_f16 v[82:85], v[220:223], v[176:179], v[82:85]
	v_mfma_f32_16x16x32_f16 v[70:73], v[192:195], v[184:187], v[70:73]
	v_mfma_f32_16x16x32_f16 v[66:69], v[220:223], v[184:187], v[66:69]
	s_barrier
; #define PG8_STAGE(bufoff, gbase, voff) do { _Pragma("unroll") for (int _i = 0; _i < 2; ++_i) \
;         __builtin_amdgcn_global_load_lds((const unsigned*)((const char*)(gbase) + (voff)[_i]), (LAS unsigned*)(lds + (bufoff) + ldsw + _i * 8192), 16, 0, 0); } while (0)
; #define PG8_LDA(dst, b, h) do { _Pragma("unroll") for (int m = 0; m < 4; ++m) _Pragma("unroll") for (int k = 0; k < 2; ++k) dst[m][k] = *(const LAS h16x8*)(lds + PG8_SA(b, h) + aoff + m * 2048 + k * 1024); } while (0)
; #define PG8_MMA(ai, bj, At, Bt_) do { __builtin_amdgcn_s_setprio(1); _Pragma("unroll") for (int m = 0; m < 4; ++m) _Pragma("unroll") for (int n = 0; n < 2; ++n) _Pragma("unroll") for (int k = 0; k < 2; ++k) \
;         acc[ai][bj][m][n] = __builtin_amdgcn_mfma_f32_16x16x32_f16(Bt_[n][k], At[m][k], acc[ai][bj][m][n], 0, 0, 0); __builtin_amdgcn_s_setprio(0); } while (0)
; #define PG8_WAIT_V(n) asm volatile("s_waitcnt vmcnt(" #n ")" ::: "memory")
; #define PG8_WAIT_L(n) asm volatile("s_waitcnt lgkmcnt(" #n ")" ::: "memory")
; #define PG8_BAR __builtin_amdgcn_s_barrier()
; #define PG8_SCHED __builtin_amdgcn_sched_barrier(0)
; template <class Epi, class AMap>
; __device__ __forceinline__ void gemm_phase(LAS unsigned char* lds, const AMap am, const int lda, const h16* Bt, const int ldb, const int M, const int N, const int K, const Epi& E) {
;     ...
;             PG8_LDA(At, 1, 1); PG8_STAGE(PG8_SA(1, 0), a3, voffA);
;             PG8_BAR; PG8_WAIT_L(0); PG8_MMA(1, 0, At, B0); PG8_BAR; PG8_SCHED;
;             PG8_STAGE(PG8_SB(1, 1), b3 + hstepB, voffB);
;             PG8_WAIT_V(6); PG8_BAR; PG8_MMA(1, 1, At, B1); PG8_BAR;
;         }
	global_load_lds_dwordx4 v[200:201], off
	v_lshl_add_u64 v[200:201], v[206:207], 0, s[92:93]
	s_add_i32 m0, s22, 0x2000
	s_nop 0
	global_load_lds_dwordx4 v[200:201], off
	s_mov_b32 m0, s78
	v_lshl_add_u64 v[200:201], v[212:213], 0, s[92:93]
	ds_read_b128 v[156:159], v205 offset:49152
	ds_read_b128 v[160:163], v205 offset:50176
	ds_read_b128 v[164:167], v205 offset:51200
	ds_read_b128 v[168:171], v205 offset:52224
	ds_read_b128 v[172:175], v205 offset:53248
	ds_read_b128 v[176:179], v205 offset:54272
	ds_read_b128 v[180:183], v205 offset:55296
	ds_read_b128 v[184:187], v205 offset:56320
	global_load_lds_dwordx4 v[200:201], off
	v_lshl_add_u64 v[200:201], v[224:225], 0, s[92:93]
	s_mov_b32 m0, s79
	s_nop 0
	global_load_lds_dwordx4 v[200:201], off
	s_add_u32 s22, s26, 0x10080
	s_addc_u32 s23, s27, 0
	s_add_i32 s26, s48, s71
	v_lshl_add_u64 v[232:233], s[22:23], 0, v[0:1]
	s_mov_b32 m0, s26
	s_nop 0
	global_load_lds_dwordx4 v[232:233], off
	v_lshl_add_u64 v[232:233], s[22:23], 0, v[146:147]
	s_add_i32 m0, s26, 0x2000
	s_nop 0
	global_load_lds_dwordx4 v[232:233], off
	s_waitcnt vmcnt(6) lgkmcnt(0)
	s_barrier
	v_mfma_f32_16x16x32_f16 v[62:65], v[130:133], v[156:159], v[62:65]
	v_mfma_f32_16x16x32_f16 v[58:61], v[138:141], v[156:159], v[58:61]
	v_mfma_f32_16x16x32_f16 v[46:49], v[130:133], v[164:167], v[46:49]
	v_mfma_f32_16x16x32_f16 v[42:45], v[138:141], v[164:167], v[42:45]
	v_mfma_f32_16x16x32_f16 v[30:33], v[130:133], v[172:175], v[30:33]
	v_mfma_f32_16x16x32_f16 v[26:29], v[138:141], v[172:175], v[26:29]
	v_mfma_f32_16x16x32_f16 v[14:17], v[130:133], v[180:183], v[14:17]
	v_mfma_f32_16x16x32_f16 v[10:13], v[138:141], v[180:183], v[10:13]
	v_mfma_f32_16x16x32_f16 v[62:65], v[134:137], v[160:163], v[62:65]
	v_mfma_f32_16x16x32_f16 v[58:61], v[152:155], v[160:163], v[58:61]
	v_mfma_f32_16x16x32_f16 v[46:49], v[134:137], v[168:171], v[46:49]
	v_mfma_f32_16x16x32_f16 v[42:45], v[152:155], v[168:171], v[42:45]
	v_mfma_f32_16x16x32_f16 v[30:33], v[134:137], v[176:179], v[30:33]
	v_mfma_f32_16x16x32_f16 v[26:29], v[152:155], v[176:179], v[26:29]
	v_mfma_f32_16x16x32_f16 v[14:17], v[134:137], v[184:187], v[14:17]
	v_mfma_f32_16x16x32_f16 v[10:13], v[152:155], v[184:187], v[10:13]
	v_mfma_f32_16x16x32_f16 v[54:57], v[188:191], v[156:159], v[54:57]
	v_mfma_f32_16x16x32_f16 v[50:53], v[196:199], v[156:159], v[50:53]
	v_mfma_f32_16x16x32_f16 v[38:41], v[188:191], v[164:167], v[38:41]
	v_mfma_f32_16x16x32_f16 v[34:37], v[196:199], v[164:167], v[34:37]
	v_mfma_f32_16x16x32_f16 v[22:25], v[188:191], v[172:175], v[22:25]
	v_mfma_f32_16x16x32_f16 v[18:21], v[196:199], v[172:175], v[18:21]
	v_mfma_f32_16x16x32_f16 v[6:9], v[188:191], v[180:183], v[6:9]
	v_mfma_f32_16x16x32_f16 v[2:5], v[196:199], v[180:183], v[2:5]
	v_mfma_f32_16x16x32_f16 v[54:57], v[192:195], v[160:163], v[54:57]
	v_mfma_f32_16x16x32_f16 v[50:53], v[220:223], v[160:163], v[50:53]
	v_mfma_f32_16x16x32_f16 v[38:41], v[192:195], v[168:171], v[38:41]
	v_mfma_f32_16x16x32_f16 v[34:37], v[220:223], v[168:171], v[34:37]
	v_mfma_f32_16x16x32_f16 v[22:25], v[192:195], v[176:179], v[22:25]
	v_mfma_f32_16x16x32_f16 v[18:21], v[220:223], v[176:179], v[18:21]
	v_mfma_f32_16x16x32_f16 v[6:9], v[192:195], v[184:187], v[6:9]
	v_mfma_f32_16x16x32_f16 v[2:5], v[220:223], v[184:187], v[2:5]
	s_add_u32 s29, s29, 0x100
	s_addc_u32 s45, s45, 0
	s_cmp_ge_i32 s51, s24
	s_mov_b64 s[22:23], s[0:1]
	s_mov_b32 s26, s51
	s_barrier
	s_cbranch_scc0 .LBB0_644
	s_branch .LBB0_633

; #define PG8_STAGE(bufoff, gbase, voff) do { _Pragma("unroll") for (int _i = 0; _i < 2; ++_i) \
;         __builtin_amdgcn_global_load_lds((const unsigned*)((const char*)(gbase) + (voff)[_i]), (LAS unsigned*)(lds + (bufoff) + ldsw + _i * 8192), 16, 0, 0); } while (0)
; #define PG8_WAIT_V(n) asm volatile("s_waitcnt vmcnt(" #n ")" ::: "memory")
; #define PG8_BAR __builtin_amdgcn_s_barrier()
; template <class Epi, class AMap>
; __device__ __forceinline__ void gemm_phase(LAS unsigned char* lds, const AMap am, const int lda, const h16* Bt, const int ldb, const int M, const int N, const int K, const Epi& E) {
;     ...
;     const char* cA = am(cur.pn) + (size_t)cur.pm * tstepA; const char* cB = (const char*)Bt + (size_t)cur.pn * tstepB;
;     PG8_STAGE(PG8_SB(0, 0), cB, voffB); PG8_STAGE(PG8_SA(0, 0), cA, voffA); PG8_STAGE(PG8_SB(0, 1), cB + hstepB, voffB); PG8_STAGE(PG8_SA(0, 1), cA + hstepA, voffA);
;     if (wr == 1) PG8_BAR;
;     PG8_WAIT_V(4); PG8_BAR;
;     PG8_STAGE(PG8_SB(1, 0), cB + kstep, voffB); PG8_STAGE(PG8_SA(1, 0), cA + kstep, voffA); PG8_STAGE(PG8_SB(1, 1), cB + hstepB + kstep, voffB);
;     PG8_WAIT_V(6); PG8_BAR;
.LBB0_655:
	v_lshrrev_b32_e32 v20, 1, v18
	v_and_b32_e32 v20, 24, v20
	v_and_b32_e32 v19, 15, v18
	v_lshlrev_b32_e32 v21, 1, v20
	v_lshlrev_b32_e32 v18, 2, v18
	s_sext_i32_i8 s76, s0
	v_lshl_or_b32 v160, s20, 6, v19
	v_lshl_or_b32 v19, v19, 6, v21
	s_lshl_b32 s0, s20, 13
	v_and_b32_e32 v18, 32, v18
	v_bitop3_b32 v21, v19, s0, v18 bitop3:0xde
	s_lshl_b32 s0, s1, 5
	s_and_b32 s20, s0, 0x60
	s_add_i32 m0, s65, 0x18000
	v_lshl_add_u64 v[8:9], v[8:9], 0, s[92:93]
	s_lshl_b32 s0, s20, 7
	s_waitcnt vmcnt(0)
	s_barrier
	global_load_lds_dwordx4 v[8:9], off
	v_lshl_add_u64 v[6:7], v[6:7], 0, s[92:93]
	s_add_i32 m0, s65, 0x1a000
	s_add_i32 s71, s65, 0x8000
	s_add_i32 s72, s65, 0xa000
	v_bitop3_b32 v161, v19, s0, v18 bitop3:0xde
	global_load_lds_dwordx4 v[6:7], off
	v_lshl_add_u64 v[4:5], v[4:5], 0, s[92:93]
	s_mov_b32 m0, s71
	s_add_u32 s0, s46, 0x10080
	global_load_lds_dwordx4 v[4:5], off
	v_lshl_add_u64 v[2:3], v[2:3], 0, s[92:93]
	s_mov_b32 m0, s72
	s_addc_u32 s1, s47, 0
	global_load_lds_dwordx4 v[2:3], off
	s_add_i32 m0, s65, 0x1c000
	v_lshl_add_u64 v[2:3], s[0:1], 0, v[0:1]
	global_load_lds_dwordx4 v[2:3], off
	v_lshl_add_u64 v[2:3], s[0:1], 0, v[134:135]
	s_add_i32 m0, s65, 0x1e000
	s_movk_i32 s6, 0x1c00
	global_load_lds_dwordx4 v[2:3], off
	v_lshrrev_b32_e32 v3, 1, v10
	v_mul_lo_u32 v2, v12, s6
	s_mov_b32 s4, 0x1c000
	v_mad_u64_u32 v[2:3], s[0:1], v3, s4, v[2:3]
	v_or_b32_e32 v2, v2, v11
	v_or_b32_e32 v162, s20, v20
	v_add_lshl_u32 v2, v2, v13, 1
	v_mov_b32_e32 v3, v1
	s_mov_b64 s[20:21], 0x1c0080
	v_lshl_add_u64 v[136:137], v[2:3], 0, s[20:21]
	v_lshrrev_b32_e32 v3, 1, v14
	v_mul_lo_u32 v2, v16, s6
	v_mad_u64_u32 v[2:3], s[0:1], v3, s4, v[2:3]
	s_waitcnt vmcnt(6)
	v_or_b32_e32 v2, v2, v15
	s_cmp_gt_i32 s61, 63
	v_add_lshl_u32 v2, v2, v17, 1
	v_mov_b32_e32 v3, v1
	s_cselect_b64 s[22:23], -1, 0
	s_add_i32 s73, s24, -2
	v_lshl_add_u64 v[138:139], v[2:3], 0, s[20:21]
	s_mov_b32 s75, 0
	v_add_u32_e32 v163, 0, v21
	s_barrier
	s_branch .LBB0_657

; #define PG8_STAGE(bufoff, gbase, voff) do { _Pragma("unroll") for (int _i = 0; _i < 2; ++_i) \
;         __builtin_amdgcn_global_load_lds((const unsigned*)((const char*)(gbase) + (voff)[_i]), (LAS unsigned*)(lds + (bufoff) + ldsw + _i * 8192), 16, 0, 0); } while (0)
; #define PG8_LDA(dst, b, h) do { _Pragma("unroll") for (int m = 0; m < 4; ++m) _Pragma("unroll") for (int k = 0; k < 2; ++k) dst[m][k] = *(const LAS h16x8*)(lds + PG8_SA(b, h) + aoff + m * 2048 + k * 1024); } while (0)
; #define PG8_LDB(dst, b, h) do { _Pragma("unroll") for (int n = 0; n < 2; ++n) _Pragma("unroll") for (int k = 0; k < 2; ++k) dst[n][k] = *(const LAS h16x8*)(lds + PG8_SB(b, h) + boff + n * 2048 + k * 1024); } while (0)
; #define PG8_MMA(ai, bj, At, Bt_) do { __builtin_amdgcn_s_setprio(1); _Pragma("unroll") for (int m = 0; m < 4; ++m) _Pragma("unroll") for (int n = 0; n < 2; ++n) _Pragma("unroll") for (int k = 0; k < 2; ++k) \
;         acc[ai][bj][m][n] = __builtin_amdgcn_mfma_f32_16x16x32_f16(Bt_[n][k], At[m][k], acc[ai][bj][m][n], 0, 0, 0); __builtin_amdgcn_s_setprio(0); } while (0)
; #define PG8_WAIT_V(n) asm volatile("s_waitcnt vmcnt(" #n ")" ::: "memory")
; template <class Epi, class AMap>
; __device__ __forceinline__ void gemm_phase(LAS unsigned char* lds, const AMap am, const int lda, const h16* Bt, const int ldb, const int M, const int N, const int K, const Epi& E) {
;     ...
;         for (int t = 0; t < nt; t += 2) {
;             const bool last = (t == nt - 2);
;             const char* a1 = cA + (size_t)(t + 1) * kstep;
;             const char* a2 = last ? nA : cA + (size_t)(t + 2) * kstep; const char* b2 = last ? nB : cB + (size_t)(t + 2) * kstep;
;             const char* a3 = a2 + kstep; const char* b3 = b2 + kstep;
;             PG8_LDB(B0, 0, 0); PG8_SCHED; PG8_LDA(At, 0, 0); PG8_STAGE(PG8_SA(1, 1), a1 + hstepA, voffA);
;             PG8_WAIT_L(8); PG8_BAR; PG8_WAIT_L(0); PG8_MMA(0, 0, At, B0); PG8_BAR; PG8_SCHED;
;             PG8_LDB(B1, 0, 1); PG8_STAGE(PG8_SB(0, 0), b2, voffB);
;             PG8_BAR; PG8_WAIT_L(0); PG8_MMA(0, 1, At, B1); PG8_BAR;
;             PG8_LDA(At, 0, 1); PG8_STAGE(PG8_SA(0, 0), a2, voffA);
;             PG8_BAR; PG8_WAIT_L(0); PG8_MMA(1, 0, At, B0); PG8_BAR; PG8_SCHED;
;             PG8_STAGE(PG8_SB(0, 1), b2 + hstepB, voffB);
;             PG8_WAIT_V(6); PG8_BAR; PG8_MMA(1, 1, At, B1); PG8_BAR;
.LBB0_667:
	s_add_i32 s60, s46, 2
	s_add_u32 s0, s44, 0x100
	s_addc_u32 s1, s45, 0
	s_add_i32 s66, 0, 0x10000
	v_add_u32_e32 v234, s66, v161
	ds_read_b128 v[140:143], v234
	ds_read_b128 v[144:147], v234 offset:1024
	ds_read_b128 v[148:151], v234 offset:2048
	ds_read_b128 v[152:155], v234 offset:3072
	s_cmp_eq_u32 s73, s46
	s_cselect_b32 s46, s21, s27
	s_cselect_b32 s49, s41, s1
	s_cselect_b32 s48, s40, s0
	s_cselect_b32 s47, s20, s29
	v_lshl_add_u64 v[232:233], s[44:45], 0, v[136:137]
	s_add_i32 m0, s65, 0xc000
	ds_read_b128 v[156:159], v163
	ds_read_b128 v[164:167], v163 offset:1024
	ds_read_b128 v[168:171], v163 offset:2048
	ds_read_b128 v[172:175], v163 offset:3072
	ds_read_b128 v[176:179], v163 offset:4096
	ds_read_b128 v[180:183], v163 offset:5120
	ds_read_b128 v[184:187], v163 offset:6144
	ds_read_b128 v[188:191], v163 offset:7168
	global_load_lds_dwordx4 v[232:233], off
	v_lshl_add_u64 v[232:233], s[44:45], 0, v[138:139]
	s_add_i32 m0, s65, 0xe000
	s_nop 0
	global_load_lds_dwordx4 v[232:233], off
	s_waitcnt lgkmcnt(11)
	s_add_i32 s78, 0, 0x14000
	s_add_i32 s44, s66, s62
	v_add_u32_e32 v234, s78, v161
	v_lshl_add_u64 v[212:213], s[46:47], 0, v[0:1]
	s_mov_b32 m0, s44
	ds_read_b128 v[192:195], v234
	ds_read_b128 v[196:199], v234 offset:1024
	ds_read_b128 v[200:203], v234 offset:2048
	ds_read_b128 v[204:207], v234 offset:3072
	s_waitcnt lgkmcnt(0)
	s_barrier
	v_mfma_f32_16x16x32_f16 v[126:129], v[140:143], v[156:159], v[126:129]
	v_mfma_f32_16x16x32_f16 v[122:125], v[148:151], v[156:159], v[122:125]
	v_mfma_f32_16x16x32_f16 v[118:121], v[140:143], v[168:171], v[118:121]
	v_mfma_f32_16x16x32_f16 v[114:117], v[148:151], v[168:171], v[114:117]
	v_mfma_f32_16x16x32_f16 v[110:113], v[140:143], v[176:179], v[110:113]
	v_mfma_f32_16x16x32_f16 v[106:109], v[148:151], v[176:179], v[106:109]
	v_mfma_f32_16x16x32_f16 v[102:105], v[140:143], v[184:187], v[102:105]
	v_mfma_f32_16x16x32_f16 v[98:101], v[148:151], v[184:187], v[98:101]
	v_mfma_f32_16x16x32_f16 v[126:129], v[144:147], v[164:167], v[126:129]
	v_mfma_f32_16x16x32_f16 v[122:125], v[152:155], v[164:167], v[122:125]
	v_mfma_f32_16x16x32_f16 v[118:121], v[144:147], v[172:175], v[118:121]
	v_mfma_f32_16x16x32_f16 v[114:117], v[152:155], v[172:175], v[114:117]
	v_mfma_f32_16x16x32_f16 v[110:113], v[144:147], v[180:183], v[110:113]
	v_mfma_f32_16x16x32_f16 v[106:109], v[152:155], v[180:183], v[106:109]
	v_mfma_f32_16x16x32_f16 v[102:105], v[144:147], v[188:191], v[102:105]
	v_mfma_f32_16x16x32_f16 v[98:101], v[152:155], v[188:191], v[98:101]
	v_mfma_f32_16x16x32_f16 v[94:97], v[192:195], v[156:159], v[94:97]
	v_mfma_f32_16x16x32_f16 v[86:89], v[200:203], v[156:159], v[86:89]
	v_mfma_f32_16x16x32_f16 v[78:81], v[192:195], v[168:171], v[78:81]
	v_mfma_f32_16x16x32_f16 v[70:73], v[200:203], v[168:171], v[70:73]
	v_mfma_f32_16x16x32_f16 v[62:65], v[192:195], v[176:179], v[62:65]
	v_mfma_f32_16x16x32_f16 v[54:57], v[200:203], v[176:179], v[54:57]
	v_mfma_f32_16x16x32_f16 v[46:49], v[192:195], v[184:187], v[46:49]
	v_mfma_f32_16x16x32_f16 v[38:41], v[200:203], v[184:187], v[38:41]
	v_mfma_f32_16x16x32_f16 v[94:97], v[196:199], v[164:167], v[94:97]
	v_mfma_f32_16x16x32_f16 v[86:89], v[204:207], v[164:167], v[86:89]
	v_mfma_f32_16x16x32_f16 v[78:81], v[196:199], v[172:175], v[78:81]
	v_mfma_f32_16x16x32_f16 v[70:73], v[204:207], v[172:175], v[70:73]
	v_mfma_f32_16x16x32_f16 v[62:65], v[196:199], v[180:183], v[62:65]
	v_mfma_f32_16x16x32_f16 v[54:57], v[204:207], v[180:183], v[54:57]
	v_mfma_f32_16x16x32_f16 v[46:49], v[196:199], v[188:191], v[46:49]
	v_mfma_f32_16x16x32_f16 v[38:41], v[204:207], v[188:191], v[38:41]
	s_barrier
	global_load_lds_dwordx4 v[212:213], off
	v_lshl_add_u64 v[220:221], s[46:47], 0, v[134:135]
	s_add_i32 m0, s44, 0x2000
	s_nop 0
	global_load_lds_dwordx4 v[220:221], off
	s_mov_b32 m0, s65
	v_lshl_add_u64 v[222:223], s[48:49], 0, v[130:131]
	ds_read_b128 v[156:159], v163 offset:16384
	ds_read_b128 v[164:167], v163 offset:17408
	ds_read_b128 v[168:171], v163 offset:18432
	ds_read_b128 v[172:175], v163 offset:19456
	ds_read_b128 v[176:179], v163 offset:20480
	ds_read_b128 v[180:183], v163 offset:21504
	ds_read_b128 v[184:187], v163 offset:22528
	ds_read_b128 v[188:191], v163 offset:23552
	global_load_lds_dwordx4 v[222:223], off
	v_lshl_add_u64 v[224:225], s[48:49], 0, v[132:133]
	s_mov_b32 m0, s68
	s_nop 0
	global_load_lds_dwordx4 v[224:225], off
	s_add_u32 s44, s46, 0x10000
	s_addc_u32 s45, s47, 0
	s_add_i32 s66, s78, s62
	v_lshl_add_u64 v[232:233], s[44:45], 0, v[0:1]
	s_mov_b32 m0, s66
	s_nop 0
	global_load_lds_dwordx4 v[232:233], off
	v_lshl_add_u64 v[232:233], s[44:45], 0, v[134:135]
	s_add_i32 m0, s66, 0x2000
	s_nop 0
	global_load_lds_dwordx4 v[232:233], off
	s_waitcnt vmcnt(6) lgkmcnt(0)
	s_barrier
; #define PG8_STAGE(bufoff, gbase, voff) do { _Pragma("unroll") for (int _i = 0; _i < 2; ++_i) \
;         __builtin_amdgcn_global_load_lds((const unsigned*)((const char*)(gbase) + (voff)[_i]), (LAS unsigned*)(lds + (bufoff) + ldsw + _i * 8192), 16, 0, 0); } while (0)
; #define PG8_LDA(dst, b, h) do { _Pragma("unroll") for (int m = 0; m < 4; ++m) _Pragma("unroll") for (int k = 0; k < 2; ++k) dst[m][k] = *(const LAS h16x8*)(lds + PG8_SA(b, h) + aoff + m * 2048 + k * 1024); } while (0)
; #define PG8_LDB(dst, b, h) do { _Pragma("unroll") for (int n = 0; n < 2; ++n) _Pragma("unroll") for (int k = 0; k < 2; ++k) dst[n][k] = *(const LAS h16x8*)(lds + PG8_SB(b, h) + boff + n * 2048 + k * 1024); } while (0)
; #define PG8_MMA(ai, bj, At, Bt_) do { __builtin_amdgcn_s_setprio(1); _Pragma("unroll") for (int m = 0; m < 4; ++m) _Pragma("unroll") for (int n = 0; n < 2; ++n) _Pragma("unroll") for (int k = 0; k < 2; ++k) \
;         acc[ai][bj][m][n] = __builtin_amdgcn_mfma_f32_16x16x32_f16(Bt_[n][k], At[m][k], acc[ai][bj][m][n], 0, 0, 0); __builtin_amdgcn_s_setprio(0); } while (0)
; #define PG8_WAIT_V(n) asm volatile("s_waitcnt vmcnt(" #n ")" ::: "memory")
; #define PG8_WAIT_L(n) asm volatile("s_waitcnt lgkmcnt(" #n ")" ::: "memory")
; #define PG8_BAR __builtin_amdgcn_s_barrier()
; #define PG8_SCHED __builtin_amdgcn_sched_barrier(0)
; template <class Epi, class AMap>
; __device__ __forceinline__ void gemm_phase(LAS unsigned char* lds, const AMap am, const int lda, const h16* Bt, const int ldb, const int M, const int N, const int K, const Epi& E) {
;     ...
;             PG8_BAR; PG8_WAIT_L(0); PG8_MMA(1, 0, At, B0); PG8_BAR; PG8_SCHED;
;             PG8_STAGE(PG8_SB(0, 1), b2 + hstepB, voffB);
;             PG8_WAIT_V(6); PG8_BAR; PG8_MMA(1, 1, At, B1); PG8_BAR;
;             PG8_LDB(B0, 1, 0); PG8_SCHED; PG8_LDA(At, 1, 0); PG8_STAGE(PG8_SA(0, 1), a2 + hstepA, voffA);
;             PG8_WAIT_L(8); PG8_BAR; PG8_WAIT_L(0); PG8_MMA(0, 0, At, B0); PG8_BAR; PG8_SCHED;
;             PG8_LDB(B1, 1, 1); PG8_STAGE(PG8_SB(1, 0), b3, voffB);
;             PG8_BAR; PG8_WAIT_L(0); PG8_MMA(0, 1, At, B1); PG8_BAR;
;             PG8_LDA(At, 1, 1); PG8_STAGE(PG8_SA(1, 0), a3, voffA);
;             PG8_BAR; PG8_WAIT_L(0); PG8_MMA(1, 0, At, B0); PG8_BAR; PG8_SCHED;
	v_mfma_f32_16x16x32_f16 v[90:93], v[140:143], v[156:159], v[90:93]
	v_mfma_f32_16x16x32_f16 v[82:85], v[148:151], v[156:159], v[82:85]
	v_mfma_f32_16x16x32_f16 v[74:77], v[140:143], v[168:171], v[74:77]
	v_mfma_f32_16x16x32_f16 v[66:69], v[148:151], v[168:171], v[66:69]
	v_mfma_f32_16x16x32_f16 v[58:61], v[140:143], v[176:179], v[58:61]
	v_mfma_f32_16x16x32_f16 v[50:53], v[148:151], v[176:179], v[50:53]
	v_mfma_f32_16x16x32_f16 v[42:45], v[140:143], v[184:187], v[42:45]
	v_mfma_f32_16x16x32_f16 v[34:37], v[148:151], v[184:187], v[34:37]
	v_mfma_f32_16x16x32_f16 v[90:93], v[144:147], v[164:167], v[90:93]
	v_mfma_f32_16x16x32_f16 v[82:85], v[152:155], v[164:167], v[82:85]
	v_mfma_f32_16x16x32_f16 v[74:77], v[144:147], v[172:175], v[74:77]
	v_mfma_f32_16x16x32_f16 v[66:69], v[152:155], v[172:175], v[66:69]
	v_mfma_f32_16x16x32_f16 v[58:61], v[144:147], v[180:183], v[58:61]
	v_mfma_f32_16x16x32_f16 v[50:53], v[152:155], v[180:183], v[50:53]
	v_mfma_f32_16x16x32_f16 v[42:45], v[144:147], v[188:191], v[42:45]
	v_mfma_f32_16x16x32_f16 v[34:37], v[152:155], v[188:191], v[34:37]
	v_mfma_f32_16x16x32_f16 v[30:33], v[192:195], v[156:159], v[30:33]
	v_mfma_f32_16x16x32_f16 v[26:29], v[200:203], v[156:159], v[26:29]
	v_mfma_f32_16x16x32_f16 v[22:25], v[192:195], v[168:171], v[22:25]
	v_mfma_f32_16x16x32_f16 v[18:21], v[200:203], v[168:171], v[18:21]
	v_mfma_f32_16x16x32_f16 v[14:17], v[192:195], v[176:179], v[14:17]
	v_mfma_f32_16x16x32_f16 v[10:13], v[200:203], v[176:179], v[10:13]
	v_mfma_f32_16x16x32_f16 v[6:9], v[192:195], v[184:187], v[6:9]
	v_mfma_f32_16x16x32_f16 v[2:5], v[200:203], v[184:187], v[2:5]
	v_mfma_f32_16x16x32_f16 v[30:33], v[196:199], v[164:167], v[30:33]
	v_mfma_f32_16x16x32_f16 v[26:29], v[204:207], v[164:167], v[26:29]
	v_mfma_f32_16x16x32_f16 v[22:25], v[196:199], v[172:175], v[22:25]
	v_mfma_f32_16x16x32_f16 v[18:21], v[204:207], v[172:175], v[18:21]
	v_mfma_f32_16x16x32_f16 v[14:17], v[196:199], v[180:183], v[14:17]
	v_mfma_f32_16x16x32_f16 v[10:13], v[204:207], v[180:183], v[10:13]
	v_mfma_f32_16x16x32_f16 v[6:9], v[196:199], v[188:191], v[6:9]
	v_mfma_f32_16x16x32_f16 v[2:5], v[204:207], v[188:191], v[2:5]
	s_barrier
	s_add_i32 s66, 0, 0x18000
	v_add_u32_e32 v234, s66, v161
	ds_read_b128 v[140:143], v234
	ds_read_b128 v[144:147], v234 offset:1024
	ds_read_b128 v[148:151], v234 offset:2048
	ds_read_b128 v[152:155], v234 offset:3072
	s_add_u32 s44, s48, 0x1c0000
	s_addc_u32 s45, s49, 0
	s_mov_b32 m0, s69
	v_lshl_add_u64 v[232:233], s[44:45], 0, v[130:131]
	ds_read_b128 v[156:159], v163 offset:32768
	ds_read_b128 v[164:167], v163 offset:33792
	ds_read_b128 v[168:171], v163 offset:34816
	ds_read_b128 v[172:175], v163 offset:35840
	ds_read_b128 v[176:179], v163 offset:36864
	ds_read_b128 v[180:183], v163 offset:37888
	ds_read_b128 v[184:187], v163 offset:38912
	ds_read_b128 v[188:191], v163 offset:39936
	global_load_lds_dwordx4 v[232:233], off
	v_lshl_add_u64 v[232:233], s[44:45], 0, v[132:133]
	s_mov_b32 m0, s70
	s_nop 0
	global_load_lds_dwordx4 v[232:233], off
	s_waitcnt lgkmcnt(11)
	s_add_i32 s48, 0, 0x1c000
	s_add_i32 s44, s66, s62
	v_add_u32_e32 v234, s48, v161
	v_lshl_add_u64 v[212:213], v[212:213], 0, s[92:93]
	s_mov_b32 m0, s44
	ds_read_b128 v[192:195], v234
	ds_read_b128 v[196:199], v234 offset:1024
	ds_read_b128 v[200:203], v234 offset:2048
	ds_read_b128 v[204:207], v234 offset:3072
	s_waitcnt lgkmcnt(0)
	s_barrier
	v_mfma_f32_16x16x32_f16 v[126:129], v[140:143], v[156:159], v[126:129]
	v_mfma_f32_16x16x32_f16 v[122:125], v[148:151], v[156:159], v[122:125]
	v_mfma_f32_16x16x32_f16 v[118:121], v[140:143], v[168:171], v[118:121]
	v_mfma_f32_16x16x32_f16 v[114:117], v[148:151], v[168:171], v[114:117]
	v_mfma_f32_16x16x32_f16 v[110:113], v[140:143], v[176:179], v[110:113]
	v_mfma_f32_16x16x32_f16 v[106:109], v[148:151], v[176:179], v[106:109]
	v_mfma_f32_16x16x32_f16 v[102:105], v[140:143], v[184:187], v[102:105]
	v_mfma_f32_16x16x32_f16 v[98:101], v[148:151], v[184:187], v[98:101]
	v_mfma_f32_16x16x32_f16 v[126:129], v[144:147], v[164:167], v[126:129]
	v_mfma_f32_16x16x32_f16 v[122:125], v[152:155], v[164:167], v[122:125]
	v_mfma_f32_16x16x32_f16 v[118:121], v[144:147], v[172:175], v[118:121]
	v_mfma_f32_16x16x32_f16 v[114:117], v[152:155], v[172:175], v[114:117]
	v_mfma_f32_16x16x32_f16 v[110:113], v[144:147], v[180:183], v[110:113]
	v_mfma_f32_16x16x32_f16 v[106:109], v[152:155], v[180:183], v[106:109]
	v_mfma_f32_16x16x32_f16 v[102:105], v[144:147], v[188:191], v[102:105]
	v_mfma_f32_16x16x32_f16 v[98:101], v[152:155], v[188:191], v[98:101]
	v_mfma_f32_16x16x32_f16 v[94:97], v[192:195], v[156:159], v[94:97]
	v_mfma_f32_16x16x32_f16 v[86:89], v[200:203], v[156:159], v[86:89]
	v_mfma_f32_16x16x32_f16 v[78:81], v[192:195], v[168:171], v[78:81]
	v_mfma_f32_16x16x32_f16 v[70:73], v[200:203], v[168:171], v[70:73]
	v_mfma_f32_16x16x32_f16 v[62:65], v[192:195], v[176:179], v[62:65]
	v_mfma_f32_16x16x32_f16 v[54:57], v[200:203], v[176:179], v[54:57]
	v_mfma_f32_16x16x32_f16 v[46:49], v[192:195], v[184:187], v[46:49]
	v_mfma_f32_16x16x32_f16 v[38:41], v[200:203], v[184:187], v[38:41]
	v_mfma_f32_16x16x32_f16 v[94:97], v[196:199], v[164:167], v[94:97]
	v_mfma_f32_16x16x32_f16 v[86:89], v[204:207], v[164:167], v[86:89]
	v_mfma_f32_16x16x32_f16 v[78:81], v[196:199], v[172:175], v[78:81]
	v_mfma_f32_16x16x32_f16 v[70:73], v[204:207], v[172:175], v[70:73]
	v_mfma_f32_16x16x32_f16 v[62:65], v[196:199], v[180:183], v[62:65]
	v_mfma_f32_16x16x32_f16 v[54:57], v[204:207], v[180:183], v[54:57]
	v_mfma_f32_16x16x32_f16 v[46:49], v[196:199], v[188:191], v[46:49]
	v_mfma_f32_16x16x32_f16 v[38:41], v[204:207], v[188:191], v[38:41]
	s_barrier
; __device__ __forceinline__ float sigmoidf_(float x) { return 1.0f / (1.0f + __expf(-x)); }
; #define PG8_STAGE(bufoff, gbase, voff) do { _Pragma("unroll") for (int _i = 0; _i < 2; ++_i) \
;         __builtin_amdgcn_global_load_lds((const unsigned*)((const char*)(gbase) + (voff)[_i]), (LAS unsigned*)(lds + (bufoff) + ldsw + _i * 8192), 16, 0, 0); } while (0)
; #define PG8_WAIT_V(n) asm volatile("s_waitcnt vmcnt(" #n ")" ::: "memory")
; template <class Epi, class AMap>
; __device__ __forceinline__ void gemm_phase(LAS unsigned char* lds, const AMap am, const int lda, const h16* Bt, const int ldb, const int M, const int N, const int K, const Epi& E) {
;     ...
;             PG8_LDA(At, 1, 1); PG8_STAGE(PG8_SA(1, 0), a3, voffA);
;             PG8_BAR; PG8_WAIT_L(0); PG8_MMA(1, 0, At, B0); PG8_BAR; PG8_SCHED;
;             PG8_STAGE(PG8_SB(1, 1), b3 + hstepB, voffB);
;             PG8_WAIT_V(6); PG8_BAR; PG8_MMA(1, 1, At, B1); PG8_BAR;
;         }
;     template <int GI>
;     __device__ __forceinline__ void body(const f32x4 (&acc)[2][2][4][2], int row0, int colt) const {
;     ...
;             f32x4 b0 = (f32x4){0.f, 0.f, 0.f, 0.f}, b1 = b0;
;             if (GI == 0) { b0 = *(const f32x4*)(w0 + c); b1 = *(const f32x4*)(w0 + c + 4); }
;             else if (GI == 1) { b0 = *(const f32x4*)(a0 + c); b1 = *(const f32x4*)(a0 + c + 4); }
;             else if (GI == 3) { b0 = *(const f32x4*)(v0 + c); b1 = *(const f32x4*)(v0 + c + 4); }
; #pragma unroll
;             for (int ai = 0; ai < 2; ++ai)
; #pragma unroll
;                 for (int m = 0; m < 4; ++m) {
;                     const size_t row = (size_t)(row0 + ai * 128 + m * 16);
;                     f32x4 x0 = acc[ai][bj][m][0] + b0, x1 = acc[ai][bj][m][1] + b1;
;                     if (GI == 0) {
; #pragma unroll
;                         for (int j = 0; j < 4; ++j) {
;                             x0[j] = 0.6065306597126334f * sigmoidf_(x0[j]); x1[j] = 0.6065306597126334f * sigmoidf_(x1[j]); }
;                         *(u32x4*)(DEC + row * DM + c) = pack8(x0, x1);
;                     } else if (GI == 1) {
; #pragma unroll
;                         for (int j = 0; j < 4; ++j) { x0[j] = sigmoidf_(x0[j]); x1[j] = sigmoidf_(x1[j]); }
;                         *(u32x4*)(Ab + row * DM + c) = pack8(x0, x1);
;                     } else if (GI == 2) {
;                         *(u32x4*)(Gb + row * DM + c) = pack8(x0, x1);
	global_load_lds_dwordx4 v[212:213], off
	v_lshl_add_u64 v[212:213], v[220:221], 0, s[92:93]
	s_add_i32 m0, s44, 0x2000
	s_nop 0
	global_load_lds_dwordx4 v[212:213], off
	s_mov_b32 m0, s71
	v_lshl_add_u64 v[212:213], v[222:223], 0, s[92:93]
	ds_read_b128 v[156:159], v163 offset:49152
	ds_read_b128 v[164:167], v163 offset:50176
	ds_read_b128 v[168:171], v163 offset:51200
	ds_read_b128 v[172:175], v163 offset:52224
	ds_read_b128 v[176:179], v163 offset:53248
	ds_read_b128 v[180:183], v163 offset:54272
	ds_read_b128 v[184:187], v163 offset:55296
	ds_read_b128 v[188:191], v163 offset:56320
	global_load_lds_dwordx4 v[212:213], off
	v_lshl_add_u64 v[212:213], v[224:225], 0, s[92:93]
	s_mov_b32 m0, s72
	s_nop 0
	global_load_lds_dwordx4 v[212:213], off
	s_add_u32 s44, s46, 0x10080
	s_addc_u32 s45, s47, 0
	s_add_i32 s46, s48, s62
	v_lshl_add_u64 v[232:233], s[44:45], 0, v[0:1]
	s_mov_b32 m0, s46
	s_nop 0
	global_load_lds_dwordx4 v[232:233], off
	v_lshl_add_u64 v[232:233], s[44:45], 0, v[134:135]
	s_add_i32 m0, s46, 0x2000
	s_nop 0
	global_load_lds_dwordx4 v[232:233], off
	s_waitcnt vmcnt(6) lgkmcnt(0)
	s_barrier
	v_mfma_f32_16x16x32_f16 v[90:93], v[140:143], v[156:159], v[90:93]
	v_mfma_f32_16x16x32_f16 v[82:85], v[148:151], v[156:159], v[82:85]
	v_mfma_f32_16x16x32_f16 v[74:77], v[140:143], v[168:171], v[74:77]
	v_mfma_f32_16x16x32_f16 v[66:69], v[148:151], v[168:171], v[66:69]
	v_mfma_f32_16x16x32_f16 v[58:61], v[140:143], v[176:179], v[58:61]
	v_mfma_f32_16x16x32_f16 v[50:53], v[148:151], v[176:179], v[50:53]
	v_mfma_f32_16x16x32_f16 v[42:45], v[140:143], v[184:187], v[42:45]
	v_mfma_f32_16x16x32_f16 v[34:37], v[148:151], v[184:187], v[34:37]
	v_mfma_f32_16x16x32_f16 v[90:93], v[144:147], v[164:167], v[90:93]
	v_mfma_f32_16x16x32_f16 v[82:85], v[152:155], v[164:167], v[82:85]
	v_mfma_f32_16x16x32_f16 v[74:77], v[144:147], v[172:175], v[74:77]
	v_mfma_f32_16x16x32_f16 v[66:69], v[152:155], v[172:175], v[66:69]
	v_mfma_f32_16x16x32_f16 v[58:61], v[144:147], v[180:183], v[58:61]
	v_mfma_f32_16x16x32_f16 v[50:53], v[152:155], v[180:183], v[50:53]
	v_mfma_f32_16x16x32_f16 v[42:45], v[144:147], v[188:191], v[42:45]
	v_mfma_f32_16x16x32_f16 v[34:37], v[152:155], v[188:191], v[34:37]
	v_mfma_f32_16x16x32_f16 v[30:33], v[192:195], v[156:159], v[30:33]
	v_mfma_f32_16x16x32_f16 v[26:29], v[200:203], v[156:159], v[26:29]
	v_mfma_f32_16x16x32_f16 v[22:25], v[192:195], v[168:171], v[22:25]
	v_mfma_f32_16x16x32_f16 v[18:21], v[200:203], v[168:171], v[18:21]
	v_mfma_f32_16x16x32_f16 v[14:17], v[192:195], v[176:179], v[14:17]
	v_mfma_f32_16x16x32_f16 v[10:13], v[200:203], v[176:179], v[10:13]
	v_mfma_f32_16x16x32_f16 v[6:9], v[192:195], v[184:187], v[6:9]
	v_mfma_f32_16x16x32_f16 v[2:5], v[200:203], v[184:187], v[2:5]
	v_mfma_f32_16x16x32_f16 v[30:33], v[196:199], v[164:167], v[30:33]
	v_mfma_f32_16x16x32_f16 v[26:29], v[204:207], v[164:167], v[26:29]
	v_mfma_f32_16x16x32_f16 v[22:25], v[196:199], v[172:175], v[22:25]
	v_mfma_f32_16x16x32_f16 v[18:21], v[204:207], v[172:175], v[18:21]
	v_mfma_f32_16x16x32_f16 v[14:17], v[196:199], v[180:183], v[14:17]
	v_mfma_f32_16x16x32_f16 v[10:13], v[204:207], v[180:183], v[10:13]
	v_mfma_f32_16x16x32_f16 v[6:9], v[196:199], v[188:191], v[6:9]
	v_mfma_f32_16x16x32_f16 v[2:5], v[204:207], v[188:191], v[2:5]
	s_add_u32 s27, s27, 0x100
	s_addc_u32 s29, s29, 0
	s_cmp_ge_i32 s60, s24
	s_mov_b64 s[44:45], s[0:1]
	s_mov_b32 s46, s60
	s_barrier
	s_cbranch_scc0 .LBB0_667
	v_pk_add_f32 v[128:129], v[128:129], 0 op_sel_hi:[1,0]
	v_pk_add_f32 v[126:127], v[126:127], 0 op_sel_hi:[1,0]
	v_pk_add_f32 v[124:125], v[124:125], 0 op_sel_hi:[1,0]
	v_pk_add_f32 v[122:123], v[122:123], 0 op_sel_hi:[1,0]
	v_pk_add_f32 v[120:121], v[120:121], 0 op_sel_hi:[1,0]
	v_pk_add_f32 v[118:119], v[118:119], 0 op_sel_hi:[1,0]
	v_pk_add_f32 v[116:117], v[116:117], 0 op_sel_hi:[1,0]
	v_pk_add_f32 v[114:115], v[114:115], 0 op_sel_hi:[1,0]
	v_pk_add_f32 v[112:113], v[112:113], 0 op_sel_hi:[1,0]
	v_pk_add_f32 v[110:111], v[110:111], 0 op_sel_hi:[1,0]
	v_pk_add_f32 v[108:109], v[108:109], 0 op_sel_hi:[1,0]
	v_pk_add_f32 v[106:107], v[106:107], 0 op_sel_hi:[1,0]
	v_pk_add_f32 v[104:105], v[104:105], 0 op_sel_hi:[1,0]
	v_pk_add_f32 v[102:103], v[102:103], 0 op_sel_hi:[1,0]
	v_pk_add_f32 v[100:101], v[100:101], 0 op_sel_hi:[1,0]
	v_pk_add_f32 v[98:99], v[98:99], 0 op_sel_hi:[1,0]
	v_pk_add_f32 v[92:93], v[92:93], 0 op_sel_hi:[1,0]
	v_pk_add_f32 v[90:91], v[90:91], 0 op_sel_hi:[1,0]
	v_pk_add_f32 v[144:145], v[84:85], 0 op_sel_hi:[1,0]
	v_pk_add_f32 v[152:153], v[82:83], 0 op_sel_hi:[1,0]
	v_pk_add_f32 v[76:77], v[76:77], 0 op_sel_hi:[1,0]
	v_pk_add_f32 v[84:85], v[74:75], 0 op_sel_hi:[1,0]
	v_pk_add_f32 v[146:147], v[68:69], 0 op_sel_hi:[1,0]
	v_pk_add_f32 v[154:155], v[66:67], 0 op_sel_hi:[1,0]
	v_pk_add_f32 v[74:75], v[60:61], 0 op_sel_hi:[1,0]
	v_pk_add_f32 v[140:141], v[58:59], 0 op_sel_hi:[1,0]
	v_pk_add_f32 v[148:149], v[52:53], 0 op_sel_hi:[1,0]
	v_pk_add_f32 v[156:157], v[50:51], 0 op_sel_hi:[1,0]
	v_pk_add_f32 v[82:83], v[44:45], 0 op_sel_hi:[1,0]
	v_pk_add_f32 v[142:143], v[42:43], 0 op_sel_hi:[1,0]
	v_pk_add_f32 v[150:151], v[36:37], 0 op_sel_hi:[1,0]
	v_pk_add_f32 v[158:159], v[34:35], 0 op_sel_hi:[1,0]
	v_pk_add_f32 v[34:35], v[96:97], 0 op_sel_hi:[1,0]
	v_pk_add_f32 v[36:37], v[94:95], 0 op_sel_hi:[1,0]
	v_pk_add_f32 v[50:51], v[88:89], 0 op_sel_hi:[1,0]
	v_pk_add_f32 v[52:53], v[86:87], 0 op_sel_hi:[1,0]
	v_pk_add_f32 v[42:43], v[80:81], 0 op_sel_hi:[1,0]
	v_pk_add_f32 v[44:45], v[78:79], 0 op_sel_hi:[1,0]
	v_pk_add_f32 v[66:67], v[72:73], 0 op_sel_hi:[1,0]
	v_pk_add_f32 v[68:69], v[70:71], 0 op_sel_hi:[1,0]
	v_pk_add_f32 v[58:59], v[64:65], 0 op_sel_hi:[1,0]
	v_pk_add_f32 v[60:61], v[62:63], 0 op_sel_hi:[1,0]
	v_pk_add_f32 v[56:57], v[56:57], 0 op_sel_hi:[1,0]
	v_pk_add_f32 v[54:55], v[54:55], 0 op_sel_hi:[1,0]
	v_pk_add_f32 v[48:49], v[48:49], 0 op_sel_hi:[1,0]
	v_pk_add_f32 v[46:47], v[46:47], 0 op_sel_hi:[1,0]
	v_pk_add_f32 v[40:41], v[40:41], 0 op_sel_hi:[1,0]
	v_pk_add_f32 v[38:39], v[38:39], 0 op_sel_hi:[1,0]
	v_pk_add_f32 v[32:33], v[32:33], 0 op_sel_hi:[1,0]
	v_pk_add_f32 v[30:31], v[30:31], 0 op_sel_hi:[1,0]
	v_pk_add_f32 v[28:29], v[28:29], 0 op_sel_hi:[1,0]
	v_pk_add_f32 v[26:27], v[26:27], 0 op_sel_hi:[1,0]
	v_pk_add_f32 v[24:25], v[24:25], 0 op_sel_hi:[1,0]
	v_pk_add_f32 v[22:23], v[22:23], 0 op_sel_hi:[1,0]
	v_pk_add_f32 v[20:21], v[20:21], 0 op_sel_hi:[1,0]
	v_pk_add_f32 v[18:19], v[18:19], 0 op_sel_hi:[1,0]
	v_pk_add_f32 v[16:17], v[16:17], 0 op_sel_hi:[1,0]
	v_pk_add_f32 v[14:15], v[14:15], 0 op_sel_hi:[1,0]
	v_pk_add_f32 v[12:13], v[12:13], 0 op_sel_hi:[1,0]
	v_pk_add_f32 v[10:11], v[10:11], 0 op_sel_hi:[1,0]
	v_pk_add_f32 v[8:9], v[8:9], 0 op_sel_hi:[1,0]
	v_pk_add_f32 v[6:7], v[6:7], 0 op_sel_hi:[1,0]
	v_pk_add_f32 v[4:5], v[4:5], 0 op_sel_hi:[1,0]
	v_pk_add_f32 v[2:3], v[2:3], 0 op_sel_hi:[1,0]
	s_movk_i32 s66, 0x80
	s_branch .LBB0_656

; #define PG8_STAGE(bufoff, gbase, voff) do { _Pragma("unroll") for (int _i = 0; _i < 2; ++_i) \
;         __builtin_amdgcn_global_load_lds((const unsigned*)((const char*)(gbase) + (voff)[_i]), (LAS unsigned*)(lds + (bufoff) + ldsw + _i * 8192), 16, 0, 0); } while (0)
; #define PG8_WAIT_V(n) asm volatile("s_waitcnt vmcnt(" #n ")" ::: "memory")
; #define PG8_BAR __builtin_amdgcn_s_barrier()
; template <class Epi, class AMap>
; __device__ __forceinline__ void gemm_phase(LAS unsigned char* lds, const AMap am, const int lda, const h16* Bt, const int ldb, const int M, const int N, const int K, const Epi& E) {
;     ...
;     const char* cA = am(cur.pn) + (size_t)cur.pm * tstepA; const char* cB = (const char*)Bt + (size_t)cur.pn * tstepB;
;     PG8_STAGE(PG8_SB(0, 0), cB, voffB); PG8_STAGE(PG8_SA(0, 0), cA, voffA); PG8_STAGE(PG8_SB(0, 1), cB + hstepB, voffB); PG8_STAGE(PG8_SA(0, 1), cA + hstepA, voffA);
;     if (wr == 1) PG8_BAR;
;     PG8_WAIT_V(4); PG8_BAR;
;     PG8_STAGE(PG8_SB(1, 0), cB + kstep, voffB); PG8_STAGE(PG8_SA(1, 0), cA + kstep, voffA); PG8_STAGE(PG8_SB(1, 1), cB + hstepB + kstep, voffB);
;     PG8_WAIT_V(6); PG8_BAR;
.LBB0_680:
	v_lshrrev_b32_e32 v20, 1, v18
	v_and_b32_e32 v20, 24, v20
	v_and_b32_e32 v19, 15, v18
	v_lshlrev_b32_e32 v21, 1, v20
	v_lshlrev_b32_e32 v18, 2, v18
	s_sext_i32_i8 s50, s0
	v_lshl_or_b32 v174, s20, 6, v19
	v_lshl_or_b32 v19, v19, 6, v21
	s_lshl_b32 s0, s20, 13
	v_and_b32_e32 v18, 32, v18
	v_bitop3_b32 v21, v19, s0, v18 bitop3:0xde
	s_lshl_b32 s0, s1, 5
	s_and_b32 s20, s0, 0x60
	s_lshl_b32 s0, s20, 7
	v_bitop3_b32 v175, v19, s0, v18 bitop3:0xde
	v_readlane_b32 s0, v255, 7
	v_readlane_b32 s1, v255, 8
	s_mov_b32 s1, s25
	s_lshl_b64 s[0:1], s[0:1], 11
	s_add_u32 s21, s0, 0xfffff800
	s_addc_u32 s29, s1, -1
	s_and_b64 s[0:1], s[82:83], exec
	s_cselect_b32 s1, 0, s29
	s_cselect_b32 s0, 0, s21
	v_readlane_b32 s4, v251, 37
	s_lshl_b64 s[0:1], s[0:1], 2
	v_readlane_b32 s10, v251, 43
	v_readlane_b32 s11, v251, 44
	s_add_u32 s40, s10, s0
	s_addc_u32 s41, s11, s1
	s_add_i32 m0, s74, 0x18000
	v_lshl_add_u64 v[8:9], v[8:9], 0, s[92:93]
	s_waitcnt vmcnt(0)
	s_barrier
	global_load_lds_dwordx4 v[8:9], off
	v_lshl_add_u64 v[6:7], v[6:7], 0, s[92:93]
	s_add_i32 m0, s74, 0x1a000
	s_add_i32 s79, s74, 0x8000
	s_add_i32 s80, s74, 0xa000
	global_load_lds_dwordx4 v[6:7], off
	v_lshl_add_u64 v[4:5], v[4:5], 0, s[92:93]
	s_mov_b32 m0, s79
	s_add_u32 s0, s26, 0x10080
	global_load_lds_dwordx4 v[4:5], off
	v_lshl_add_u64 v[2:3], v[2:3], 0, s[92:93]
	s_mov_b32 m0, s80
	s_addc_u32 s1, s27, 0
	global_load_lds_dwordx4 v[2:3], off
	s_add_i32 m0, s74, 0x1c000
	v_lshl_add_u64 v[2:3], s[0:1], 0, v[0:1]
	global_load_lds_dwordx4 v[2:3], off
	v_lshl_add_u64 v[2:3], s[0:1], 0, v[150:151]
	s_add_i32 m0, s74, 0x1e000
	v_readlane_b32 s5, v251, 38
	global_load_lds_dwordx4 v[2:3], off
	s_movk_i32 s5, 0x1c00
	v_lshrrev_b32_e32 v3, 1, v10
	v_mul_lo_u32 v2, v12, s5
	s_mov_b32 s4, 0x1c000
	v_mad_u64_u32 v[2:3], s[0:1], v3, s4, v[2:3]
	v_readlane_b32 s6, v251, 39
	v_readlane_b32 s7, v251, 40
	v_or_b32_e32 v2, v2, v11
	v_add_lshl_u32 v2, v2, v13, 1
	v_mov_b32_e32 v3, v1
	s_mov_b64 s[6:7], 0x1c0080
	v_lshl_add_u64 v[152:153], v[2:3], 0, s[6:7]
	v_lshrrev_b32_e32 v3, 1, v14
	v_mul_lo_u32 v2, v16, s5
	v_mad_u64_u32 v[2:3], s[0:1], v3, s4, v[2:3]
	v_readlane_b32 s8, v251, 41
	v_readlane_b32 s9, v251, 42
	s_waitcnt vmcnt(6)
	v_or_b32_e32 v2, v2, v15
	v_readlane_b32 s12, v251, 45
	v_readlane_b32 s13, v251, 46
	s_cmp_gt_i32 s61, 63
	v_add_lshl_u32 v2, v2, v17, 1
	v_mov_b32_e32 v3, v1
	v_readlane_b32 s8, v254, 58
	s_mov_b32 s78, 0
	s_cselect_b64 s[42:43], -1, 0
	s_add_i32 s61, s24, -2
	v_or_b32_e32 v176, s20, v20
	v_lshl_add_u64 v[154:155], v[2:3], 0, s[6:7]
	v_add_u32_e32 v177, 0, v21
	v_readlane_b32 s9, v254, 59
	v_readlane_b32 s12, v254, 62
	s_movk_i32 s5, 0x3800
	s_movk_i32 s13, 0x2b00
	v_readlane_b32 s14, v251, 47
	v_readlane_b32 s15, v251, 48
	v_readlane_b32 s16, v251, 49
	v_readlane_b32 s17, v251, 50
	v_readlane_b32 s18, v251, 51
	v_readlane_b32 s19, v251, 52
	s_barrier
	s_branch .LBB0_682

; #define PG8_STAGE(bufoff, gbase, voff) do { _Pragma("unroll") for (int _i = 0; _i < 2; ++_i) \
;         __builtin_amdgcn_global_load_lds((const unsigned*)((const char*)(gbase) + (voff)[_i]), (LAS unsigned*)(lds + (bufoff) + ldsw + _i * 8192), 16, 0, 0); } while (0)
; #define PG8_LDA(dst, b, h) do { _Pragma("unroll") for (int m = 0; m < 4; ++m) _Pragma("unroll") for (int k = 0; k < 2; ++k) dst[m][k] = *(const LAS h16x8*)(lds + PG8_SA(b, h) + aoff + m * 2048 + k * 1024); } while (0)
; #define PG8_LDB(dst, b, h) do { _Pragma("unroll") for (int n = 0; n < 2; ++n) _Pragma("unroll") for (int k = 0; k < 2; ++k) dst[n][k] = *(const LAS h16x8*)(lds + PG8_SB(b, h) + boff + n * 2048 + k * 1024); } while (0)
; #define PG8_MMA(ai, bj, At, Bt_) do { __builtin_amdgcn_s_setprio(1); _Pragma("unroll") for (int m = 0; m < 4; ++m) _Pragma("unroll") for (int n = 0; n < 2; ++n) _Pragma("unroll") for (int k = 0; k < 2; ++k) \
;         acc[ai][bj][m][n] = __builtin_amdgcn_mfma_f32_16x16x32_f16(Bt_[n][k], At[m][k], acc[ai][bj][m][n], 0, 0, 0); __builtin_amdgcn_s_setprio(0); } while (0)
; #define PG8_WAIT_V(n) asm volatile("s_waitcnt vmcnt(" #n ")" ::: "memory")
; template <class Epi, class AMap>
; __device__ __forceinline__ void gemm_phase(LAS unsigned char* lds, const AMap am, const int lda, const h16* Bt, const int ldb, const int M, const int N, const int K, const Epi& E) {
;     ...
;         for (int t = 0; t < nt; t += 2) {
;             const bool last = (t == nt - 2);
;             const char* a1 = cA + (size_t)(t + 1) * kstep;
;             const char* a2 = last ? nA : cA + (size_t)(t + 2) * kstep; const char* b2 = last ? nB : cB + (size_t)(t + 2) * kstep;
;             const char* a3 = a2 + kstep; const char* b3 = b2 + kstep;
;             PG8_LDB(B0, 0, 0); PG8_SCHED; PG8_LDA(At, 0, 0); PG8_STAGE(PG8_SA(1, 1), a1 + hstepA, voffA);
;             PG8_WAIT_L(8); PG8_BAR; PG8_WAIT_L(0); PG8_MMA(0, 0, At, B0); PG8_BAR; PG8_SCHED;
;             PG8_LDB(B1, 0, 1); PG8_STAGE(PG8_SB(0, 0), b2, voffB);
;             PG8_BAR; PG8_WAIT_L(0); PG8_MMA(0, 1, At, B1); PG8_BAR;
;             PG8_LDA(At, 0, 1); PG8_STAGE(PG8_SA(0, 0), a2, voffA);
;             PG8_BAR; PG8_WAIT_L(0); PG8_MMA(1, 0, At, B0); PG8_BAR; PG8_SCHED;
;             PG8_STAGE(PG8_SB(0, 1), b2 + hstepB, voffB);
;             PG8_WAIT_V(6); PG8_BAR; PG8_MMA(1, 1, At, B1); PG8_BAR;
.LBB0_692:
	s_add_i32 s51, s26, 2
	s_add_u32 s0, s22, 0x100
	s_addc_u32 s1, s23, 0
	s_add_i32 s60, 0, 0x10000
	v_add_u32_e32 v234, s60, v175
	ds_read_b128 v[82:85], v234
	ds_read_b128 v[86:89], v234 offset:1024
	ds_read_b128 v[138:141], v234 offset:2048
	ds_read_b128 v[142:145], v234 offset:3072
	s_cmp_eq_u32 s61, s26
	s_cselect_b32 s26, s21, s29
	s_cselect_b32 s49, s47, s1
	s_cselect_b32 s48, s46, s0
	s_cselect_b32 s27, s20, s45
	v_lshl_add_u64 v[172:173], s[22:23], 0, v[152:153]
	s_add_i32 m0, s74, 0xc000
	ds_read_b128 v[156:159], v177
	ds_read_b128 v[160:163], v177 offset:1024
	ds_read_b128 v[164:167], v177 offset:2048
	ds_read_b128 v[168:171], v177 offset:3072
	ds_read_b128 v[178:181], v177 offset:4096
	ds_read_b128 v[182:185], v177 offset:5120
	ds_read_b128 v[186:189], v177 offset:6144
	ds_read_b128 v[190:193], v177 offset:7168
	global_load_lds_dwordx4 v[172:173], off
	v_lshl_add_u64 v[172:173], s[22:23], 0, v[154:155]
	s_add_i32 m0, s74, 0xe000
	s_nop 0
	global_load_lds_dwordx4 v[172:173], off
	s_waitcnt lgkmcnt(11)
	s_add_i32 s62, 0, 0x14000
	v_add_u32_e32 v172, s62, v175
	s_add_i32 s22, s60, s71
	ds_read_b128 v[194:197], v172
	ds_read_b128 v[198:201], v172 offset:1024
	ds_read_b128 v[202:205], v172 offset:2048
	ds_read_b128 v[220:223], v172 offset:3072
	s_waitcnt lgkmcnt(0)
	s_barrier
	v_mfma_f32_16x16x32_f16 v[134:137], v[82:85], v[156:159], v[134:137]
	v_mfma_f32_16x16x32_f16 v[130:133], v[138:141], v[156:159], v[130:133]
	v_mfma_f32_16x16x32_f16 v[126:129], v[82:85], v[164:167], v[126:129]
	v_mfma_f32_16x16x32_f16 v[122:125], v[138:141], v[164:167], v[122:125]
	v_mfma_f32_16x16x32_f16 v[118:121], v[82:85], v[178:181], v[118:121]
	v_mfma_f32_16x16x32_f16 v[114:117], v[138:141], v[178:181], v[114:117]
	v_mfma_f32_16x16x32_f16 v[110:113], v[82:85], v[186:189], v[110:113]
	v_mfma_f32_16x16x32_f16 v[106:109], v[138:141], v[186:189], v[106:109]
	v_mfma_f32_16x16x32_f16 v[134:137], v[86:89], v[160:163], v[134:137]
	v_mfma_f32_16x16x32_f16 v[130:133], v[142:145], v[160:163], v[130:133]
	v_mfma_f32_16x16x32_f16 v[126:129], v[86:89], v[168:171], v[126:129]
	v_mfma_f32_16x16x32_f16 v[122:125], v[142:145], v[168:171], v[122:125]
	v_mfma_f32_16x16x32_f16 v[118:121], v[86:89], v[182:185], v[118:121]
	v_mfma_f32_16x16x32_f16 v[114:117], v[142:145], v[182:185], v[114:117]
	v_mfma_f32_16x16x32_f16 v[110:113], v[86:89], v[190:193], v[110:113]
	v_mfma_f32_16x16x32_f16 v[106:109], v[142:145], v[190:193], v[106:109]
	v_mfma_f32_16x16x32_f16 v[62:65], v[194:197], v[156:159], v[62:65]
	v_mfma_f32_16x16x32_f16 v[58:61], v[202:205], v[156:159], v[58:61]
	v_mfma_f32_16x16x32_f16 v[54:57], v[194:197], v[164:167], v[54:57]
	v_mfma_f32_16x16x32_f16 v[50:53], v[202:205], v[164:167], v[50:53]
	v_mfma_f32_16x16x32_f16 v[46:49], v[194:197], v[178:181], v[46:49]
	v_mfma_f32_16x16x32_f16 v[42:45], v[202:205], v[178:181], v[42:45]
	v_mfma_f32_16x16x32_f16 v[38:41], v[194:197], v[186:189], v[38:41]
	v_mfma_f32_16x16x32_f16 v[34:37], v[202:205], v[186:189], v[34:37]
	v_mfma_f32_16x16x32_f16 v[62:65], v[198:201], v[160:163], v[62:65]
	v_mfma_f32_16x16x32_f16 v[58:61], v[220:223], v[160:163], v[58:61]
	v_mfma_f32_16x16x32_f16 v[54:57], v[198:201], v[168:171], v[54:57]
	v_mfma_f32_16x16x32_f16 v[50:53], v[220:223], v[168:171], v[50:53]
	v_mfma_f32_16x16x32_f16 v[46:49], v[198:201], v[182:185], v[46:49]
	v_mfma_f32_16x16x32_f16 v[42:45], v[220:223], v[182:185], v[42:45]
	v_mfma_f32_16x16x32_f16 v[38:41], v[198:201], v[190:193], v[38:41]
	v_mfma_f32_16x16x32_f16 v[34:37], v[220:223], v[190:193], v[34:37]
	s_barrier
	v_lshl_add_u64 v[172:173], s[26:27], 0, v[0:1]
	s_mov_b32 m0, s22
	v_lshl_add_u64 v[206:207], s[26:27], 0, v[150:151]
	global_load_lds_dwordx4 v[172:173], off
	s_add_i32 m0, s22, 0x2000
	s_nop 0
	global_load_lds_dwordx4 v[206:207], off
	s_mov_b32 m0, s74
	v_lshl_add_u64 v[212:213], s[48:49], 0, v[146:147]
	ds_read_b128 v[156:159], v177 offset:16384
	ds_read_b128 v[160:163], v177 offset:17408
	ds_read_b128 v[164:167], v177 offset:18432
	ds_read_b128 v[168:171], v177 offset:19456
	ds_read_b128 v[178:181], v177 offset:20480
	ds_read_b128 v[182:185], v177 offset:21504
	ds_read_b128 v[186:189], v177 offset:22528
	ds_read_b128 v[190:193], v177 offset:23552
	global_load_lds_dwordx4 v[212:213], off
	v_lshl_add_u64 v[224:225], s[48:49], 0, v[148:149]
	s_mov_b32 m0, s75
	s_nop 0
	global_load_lds_dwordx4 v[224:225], off
	s_add_u32 s22, s26, 0x10000
	s_addc_u32 s23, s27, 0
	s_add_i32 s60, s62, s71
	v_lshl_add_u64 v[232:233], s[22:23], 0, v[0:1]
	s_mov_b32 m0, s60
	s_nop 0
	global_load_lds_dwordx4 v[232:233], off
	v_lshl_add_u64 v[232:233], s[22:23], 0, v[150:151]
	s_add_i32 m0, s60, 0x2000
	s_nop 0
	global_load_lds_dwordx4 v[232:233], off
	s_waitcnt vmcnt(6) lgkmcnt(0)
	s_barrier
; #define PG8_STAGE(bufoff, gbase, voff) do { _Pragma("unroll") for (int _i = 0; _i < 2; ++_i) \
;         __builtin_amdgcn_global_load_lds((const unsigned*)((const char*)(gbase) + (voff)[_i]), (LAS unsigned*)(lds + (bufoff) + ldsw + _i * 8192), 16, 0, 0); } while (0)
; #define PG8_LDA(dst, b, h) do { _Pragma("unroll") for (int m = 0; m < 4; ++m) _Pragma("unroll") for (int k = 0; k < 2; ++k) dst[m][k] = *(const LAS h16x8*)(lds + PG8_SA(b, h) + aoff + m * 2048 + k * 1024); } while (0)
; #define PG8_LDB(dst, b, h) do { _Pragma("unroll") for (int n = 0; n < 2; ++n) _Pragma("unroll") for (int k = 0; k < 2; ++k) dst[n][k] = *(const LAS h16x8*)(lds + PG8_SB(b, h) + boff + n * 2048 + k * 1024); } while (0)
; #define PG8_MMA(ai, bj, At, Bt_) do { __builtin_amdgcn_s_setprio(1); _Pragma("unroll") for (int m = 0; m < 4; ++m) _Pragma("unroll") for (int n = 0; n < 2; ++n) _Pragma("unroll") for (int k = 0; k < 2; ++k) \
;         acc[ai][bj][m][n] = __builtin_amdgcn_mfma_f32_16x16x32_f16(Bt_[n][k], At[m][k], acc[ai][bj][m][n], 0, 0, 0); __builtin_amdgcn_s_setprio(0); } while (0)
; #define PG8_WAIT_V(n) asm volatile("s_waitcnt vmcnt(" #n ")" ::: "memory")
; #define PG8_WAIT_L(n) asm volatile("s_waitcnt lgkmcnt(" #n ")" ::: "memory")
; #define PG8_BAR __builtin_amdgcn_s_barrier()
; #define PG8_SCHED __builtin_amdgcn_sched_barrier(0)
; template <class Epi, class AMap>
; __device__ __forceinline__ void gemm_phase(LAS unsigned char* lds, const AMap am, const int lda, const h16* Bt, const int ldb, const int M, const int N, const int K, const Epi& E) {
;     ...
;             PG8_BAR; PG8_WAIT_L(0); PG8_MMA(1, 0, At, B0); PG8_BAR; PG8_SCHED;
;             PG8_STAGE(PG8_SB(0, 1), b2 + hstepB, voffB);
;             PG8_WAIT_V(6); PG8_BAR; PG8_MMA(1, 1, At, B1); PG8_BAR;
;             PG8_LDB(B0, 1, 0); PG8_SCHED; PG8_LDA(At, 1, 0); PG8_STAGE(PG8_SA(0, 1), a2 + hstepA, voffA);
;             PG8_WAIT_L(8); PG8_BAR; PG8_WAIT_L(0); PG8_MMA(0, 0, At, B0); PG8_BAR; PG8_SCHED;
;             PG8_LDB(B1, 1, 1); PG8_STAGE(PG8_SB(1, 0), b3, voffB);
;             PG8_BAR; PG8_WAIT_L(0); PG8_MMA(0, 1, At, B1); PG8_BAR;
;             PG8_LDA(At, 1, 1); PG8_STAGE(PG8_SA(1, 0), a3, voffA);
;             PG8_BAR; PG8_WAIT_L(0); PG8_MMA(1, 0, At, B0); PG8_BAR; PG8_SCHED;
	v_mfma_f32_16x16x32_f16 v[102:105], v[82:85], v[156:159], v[102:105]
	v_mfma_f32_16x16x32_f16 v[98:101], v[138:141], v[156:159], v[98:101]
	v_mfma_f32_16x16x32_f16 v[94:97], v[82:85], v[164:167], v[94:97]
	v_mfma_f32_16x16x32_f16 v[90:93], v[138:141], v[164:167], v[90:93]
	v_mfma_f32_16x16x32_f16 v[78:81], v[82:85], v[178:181], v[78:81]
	v_mfma_f32_16x16x32_f16 v[74:77], v[138:141], v[178:181], v[74:77]
	v_mfma_f32_16x16x32_f16 v[70:73], v[82:85], v[186:189], v[70:73]
	v_mfma_f32_16x16x32_f16 v[66:69], v[138:141], v[186:189], v[66:69]
	v_mfma_f32_16x16x32_f16 v[102:105], v[86:89], v[160:163], v[102:105]
	v_mfma_f32_16x16x32_f16 v[98:101], v[142:145], v[160:163], v[98:101]
	v_mfma_f32_16x16x32_f16 v[94:97], v[86:89], v[168:171], v[94:97]
	v_mfma_f32_16x16x32_f16 v[90:93], v[142:145], v[168:171], v[90:93]
	v_mfma_f32_16x16x32_f16 v[78:81], v[86:89], v[182:185], v[78:81]
	v_mfma_f32_16x16x32_f16 v[74:77], v[142:145], v[182:185], v[74:77]
	v_mfma_f32_16x16x32_f16 v[70:73], v[86:89], v[190:193], v[70:73]
	v_mfma_f32_16x16x32_f16 v[66:69], v[142:145], v[190:193], v[66:69]
	v_mfma_f32_16x16x32_f16 v[30:33], v[194:197], v[156:159], v[30:33]
	v_mfma_f32_16x16x32_f16 v[26:29], v[202:205], v[156:159], v[26:29]
	v_mfma_f32_16x16x32_f16 v[22:25], v[194:197], v[164:167], v[22:25]
	v_mfma_f32_16x16x32_f16 v[18:21], v[202:205], v[164:167], v[18:21]
	v_mfma_f32_16x16x32_f16 v[14:17], v[194:197], v[178:181], v[14:17]
	v_mfma_f32_16x16x32_f16 v[10:13], v[202:205], v[178:181], v[10:13]
	v_mfma_f32_16x16x32_f16 v[6:9], v[194:197], v[186:189], v[6:9]
	v_mfma_f32_16x16x32_f16 v[2:5], v[202:205], v[186:189], v[2:5]
	v_mfma_f32_16x16x32_f16 v[30:33], v[198:201], v[160:163], v[30:33]
	v_mfma_f32_16x16x32_f16 v[26:29], v[220:223], v[160:163], v[26:29]
	v_mfma_f32_16x16x32_f16 v[22:25], v[198:201], v[168:171], v[22:25]
	v_mfma_f32_16x16x32_f16 v[18:21], v[220:223], v[168:171], v[18:21]
	v_mfma_f32_16x16x32_f16 v[14:17], v[198:201], v[182:185], v[14:17]
	v_mfma_f32_16x16x32_f16 v[10:13], v[220:223], v[182:185], v[10:13]
	v_mfma_f32_16x16x32_f16 v[6:9], v[198:201], v[190:193], v[6:9]
	v_mfma_f32_16x16x32_f16 v[2:5], v[220:223], v[190:193], v[2:5]
	s_barrier
	s_add_i32 s60, 0, 0x18000
	v_add_u32_e32 v234, s60, v175
	ds_read_b128 v[82:85], v234
	ds_read_b128 v[86:89], v234 offset:1024
	ds_read_b128 v[138:141], v234 offset:2048
	ds_read_b128 v[142:145], v234 offset:3072
	s_add_u32 s22, s48, 0x1c0000
	s_addc_u32 s23, s49, 0
	s_mov_b32 m0, s76
	v_lshl_add_u64 v[232:233], s[22:23], 0, v[146:147]
	ds_read_b128 v[156:159], v177 offset:32768
	ds_read_b128 v[160:163], v177 offset:33792
	ds_read_b128 v[164:167], v177 offset:34816
	ds_read_b128 v[168:171], v177 offset:35840
	ds_read_b128 v[178:181], v177 offset:36864
	ds_read_b128 v[182:185], v177 offset:37888
	ds_read_b128 v[186:189], v177 offset:38912
	ds_read_b128 v[190:193], v177 offset:39936
	global_load_lds_dwordx4 v[232:233], off
	v_lshl_add_u64 v[232:233], s[22:23], 0, v[148:149]
	s_mov_b32 m0, s77
	s_nop 0
	global_load_lds_dwordx4 v[232:233], off
	s_waitcnt lgkmcnt(11)
	s_add_i32 s48, 0, 0x1c000
	s_add_i32 s22, s60, s71
	v_add_u32_e32 v214, s48, v175
	v_lshl_add_u64 v[172:173], v[172:173], 0, s[92:93]
	s_mov_b32 m0, s22
	ds_read_b128 v[194:197], v214
	ds_read_b128 v[198:201], v214 offset:1024
	ds_read_b128 v[202:205], v214 offset:2048
	ds_read_b128 v[220:223], v214 offset:3072
	s_waitcnt lgkmcnt(0)
	s_barrier
	v_mfma_f32_16x16x32_f16 v[134:137], v[82:85], v[156:159], v[134:137]
	v_mfma_f32_16x16x32_f16 v[130:133], v[138:141], v[156:159], v[130:133]
	v_mfma_f32_16x16x32_f16 v[126:129], v[82:85], v[164:167], v[126:129]
	v_mfma_f32_16x16x32_f16 v[122:125], v[138:141], v[164:167], v[122:125]
	v_mfma_f32_16x16x32_f16 v[118:121], v[82:85], v[178:181], v[118:121]
	v_mfma_f32_16x16x32_f16 v[114:117], v[138:141], v[178:181], v[114:117]
	v_mfma_f32_16x16x32_f16 v[110:113], v[82:85], v[186:189], v[110:113]
	v_mfma_f32_16x16x32_f16 v[106:109], v[138:141], v[186:189], v[106:109]
	v_mfma_f32_16x16x32_f16 v[134:137], v[86:89], v[160:163], v[134:137]
	v_mfma_f32_16x16x32_f16 v[130:133], v[142:145], v[160:163], v[130:133]
	v_mfma_f32_16x16x32_f16 v[126:129], v[86:89], v[168:171], v[126:129]
	v_mfma_f32_16x16x32_f16 v[122:125], v[142:145], v[168:171], v[122:125]
	v_mfma_f32_16x16x32_f16 v[118:121], v[86:89], v[182:185], v[118:121]
	v_mfma_f32_16x16x32_f16 v[114:117], v[142:145], v[182:185], v[114:117]
	v_mfma_f32_16x16x32_f16 v[110:113], v[86:89], v[190:193], v[110:113]
	v_mfma_f32_16x16x32_f16 v[106:109], v[142:145], v[190:193], v[106:109]
	v_mfma_f32_16x16x32_f16 v[62:65], v[194:197], v[156:159], v[62:65]
	v_mfma_f32_16x16x32_f16 v[58:61], v[202:205], v[156:159], v[58:61]
	v_mfma_f32_16x16x32_f16 v[54:57], v[194:197], v[164:167], v[54:57]
	v_mfma_f32_16x16x32_f16 v[50:53], v[202:205], v[164:167], v[50:53]
	v_mfma_f32_16x16x32_f16 v[46:49], v[194:197], v[178:181], v[46:49]
	v_mfma_f32_16x16x32_f16 v[42:45], v[202:205], v[178:181], v[42:45]
	v_mfma_f32_16x16x32_f16 v[38:41], v[194:197], v[186:189], v[38:41]
	v_mfma_f32_16x16x32_f16 v[34:37], v[202:205], v[186:189], v[34:37]
	v_mfma_f32_16x16x32_f16 v[62:65], v[198:201], v[160:163], v[62:65]
	v_mfma_f32_16x16x32_f16 v[58:61], v[220:223], v[160:163], v[58:61]
	v_mfma_f32_16x16x32_f16 v[54:57], v[198:201], v[168:171], v[54:57]
	v_mfma_f32_16x16x32_f16 v[50:53], v[220:223], v[168:171], v[50:53]
	v_mfma_f32_16x16x32_f16 v[46:49], v[198:201], v[182:185], v[46:49]
	v_mfma_f32_16x16x32_f16 v[42:45], v[220:223], v[182:185], v[42:45]
	v_mfma_f32_16x16x32_f16 v[38:41], v[198:201], v[190:193], v[38:41]
	v_mfma_f32_16x16x32_f16 v[34:37], v[220:223], v[190:193], v[34:37]
	s_barrier
; #define PG8_STAGE(bufoff, gbase, voff) do { _Pragma("unroll") for (int _i = 0; _i < 2; ++_i) \
;         __builtin_amdgcn_global_load_lds((const unsigned*)((const char*)(gbase) + (voff)[_i]), (LAS unsigned*)(lds + (bufoff) + ldsw + _i * 8192), 16, 0, 0); } while (0)
; #define PG8_LDA(dst, b, h) do { _Pragma("unroll") for (int m = 0; m < 4; ++m) _Pragma("unroll") for (int k = 0; k < 2; ++k) dst[m][k] = *(const LAS h16x8*)(lds + PG8_SA(b, h) + aoff + m * 2048 + k * 1024); } while (0)
; #define PG8_MMA(ai, bj, At, Bt_) do { __builtin_amdgcn_s_setprio(1); _Pragma("unroll") for (int m = 0; m < 4; ++m) _Pragma("unroll") for (int n = 0; n < 2; ++n) _Pragma("unroll") for (int k = 0; k < 2; ++k) \
;         acc[ai][bj][m][n] = __builtin_amdgcn_mfma_f32_16x16x32_f16(Bt_[n][k], At[m][k], acc[ai][bj][m][n], 0, 0, 0); __builtin_amdgcn_s_setprio(0); } while (0)
; #define PG8_WAIT_V(n) asm volatile("s_waitcnt vmcnt(" #n ")" ::: "memory")
; #define PG8_WAIT_L(n) asm volatile("s_waitcnt lgkmcnt(" #n ")" ::: "memory")
; #define PG8_BAR __builtin_amdgcn_s_barrier()
; #define PG8_SCHED __builtin_amdgcn_sched_barrier(0)
; template <class Epi, class AMap>
; __device__ __forceinline__ void gemm_phase(LAS unsigned char* lds, const AMap am, const int lda, const h16* Bt, const int ldb, const int M, const int N, const int K, const Epi& E) {
;     ...
;             PG8_LDA(At, 1, 1); PG8_STAGE(PG8_SA(1, 0), a3, voffA);
;             PG8_BAR; PG8_WAIT_L(0); PG8_MMA(1, 0, At, B0); PG8_BAR; PG8_SCHED;
;             PG8_STAGE(PG8_SB(1, 1), b3 + hstepB, voffB);
;             PG8_WAIT_V(6); PG8_BAR; PG8_MMA(1, 1, At, B1); PG8_BAR;
;         }
	global_load_lds_dwordx4 v[172:173], off
	v_lshl_add_u64 v[172:173], v[206:207], 0, s[92:93]
	s_add_i32 m0, s22, 0x2000
	s_nop 0
	global_load_lds_dwordx4 v[172:173], off
	s_mov_b32 m0, s79
	v_lshl_add_u64 v[172:173], v[212:213], 0, s[92:93]
	ds_read_b128 v[156:159], v177 offset:49152
	ds_read_b128 v[160:163], v177 offset:50176
	ds_read_b128 v[164:167], v177 offset:51200
	ds_read_b128 v[168:171], v177 offset:52224
	ds_read_b128 v[178:181], v177 offset:53248
	ds_read_b128 v[182:185], v177 offset:54272
	ds_read_b128 v[186:189], v177 offset:55296
	ds_read_b128 v[190:193], v177 offset:56320
	global_load_lds_dwordx4 v[172:173], off
	v_lshl_add_u64 v[172:173], v[224:225], 0, s[92:93]
	s_mov_b32 m0, s80
	s_nop 0
	global_load_lds_dwordx4 v[172:173], off
	s_add_u32 s22, s26, 0x10080
	s_addc_u32 s23, s27, 0
	s_add_i32 s26, s48, s71
	v_lshl_add_u64 v[232:233], s[22:23], 0, v[0:1]
	s_mov_b32 m0, s26
	s_nop 0
	global_load_lds_dwordx4 v[232:233], off
	v_lshl_add_u64 v[232:233], s[22:23], 0, v[150:151]
	s_add_i32 m0, s26, 0x2000
	s_nop 0
	global_load_lds_dwordx4 v[232:233], off
	s_waitcnt vmcnt(6) lgkmcnt(0)
	s_barrier
	v_mfma_f32_16x16x32_f16 v[102:105], v[82:85], v[156:159], v[102:105]
	v_mfma_f32_16x16x32_f16 v[98:101], v[138:141], v[156:159], v[98:101]
	v_mfma_f32_16x16x32_f16 v[94:97], v[82:85], v[164:167], v[94:97]
	v_mfma_f32_16x16x32_f16 v[90:93], v[138:141], v[164:167], v[90:93]
	v_mfma_f32_16x16x32_f16 v[78:81], v[82:85], v[178:181], v[78:81]
	v_mfma_f32_16x16x32_f16 v[74:77], v[138:141], v[178:181], v[74:77]
	v_mfma_f32_16x16x32_f16 v[70:73], v[82:85], v[186:189], v[70:73]
	v_mfma_f32_16x16x32_f16 v[66:69], v[138:141], v[186:189], v[66:69]
	v_mfma_f32_16x16x32_f16 v[102:105], v[86:89], v[160:163], v[102:105]
	v_mfma_f32_16x16x32_f16 v[98:101], v[142:145], v[160:163], v[98:101]
	v_mfma_f32_16x16x32_f16 v[94:97], v[86:89], v[168:171], v[94:97]
	v_mfma_f32_16x16x32_f16 v[90:93], v[142:145], v[168:171], v[90:93]
	v_mfma_f32_16x16x32_f16 v[78:81], v[86:89], v[182:185], v[78:81]
	v_mfma_f32_16x16x32_f16 v[74:77], v[142:145], v[182:185], v[74:77]
	v_mfma_f32_16x16x32_f16 v[70:73], v[86:89], v[190:193], v[70:73]
	v_mfma_f32_16x16x32_f16 v[66:69], v[142:145], v[190:193], v[66:69]
	v_mfma_f32_16x16x32_f16 v[30:33], v[194:197], v[156:159], v[30:33]
	v_mfma_f32_16x16x32_f16 v[26:29], v[202:205], v[156:159], v[26:29]
	v_mfma_f32_16x16x32_f16 v[22:25], v[194:197], v[164:167], v[22:25]
	v_mfma_f32_16x16x32_f16 v[18:21], v[202:205], v[164:167], v[18:21]
	v_mfma_f32_16x16x32_f16 v[14:17], v[194:197], v[178:181], v[14:17]
	v_mfma_f32_16x16x32_f16 v[10:13], v[202:205], v[178:181], v[10:13]
	v_mfma_f32_16x16x32_f16 v[6:9], v[194:197], v[186:189], v[6:9]
	v_mfma_f32_16x16x32_f16 v[2:5], v[202:205], v[186:189], v[2:5]
	v_mfma_f32_16x16x32_f16 v[30:33], v[198:201], v[160:163], v[30:33]
	v_mfma_f32_16x16x32_f16 v[26:29], v[220:223], v[160:163], v[26:29]
	v_mfma_f32_16x16x32_f16 v[22:25], v[198:201], v[168:171], v[22:25]
	v_mfma_f32_16x16x32_f16 v[18:21], v[220:223], v[168:171], v[18:21]
	v_mfma_f32_16x16x32_f16 v[14:17], v[198:201], v[182:185], v[14:17]
	v_mfma_f32_16x16x32_f16 v[10:13], v[220:223], v[182:185], v[10:13]
	v_mfma_f32_16x16x32_f16 v[6:9], v[198:201], v[190:193], v[6:9]
	v_mfma_f32_16x16x32_f16 v[2:5], v[220:223], v[190:193], v[2:5]
	s_add_u32 s29, s29, 0x100
	s_addc_u32 s45, s45, 0
	s_cmp_ge_i32 s51, s24
	s_mov_b64 s[22:23], s[0:1]
	s_mov_b32 s26, s51
	s_barrier
	s_cbranch_scc0 .LBB0_692
	s_branch .LBB0_681

; #define PG8_STAGE(bufoff, gbase, voff) do { _Pragma("unroll") for (int _i = 0; _i < 2; ++_i) \
;         __builtin_amdgcn_global_load_lds((const unsigned*)((const char*)(gbase) + (voff)[_i]), (LAS unsigned*)(lds + (bufoff) + ldsw + _i * 8192), 16, 0, 0); } while (0)
; #define PG8_WAIT_V(n) asm volatile("s_waitcnt vmcnt(" #n ")" ::: "memory")
; #define PG8_BAR __builtin_amdgcn_s_barrier()
; template <class Epi, class AMap>
; __device__ __forceinline__ void gemm_phase(LAS unsigned char* lds, const AMap am, const int lda, const h16* Bt, const int ldb, const int M, const int N, const int K, const Epi& E) {
;     ...
;     const char* cA = am(cur.pn) + (size_t)cur.pm * tstepA; const char* cB = (const char*)Bt + (size_t)cur.pn * tstepB;
;     PG8_STAGE(PG8_SB(0, 0), cB, voffB); PG8_STAGE(PG8_SA(0, 0), cA, voffA); PG8_STAGE(PG8_SB(0, 1), cB + hstepB, voffB); PG8_STAGE(PG8_SA(0, 1), cA + hstepA, voffA);
;     if (wr == 1) PG8_BAR;
;     PG8_WAIT_V(4); PG8_BAR;
;     PG8_STAGE(PG8_SB(1, 0), cB + kstep, voffB); PG8_STAGE(PG8_SA(1, 0), cA + kstep, voffA); PG8_STAGE(PG8_SB(1, 1), cB + hstepB + kstep, voffB);
;     PG8_WAIT_V(6); PG8_BAR;
.LBB0_780:
	v_lshrrev_b32_e32 v18, 1, v2
	v_and_b32_e32 v18, 24, v18
	v_and_b32_e32 v9, 15, v2
	v_lshlrev_b32_e32 v19, 1, v18
	v_lshlrev_b32_e32 v2, 2, v2
	v_lshl_or_b32 v154, s20, 6, v9
	v_lshl_or_b32 v9, v9, 6, v19
	s_lshl_b32 s0, s20, 13
	v_and_b32_e32 v2, 32, v2
	v_lshl_add_u64 v[10:11], s[40:41], 0, v[0:1]
	v_mov_b32_e32 v143, v1
	v_bitop3_b32 v19, v9, s0, v2 bitop3:0xde
	s_lshl_b32 s0, s21, 5
	v_lshl_add_u64 v[12:13], s[40:41], 0, v[142:143]
	v_mov_b32_e32 v139, v1
	s_and_b32 s20, s0, 0x60
	s_add_i32 m0, s23, 0x18000
	v_lshl_add_u64 v[10:11], v[10:11], 0, s[92:93]
	v_lshl_add_u64 v[14:15], s[48:49], 0, v[138:139]
	v_mov_b32_e32 v141, v1
	s_lshl_b32 s0, s20, 7
	s_waitcnt vmcnt(0)
	s_barrier
	global_load_lds_dwordx4 v[10:11], off
	v_lshl_add_u64 v[10:11], v[12:13], 0, s[92:93]
	s_add_i32 m0, s23, 0x1a000
	s_add_i32 s75, s23, 0x8000
	s_add_i32 s76, s23, 0xa000
	v_lshl_add_u64 v[16:17], s[48:49], 0, v[140:141]
	v_bitop3_b32 v155, v9, s0, v2 bitop3:0xde
	global_load_lds_dwordx4 v[10:11], off
	v_lshl_add_u64 v[10:11], v[14:15], 0, s[92:93]
	s_mov_b32 m0, s75
	s_add_u32 s0, s40, 0x80080
	global_load_lds_dwordx4 v[10:11], off
	v_lshl_add_u64 v[10:11], v[16:17], 0, s[92:93]
	s_mov_b32 m0, s76
	s_addc_u32 s1, s41, 0
	global_load_lds_dwordx4 v[10:11], off
	s_add_i32 m0, s23, 0x1c000
	v_lshl_add_u64 v[10:11], s[0:1], 0, v[0:1]
	global_load_lds_dwordx4 v[10:11], off
	v_lshl_add_u64 v[10:11], s[0:1], 0, v[142:143]
	s_add_i32 m0, s23, 0x1e000
	v_cvt_f32_ubyte0_e32 v2, s68
	global_load_lds_dwordx4 v[10:11], off
	v_rcp_iflag_f32_e32 v2, v2
	s_sub_i32 s0, 0, s68
	s_waitcnt vmcnt(6)
	v_or_b32_e32 v156, s20, v18
	v_mul_f32_e32 v2, 0x4f7ffffe, v2
	v_cvt_u32_f32_e32 v2, v2
	s_mov_b32 s77, 0
	v_mov_b32_e32 v145, v1
	v_mov_b32_e32 v147, v1
	v_readfirstlane_b32 s1, v2
	v_lshlrev_b32_e32 v2, 15, v3
	v_and_b32_e32 v2, 0xffff0000, v2
	v_lshl_add_u32 v2, v4, 12, v2
	v_and_b32_e32 v3, 1, v3
	v_lshl_or_b32 v2, v3, 6, v2
	v_lshl_add_u32 v144, v5, 1, v2
	v_lshlrev_b32_e32 v2, 15, v6
	v_and_b32_e32 v2, 0xffff0000, v2
	s_mul_i32 s0, s0, s1
	v_lshl_add_u32 v2, v7, 12, v2
	v_and_b32_e32 v3, 1, v6
	s_mul_hi_u32 s0, s1, s0
	v_lshl_or_b32 v2, v3, 6, v2
	s_add_i32 s78, s1, s0
	v_lshl_add_u32 v146, v8, 1, v2
	v_add_u32_e32 v157, 0, v19
	s_barrier
	s_branch .LBB0_782

; #define PG8_STAGE(bufoff, gbase, voff) do { _Pragma("unroll") for (int _i = 0; _i < 2; ++_i) \
;         __builtin_amdgcn_global_load_lds((const unsigned*)((const char*)(gbase) + (voff)[_i]), (LAS unsigned*)(lds + (bufoff) + ldsw + _i * 8192), 16, 0, 0); } while (0)
; #define PG8_LDA(dst, b, h) do { _Pragma("unroll") for (int m = 0; m < 4; ++m) _Pragma("unroll") for (int k = 0; k < 2; ++k) dst[m][k] = *(const LAS h16x8*)(lds + PG8_SA(b, h) + aoff + m * 2048 + k * 1024); } while (0)
; #define PG8_LDB(dst, b, h) do { _Pragma("unroll") for (int n = 0; n < 2; ++n) _Pragma("unroll") for (int k = 0; k < 2; ++k) dst[n][k] = *(const LAS h16x8*)(lds + PG8_SB(b, h) + boff + n * 2048 + k * 1024); } while (0)
; #define PG8_MMA(ai, bj, At, Bt_) do { __builtin_amdgcn_s_setprio(1); _Pragma("unroll") for (int m = 0; m < 4; ++m) _Pragma("unroll") for (int n = 0; n < 2; ++n) _Pragma("unroll") for (int k = 0; k < 2; ++k) \
;         acc[ai][bj][m][n] = __builtin_amdgcn_mfma_f32_16x16x32_f16(Bt_[n][k], At[m][k], acc[ai][bj][m][n], 0, 0, 0); __builtin_amdgcn_s_setprio(0); } while (0)
; #define PG8_WAIT_V(n) asm volatile("s_waitcnt vmcnt(" #n ")" ::: "memory")
; template <class Epi, class AMap>
; __device__ __forceinline__ void gemm_phase(LAS unsigned char* lds, const AMap am, const int lda, const h16* Bt, const int ldb, const int M, const int N, const int K, const Epi& E) {
;     ...
;         for (int t = 0; t < nt; t += 2) {
;             const bool last = (t == nt - 2);
;             const char* a1 = cA + (size_t)(t + 1) * kstep;
;             const char* a2 = last ? nA : cA + (size_t)(t + 2) * kstep; const char* b2 = last ? nB : cB + (size_t)(t + 2) * kstep;
;             const char* a3 = a2 + kstep; const char* b3 = b2 + kstep;
;             PG8_LDB(B0, 0, 0); PG8_SCHED; PG8_LDA(At, 0, 0); PG8_STAGE(PG8_SA(1, 1), a1 + hstepA, voffA);
;             PG8_WAIT_L(8); PG8_BAR; PG8_WAIT_L(0); PG8_MMA(0, 0, At, B0); PG8_BAR; PG8_SCHED;
;             PG8_LDB(B1, 0, 1); PG8_STAGE(PG8_SB(0, 0), b2, voffB);
;             PG8_BAR; PG8_WAIT_L(0); PG8_MMA(0, 1, At, B1); PG8_BAR;
;             PG8_LDA(At, 0, 1); PG8_STAGE(PG8_SA(0, 0), a2, voffA);
;             PG8_BAR; PG8_WAIT_L(0); PG8_MMA(1, 0, At, B0); PG8_BAR; PG8_SCHED;
;             PG8_STAGE(PG8_SB(0, 1), b2 + hstepB, voffB);
;             PG8_WAIT_V(6); PG8_BAR; PG8_MMA(1, 1, At, B1); PG8_BAR;
.LBB0_799:
	s_add_u32 s40, s0, 0xfff80080
	s_addc_u32 s41, s1, -1
	s_add_i32 s45, 0, 0x10000
	v_add_u32_e32 v152, s45, v155
	ds_read_b128 v[130:133], v152
	ds_read_b128 v[134:137], v152 offset:1024
	ds_read_b128 v[148:151], v152 offset:2048
	ds_read_b128 v[158:161], v152 offset:3072
	s_cmp_eq_u32 s43, 28
	s_cselect_b32 s49, s47, s41
	s_cselect_b32 s48, s46, s40
	s_cselect_b32 s41, s29, s35
	s_cselect_b32 s40, s20, s21
	v_lshl_add_u64 v[152:153], s[0:1], 0, v[144:145]
	s_add_i32 m0, s23, 0xc000
	ds_read_b128 v[162:165], v157
	ds_read_b128 v[166:169], v157 offset:1024
	ds_read_b128 v[170:173], v157 offset:2048
	ds_read_b128 v[174:177], v157 offset:3072
	ds_read_b128 v[178:181], v157 offset:4096
	ds_read_b128 v[182:185], v157 offset:5120
	ds_read_b128 v[186:189], v157 offset:6144
	ds_read_b128 v[190:193], v157 offset:7168
	global_load_lds_dwordx4 v[152:153], off
	v_lshl_add_u64 v[152:153], s[0:1], 0, v[146:147]
	s_add_i32 m0, s23, 0xe000
	s_nop 0
	global_load_lds_dwordx4 v[152:153], off
	s_waitcnt lgkmcnt(11)
	s_add_i32 s60, 0, 0x14000
	v_add_u32_e32 v152, s60, v155
	s_add_i32 s45, s45, s72
	ds_read_b128 v[194:197], v152
	ds_read_b128 v[198:201], v152 offset:1024
	ds_read_b128 v[202:205], v152 offset:2048
	ds_read_b128 v[220:223], v152 offset:3072
	s_waitcnt lgkmcnt(0)
	s_barrier
	v_mfma_f32_16x16x32_f16 v[126:129], v[130:133], v[162:165], v[126:129]
	v_mfma_f32_16x16x32_f16 v[122:125], v[148:151], v[162:165], v[122:125]
	v_mfma_f32_16x16x32_f16 v[110:113], v[130:133], v[170:173], v[110:113]
	v_mfma_f32_16x16x32_f16 v[106:109], v[148:151], v[170:173], v[106:109]
	v_mfma_f32_16x16x32_f16 v[94:97], v[130:133], v[178:181], v[94:97]
	v_mfma_f32_16x16x32_f16 v[90:93], v[148:151], v[178:181], v[90:93]
	v_mfma_f32_16x16x32_f16 v[78:81], v[130:133], v[186:189], v[78:81]
	v_mfma_f32_16x16x32_f16 v[74:77], v[148:151], v[186:189], v[74:77]
	v_mfma_f32_16x16x32_f16 v[126:129], v[134:137], v[166:169], v[126:129]
	v_mfma_f32_16x16x32_f16 v[122:125], v[158:161], v[166:169], v[122:125]
	v_mfma_f32_16x16x32_f16 v[110:113], v[134:137], v[174:177], v[110:113]
	v_mfma_f32_16x16x32_f16 v[106:109], v[158:161], v[174:177], v[106:109]
	v_mfma_f32_16x16x32_f16 v[94:97], v[134:137], v[182:185], v[94:97]
	v_mfma_f32_16x16x32_f16 v[90:93], v[158:161], v[182:185], v[90:93]
	v_mfma_f32_16x16x32_f16 v[78:81], v[134:137], v[190:193], v[78:81]
	v_mfma_f32_16x16x32_f16 v[74:77], v[158:161], v[190:193], v[74:77]
	v_mfma_f32_16x16x32_f16 v[118:121], v[194:197], v[162:165], v[118:121]
	v_mfma_f32_16x16x32_f16 v[114:117], v[202:205], v[162:165], v[114:117]
	v_mfma_f32_16x16x32_f16 v[102:105], v[194:197], v[170:173], v[102:105]
	v_mfma_f32_16x16x32_f16 v[98:101], v[202:205], v[170:173], v[98:101]
	v_mfma_f32_16x16x32_f16 v[86:89], v[194:197], v[178:181], v[86:89]
	v_mfma_f32_16x16x32_f16 v[82:85], v[202:205], v[178:181], v[82:85]
	v_mfma_f32_16x16x32_f16 v[70:73], v[194:197], v[186:189], v[70:73]
	v_mfma_f32_16x16x32_f16 v[66:69], v[202:205], v[186:189], v[66:69]
	v_mfma_f32_16x16x32_f16 v[118:121], v[198:201], v[166:169], v[118:121]
	v_mfma_f32_16x16x32_f16 v[114:117], v[220:223], v[166:169], v[114:117]
	v_mfma_f32_16x16x32_f16 v[102:105], v[198:201], v[174:177], v[102:105]
	v_mfma_f32_16x16x32_f16 v[98:101], v[220:223], v[174:177], v[98:101]
	v_mfma_f32_16x16x32_f16 v[86:89], v[198:201], v[182:185], v[86:89]
	v_mfma_f32_16x16x32_f16 v[82:85], v[220:223], v[182:185], v[82:85]
	v_mfma_f32_16x16x32_f16 v[70:73], v[198:201], v[190:193], v[70:73]
	v_mfma_f32_16x16x32_f16 v[66:69], v[220:223], v[190:193], v[66:69]
	s_barrier
	v_lshl_add_u64 v[152:153], s[40:41], 0, v[0:1]
	s_mov_b32 m0, s45
	v_lshl_add_u64 v[206:207], s[40:41], 0, v[142:143]
	global_load_lds_dwordx4 v[152:153], off
	s_add_i32 m0, s45, 0x2000
	s_nop 0
	global_load_lds_dwordx4 v[206:207], off
	s_mov_b32 m0, s23
	v_lshl_add_u64 v[212:213], s[48:49], 0, v[138:139]
	ds_read_b128 v[162:165], v157 offset:16384
	ds_read_b128 v[166:169], v157 offset:17408
	ds_read_b128 v[170:173], v157 offset:18432
	ds_read_b128 v[174:177], v157 offset:19456
	ds_read_b128 v[178:181], v157 offset:20480
	ds_read_b128 v[182:185], v157 offset:21504
	ds_read_b128 v[186:189], v157 offset:22528
	ds_read_b128 v[190:193], v157 offset:23552
	global_load_lds_dwordx4 v[212:213], off
	v_lshl_add_u64 v[224:225], s[48:49], 0, v[140:141]
	s_mov_b32 m0, s27
	s_nop 0
	global_load_lds_dwordx4 v[224:225], off
	s_add_u32 s50, s40, 0x80000
	s_addc_u32 s51, s41, 0
	s_add_i32 s45, s60, s72
	v_lshl_add_u64 v[232:233], s[50:51], 0, v[0:1]
	s_mov_b32 m0, s45
	s_nop 0
	global_load_lds_dwordx4 v[232:233], off
	v_lshl_add_u64 v[232:233], s[50:51], 0, v[142:143]
	s_add_i32 m0, s45, 0x2000
	s_nop 0
	global_load_lds_dwordx4 v[232:233], off
	s_waitcnt vmcnt(6) lgkmcnt(0)
	s_barrier
; #define PG8_STAGE(bufoff, gbase, voff) do { _Pragma("unroll") for (int _i = 0; _i < 2; ++_i) \
;         __builtin_amdgcn_global_load_lds((const unsigned*)((const char*)(gbase) + (voff)[_i]), (LAS unsigned*)(lds + (bufoff) + ldsw + _i * 8192), 16, 0, 0); } while (0)
; #define PG8_LDA(dst, b, h) do { _Pragma("unroll") for (int m = 0; m < 4; ++m) _Pragma("unroll") for (int k = 0; k < 2; ++k) dst[m][k] = *(const LAS h16x8*)(lds + PG8_SA(b, h) + aoff + m * 2048 + k * 1024); } while (0)
; #define PG8_LDB(dst, b, h) do { _Pragma("unroll") for (int n = 0; n < 2; ++n) _Pragma("unroll") for (int k = 0; k < 2; ++k) dst[n][k] = *(const LAS h16x8*)(lds + PG8_SB(b, h) + boff + n * 2048 + k * 1024); } while (0)
; #define PG8_MMA(ai, bj, At, Bt_) do { __builtin_amdgcn_s_setprio(1); _Pragma("unroll") for (int m = 0; m < 4; ++m) _Pragma("unroll") for (int n = 0; n < 2; ++n) _Pragma("unroll") for (int k = 0; k < 2; ++k) \
;         acc[ai][bj][m][n] = __builtin_amdgcn_mfma_f32_16x16x32_f16(Bt_[n][k], At[m][k], acc[ai][bj][m][n], 0, 0, 0); __builtin_amdgcn_s_setprio(0); } while (0)
; #define PG8_WAIT_V(n) asm volatile("s_waitcnt vmcnt(" #n ")" ::: "memory")
; #define PG8_WAIT_L(n) asm volatile("s_waitcnt lgkmcnt(" #n ")" ::: "memory")
; #define PG8_BAR __builtin_amdgcn_s_barrier()
; #define PG8_SCHED __builtin_amdgcn_sched_barrier(0)
; template <class Epi, class AMap>
; __device__ __forceinline__ void gemm_phase(LAS unsigned char* lds, const AMap am, const int lda, const h16* Bt, const int ldb, const int M, const int N, const int K, const Epi& E) {
;     ...
;             PG8_BAR; PG8_WAIT_L(0); PG8_MMA(1, 0, At, B0); PG8_BAR; PG8_SCHED;
;             PG8_STAGE(PG8_SB(0, 1), b2 + hstepB, voffB);
;             PG8_WAIT_V(6); PG8_BAR; PG8_MMA(1, 1, At, B1); PG8_BAR;
;             PG8_LDB(B0, 1, 0); PG8_SCHED; PG8_LDA(At, 1, 0); PG8_STAGE(PG8_SA(0, 1), a2 + hstepA, voffA);
;             PG8_WAIT_L(8); PG8_BAR; PG8_WAIT_L(0); PG8_MMA(0, 0, At, B0); PG8_BAR; PG8_SCHED;
;             PG8_LDB(B1, 1, 1); PG8_STAGE(PG8_SB(1, 0), b3, voffB);
;             PG8_BAR; PG8_WAIT_L(0); PG8_MMA(0, 1, At, B1); PG8_BAR;
;             PG8_LDA(At, 1, 1); PG8_STAGE(PG8_SA(1, 0), a3, voffA);
;             PG8_BAR; PG8_WAIT_L(0); PG8_MMA(1, 0, At, B0); PG8_BAR; PG8_SCHED;
	v_mfma_f32_16x16x32_f16 v[62:65], v[130:133], v[162:165], v[62:65]
	v_mfma_f32_16x16x32_f16 v[58:61], v[148:151], v[162:165], v[58:61]
	v_mfma_f32_16x16x32_f16 v[46:49], v[130:133], v[170:173], v[46:49]
	v_mfma_f32_16x16x32_f16 v[42:45], v[148:151], v[170:173], v[42:45]
	v_mfma_f32_16x16x32_f16 v[30:33], v[130:133], v[178:181], v[30:33]
	v_mfma_f32_16x16x32_f16 v[26:29], v[148:151], v[178:181], v[26:29]
	v_mfma_f32_16x16x32_f16 v[14:17], v[130:133], v[186:189], v[14:17]
	v_mfma_f32_16x16x32_f16 v[10:13], v[148:151], v[186:189], v[10:13]
	v_mfma_f32_16x16x32_f16 v[62:65], v[134:137], v[166:169], v[62:65]
	v_mfma_f32_16x16x32_f16 v[58:61], v[158:161], v[166:169], v[58:61]
	v_mfma_f32_16x16x32_f16 v[46:49], v[134:137], v[174:177], v[46:49]
	v_mfma_f32_16x16x32_f16 v[42:45], v[158:161], v[174:177], v[42:45]
	v_mfma_f32_16x16x32_f16 v[30:33], v[134:137], v[182:185], v[30:33]
	v_mfma_f32_16x16x32_f16 v[26:29], v[158:161], v[182:185], v[26:29]
	v_mfma_f32_16x16x32_f16 v[14:17], v[134:137], v[190:193], v[14:17]
	v_mfma_f32_16x16x32_f16 v[10:13], v[158:161], v[190:193], v[10:13]
	v_mfma_f32_16x16x32_f16 v[54:57], v[194:197], v[162:165], v[54:57]
	v_mfma_f32_16x16x32_f16 v[50:53], v[202:205], v[162:165], v[50:53]
	v_mfma_f32_16x16x32_f16 v[38:41], v[194:197], v[170:173], v[38:41]
	v_mfma_f32_16x16x32_f16 v[34:37], v[202:205], v[170:173], v[34:37]
	v_mfma_f32_16x16x32_f16 v[22:25], v[194:197], v[178:181], v[22:25]
	v_mfma_f32_16x16x32_f16 v[18:21], v[202:205], v[178:181], v[18:21]
	v_mfma_f32_16x16x32_f16 v[6:9], v[194:197], v[186:189], v[6:9]
	v_mfma_f32_16x16x32_f16 v[2:5], v[202:205], v[186:189], v[2:5]
	v_mfma_f32_16x16x32_f16 v[54:57], v[198:201], v[166:169], v[54:57]
	v_mfma_f32_16x16x32_f16 v[50:53], v[220:223], v[166:169], v[50:53]
	v_mfma_f32_16x16x32_f16 v[38:41], v[198:201], v[174:177], v[38:41]
	v_mfma_f32_16x16x32_f16 v[34:37], v[220:223], v[174:177], v[34:37]
	v_mfma_f32_16x16x32_f16 v[22:25], v[198:201], v[182:185], v[22:25]
	v_mfma_f32_16x16x32_f16 v[18:21], v[220:223], v[182:185], v[18:21]
	v_mfma_f32_16x16x32_f16 v[6:9], v[198:201], v[190:193], v[6:9]
	v_mfma_f32_16x16x32_f16 v[2:5], v[220:223], v[190:193], v[2:5]
	s_barrier
	s_add_i32 s45, 0, 0x18000
	v_add_u32_e32 v234, s45, v155
	ds_read_b128 v[130:133], v234
	ds_read_b128 v[134:137], v234 offset:1024
	ds_read_b128 v[148:151], v234 offset:2048
	ds_read_b128 v[158:161], v234 offset:3072
	s_add_u32 s48, s48, 0x80000
	s_addc_u32 s49, s49, 0
	s_mov_b32 m0, s73
	v_lshl_add_u64 v[232:233], s[48:49], 0, v[138:139]
	ds_read_b128 v[162:165], v157 offset:32768
	ds_read_b128 v[166:169], v157 offset:33792
	ds_read_b128 v[170:173], v157 offset:34816
	ds_read_b128 v[174:177], v157 offset:35840
	ds_read_b128 v[178:181], v157 offset:36864
	ds_read_b128 v[182:185], v157 offset:37888
	ds_read_b128 v[186:189], v157 offset:38912
	ds_read_b128 v[190:193], v157 offset:39936
	global_load_lds_dwordx4 v[232:233], off
	v_lshl_add_u64 v[232:233], s[48:49], 0, v[140:141]
	s_mov_b32 m0, s74
	s_nop 0
	global_load_lds_dwordx4 v[232:233], off
	s_waitcnt lgkmcnt(11)
	s_add_i32 s48, 0, 0x1c000
	s_add_i32 s45, s45, s72
	v_add_u32_e32 v214, s48, v155
	v_lshl_add_u64 v[152:153], v[152:153], 0, s[92:93]
	s_mov_b32 m0, s45
	ds_read_b128 v[194:197], v214
	ds_read_b128 v[198:201], v214 offset:1024
	ds_read_b128 v[202:205], v214 offset:2048
	ds_read_b128 v[220:223], v214 offset:3072
	s_waitcnt lgkmcnt(0)
	s_barrier
	v_mfma_f32_16x16x32_f16 v[126:129], v[130:133], v[162:165], v[126:129]
	v_mfma_f32_16x16x32_f16 v[122:125], v[148:151], v[162:165], v[122:125]
	v_mfma_f32_16x16x32_f16 v[110:113], v[130:133], v[170:173], v[110:113]
	v_mfma_f32_16x16x32_f16 v[106:109], v[148:151], v[170:173], v[106:109]
	v_mfma_f32_16x16x32_f16 v[94:97], v[130:133], v[178:181], v[94:97]
	v_mfma_f32_16x16x32_f16 v[90:93], v[148:151], v[178:181], v[90:93]
	v_mfma_f32_16x16x32_f16 v[78:81], v[130:133], v[186:189], v[78:81]
	v_mfma_f32_16x16x32_f16 v[74:77], v[148:151], v[186:189], v[74:77]
	v_mfma_f32_16x16x32_f16 v[126:129], v[134:137], v[166:169], v[126:129]
	v_mfma_f32_16x16x32_f16 v[122:125], v[158:161], v[166:169], v[122:125]
	v_mfma_f32_16x16x32_f16 v[110:113], v[134:137], v[174:177], v[110:113]
	v_mfma_f32_16x16x32_f16 v[106:109], v[158:161], v[174:177], v[106:109]
	v_mfma_f32_16x16x32_f16 v[94:97], v[134:137], v[182:185], v[94:97]
	v_mfma_f32_16x16x32_f16 v[90:93], v[158:161], v[182:185], v[90:93]
	v_mfma_f32_16x16x32_f16 v[78:81], v[134:137], v[190:193], v[78:81]
	v_mfma_f32_16x16x32_f16 v[74:77], v[158:161], v[190:193], v[74:77]
	v_mfma_f32_16x16x32_f16 v[118:121], v[194:197], v[162:165], v[118:121]
	v_mfma_f32_16x16x32_f16 v[114:117], v[202:205], v[162:165], v[114:117]
	v_mfma_f32_16x16x32_f16 v[102:105], v[194:197], v[170:173], v[102:105]
	v_mfma_f32_16x16x32_f16 v[98:101], v[202:205], v[170:173], v[98:101]
	v_mfma_f32_16x16x32_f16 v[86:89], v[194:197], v[178:181], v[86:89]
	v_mfma_f32_16x16x32_f16 v[82:85], v[202:205], v[178:181], v[82:85]
	v_mfma_f32_16x16x32_f16 v[70:73], v[194:197], v[186:189], v[70:73]
	v_mfma_f32_16x16x32_f16 v[66:69], v[202:205], v[186:189], v[66:69]
	v_mfma_f32_16x16x32_f16 v[118:121], v[198:201], v[166:169], v[118:121]
	v_mfma_f32_16x16x32_f16 v[114:117], v[220:223], v[166:169], v[114:117]
	v_mfma_f32_16x16x32_f16 v[102:105], v[198:201], v[174:177], v[102:105]
	v_mfma_f32_16x16x32_f16 v[98:101], v[220:223], v[174:177], v[98:101]
	v_mfma_f32_16x16x32_f16 v[86:89], v[198:201], v[182:185], v[86:89]
	v_mfma_f32_16x16x32_f16 v[82:85], v[220:223], v[182:185], v[82:85]
	v_mfma_f32_16x16x32_f16 v[70:73], v[198:201], v[190:193], v[70:73]
	v_mfma_f32_16x16x32_f16 v[66:69], v[220:223], v[190:193], v[66:69]
	s_barrier
; #define PG8_STAGE(bufoff, gbase, voff) do { _Pragma("unroll") for (int _i = 0; _i < 2; ++_i) \
;         __builtin_amdgcn_global_load_lds((const unsigned*)((const char*)(gbase) + (voff)[_i]), (LAS unsigned*)(lds + (bufoff) + ldsw + _i * 8192), 16, 0, 0); } while (0)
; #define PG8_LDA(dst, b, h) do { _Pragma("unroll") for (int m = 0; m < 4; ++m) _Pragma("unroll") for (int k = 0; k < 2; ++k) dst[m][k] = *(const LAS h16x8*)(lds + PG8_SA(b, h) + aoff + m * 2048 + k * 1024); } while (0)
; #define PG8_MMA(ai, bj, At, Bt_) do { __builtin_amdgcn_s_setprio(1); _Pragma("unroll") for (int m = 0; m < 4; ++m) _Pragma("unroll") for (int n = 0; n < 2; ++n) _Pragma("unroll") for (int k = 0; k < 2; ++k) \
;         acc[ai][bj][m][n] = __builtin_amdgcn_mfma_f32_16x16x32_f16(Bt_[n][k], At[m][k], acc[ai][bj][m][n], 0, 0, 0); __builtin_amdgcn_s_setprio(0); } while (0)
; #define PG8_WAIT_V(n) asm volatile("s_waitcnt vmcnt(" #n ")" ::: "memory")
; #define PG8_WAIT_L(n) asm volatile("s_waitcnt lgkmcnt(" #n ")" ::: "memory")
; #define PG8_BAR __builtin_amdgcn_s_barrier()
; #define PG8_SCHED __builtin_amdgcn_sched_barrier(0)
; template <class Epi, class AMap>
; __device__ __forceinline__ void gemm_phase(LAS unsigned char* lds, const AMap am, const int lda, const h16* Bt, const int ldb, const int M, const int N, const int K, const Epi& E) {
;     ...
;             PG8_LDA(At, 1, 1); PG8_STAGE(PG8_SA(1, 0), a3, voffA);
;             PG8_BAR; PG8_WAIT_L(0); PG8_MMA(1, 0, At, B0); PG8_BAR; PG8_SCHED;
;             PG8_STAGE(PG8_SB(1, 1), b3 + hstepB, voffB);
;             PG8_WAIT_V(6); PG8_BAR; PG8_MMA(1, 1, At, B1); PG8_BAR;
;         }
;     __device__ __forceinline__ void operator()(const f32x4 (&acc)[2][2][4][2], const Unit& u, int wr, int wc, int fr, int fq) const {
;     ...
;         const int mode = u.pn == 24 ? 1 : (u.pn == 26 ? 2 : 0);
	global_load_lds_dwordx4 v[152:153], off
	v_lshl_add_u64 v[152:153], v[206:207], 0, s[92:93]
	s_add_i32 m0, s45, 0x2000
	s_nop 0
	global_load_lds_dwordx4 v[152:153], off
	s_mov_b32 m0, s75
	v_lshl_add_u64 v[152:153], v[212:213], 0, s[92:93]
	ds_read_b128 v[162:165], v157 offset:49152
	ds_read_b128 v[166:169], v157 offset:50176
	ds_read_b128 v[170:173], v157 offset:51200
	ds_read_b128 v[174:177], v157 offset:52224
	ds_read_b128 v[178:181], v157 offset:53248
	ds_read_b128 v[182:185], v157 offset:54272
	ds_read_b128 v[186:189], v157 offset:55296
	ds_read_b128 v[190:193], v157 offset:56320
	global_load_lds_dwordx4 v[152:153], off
	v_lshl_add_u64 v[152:153], v[224:225], 0, s[92:93]
	s_mov_b32 m0, s76
	s_nop 0
	global_load_lds_dwordx4 v[152:153], off
	s_add_u32 s40, s40, 0x80080
	s_addc_u32 s41, s41, 0
	s_add_i32 s45, s48, s72
	v_lshl_add_u64 v[232:233], s[40:41], 0, v[0:1]
	s_mov_b32 m0, s45
	s_nop 0
	global_load_lds_dwordx4 v[232:233], off
	v_lshl_add_u64 v[232:233], s[40:41], 0, v[142:143]
	s_add_i32 m0, s45, 0x2000
	s_nop 0
	global_load_lds_dwordx4 v[232:233], off
	s_waitcnt vmcnt(6) lgkmcnt(0)
	s_barrier
	v_mfma_f32_16x16x32_f16 v[62:65], v[130:133], v[162:165], v[62:65]
	v_mfma_f32_16x16x32_f16 v[58:61], v[148:151], v[162:165], v[58:61]
	v_mfma_f32_16x16x32_f16 v[46:49], v[130:133], v[170:173], v[46:49]
	v_mfma_f32_16x16x32_f16 v[42:45], v[148:151], v[170:173], v[42:45]
	v_mfma_f32_16x16x32_f16 v[30:33], v[130:133], v[178:181], v[30:33]
	v_mfma_f32_16x16x32_f16 v[26:29], v[148:151], v[178:181], v[26:29]
	v_mfma_f32_16x16x32_f16 v[14:17], v[130:133], v[186:189], v[14:17]
	v_mfma_f32_16x16x32_f16 v[10:13], v[148:151], v[186:189], v[10:13]
	v_mfma_f32_16x16x32_f16 v[62:65], v[134:137], v[166:169], v[62:65]
	v_mfma_f32_16x16x32_f16 v[58:61], v[158:161], v[166:169], v[58:61]
	v_mfma_f32_16x16x32_f16 v[46:49], v[134:137], v[174:177], v[46:49]
	v_mfma_f32_16x16x32_f16 v[42:45], v[158:161], v[174:177], v[42:45]
	v_mfma_f32_16x16x32_f16 v[30:33], v[134:137], v[182:185], v[30:33]
	v_mfma_f32_16x16x32_f16 v[26:29], v[158:161], v[182:185], v[26:29]
	v_mfma_f32_16x16x32_f16 v[14:17], v[134:137], v[190:193], v[14:17]
	v_mfma_f32_16x16x32_f16 v[10:13], v[158:161], v[190:193], v[10:13]
	v_mfma_f32_16x16x32_f16 v[54:57], v[194:197], v[162:165], v[54:57]
	v_mfma_f32_16x16x32_f16 v[50:53], v[202:205], v[162:165], v[50:53]
	v_mfma_f32_16x16x32_f16 v[38:41], v[194:197], v[170:173], v[38:41]
	v_mfma_f32_16x16x32_f16 v[34:37], v[202:205], v[170:173], v[34:37]
	v_mfma_f32_16x16x32_f16 v[22:25], v[194:197], v[178:181], v[22:25]
	v_mfma_f32_16x16x32_f16 v[18:21], v[202:205], v[178:181], v[18:21]
	v_mfma_f32_16x16x32_f16 v[6:9], v[194:197], v[186:189], v[6:9]
	v_mfma_f32_16x16x32_f16 v[2:5], v[202:205], v[186:189], v[2:5]
	v_mfma_f32_16x16x32_f16 v[54:57], v[198:201], v[166:169], v[54:57]
	v_mfma_f32_16x16x32_f16 v[50:53], v[220:223], v[166:169], v[50:53]
	v_mfma_f32_16x16x32_f16 v[38:41], v[198:201], v[174:177], v[38:41]
	v_mfma_f32_16x16x32_f16 v[34:37], v[220:223], v[174:177], v[34:37]
	v_mfma_f32_16x16x32_f16 v[22:25], v[198:201], v[182:185], v[22:25]
	v_mfma_f32_16x16x32_f16 v[18:21], v[220:223], v[182:185], v[18:21]
	v_mfma_f32_16x16x32_f16 v[6:9], v[198:201], v[190:193], v[6:9]
	v_mfma_f32_16x16x32_f16 v[2:5], v[220:223], v[190:193], v[2:5]
	s_add_i32 s43, s43, 2
	s_add_u32 s0, s0, 0x100
	s_addc_u32 s1, s1, 0
	s_add_u32 s21, s21, 0x100
	s_addc_u32 s35, s35, 0
	s_cmp_gt_u32 s43, 29
	s_barrier
	s_cbranch_scc0 .LBB0_799
	s_cmp_eq_u32 s22, 26
	s_cselect_b32 s0, 2, 0
	s_cmp_lg_u32 s22, 24
	s_cselect_b32 s43, s0, 1
	s_cmp_gt_i32 s43, 1
	s_mov_b64 s[0:1], -1
	s_cbranch_scc0 .LBB0_802
; __device__ __forceinline__ float sigmoidf_(float x) { return 1.0f / (1.0f + __expf(-x)); }
;     __device__ __forceinline__ void operator()(const f32x4 (&acc)[2][2][4][2], const Unit& u, int wr, int wc, int fr, int fq) const {
;     ...
;                     if (mode == 1) {
; #pragma unroll
;                         for (int j = 0; j < 4; ++j) { v0[j] = 1.0f - 2.0f / (1.0f + __expf(2.0f * v0[j])); v1[j] = 1.0f - 2.0f / (1.0f + __expf(2.0f * v1[j])); } }
;                     else if (mode == 2) {
; #pragma unroll
;                         for (int j = 0; j < 4; ++j) { v0[j] = sigmoidf_(v0[j]); v1[j] = sigmoidf_(v1[j]); } }
	v_mul_f32_e32 v132, 0xbfb8aa3b, v123
	v_mul_f32_e32 v133, 0xbfb8aa3b, v124
	v_exp_f32_e32 v135, v132
	v_mul_f32_e32 v132, 0xbfb8aa3b, v128
	v_exp_f32_e32 v136, v133
	v_mul_f32_e32 v133, 0xbfb8aa3b, v129
	v_exp_f32_e32 v132, v132
	v_exp_f32_e32 v133, v133
	v_mul_f32_e32 v131, 0xbfb8aa3b, v122
	v_mul_f32_e32 v130, 0xbfb8aa3b, v126
	v_exp_f32_e32 v134, v131
	v_pk_add_f32 v[132:133], v[132:133], 1.0 op_sel_hi:[1,0]
	v_mul_f32_e32 v131, 0xbfb8aa3b, v127
	v_div_scale_f32 v137, s[0:1], v133, v133, 1.0
	v_rcp_f32_e32 v148, v137
	v_exp_f32_e32 v130, v130
	v_exp_f32_e32 v131, v131
	v_pk_add_f32 v[134:135], v[134:135], 1.0 op_sel_hi:[1,0]
	v_fma_f32 v149, -v137, v148, 1.0
	v_fmac_f32_e32 v148, v149, v148
	v_div_scale_f32 v149, vcc, 1.0, v133, 1.0
	v_mul_f32_e32 v150, v149, v148
	v_fma_f32 v151, -v137, v150, v149
	v_fmac_f32_e32 v150, v151, v148
	v_fma_f32 v137, -v137, v150, v149
	v_div_fmas_f32 v137, v137, v148, v150
	v_div_fixup_f32 v133, v137, v133, 1.0
	v_div_scale_f32 v137, s[0:1], v132, v132, 1.0
	v_rcp_f32_e32 v148, v137
	v_pk_add_f32 v[130:131], v[130:131], 1.0 op_sel_hi:[1,0]
	v_fma_f32 v149, -v137, v148, 1.0
	v_fmac_f32_e32 v148, v149, v148
	v_div_scale_f32 v149, vcc, 1.0, v132, 1.0
	v_mul_f32_e32 v150, v149, v148
	v_fma_f32 v151, -v137, v150, v149
	v_fmac_f32_e32 v150, v151, v148
	v_fma_f32 v137, -v137, v150, v149
	v_div_fmas_f32 v137, v137, v148, v150
	v_div_fixup_f32 v132, v137, v132, 1.0
	v_div_scale_f32 v137, s[0:1], v131, v131, 1.0
	v_rcp_f32_e32 v148, v137
	s_nop 0
	v_fma_f32 v149, -v137, v148, 1.0
	v_fmac_f32_e32 v148, v149, v148
	v_div_scale_f32 v149, vcc, 1.0, v131, 1.0
	v_mul_f32_e32 v150, v149, v148
	v_fma_f32 v151, -v137, v150, v149
	v_fmac_f32_e32 v150, v151, v148
	v_fma_f32 v137, -v137, v150, v149
	v_div_fmas_f32 v137, v137, v148, v150
	v_div_fixup_f32 v131, v137, v131, 1.0
	v_div_scale_f32 v137, s[0:1], v130, v130, 1.0
	v_rcp_f32_e32 v148, v137
	s_nop 0
	v_fma_f32 v149, -v137, v148, 1.0
	v_fmac_f32_e32 v148, v149, v148
	v_div_scale_f32 v149, vcc, 1.0, v130, 1.0
	v_mul_f32_e32 v150, v149, v148
	v_fma_f32 v151, -v137, v150, v149
	v_fmac_f32_e32 v150, v151, v148
	v_fma_f32 v137, -v137, v150, v149
	v_div_fmas_f32 v137, v137, v148, v150
	v_div_fixup_f32 v130, v137, v130, 1.0
	v_mul_f32_e32 v137, 0xbfb8aa3b, v125
	v_exp_f32_e32 v137, v137
	s_nop 0
	v_pk_add_f32 v[136:137], v[136:137], 1.0 op_sel_hi:[1,0]
	s_nop 0
	v_div_scale_f32 v148, s[0:1], v137, v137, 1.0
	v_rcp_f32_e32 v149, v148
	s_nop 0
	v_fma_f32 v150, -v148, v149, 1.0
	v_fmac_f32_e32 v149, v150, v149
	v_div_scale_f32 v150, vcc, 1.0, v137, 1.0
	v_mul_f32_e32 v151, v150, v149
	v_fma_f32 v152, -v148, v151, v150
	v_fmac_f32_e32 v151, v152, v149
	v_fma_f32 v148, -v148, v151, v150
	v_div_fmas_f32 v148, v148, v149, v151
	v_div_fixup_f32 v137, v148, v137, 1.0
	v_div_scale_f32 v148, s[0:1], v136, v136, 1.0
	v_rcp_f32_e32 v149, v148
	s_nop 0
	v_fma_f32 v150, -v148, v149, 1.0
	v_fmac_f32_e32 v149, v150, v149
	v_div_scale_f32 v150, vcc, 1.0, v136, 1.0
	v_mul_f32_e32 v151, v150, v149
	v_fma_f32 v152, -v148, v151, v150
	v_fmac_f32_e32 v151, v152, v149
	v_fma_f32 v148, -v148, v151, v150
	v_div_fmas_f32 v148, v148, v149, v151
	v_div_fixup_f32 v136, v148, v136, 1.0
	v_div_scale_f32 v148, s[0:1], v135, v135, 1.0
	v_rcp_f32_e32 v149, v148
	s_nop 0
	v_fma_f32 v150, -v148, v149, 1.0
	v_fmac_f32_e32 v149, v150, v149
	v_div_scale_f32 v150, vcc, 1.0, v135, 1.0
	v_mul_f32_e32 v151, v150, v149
	v_fma_f32 v152, -v148, v151, v150
	v_fmac_f32_e32 v151, v152, v149
	v_fma_f32 v148, -v148, v151, v150
	v_div_fmas_f32 v148, v148, v149, v151
	v_div_fixup_f32 v135, v148, v135, 1.0
	v_div_scale_f32 v148, s[0:1], v134, v134, 1.0
	v_rcp_f32_e32 v149, v148
	s_mov_b64 s[0:1], 0
	v_fma_f32 v150, -v148, v149, 1.0
	v_fmac_f32_e32 v149, v150, v149
	v_div_scale_f32 v150, vcc, 1.0, v134, 1.0
	v_mul_f32_e32 v151, v150, v149
	v_fma_f32 v152, -v148, v151, v150
	v_fmac_f32_e32 v151, v152, v149
	v_fma_f32 v148, -v148, v151, v150
	v_div_fmas_f32 v148, v148, v149, v151
	v_div_fixup_f32 v134, v148, v134, 1.0
